# early barrier K2 + trailing half re-offset barrier moved to just before next unit K-loop
# baseline (speedup 1.0000x reference)
_Z8mega_fwd4Args:
	s_mov_b32 s99, 0
	s_load_dwordx2 s[88:89], s[0:1], 0xb0
	s_load_dwordx4 s[4:7], s[0:1], 0xa0
	s_mov_b32 s72, s2
	s_add_u32 s2, s0, 0xc8
	s_addc_u32 s3, s1, 0
	s_waitcnt lgkmcnt(0)
	v_writelane_b32 v250, s4, 0
	s_nop 1
	v_writelane_b32 v250, s5, 1
	v_writelane_b32 v250, s6, 2
	v_writelane_b32 v250, s7, 3
	s_load_dwordx8 s[4:11], s[0:1], 0x80
	s_waitcnt lgkmcnt(0)
	v_writelane_b32 v250, s4, 4
	s_nop 1
	v_writelane_b32 v250, s5, 5
	v_writelane_b32 v250, s6, 6
	v_writelane_b32 v250, s7, 7
	v_writelane_b32 v250, s8, 8
	v_writelane_b32 v250, s9, 9
	v_writelane_b32 v250, s10, 10
	v_writelane_b32 v250, s11, 11
	s_load_dwordx4 s[4:7], s[0:1], 0xb8
	s_waitcnt lgkmcnt(0)
	v_writelane_b32 v250, s4, 12
	s_nop 1
	v_writelane_b32 v250, s5, 13
	v_writelane_b32 v250, s6, 14
	v_writelane_b32 v250, s7, 15
	v_writelane_b32 v250, s2, 16
	s_nop 1
	v_writelane_b32 v250, s3, 17
	s_movk_i32 s2, 0x200
	v_cmp_gt_u32_e32 vcc, s2, v0
	s_and_saveexec_b64 s[2:3], vcc
	v_lshl_add_u32 v1, v0, 2, 0
	v_add_u32_e32 v1, 0x24000, v1
	v_mov_b32_e32 v2, 0
	ds_write_b32 v1, v2
	s_or_b64 exec, exec, s[2:3]
	s_load_dword s38, s[0:1], 0xc8
	s_load_dwordx4 s[4:7], s[0:1], 0xb8
	s_waitcnt lgkmcnt(0)
	s_barrier
	v_cmp_eq_u32_e64 s[4:5], 0, v0
	s_mul_i32 s2, s6, 0xd80
	s_ashr_i32 s3, s2, 31
	s_lshl_b64 s[2:3], s[2:3], 2
	s_add_u32 s2, s88, s2
	s_addc_u32 s3, s89, s3
	s_add_u32 s90, s2, 0x4000
	s_getreg_b32 s2, hwreg(HW_REG_XCC_ID, 0, 4)
	s_addc_u32 s91, s3, 0
	s_and_b32 s39, s2, 15
	s_mov_b64 s[2:3], exec
	v_writelane_b32 v250, s4, 18
	s_nop 1
	v_writelane_b32 v250, s5, 19
	s_and_b64 s[4:5], s[2:3], s[4:5]
	s_mov_b64 exec, s[4:5]
	s_cbranch_execz .LBB0_5
	s_mov_b64 s[4:5], exec
	v_mbcnt_lo_u32_b32 v1, s4, 0
	v_mbcnt_hi_u32_b32 v1, s5, v1
	v_cmp_eq_u32_e32 vcc, 0, v1
	s_and_b64 s[6:7], exec, vcc
	s_mov_b64 exec, s[6:7]
	s_cbranch_execz .LBB0_5
	s_lshl_b32 s6, s39, 8
	s_bcnt1_i32_b64 s4, s[4:5]
	v_mov_b32_e32 v1, s6
	v_mov_b32_e32 v2, s4
	global_atomic_add v1, v2, s[90:91] offset:1024

.LBB0_343:
	s_ashr_i32 s11, s10, 31
	s_lshl_b64 s[12:13], s[10:11], 20
	s_add_u32 s12, s26, s12
	s_addc_u32 s13, s27, s13
	s_and_b64 s[14:15], s[2:3], exec
	s_cselect_b32 s11, s13, s21
	s_cselect_b32 s75, s12, s20
	s_ashr_i32 s9, s8, 31
	s_lshl_b64 s[14:15], s[8:9], 20
	s_add_u32 s14, s28, s14
	s_addc_u32 s15, s29, s15
	s_and_b64 s[22:23], s[2:3], exec
	s_cselect_b32 s9, s15, s19
	s_cselect_b32 s76, s14, s18
	s_add_u32 s77, s18, 0x100
	s_addc_u32 s78, s19, 0
	s_add_u32 s18, s20, 0x80080
	s_addc_u32 s19, s21, 0
	s_add_u32 s79, s20, 0x100
	v_mov_b32_e32 v2, 0
	s_addc_u32 s80, s21, 0
	s_mov_b32 s81, -2
	v_mov_b32_e32 v3, v2
	v_mov_b32_e32 v4, v2
	v_mov_b32_e32 v5, v2
	v_mov_b32_e32 v6, v2
	v_mov_b32_e32 v7, v2
	v_mov_b32_e32 v8, v2
	v_mov_b32_e32 v9, v2
	v_mov_b32_e32 v18, v2
	v_mov_b32_e32 v19, v2
	v_mov_b32_e32 v20, v2
	v_mov_b32_e32 v21, v2
	v_mov_b32_e32 v22, v2
	v_mov_b32_e32 v23, v2
	v_mov_b32_e32 v24, v2
	v_mov_b32_e32 v25, v2
	v_mov_b32_e32 v34, v2
	v_mov_b32_e32 v35, v2
	v_mov_b32_e32 v36, v2
	v_mov_b32_e32 v37, v2
	v_mov_b32_e32 v38, v2
	v_mov_b32_e32 v39, v2
	v_mov_b32_e32 v40, v2
	v_mov_b32_e32 v41, v2
	v_mov_b32_e32 v50, v2
	v_mov_b32_e32 v51, v2
	v_mov_b32_e32 v52, v2
	v_mov_b32_e32 v53, v2
	v_mov_b32_e32 v54, v2
	v_mov_b32_e32 v55, v2
	v_mov_b32_e32 v56, v2
	v_mov_b32_e32 v57, v2
	v_mov_b32_e32 v10, v2
	v_mov_b32_e32 v11, v2
	v_mov_b32_e32 v12, v2
	v_mov_b32_e32 v13, v2
	v_mov_b32_e32 v14, v2
	v_mov_b32_e32 v15, v2
	v_mov_b32_e32 v16, v2
	v_mov_b32_e32 v17, v2
	v_mov_b32_e32 v26, v2
	v_mov_b32_e32 v27, v2
	v_mov_b32_e32 v28, v2
	v_mov_b32_e32 v29, v2
	v_mov_b32_e32 v30, v2
	v_mov_b32_e32 v31, v2
	v_mov_b32_e32 v32, v2
	v_mov_b32_e32 v33, v2
	v_mov_b32_e32 v42, v2
	v_mov_b32_e32 v43, v2
	v_mov_b32_e32 v44, v2
	v_mov_b32_e32 v45, v2
	v_mov_b32_e32 v46, v2
	v_mov_b32_e32 v47, v2
	v_mov_b32_e32 v48, v2
	v_mov_b32_e32 v49, v2
	v_mov_b32_e32 v58, v2
	v_mov_b32_e32 v59, v2
	v_mov_b32_e32 v60, v2
	v_mov_b32_e32 v61, v2
	v_mov_b32_e32 v62, v2
	v_mov_b32_e32 v63, v2
	v_mov_b32_e32 v64, v2
	v_mov_b32_e32 v65, v2
	v_mov_b32_e32 v66, v2
	v_mov_b32_e32 v67, v2
	v_mov_b32_e32 v68, v2
	v_mov_b32_e32 v69, v2
	v_mov_b32_e32 v70, v2
	v_mov_b32_e32 v71, v2
	v_mov_b32_e32 v72, v2
	v_mov_b32_e32 v73, v2
	v_mov_b32_e32 v82, v2
	v_mov_b32_e32 v83, v2
	v_mov_b32_e32 v84, v2
	v_mov_b32_e32 v85, v2
	v_mov_b32_e32 v86, v2
	v_mov_b32_e32 v87, v2
	v_mov_b32_e32 v88, v2
	v_mov_b32_e32 v89, v2
	v_mov_b32_e32 v98, v2
	v_mov_b32_e32 v99, v2
	v_mov_b32_e32 v100, v2
	v_mov_b32_e32 v101, v2
	v_mov_b32_e32 v102, v2
	v_mov_b32_e32 v103, v2
	v_mov_b32_e32 v104, v2
	v_mov_b32_e32 v105, v2
	v_mov_b32_e32 v114, v2
	v_mov_b32_e32 v115, v2
	v_mov_b32_e32 v116, v2
	v_mov_b32_e32 v117, v2
	v_mov_b32_e32 v118, v2
	v_mov_b32_e32 v119, v2
	v_mov_b32_e32 v120, v2
	v_mov_b32_e32 v121, v2
	v_mov_b32_e32 v74, v2
	v_mov_b32_e32 v75, v2
	v_mov_b32_e32 v76, v2
	v_mov_b32_e32 v77, v2
	v_mov_b32_e32 v78, v2
	v_mov_b32_e32 v79, v2
	v_mov_b32_e32 v80, v2
	v_mov_b32_e32 v81, v2
	v_mov_b32_e32 v90, v2
	v_mov_b32_e32 v91, v2
	v_mov_b32_e32 v92, v2
	v_mov_b32_e32 v93, v2
	v_mov_b32_e32 v94, v2
	v_mov_b32_e32 v95, v2
	v_mov_b32_e32 v96, v2
	v_mov_b32_e32 v97, v2
	v_mov_b32_e32 v106, v2
	v_mov_b32_e32 v107, v2
	v_mov_b32_e32 v108, v2
	v_mov_b32_e32 v109, v2
	v_mov_b32_e32 v110, v2
	v_mov_b32_e32 v111, v2
	v_mov_b32_e32 v112, v2
	v_mov_b32_e32 v113, v2
	v_mov_b32_e32 v122, v2
	v_mov_b32_e32 v123, v2
	v_mov_b32_e32 v124, v2
	v_mov_b32_e32 v125, v2
	v_mov_b32_e32 v126, v2
	v_mov_b32_e32 v127, v2
	v_mov_b32_e32 v128, v2
	v_mov_b32_e32 v129, v2
	s_cmp_eq_u32 s99, 0
	s_cbranch_scc1 .Lro_skip_13
	s_barrier
	s_mov_b32 s99, 0
.Lro_skip_13:
.LBB0_344:
	ds_read_b128 v[148:151], v143
	ds_read_b128 v[152:155], v143 offset:1024
	ds_read_b128 v[156:159], v143 offset:2048
	ds_read_b128 v[160:163], v143 offset:3072
	ds_read_b128 v[164:167], v144
	ds_read_b128 v[168:171], v144 offset:1024
	ds_read_b128 v[172:175], v144 offset:2048
	ds_read_b128 v[176:179], v144 offset:3072
	s_cmp_eq_u32 s81, 28
	s_cselect_b32 s21, s9, s78
	s_cselect_b32 s20, s76, s77
	s_cselect_b32 s23, s11, s80
	s_cselect_b32 s22, s75, s79
	ds_read_b128 v[180:183], v145
	ds_read_b128 v[184:187], v145 offset:1024
	ds_read_b128 v[188:191], v145 offset:2048
	ds_read_b128 v[192:195], v145 offset:3072
	ds_read_b128 v[196:199], v145 offset:4096
	ds_read_b128 v[200:203], v145 offset:5120
	ds_read_b128 v[204:207], v145 offset:6144
	ds_read_b128 v[208:211], v145 offset:7168
	s_add_u32 s82, s18, 0xfff80000
	s_addc_u32 s83, s19, -1
	s_mov_b32 s86, m0
	s_mov_b32 m0, s64
	s_nop 0
	global_load_lds_dwordx4 v138, s[82:83]
	s_mov_b32 m0, s86
	s_nop 0
	s_mov_b32 s86, m0
	s_mov_b32 m0, s67
	s_nop 0
	global_load_lds_dwordx4 v140, s[82:83]
	s_mov_b32 m0, s86
	s_mov_b32 s82, m0
	s_mov_b32 m0, s65
	s_nop 0
	global_load_lds_dwordx4 v138, s[18:19]
	s_mov_b32 m0, s82
	s_nop 0
	s_mov_b32 s82, m0
	s_mov_b32 m0, s73
	s_nop 0
	global_load_lds_dwordx4 v140, s[18:19]
	s_mov_b32 m0, s82
	s_waitcnt vmcnt(8)
	s_waitcnt lgkmcnt(0)
	s_barrier
	s_setprio 1
	s_waitcnt lgkmcnt(7)
	v_mfma_f32_16x16x32_bf16 v[126:129], v[148:151], v[180:183], v[126:129]
	v_mfma_f32_16x16x32_bf16 v[122:125], v[156:159], v[180:183], v[122:125]
	s_waitcnt lgkmcnt(5)
	v_mfma_f32_16x16x32_bf16 v[110:113], v[148:151], v[188:191], v[110:113]
	v_mfma_f32_16x16x32_bf16 v[106:109], v[156:159], v[188:191], v[106:109]
	s_waitcnt lgkmcnt(3)
	v_mfma_f32_16x16x32_bf16 v[94:97], v[148:151], v[196:199], v[94:97]
	v_mfma_f32_16x16x32_bf16 v[90:93], v[156:159], v[196:199], v[90:93]
	s_waitcnt lgkmcnt(1)
	v_mfma_f32_16x16x32_bf16 v[78:81], v[148:151], v[204:207], v[78:81]
	v_mfma_f32_16x16x32_bf16 v[74:77], v[156:159], v[204:207], v[74:77]
	v_mfma_f32_16x16x32_bf16 v[126:129], v[152:155], v[184:187], v[126:129]
	v_mfma_f32_16x16x32_bf16 v[122:125], v[160:163], v[184:187], v[122:125]
	v_mfma_f32_16x16x32_bf16 v[110:113], v[152:155], v[192:195], v[110:113]
	v_mfma_f32_16x16x32_bf16 v[106:109], v[160:163], v[192:195], v[106:109]
	v_mfma_f32_16x16x32_bf16 v[94:97], v[152:155], v[200:203], v[94:97]
	v_mfma_f32_16x16x32_bf16 v[90:93], v[160:163], v[200:203], v[90:93]
	s_waitcnt lgkmcnt(0)
	v_mfma_f32_16x16x32_bf16 v[78:81], v[152:155], v[208:211], v[78:81]
	v_mfma_f32_16x16x32_bf16 v[74:77], v[160:163], v[208:211], v[74:77]
	s_setprio 0
	s_setprio 1
	v_mfma_f32_16x16x32_bf16 v[118:121], v[164:167], v[180:183], v[118:121]
	v_mfma_f32_16x16x32_bf16 v[114:117], v[172:175], v[180:183], v[114:117]
	v_mfma_f32_16x16x32_bf16 v[102:105], v[164:167], v[188:191], v[102:105]
	v_mfma_f32_16x16x32_bf16 v[98:101], v[172:175], v[188:191], v[98:101]
	v_mfma_f32_16x16x32_bf16 v[86:89], v[164:167], v[196:199], v[86:89]
	v_mfma_f32_16x16x32_bf16 v[82:85], v[172:175], v[196:199], v[82:85]
	v_mfma_f32_16x16x32_bf16 v[70:73], v[164:167], v[204:207], v[70:73]
	v_mfma_f32_16x16x32_bf16 v[66:69], v[172:175], v[204:207], v[66:69]
	v_mfma_f32_16x16x32_bf16 v[118:121], v[168:171], v[184:187], v[118:121]
	v_mfma_f32_16x16x32_bf16 v[114:117], v[176:179], v[184:187], v[114:117]
	v_mfma_f32_16x16x32_bf16 v[102:105], v[168:171], v[192:195], v[102:105]
	v_mfma_f32_16x16x32_bf16 v[98:101], v[176:179], v[192:195], v[98:101]
	v_mfma_f32_16x16x32_bf16 v[86:89], v[168:171], v[200:203], v[86:89]
	v_mfma_f32_16x16x32_bf16 v[82:85], v[176:179], v[200:203], v[82:85]
	s_setprio 2
	s_barrier
	v_mfma_f32_16x16x32_bf16 v[70:73], v[168:171], v[208:211], v[70:73]
	v_mfma_f32_16x16x32_bf16 v[66:69], v[176:179], v[208:211], v[66:69]
	s_setprio 0
	ds_read_b128 v[180:183], v145 offset:16384
	ds_read_b128 v[184:187], v145 offset:17408
	ds_read_b128 v[188:191], v145 offset:18432
	ds_read_b128 v[192:195], v145 offset:19456
	ds_read_b128 v[196:199], v145 offset:20480
	ds_read_b128 v[200:203], v145 offset:21504
	ds_read_b128 v[204:207], v145 offset:22528
	ds_read_b128 v[208:211], v145 offset:23552
	s_mov_b32 s82, m0
	s_mov_b32 m0, s35
	s_nop 0
	global_load_lds_dwordx4 v139, s[20:21]
	s_mov_b32 m0, s82
	s_nop 0
	s_mov_b32 s82, m0
	s_mov_b32 m0, s36
	s_nop 0
	global_load_lds_dwordx4 v141, s[20:21]
	s_mov_b32 m0, s82
	s_add_u32 s82, s20, 0x80000
	s_addc_u32 s83, s21, 0
	s_mov_b32 s86, m0
	s_mov_b32 m0, s37
	s_nop 0
	global_load_lds_dwordx4 v139, s[82:83]
	s_mov_b32 m0, s86
	s_nop 0
	s_mov_b32 s86, m0
	s_mov_b32 m0, s42
	s_nop 0
	global_load_lds_dwordx4 v141, s[82:83]
	s_mov_b32 m0, s86
	s_waitcnt vmcnt(4)
	s_waitcnt lgkmcnt(0)
	s_barrier
	s_setprio 1
	s_waitcnt lgkmcnt(7)
	v_mfma_f32_16x16x32_bf16 v[62:65], v[148:151], v[180:183], v[62:65]
	v_mfma_f32_16x16x32_bf16 v[58:61], v[156:159], v[180:183], v[58:61]
	s_waitcnt lgkmcnt(5)
	v_mfma_f32_16x16x32_bf16 v[46:49], v[148:151], v[188:191], v[46:49]
	v_mfma_f32_16x16x32_bf16 v[42:45], v[156:159], v[188:191], v[42:45]
	s_waitcnt lgkmcnt(3)
	v_mfma_f32_16x16x32_bf16 v[30:33], v[148:151], v[196:199], v[30:33]
	v_mfma_f32_16x16x32_bf16 v[26:29], v[156:159], v[196:199], v[26:29]
	s_waitcnt lgkmcnt(1)
	v_mfma_f32_16x16x32_bf16 v[14:17], v[148:151], v[204:207], v[14:17]
	v_mfma_f32_16x16x32_bf16 v[10:13], v[156:159], v[204:207], v[10:13]
	v_mfma_f32_16x16x32_bf16 v[62:65], v[152:155], v[184:187], v[62:65]
	v_mfma_f32_16x16x32_bf16 v[58:61], v[160:163], v[184:187], v[58:61]
	v_mfma_f32_16x16x32_bf16 v[46:49], v[152:155], v[192:195], v[46:49]
	v_mfma_f32_16x16x32_bf16 v[42:45], v[160:163], v[192:195], v[42:45]
	v_mfma_f32_16x16x32_bf16 v[30:33], v[152:155], v[200:203], v[30:33]
	v_mfma_f32_16x16x32_bf16 v[26:29], v[160:163], v[200:203], v[26:29]
	s_waitcnt lgkmcnt(0)
	v_mfma_f32_16x16x32_bf16 v[14:17], v[152:155], v[208:211], v[14:17]
	v_mfma_f32_16x16x32_bf16 v[10:13], v[160:163], v[208:211], v[10:13]
	s_setprio 0
	s_setprio 1
	v_mfma_f32_16x16x32_bf16 v[54:57], v[164:167], v[180:183], v[54:57]
	v_mfma_f32_16x16x32_bf16 v[50:53], v[172:175], v[180:183], v[50:53]
	v_mfma_f32_16x16x32_bf16 v[38:41], v[164:167], v[188:191], v[38:41]
	v_mfma_f32_16x16x32_bf16 v[34:37], v[172:175], v[188:191], v[34:37]
	v_mfma_f32_16x16x32_bf16 v[22:25], v[164:167], v[196:199], v[22:25]
	v_mfma_f32_16x16x32_bf16 v[18:21], v[172:175], v[196:199], v[18:21]
	v_mfma_f32_16x16x32_bf16 v[6:9], v[164:167], v[204:207], v[6:9]
	v_mfma_f32_16x16x32_bf16 v[2:5], v[172:175], v[204:207], v[2:5]
	v_mfma_f32_16x16x32_bf16 v[54:57], v[168:171], v[184:187], v[54:57]
	v_mfma_f32_16x16x32_bf16 v[50:53], v[176:179], v[184:187], v[50:53]
	v_mfma_f32_16x16x32_bf16 v[38:41], v[168:171], v[192:195], v[38:41]
	v_mfma_f32_16x16x32_bf16 v[34:37], v[176:179], v[192:195], v[34:37]
	v_mfma_f32_16x16x32_bf16 v[22:25], v[168:171], v[200:203], v[22:25]
	v_mfma_f32_16x16x32_bf16 v[18:21], v[176:179], v[200:203], v[18:21]
	s_setprio 2
	s_barrier
	v_mfma_f32_16x16x32_bf16 v[6:9], v[168:171], v[208:211], v[6:9]
	v_mfma_f32_16x16x32_bf16 v[2:5], v[176:179], v[208:211], v[2:5]
	s_setprio 0
	ds_read_b128 v[148:151], v146
	ds_read_b128 v[152:155], v146 offset:1024
	ds_read_b128 v[156:159], v146 offset:2048
	ds_read_b128 v[160:163], v146 offset:3072
	ds_read_b128 v[164:167], v147
	ds_read_b128 v[168:171], v147 offset:1024
	ds_read_b128 v[172:175], v147 offset:2048
	ds_read_b128 v[176:179], v147 offset:3072
	ds_read_b128 v[180:183], v145 offset:32768
	ds_read_b128 v[184:187], v145 offset:33792
	ds_read_b128 v[188:191], v145 offset:34816
	ds_read_b128 v[192:195], v145 offset:35840
	ds_read_b128 v[196:199], v145 offset:36864
	ds_read_b128 v[200:203], v145 offset:37888
	ds_read_b128 v[204:207], v145 offset:38912
	ds_read_b128 v[208:211], v145 offset:39936
	s_mov_b32 s82, m0
	s_mov_b32 m0, s31
	s_nop 0
	global_load_lds_dwordx4 v138, s[22:23]
	s_mov_b32 m0, s82
	s_nop 0
	s_mov_b32 s82, m0
	s_mov_b32 m0, s43
	s_nop 0
	global_load_lds_dwordx4 v140, s[22:23]
	s_mov_b32 m0, s82
	s_add_u32 s22, s22, 0x80000
	s_addc_u32 s23, s23, 0
	s_mov_b32 s82, m0
	s_mov_b32 m0, s46
	s_nop 0
	global_load_lds_dwordx4 v138, s[22:23]
	s_mov_b32 m0, s82
	s_nop 0
	s_mov_b32 s82, m0
	s_mov_b32 m0, s47
	s_nop 0
	global_load_lds_dwordx4 v140, s[22:23]
	s_mov_b32 m0, s82
	s_waitcnt vmcnt(8)
	s_waitcnt lgkmcnt(0)
	s_barrier
	s_setprio 1
	s_waitcnt lgkmcnt(7)
	v_mfma_f32_16x16x32_bf16 v[126:129], v[148:151], v[180:183], v[126:129]
	v_mfma_f32_16x16x32_bf16 v[122:125], v[156:159], v[180:183], v[122:125]
	s_waitcnt lgkmcnt(5)
	v_mfma_f32_16x16x32_bf16 v[110:113], v[148:151], v[188:191], v[110:113]
	v_mfma_f32_16x16x32_bf16 v[106:109], v[156:159], v[188:191], v[106:109]
	s_waitcnt lgkmcnt(3)
	v_mfma_f32_16x16x32_bf16 v[94:97], v[148:151], v[196:199], v[94:97]
	v_mfma_f32_16x16x32_bf16 v[90:93], v[156:159], v[196:199], v[90:93]
	s_waitcnt lgkmcnt(1)
	v_mfma_f32_16x16x32_bf16 v[78:81], v[148:151], v[204:207], v[78:81]
	v_mfma_f32_16x16x32_bf16 v[74:77], v[156:159], v[204:207], v[74:77]
	v_mfma_f32_16x16x32_bf16 v[126:129], v[152:155], v[184:187], v[126:129]
	v_mfma_f32_16x16x32_bf16 v[122:125], v[160:163], v[184:187], v[122:125]
	v_mfma_f32_16x16x32_bf16 v[110:113], v[152:155], v[192:195], v[110:113]
	v_mfma_f32_16x16x32_bf16 v[106:109], v[160:163], v[192:195], v[106:109]
	v_mfma_f32_16x16x32_bf16 v[94:97], v[152:155], v[200:203], v[94:97]
	v_mfma_f32_16x16x32_bf16 v[90:93], v[160:163], v[200:203], v[90:93]
	s_waitcnt lgkmcnt(0)
	v_mfma_f32_16x16x32_bf16 v[78:81], v[152:155], v[208:211], v[78:81]
	v_mfma_f32_16x16x32_bf16 v[74:77], v[160:163], v[208:211], v[74:77]
	s_setprio 0
	s_setprio 1
	v_mfma_f32_16x16x32_bf16 v[118:121], v[164:167], v[180:183], v[118:121]
	v_mfma_f32_16x16x32_bf16 v[114:117], v[172:175], v[180:183], v[114:117]
	v_mfma_f32_16x16x32_bf16 v[102:105], v[164:167], v[188:191], v[102:105]
	v_mfma_f32_16x16x32_bf16 v[98:101], v[172:175], v[188:191], v[98:101]
	v_mfma_f32_16x16x32_bf16 v[86:89], v[164:167], v[196:199], v[86:89]
	v_mfma_f32_16x16x32_bf16 v[82:85], v[172:175], v[196:199], v[82:85]
	v_mfma_f32_16x16x32_bf16 v[70:73], v[164:167], v[204:207], v[70:73]
	v_mfma_f32_16x16x32_bf16 v[66:69], v[172:175], v[204:207], v[66:69]
	v_mfma_f32_16x16x32_bf16 v[118:121], v[168:171], v[184:187], v[118:121]
	v_mfma_f32_16x16x32_bf16 v[114:117], v[176:179], v[184:187], v[114:117]
	v_mfma_f32_16x16x32_bf16 v[102:105], v[168:171], v[192:195], v[102:105]
	v_mfma_f32_16x16x32_bf16 v[98:101], v[176:179], v[192:195], v[98:101]
	v_mfma_f32_16x16x32_bf16 v[86:89], v[168:171], v[200:203], v[86:89]
	v_mfma_f32_16x16x32_bf16 v[82:85], v[176:179], v[200:203], v[82:85]
	s_setprio 2
	s_barrier
	v_mfma_f32_16x16x32_bf16 v[70:73], v[168:171], v[208:211], v[70:73]
	v_mfma_f32_16x16x32_bf16 v[66:69], v[176:179], v[208:211], v[66:69]
	s_setprio 0
	ds_read_b128 v[180:183], v145 offset:49152
	ds_read_b128 v[184:187], v145 offset:50176
	ds_read_b128 v[188:191], v145 offset:51200
	ds_read_b128 v[192:195], v145 offset:52224
	ds_read_b128 v[196:199], v145 offset:53248
	ds_read_b128 v[200:203], v145 offset:54272
	ds_read_b128 v[204:207], v145 offset:55296
	ds_read_b128 v[208:211], v145 offset:56320
	s_add_u32 s22, s20, 0x80
	s_addc_u32 s23, s21, 0
	s_mov_b32 s82, m0
	s_mov_b32 m0, s48
	s_nop 0
	global_load_lds_dwordx4 v139, s[22:23]
	s_mov_b32 m0, s82
	s_add_u32 s20, s20, 0x80080
	s_mov_b32 s82, m0
	s_mov_b32 m0, s49
	s_nop 0
	global_load_lds_dwordx4 v141, s[22:23]
	s_mov_b32 m0, s82
	s_addc_u32 s21, s21, 0
	s_mov_b32 s22, m0
	s_mov_b32 m0, s56
	s_nop 0
	global_load_lds_dwordx4 v139, s[20:21]
	s_mov_b32 m0, s22
	s_nop 0
	s_mov_b32 s22, m0
	s_mov_b32 m0, s57
	s_nop 0
	global_load_lds_dwordx4 v141, s[20:21]
	s_mov_b32 m0, s22
	s_waitcnt vmcnt(4)
	s_waitcnt lgkmcnt(0)
	s_barrier
	s_setprio 1
	s_waitcnt lgkmcnt(7)
	v_mfma_f32_16x16x32_bf16 v[62:65], v[148:151], v[180:183], v[62:65]
	v_mfma_f32_16x16x32_bf16 v[58:61], v[156:159], v[180:183], v[58:61]
	s_waitcnt lgkmcnt(5)
	v_mfma_f32_16x16x32_bf16 v[46:49], v[148:151], v[188:191], v[46:49]
	v_mfma_f32_16x16x32_bf16 v[42:45], v[156:159], v[188:191], v[42:45]
	s_waitcnt lgkmcnt(3)
	v_mfma_f32_16x16x32_bf16 v[30:33], v[148:151], v[196:199], v[30:33]
	v_mfma_f32_16x16x32_bf16 v[26:29], v[156:159], v[196:199], v[26:29]
	s_waitcnt lgkmcnt(1)
	v_mfma_f32_16x16x32_bf16 v[14:17], v[148:151], v[204:207], v[14:17]
	v_mfma_f32_16x16x32_bf16 v[10:13], v[156:159], v[204:207], v[10:13]
	v_mfma_f32_16x16x32_bf16 v[62:65], v[152:155], v[184:187], v[62:65]
	v_mfma_f32_16x16x32_bf16 v[58:61], v[160:163], v[184:187], v[58:61]
	v_mfma_f32_16x16x32_bf16 v[46:49], v[152:155], v[192:195], v[46:49]
	v_mfma_f32_16x16x32_bf16 v[42:45], v[160:163], v[192:195], v[42:45]
	v_mfma_f32_16x16x32_bf16 v[30:33], v[152:155], v[200:203], v[30:33]
	v_mfma_f32_16x16x32_bf16 v[26:29], v[160:163], v[200:203], v[26:29]
	s_waitcnt lgkmcnt(0)
	v_mfma_f32_16x16x32_bf16 v[14:17], v[152:155], v[208:211], v[14:17]
	v_mfma_f32_16x16x32_bf16 v[10:13], v[160:163], v[208:211], v[10:13]
	s_setprio 0
	s_setprio 1
	v_mfma_f32_16x16x32_bf16 v[54:57], v[164:167], v[180:183], v[54:57]
	v_mfma_f32_16x16x32_bf16 v[50:53], v[172:175], v[180:183], v[50:53]
	v_mfma_f32_16x16x32_bf16 v[38:41], v[164:167], v[188:191], v[38:41]
	v_mfma_f32_16x16x32_bf16 v[34:37], v[172:175], v[188:191], v[34:37]
	v_mfma_f32_16x16x32_bf16 v[22:25], v[164:167], v[196:199], v[22:25]
	v_mfma_f32_16x16x32_bf16 v[18:21], v[172:175], v[196:199], v[18:21]
	v_mfma_f32_16x16x32_bf16 v[6:9], v[164:167], v[204:207], v[6:9]
	v_mfma_f32_16x16x32_bf16 v[2:5], v[172:175], v[204:207], v[2:5]
	v_mfma_f32_16x16x32_bf16 v[54:57], v[168:171], v[184:187], v[54:57]
	v_mfma_f32_16x16x32_bf16 v[50:53], v[176:179], v[184:187], v[50:53]
	v_mfma_f32_16x16x32_bf16 v[38:41], v[168:171], v[192:195], v[38:41]
	v_mfma_f32_16x16x32_bf16 v[34:37], v[176:179], v[192:195], v[34:37]
	v_mfma_f32_16x16x32_bf16 v[22:25], v[168:171], v[200:203], v[22:25]
	v_mfma_f32_16x16x32_bf16 v[18:21], v[176:179], v[200:203], v[18:21]
	s_setprio 2
	s_barrier
	v_mfma_f32_16x16x32_bf16 v[6:9], v[168:171], v[208:211], v[6:9]
	v_mfma_f32_16x16x32_bf16 v[2:5], v[176:179], v[208:211], v[2:5]
	s_setprio 0
	s_add_i32 s81, s81, 2
	s_add_u32 s77, s77, 0x100
	s_addc_u32 s78, s78, 0
	s_add_u32 s18, s18, 0x100
	s_addc_u32 s19, s19, 0
	s_add_u32 s79, s79, 0x100
	s_addc_u32 s80, s80, 0
	s_cmp_gt_u32 s81, 29
	s_cbranch_scc0 .LBB0_344
	s_and_b64 vcc, exec, s[6:7]
	s_cbranch_vccz .LBB0_347
	s_barrier
.LBB0_347:
	v_exp_f32_e32 v150, v126
	v_exp_f32_e32 v152, v122
	v_exp_f32_e32 v151, v127
	v_exp_f32_e32 v156, v124
	v_exp_f32_e32 v157, v125
	v_exp_f32_e32 v153, v123
	v_exp_f32_e32 v154, v128
	v_exp_f32_e32 v155, v129
	s_lshl_b32 s9, s17, 1
	v_pk_add_f32 v[150:151], v[150:151], 1.0 op_sel_hi:[1,0]
	v_pk_add_f32 v[156:157], v[156:157], 1.0 op_sel_hi:[1,0]
	v_pk_add_f32 v[152:153], v[152:153], 1.0 op_sel_hi:[1,0]
	v_lshl_add_u32 v136, s16, 8, v142
	s_or_b32 s16, s9, s66
	v_rcp_f32_e32 v150, v150
	v_rcp_f32_e32 v152, v152
	v_rcp_f32_e32 v151, v151
	v_rcp_f32_e32 v153, v153
	v_rcp_f32_e32 v156, v156
	v_rcp_f32_e32 v157, v157
	s_ashr_i32 s17, s16, 31
	v_pk_add_f32 v[154:155], v[154:155], 1.0 op_sel_hi:[1,0]
	s_lshl_b64 s[16:17], s[16:17], 14
	v_ashrrev_i32_e32 v137, 31, v136
	v_rcp_f32_e32 v154, v154
	v_rcp_f32_e32 v155, v155
	v_lshl_add_u64 v[148:149], s[16:17], 0, v[136:137]
	v_pk_mul_f32 v[118:119], v[126:127], v[118:119]
	v_pk_mul_f32 v[116:117], v[124:125], v[116:117]
	v_pk_mul_f32 v[114:115], v[122:123], v[114:115]
	v_lshlrev_b64 v[148:149], 7, v[148:149]
	v_pk_mul_f32 v[118:119], v[150:151], v[118:119]
	v_pk_mul_f32 v[122:123], v[156:157], v[116:117]
	v_pk_mul_f32 v[116:117], v[152:153], v[114:115]
	v_lshl_add_u64 v[148:149], v[130:131], 0, v[148:149]
	v_pk_mul_f32 v[120:121], v[128:129], v[120:121]
	v_cvt_pk_bf16_f32 v114, v118, v119
	v_cvt_pk_bf16_f32 v116, v116, v117
	v_cvt_pk_bf16_f32 v117, v122, v123
	v_exp_f32_e32 v118, v106
	v_exp_f32_e32 v122, v108
	v_exp_f32_e32 v123, v109
	v_exp_f32_e32 v119, v107
	v_pk_mul_f32 v[120:121], v[154:155], v[120:121]
	v_pk_mul_f32 v[100:101], v[108:109], v[100:101]
	v_cvt_pk_bf16_f32 v115, v120, v121
	global_store_dwordx4 v[148:149], v[114:117], off
	v_exp_f32_e32 v120, v112
	v_exp_f32_e32 v121, v113
	v_exp_f32_e32 v116, v110
	v_exp_f32_e32 v117, v111
	v_pk_add_f32 v[122:123], v[122:123], 1.0 op_sel_hi:[1,0]
	v_pk_add_f32 v[118:119], v[118:119], 1.0 op_sel_hi:[1,0]
	v_rcp_f32_e32 v122, v122
	v_pk_add_f32 v[116:117], v[116:117], 1.0 op_sel_hi:[1,0]
	v_rcp_f32_e32 v118, v118
	v_rcp_f32_e32 v119, v119
	v_rcp_f32_e32 v123, v123
	v_or_b32_e32 v114, 16, v136
	v_pk_add_f32 v[120:121], v[120:121], 1.0 op_sel_hi:[1,0]
	v_rcp_f32_e32 v116, v116
	v_rcp_f32_e32 v117, v117
	v_ashrrev_i32_e32 v115, 31, v114
	v_rcp_f32_e32 v120, v120
	v_rcp_f32_e32 v121, v121
	v_lshl_add_u64 v[114:115], s[16:17], 0, v[114:115]
	v_pk_mul_f32 v[98:99], v[106:107], v[98:99]
	v_lshlrev_b64 v[114:115], 7, v[114:115]
	v_pk_mul_f32 v[102:103], v[110:111], v[102:103]
	v_pk_mul_f32 v[106:107], v[122:123], v[100:101]
	v_pk_mul_f32 v[100:101], v[118:119], v[98:99]
	v_lshl_add_u64 v[114:115], v[130:131], 0, v[114:115]
	v_pk_mul_f32 v[104:105], v[112:113], v[104:105]
	v_pk_mul_f32 v[102:103], v[116:117], v[102:103]
	v_cvt_pk_bf16_f32 v100, v100, v101
	v_cvt_pk_bf16_f32 v101, v106, v107
	v_pk_mul_f32 v[104:105], v[120:121], v[104:105]
	v_cvt_pk_bf16_f32 v98, v102, v103
	v_exp_f32_e32 v102, v90
	v_cvt_pk_bf16_f32 v99, v104, v105
	global_store_dwordx4 v[114:115], v[98:101], off
	v_exp_f32_e32 v106, v92
	v_exp_f32_e32 v107, v93
	v_exp_f32_e32 v100, v94
	v_exp_f32_e32 v101, v95
	v_exp_f32_e32 v103, v91
	v_exp_f32_e32 v104, v96
	v_exp_f32_e32 v105, v97
	v_pk_add_f32 v[100:101], v[100:101], 1.0 op_sel_hi:[1,0]
	v_pk_add_f32 v[106:107], v[106:107], 1.0 op_sel_hi:[1,0]
	v_pk_add_f32 v[102:103], v[102:103], 1.0 op_sel_hi:[1,0]
	v_rcp_f32_e32 v100, v100
	v_rcp_f32_e32 v102, v102
	v_rcp_f32_e32 v101, v101
	v_rcp_f32_e32 v103, v103
	v_rcp_f32_e32 v106, v106
	v_rcp_f32_e32 v107, v107
	v_or_b32_e32 v98, 32, v136
	v_pk_add_f32 v[104:105], v[104:105], 1.0 op_sel_hi:[1,0]
	v_ashrrev_i32_e32 v99, 31, v98
	v_rcp_f32_e32 v104, v104
	v_rcp_f32_e32 v105, v105
	v_lshl_add_u64 v[98:99], s[16:17], 0, v[98:99]
	v_pk_mul_f32 v[86:87], v[94:95], v[86:87]
	v_pk_mul_f32 v[84:85], v[92:93], v[84:85]
	v_pk_mul_f32 v[82:83], v[90:91], v[82:83]
	v_lshlrev_b64 v[98:99], 7, v[98:99]
	v_pk_mul_f32 v[86:87], v[100:101], v[86:87]
	v_pk_mul_f32 v[90:91], v[106:107], v[84:85]
	v_pk_mul_f32 v[84:85], v[102:103], v[82:83]
	v_lshl_add_u64 v[98:99], v[130:131], 0, v[98:99]
	v_pk_mul_f32 v[88:89], v[96:97], v[88:89]
	v_cvt_pk_bf16_f32 v82, v86, v87
	v_cvt_pk_bf16_f32 v84, v84, v85
	v_cvt_pk_bf16_f32 v85, v90, v91
	v_exp_f32_e32 v86, v74
	v_exp_f32_e32 v90, v76
	v_exp_f32_e32 v91, v77
	v_exp_f32_e32 v87, v75
	v_pk_mul_f32 v[88:89], v[104:105], v[88:89]
	v_pk_mul_f32 v[68:69], v[76:77], v[68:69]
	v_cvt_pk_bf16_f32 v83, v88, v89
	global_store_dwordx4 v[98:99], v[82:85], off
	v_exp_f32_e32 v88, v80
	v_exp_f32_e32 v89, v81
	v_exp_f32_e32 v84, v78
	v_exp_f32_e32 v85, v79
	v_pk_add_f32 v[90:91], v[90:91], 1.0 op_sel_hi:[1,0]
	v_pk_add_f32 v[86:87], v[86:87], 1.0 op_sel_hi:[1,0]
	v_rcp_f32_e32 v90, v90
	v_pk_add_f32 v[84:85], v[84:85], 1.0 op_sel_hi:[1,0]
	v_rcp_f32_e32 v86, v86
	v_rcp_f32_e32 v87, v87
	v_rcp_f32_e32 v91, v91
	v_or_b32_e32 v82, 48, v136
	v_pk_add_f32 v[88:89], v[88:89], 1.0 op_sel_hi:[1,0]
	v_rcp_f32_e32 v84, v84
	v_rcp_f32_e32 v85, v85
	v_ashrrev_i32_e32 v83, 31, v82
	v_rcp_f32_e32 v88, v88
	v_rcp_f32_e32 v89, v89
	v_lshl_add_u64 v[82:83], s[16:17], 0, v[82:83]
	v_pk_mul_f32 v[66:67], v[74:75], v[66:67]
	v_lshlrev_b64 v[82:83], 7, v[82:83]
	v_pk_mul_f32 v[70:71], v[78:79], v[70:71]
	v_pk_mul_f32 v[74:75], v[90:91], v[68:69]
	v_pk_mul_f32 v[68:69], v[86:87], v[66:67]
	v_lshl_add_u64 v[82:83], v[130:131], 0, v[82:83]
	v_pk_mul_f32 v[72:73], v[80:81], v[72:73]
	v_pk_mul_f32 v[70:71], v[84:85], v[70:71]
	v_cvt_pk_bf16_f32 v68, v68, v69
	v_cvt_pk_bf16_f32 v69, v74, v75
	v_pk_mul_f32 v[72:73], v[88:89], v[72:73]
	v_cvt_pk_bf16_f32 v66, v70, v71
	v_exp_f32_e32 v70, v58
	v_cvt_pk_bf16_f32 v67, v72, v73
	global_store_dwordx4 v[82:83], v[66:69], off
	v_exp_f32_e32 v74, v60
	v_exp_f32_e32 v75, v61
	v_exp_f32_e32 v68, v62
	v_exp_f32_e32 v69, v63
	v_exp_f32_e32 v71, v59
	v_exp_f32_e32 v72, v64
	v_exp_f32_e32 v73, v65
	v_pk_add_f32 v[68:69], v[68:69], 1.0 op_sel_hi:[1,0]
	v_pk_add_f32 v[74:75], v[74:75], 1.0 op_sel_hi:[1,0]
	v_pk_add_f32 v[70:71], v[70:71], 1.0 op_sel_hi:[1,0]
	v_rcp_f32_e32 v68, v68
	v_rcp_f32_e32 v70, v70
	v_rcp_f32_e32 v69, v69
	v_rcp_f32_e32 v71, v71
	v_rcp_f32_e32 v74, v74
	v_rcp_f32_e32 v75, v75
	v_add_u32_e32 v66, 0x80, v136
	v_pk_add_f32 v[72:73], v[72:73], 1.0 op_sel_hi:[1,0]
	v_ashrrev_i32_e32 v67, 31, v66
	v_rcp_f32_e32 v72, v72
	v_rcp_f32_e32 v73, v73
	v_lshl_add_u64 v[66:67], s[16:17], 0, v[66:67]
	v_pk_mul_f32 v[54:55], v[62:63], v[54:55]
	v_pk_mul_f32 v[52:53], v[60:61], v[52:53]
	v_pk_mul_f32 v[50:51], v[58:59], v[50:51]
	v_lshlrev_b64 v[66:67], 7, v[66:67]
	v_pk_mul_f32 v[54:55], v[68:69], v[54:55]
	v_pk_mul_f32 v[58:59], v[74:75], v[52:53]
	v_pk_mul_f32 v[52:53], v[70:71], v[50:51]
	v_lshl_add_u64 v[66:67], v[130:131], 0, v[66:67]
	v_pk_mul_f32 v[56:57], v[64:65], v[56:57]
	v_cvt_pk_bf16_f32 v50, v54, v55
	v_cvt_pk_bf16_f32 v52, v52, v53
	v_cvt_pk_bf16_f32 v53, v58, v59
	v_exp_f32_e32 v54, v42
	v_exp_f32_e32 v58, v44
	v_exp_f32_e32 v59, v45
	v_exp_f32_e32 v55, v43
	v_pk_mul_f32 v[56:57], v[72:73], v[56:57]
	v_pk_mul_f32 v[36:37], v[44:45], v[36:37]
	v_cvt_pk_bf16_f32 v51, v56, v57
	global_store_dwordx4 v[66:67], v[50:53], off
	v_exp_f32_e32 v56, v48
	v_exp_f32_e32 v57, v49
	v_exp_f32_e32 v52, v46
	v_exp_f32_e32 v53, v47
	v_pk_add_f32 v[58:59], v[58:59], 1.0 op_sel_hi:[1,0]
	v_pk_add_f32 v[54:55], v[54:55], 1.0 op_sel_hi:[1,0]
	v_rcp_f32_e32 v58, v58
	v_pk_add_f32 v[52:53], v[52:53], 1.0 op_sel_hi:[1,0]
	v_rcp_f32_e32 v54, v54
	v_rcp_f32_e32 v55, v55
	v_rcp_f32_e32 v59, v59
	v_add_u32_e32 v50, 0x90, v136
	v_pk_add_f32 v[56:57], v[56:57], 1.0 op_sel_hi:[1,0]
	v_rcp_f32_e32 v52, v52
	v_rcp_f32_e32 v53, v53
	v_ashrrev_i32_e32 v51, 31, v50
	v_rcp_f32_e32 v56, v56
	v_rcp_f32_e32 v57, v57
	v_lshl_add_u64 v[50:51], s[16:17], 0, v[50:51]
	v_pk_mul_f32 v[34:35], v[42:43], v[34:35]
	v_lshlrev_b64 v[50:51], 7, v[50:51]
	v_pk_mul_f32 v[38:39], v[46:47], v[38:39]
	v_pk_mul_f32 v[42:43], v[58:59], v[36:37]
	v_pk_mul_f32 v[36:37], v[54:55], v[34:35]
	v_lshl_add_u64 v[50:51], v[130:131], 0, v[50:51]
	v_pk_mul_f32 v[40:41], v[48:49], v[40:41]
	v_pk_mul_f32 v[38:39], v[52:53], v[38:39]
	v_cvt_pk_bf16_f32 v36, v36, v37
	v_cvt_pk_bf16_f32 v37, v42, v43
	v_pk_mul_f32 v[40:41], v[56:57], v[40:41]
	v_cvt_pk_bf16_f32 v34, v38, v39
	v_exp_f32_e32 v38, v26
	v_cvt_pk_bf16_f32 v35, v40, v41
	global_store_dwordx4 v[50:51], v[34:37], off
	v_exp_f32_e32 v42, v28
	v_exp_f32_e32 v43, v29
	v_exp_f32_e32 v36, v30
	v_exp_f32_e32 v37, v31
	v_exp_f32_e32 v39, v27
	v_exp_f32_e32 v40, v32
	v_exp_f32_e32 v41, v33
	v_pk_add_f32 v[36:37], v[36:37], 1.0 op_sel_hi:[1,0]
	v_pk_add_f32 v[42:43], v[42:43], 1.0 op_sel_hi:[1,0]
	v_pk_add_f32 v[38:39], v[38:39], 1.0 op_sel_hi:[1,0]
	v_pk_add_f32 v[40:41], v[40:41], 1.0 op_sel_hi:[1,0]
	v_rcp_f32_e32 v36, v36
	v_rcp_f32_e32 v38, v38
	v_rcp_f32_e32 v37, v37
	v_rcp_f32_e32 v39, v39
	v_rcp_f32_e32 v42, v42
	v_rcp_f32_e32 v43, v43
	v_add_u32_e32 v34, 0xa0, v136
	v_rcp_f32_e32 v40, v40
	v_rcp_f32_e32 v41, v41
	v_ashrrev_i32_e32 v35, 31, v34
	v_lshl_add_u64 v[34:35], s[16:17], 0, v[34:35]
	v_pk_mul_f32 v[22:23], v[30:31], v[22:23]
	v_pk_mul_f32 v[20:21], v[28:29], v[20:21]
	v_pk_mul_f32 v[18:19], v[26:27], v[18:19]
	v_lshlrev_b64 v[34:35], 7, v[34:35]
	v_pk_mul_f32 v[24:25], v[32:33], v[24:25]
	v_pk_mul_f32 v[22:23], v[36:37], v[22:23]
	v_pk_mul_f32 v[26:27], v[42:43], v[20:21]
	v_pk_mul_f32 v[20:21], v[38:39], v[18:19]
	v_lshl_add_u64 v[34:35], v[130:131], 0, v[34:35]
	v_pk_mul_f32 v[24:25], v[40:41], v[24:25]
	v_cvt_pk_bf16_f32 v18, v22, v23
	v_cvt_pk_bf16_f32 v20, v20, v21
	v_cvt_pk_bf16_f32 v21, v26, v27
	v_exp_f32_e32 v22, v10
	v_exp_f32_e32 v26, v12
	v_exp_f32_e32 v27, v13
	v_exp_f32_e32 v23, v11
	v_cvt_pk_bf16_f32 v19, v24, v25
	global_store_dwordx4 v[34:35], v[18:21], off
	v_exp_f32_e32 v24, v16
	v_exp_f32_e32 v25, v17
	v_exp_f32_e32 v20, v14
	v_exp_f32_e32 v21, v15
	v_pk_add_f32 v[26:27], v[26:27], 1.0 op_sel_hi:[1,0]
	v_pk_add_f32 v[22:23], v[22:23], 1.0 op_sel_hi:[1,0]
	v_add_u32_e32 v18, 0xb0, v136
	v_pk_add_f32 v[24:25], v[24:25], 1.0 op_sel_hi:[1,0]
	v_pk_add_f32 v[20:21], v[20:21], 1.0 op_sel_hi:[1,0]
	v_rcp_f32_e32 v22, v22
	v_rcp_f32_e32 v23, v23
	v_rcp_f32_e32 v26, v26
	v_rcp_f32_e32 v27, v27
	v_ashrrev_i32_e32 v19, 31, v18
	v_rcp_f32_e32 v20, v20
	v_rcp_f32_e32 v21, v21
	v_rcp_f32_e32 v24, v24
	v_rcp_f32_e32 v25, v25
	v_lshl_add_u64 v[18:19], s[16:17], 0, v[18:19]
	v_lshlrev_b64 v[18:19], 7, v[18:19]
	v_pk_mul_f32 v[4:5], v[12:13], v[4:5]
	v_pk_mul_f32 v[2:3], v[10:11], v[2:3]
	v_lshl_add_u64 v[18:19], v[130:131], 0, v[18:19]
	v_pk_mul_f32 v[8:9], v[16:17], v[8:9]
	v_pk_mul_f32 v[6:7], v[14:15], v[6:7]
	v_pk_mul_f32 v[10:11], v[26:27], v[4:5]
	v_pk_mul_f32 v[4:5], v[22:23], v[2:3]
	s_andn2_b64 vcc, exec, s[2:3]
	s_mov_b64 s[2:3], -1
	v_pk_mul_f32 v[8:9], v[24:25], v[8:9]
	v_pk_mul_f32 v[6:7], v[20:21], v[6:7]
	v_cvt_pk_bf16_f32 v3, v8, v9
	v_cvt_pk_bf16_f32 v4, v4, v5
	v_cvt_pk_bf16_f32 v5, v10, v11
	s_nop 0
	v_cvt_pk_bf16_f32 v2, v6, v7
	global_store_dwordx4 v[18:19], v[2:5], off
	s_cbranch_vccnz .LBB0_340
	s_andn2_b64 vcc, exec, s[4:5]
	s_cbranch_vccnz .LBB0_339
	s_mov_b32 s99, 1
	s_branch .LBB0_339

.LBB0_472:
	s_ashr_i32 s13, s12, 31
	s_lshl_b64 s[14:15], s[12:13], 15
	s_add_u32 s14, s28, s14
	s_addc_u32 s15, s29, s15
	s_and_b64 s[16:17], s[2:3], exec
	s_cselect_b32 s13, s15, s23
	s_cselect_b32 s76, s14, s22
	s_ashr_i32 s11, s10, 31
	s_lshl_b64 s[16:17], s[10:11], 15
	s_add_u32 s16, s30, s16
	s_addc_u32 s17, s31, s17
	s_and_b64 s[24:25], s[2:3], exec
	s_cselect_b32 s11, s17, s21
	s_cselect_b32 s77, s16, s20
	s_add_u32 s78, s20, 0x80000
	s_addc_u32 s79, s21, 0
	s_add_u32 s20, s22, 0x204000
	s_addc_u32 s21, s23, 0
	s_add_u32 s80, s22, 0x400000
	v_mov_b32_e32 v2, 0
	s_addc_u32 s81, s23, 0
	s_mov_b32 s82, -2
	v_mov_b32_e32 v3, v2
	v_mov_b32_e32 v4, v2
	v_mov_b32_e32 v5, v2
	v_mov_b32_e32 v6, v2
	v_mov_b32_e32 v7, v2
	s_waitcnt vmcnt(25)
	v_mov_b32_e32 v8, v2
	s_waitcnt vmcnt(24)
	v_mov_b32_e32 v9, v2
	s_waitcnt vmcnt(23)
	v_mov_b32_e32 v10, v2
	s_waitcnt vmcnt(22)
	v_mov_b32_e32 v11, v2
	s_waitcnt vmcnt(21)
	v_mov_b32_e32 v12, v2
	s_waitcnt vmcnt(20)
	v_mov_b32_e32 v13, v2
	s_waitcnt vmcnt(15)
	v_mov_b32_e32 v18, v2
	s_waitcnt vmcnt(14)
	v_mov_b32_e32 v19, v2
	s_waitcnt vmcnt(13)
	v_mov_b32_e32 v20, v2
	s_waitcnt vmcnt(12)
	v_mov_b32_e32 v21, v2
	s_waitcnt vmcnt(7)
	v_mov_b32_e32 v26, v2
	s_waitcnt vmcnt(6)
	v_mov_b32_e32 v27, v2
	s_waitcnt vmcnt(5)
	v_mov_b32_e32 v28, v2
	s_waitcnt vmcnt(4)
	v_mov_b32_e32 v29, v2
	v_mov_b32_e32 v34, v2
	v_mov_b32_e32 v35, v2
	v_mov_b32_e32 v36, v2
	v_mov_b32_e32 v37, v2
	v_mov_b32_e32 v42, v2
	v_mov_b32_e32 v43, v2
	v_mov_b32_e32 v44, v2
	v_mov_b32_e32 v45, v2
	v_mov_b32_e32 v50, v2
	v_mov_b32_e32 v51, v2
	v_mov_b32_e32 v52, v2
	v_mov_b32_e32 v53, v2
	v_mov_b32_e32 v14, v2
	v_mov_b32_e32 v15, v2
	v_mov_b32_e32 v16, v2
	v_mov_b32_e32 v17, v2
	v_mov_b32_e32 v22, v2
	v_mov_b32_e32 v23, v2
	v_mov_b32_e32 v24, v2
	v_mov_b32_e32 v25, v2
	s_waitcnt vmcnt(3)
	v_mov_b32_e32 v30, v2
	s_waitcnt vmcnt(2)
	v_mov_b32_e32 v31, v2
	s_waitcnt vmcnt(1)
	v_mov_b32_e32 v32, v2
	s_waitcnt vmcnt(0)
	v_mov_b32_e32 v33, v2
	v_mov_b32_e32 v38, v2
	v_mov_b32_e32 v39, v2
	v_mov_b32_e32 v40, v2
	v_mov_b32_e32 v41, v2
	v_mov_b32_e32 v46, v2
	v_mov_b32_e32 v47, v2
	v_mov_b32_e32 v48, v2
	v_mov_b32_e32 v49, v2
	v_mov_b32_e32 v54, v2
	v_mov_b32_e32 v55, v2
	v_mov_b32_e32 v56, v2
	v_mov_b32_e32 v57, v2
	v_mov_b32_e32 v58, v2
	v_mov_b32_e32 v59, v2
	v_mov_b32_e32 v60, v2
	v_mov_b32_e32 v61, v2
	v_mov_b32_e32 v62, v2
	v_mov_b32_e32 v63, v2
	v_mov_b32_e32 v64, v2
	v_mov_b32_e32 v65, v2
	v_mov_b32_e32 v66, v2
	v_mov_b32_e32 v67, v2
	v_mov_b32_e32 v68, v2
	v_mov_b32_e32 v69, v2
	v_mov_b32_e32 v70, v2
	v_mov_b32_e32 v71, v2
	v_mov_b32_e32 v72, v2
	v_mov_b32_e32 v73, v2
	v_mov_b32_e32 v74, v2
	v_mov_b32_e32 v75, v2
	v_mov_b32_e32 v76, v2
	v_mov_b32_e32 v77, v2
	v_mov_b32_e32 v82, v2
	v_mov_b32_e32 v83, v2
	v_mov_b32_e32 v84, v2
	v_mov_b32_e32 v85, v2
	v_mov_b32_e32 v90, v2
	v_mov_b32_e32 v91, v2
	v_mov_b32_e32 v92, v2
	v_mov_b32_e32 v93, v2
	v_mov_b32_e32 v98, v2
	v_mov_b32_e32 v99, v2
	v_mov_b32_e32 v100, v2
	v_mov_b32_e32 v101, v2
	v_mov_b32_e32 v106, v2
	v_mov_b32_e32 v107, v2
	v_mov_b32_e32 v108, v2
	v_mov_b32_e32 v109, v2
	v_mov_b32_e32 v110, v2
	v_mov_b32_e32 v111, v2
	v_mov_b32_e32 v112, v2
	v_mov_b32_e32 v113, v2
	v_mov_b32_e32 v78, v2
	v_mov_b32_e32 v79, v2
	v_mov_b32_e32 v80, v2
	v_mov_b32_e32 v81, v2
	v_mov_b32_e32 v86, v2
	v_mov_b32_e32 v87, v2
	v_mov_b32_e32 v88, v2
	v_mov_b32_e32 v89, v2
	v_mov_b32_e32 v94, v2
	v_mov_b32_e32 v95, v2
	v_mov_b32_e32 v96, v2
	v_mov_b32_e32 v97, v2
	v_mov_b32_e32 v102, v2
	v_mov_b32_e32 v103, v2
	v_mov_b32_e32 v104, v2
	v_mov_b32_e32 v105, v2
	v_mov_b32_e32 v114, v2
	v_mov_b32_e32 v115, v2
	v_mov_b32_e32 v116, v2
	v_mov_b32_e32 v117, v2
	v_mov_b32_e32 v118, v2
	v_mov_b32_e32 v119, v2
	v_mov_b32_e32 v120, v2
	v_mov_b32_e32 v121, v2
	v_mov_b32_e32 v122, v2
	v_mov_b32_e32 v123, v2
	v_mov_b32_e32 v124, v2
	v_mov_b32_e32 v125, v2
	v_mov_b32_e32 v126, v2
	v_mov_b32_e32 v127, v2
	v_mov_b32_e32 v128, v2
	v_mov_b32_e32 v129, v2
	s_cmp_eq_u32 s99, 0
	s_cbranch_scc1 .Lro_skip_12
	s_barrier
	s_mov_b32 s99, 0
.Lro_skip_12:
.LBB0_473:
	ds_read_b128 v[134:137], v161
	ds_read_b128 v[138:141], v161 offset:1024
	ds_read_b128 v[142:145], v161 offset:2048
	ds_read_b128 v[146:149], v161 offset:3072
	ds_read_b128 v[150:153], v162
	ds_read_b128 v[166:169], v162 offset:1024
	ds_read_b128 v[170:173], v162 offset:2048
	ds_read_b128 v[174:177], v162 offset:3072
	s_cmpk_eq_i32 s82, 0x52
	s_cselect_b32 s23, s11, s79
	s_cselect_b32 s22, s77, s78
	s_cselect_b32 s25, s13, s81
	s_cselect_b32 s24, s76, s80
	ds_read_b128 v[178:181], v163
	ds_read_b128 v[182:185], v163 offset:1024
	ds_read_b128 v[186:189], v163 offset:2048
	ds_read_b128 v[190:193], v163 offset:3072
	ds_read_b128 v[194:197], v163 offset:4096
	ds_read_b128 v[198:201], v163 offset:5120
	ds_read_b128 v[202:205], v163 offset:6144
	ds_read_b128 v[206:209], v163 offset:7168
	s_add_u32 s86, s20, 0xffffc000
	s_addc_u32 s87, s21, -1
	s_mov_b32 s83, m0
	s_mov_b32 m0, s65
	s_nop 0
	global_load_lds_dwordx4 v1, s[86:87]
	s_mov_b32 m0, s83
	s_nop 0
	s_mov_b32 s83, m0
	s_mov_b32 m0, s67
	s_nop 0
	global_load_lds_dwordx4 v157, s[86:87]
	s_mov_b32 m0, s83
	s_nop 0
	s_mov_b32 s83, m0
	s_mov_b32 m0, s66
	s_nop 0
	global_load_lds_dwordx4 v1, s[20:21]
	s_mov_b32 m0, s83
	s_nop 0
	s_mov_b32 s83, m0
	s_mov_b32 m0, s73
	s_nop 0
	global_load_lds_dwordx4 v157, s[20:21]
	s_mov_b32 m0, s83
	s_waitcnt vmcnt(8)
	s_waitcnt lgkmcnt(0)
	s_barrier
	s_setprio 1
	s_waitcnt lgkmcnt(7)
	v_mfma_f32_16x16x32_bf16 v[126:129], v[134:137], v[178:181], v[126:129]
	v_mfma_f32_16x16x32_bf16 v[122:125], v[142:145], v[178:181], v[122:125]
	s_waitcnt lgkmcnt(5)
	v_mfma_f32_16x16x32_bf16 v[118:121], v[134:137], v[186:189], v[118:121]
	v_mfma_f32_16x16x32_bf16 v[114:117], v[142:145], v[186:189], v[114:117]
	s_waitcnt lgkmcnt(3)
	v_mfma_f32_16x16x32_bf16 v[102:105], v[134:137], v[194:197], v[102:105]
	v_mfma_f32_16x16x32_bf16 v[94:97], v[142:145], v[194:197], v[94:97]
	s_waitcnt lgkmcnt(1)
	v_mfma_f32_16x16x32_bf16 v[86:89], v[134:137], v[202:205], v[86:89]
	v_mfma_f32_16x16x32_bf16 v[78:81], v[142:145], v[202:205], v[78:81]
	v_mfma_f32_16x16x32_bf16 v[126:129], v[138:141], v[182:185], v[126:129]
	v_mfma_f32_16x16x32_bf16 v[122:125], v[146:149], v[182:185], v[122:125]
	v_mfma_f32_16x16x32_bf16 v[118:121], v[138:141], v[190:193], v[118:121]
	v_mfma_f32_16x16x32_bf16 v[114:117], v[146:149], v[190:193], v[114:117]
	v_mfma_f32_16x16x32_bf16 v[102:105], v[138:141], v[198:201], v[102:105]
	v_mfma_f32_16x16x32_bf16 v[94:97], v[146:149], v[198:201], v[94:97]
	s_waitcnt lgkmcnt(0)
	v_mfma_f32_16x16x32_bf16 v[86:89], v[138:141], v[206:209], v[86:89]
	v_mfma_f32_16x16x32_bf16 v[78:81], v[146:149], v[206:209], v[78:81]
	s_setprio 0
	s_setprio 1
	v_mfma_f32_16x16x32_bf16 v[110:113], v[150:153], v[178:181], v[110:113]
	v_mfma_f32_16x16x32_bf16 v[106:109], v[170:173], v[178:181], v[106:109]
	v_mfma_f32_16x16x32_bf16 v[98:101], v[150:153], v[186:189], v[98:101]
	v_mfma_f32_16x16x32_bf16 v[90:93], v[170:173], v[186:189], v[90:93]
	v_mfma_f32_16x16x32_bf16 v[82:85], v[150:153], v[194:197], v[82:85]
	v_mfma_f32_16x16x32_bf16 v[74:77], v[170:173], v[194:197], v[74:77]
	v_mfma_f32_16x16x32_bf16 v[70:73], v[150:153], v[202:205], v[70:73]
	v_mfma_f32_16x16x32_bf16 v[66:69], v[170:173], v[202:205], v[66:69]
	v_mfma_f32_16x16x32_bf16 v[110:113], v[166:169], v[182:185], v[110:113]
	v_mfma_f32_16x16x32_bf16 v[106:109], v[174:177], v[182:185], v[106:109]
	v_mfma_f32_16x16x32_bf16 v[98:101], v[166:169], v[190:193], v[98:101]
	v_mfma_f32_16x16x32_bf16 v[90:93], v[174:177], v[190:193], v[90:93]
	v_mfma_f32_16x16x32_bf16 v[82:85], v[166:169], v[198:201], v[82:85]
	v_mfma_f32_16x16x32_bf16 v[74:77], v[174:177], v[198:201], v[74:77]
	s_setprio 2
	s_barrier
	v_mfma_f32_16x16x32_bf16 v[70:73], v[166:169], v[206:209], v[70:73]
	v_mfma_f32_16x16x32_bf16 v[66:69], v[174:177], v[206:209], v[66:69]
	s_setprio 0
	ds_read_b128 v[178:181], v163 offset:16384
	ds_read_b128 v[182:185], v163 offset:17408
	ds_read_b128 v[186:189], v163 offset:18432
	ds_read_b128 v[190:193], v163 offset:19456
	ds_read_b128 v[194:197], v163 offset:20480
	ds_read_b128 v[198:201], v163 offset:21504
	ds_read_b128 v[202:205], v163 offset:22528
	ds_read_b128 v[206:209], v163 offset:23552
	s_mov_b32 s83, m0
	s_mov_b32 m0, s19
	s_nop 0
	global_load_lds_dwordx4 v156, s[22:23]
	s_mov_b32 m0, s83
	s_add_u32 s86, s22, 0x4000
	s_mov_b32 s83, m0
	s_mov_b32 m0, s35
	s_nop 0
	global_load_lds_dwordx4 v158, s[22:23]
	s_mov_b32 m0, s83
	s_addc_u32 s87, s23, 0
	s_mov_b32 s83, m0
	s_mov_b32 m0, s36
	s_nop 0
	global_load_lds_dwordx4 v156, s[86:87]
	s_mov_b32 m0, s83
	s_nop 0
	s_mov_b32 s83, m0
	s_mov_b32 m0, s37
	s_nop 0
	global_load_lds_dwordx4 v158, s[86:87]
	s_mov_b32 m0, s83
	s_waitcnt vmcnt(4)
	s_waitcnt lgkmcnt(0)
	s_barrier
	s_setprio 1
	s_waitcnt lgkmcnt(7)
	v_mfma_f32_16x16x32_bf16 v[62:65], v[134:137], v[178:181], v[62:65]
	v_mfma_f32_16x16x32_bf16 v[58:61], v[142:145], v[178:181], v[58:61]
	s_waitcnt lgkmcnt(5)
	v_mfma_f32_16x16x32_bf16 v[54:57], v[134:137], v[186:189], v[54:57]
	v_mfma_f32_16x16x32_bf16 v[46:49], v[142:145], v[186:189], v[46:49]
	s_waitcnt lgkmcnt(3)
	v_mfma_f32_16x16x32_bf16 v[38:41], v[134:137], v[194:197], v[38:41]
	v_mfma_f32_16x16x32_bf16 v[30:33], v[142:145], v[194:197], v[30:33]
	s_waitcnt lgkmcnt(1)
	v_mfma_f32_16x16x32_bf16 v[22:25], v[134:137], v[202:205], v[22:25]
	v_mfma_f32_16x16x32_bf16 v[14:17], v[142:145], v[202:205], v[14:17]
	v_mfma_f32_16x16x32_bf16 v[62:65], v[138:141], v[182:185], v[62:65]
	v_mfma_f32_16x16x32_bf16 v[58:61], v[146:149], v[182:185], v[58:61]
	v_mfma_f32_16x16x32_bf16 v[54:57], v[138:141], v[190:193], v[54:57]
	v_mfma_f32_16x16x32_bf16 v[46:49], v[146:149], v[190:193], v[46:49]
	v_mfma_f32_16x16x32_bf16 v[38:41], v[138:141], v[198:201], v[38:41]
	v_mfma_f32_16x16x32_bf16 v[30:33], v[146:149], v[198:201], v[30:33]
	s_waitcnt lgkmcnt(0)
	v_mfma_f32_16x16x32_bf16 v[22:25], v[138:141], v[206:209], v[22:25]
	v_mfma_f32_16x16x32_bf16 v[14:17], v[146:149], v[206:209], v[14:17]
	s_setprio 0
	s_setprio 1
	v_mfma_f32_16x16x32_bf16 v[50:53], v[150:153], v[178:181], v[50:53]
	v_mfma_f32_16x16x32_bf16 v[42:45], v[170:173], v[178:181], v[42:45]
	v_mfma_f32_16x16x32_bf16 v[34:37], v[150:153], v[186:189], v[34:37]
	v_mfma_f32_16x16x32_bf16 v[26:29], v[170:173], v[186:189], v[26:29]
	v_mfma_f32_16x16x32_bf16 v[18:21], v[150:153], v[194:197], v[18:21]
	v_mfma_f32_16x16x32_bf16 v[10:13], v[170:173], v[194:197], v[10:13]
	v_mfma_f32_16x16x32_bf16 v[6:9], v[150:153], v[202:205], v[6:9]
	v_mfma_f32_16x16x32_bf16 v[2:5], v[170:173], v[202:205], v[2:5]
	v_mfma_f32_16x16x32_bf16 v[50:53], v[166:169], v[182:185], v[50:53]
	v_mfma_f32_16x16x32_bf16 v[42:45], v[174:177], v[182:185], v[42:45]
	v_mfma_f32_16x16x32_bf16 v[34:37], v[166:169], v[190:193], v[34:37]
	v_mfma_f32_16x16x32_bf16 v[26:29], v[174:177], v[190:193], v[26:29]
	v_mfma_f32_16x16x32_bf16 v[18:21], v[166:169], v[198:201], v[18:21]
	v_mfma_f32_16x16x32_bf16 v[10:13], v[174:177], v[198:201], v[10:13]
	s_setprio 2
	s_barrier
	v_mfma_f32_16x16x32_bf16 v[6:9], v[166:169], v[206:209], v[6:9]
	v_mfma_f32_16x16x32_bf16 v[2:5], v[174:177], v[206:209], v[2:5]
	s_setprio 0
	ds_read_b128 v[134:137], v164
	ds_read_b128 v[138:141], v164 offset:1024
	ds_read_b128 v[142:145], v164 offset:2048
	ds_read_b128 v[146:149], v164 offset:3072
	ds_read_b128 v[150:153], v165
	ds_read_b128 v[166:169], v165 offset:1024
	ds_read_b128 v[170:173], v165 offset:2048
	ds_read_b128 v[174:177], v165 offset:3072
	ds_read_b128 v[178:181], v163 offset:32768
	ds_read_b128 v[182:185], v163 offset:33792
	ds_read_b128 v[186:189], v163 offset:34816
	ds_read_b128 v[190:193], v163 offset:35840
	ds_read_b128 v[194:197], v163 offset:36864
	ds_read_b128 v[198:201], v163 offset:37888
	ds_read_b128 v[202:205], v163 offset:38912
	ds_read_b128 v[206:209], v163 offset:39936
	s_mov_b32 s83, m0
	s_mov_b32 m0, s34
	s_nop 0
	global_load_lds_dwordx4 v1, s[24:25]
	s_mov_b32 m0, s83
	s_nop 0
	s_mov_b32 s83, m0
	s_mov_b32 m0, s42
	s_nop 0
	global_load_lds_dwordx4 v157, s[24:25]
	s_mov_b32 m0, s83
	s_add_u32 s24, s24, 0x4000
	s_addc_u32 s25, s25, 0
	s_mov_b32 s83, m0
	s_mov_b32 m0, s43
	s_nop 0
	global_load_lds_dwordx4 v1, s[24:25]
	s_mov_b32 m0, s83
	s_nop 0
	s_mov_b32 s83, m0
	s_mov_b32 m0, s46
	s_nop 0
	global_load_lds_dwordx4 v157, s[24:25]
	s_mov_b32 m0, s83
	s_waitcnt vmcnt(8)
	s_waitcnt lgkmcnt(0)
	s_barrier
	s_setprio 1
	s_waitcnt lgkmcnt(7)
	v_mfma_f32_16x16x32_bf16 v[126:129], v[134:137], v[178:181], v[126:129]
	v_mfma_f32_16x16x32_bf16 v[122:125], v[142:145], v[178:181], v[122:125]
	s_waitcnt lgkmcnt(5)
	v_mfma_f32_16x16x32_bf16 v[118:121], v[134:137], v[186:189], v[118:121]
	v_mfma_f32_16x16x32_bf16 v[114:117], v[142:145], v[186:189], v[114:117]
	s_waitcnt lgkmcnt(3)
	v_mfma_f32_16x16x32_bf16 v[102:105], v[134:137], v[194:197], v[102:105]
	v_mfma_f32_16x16x32_bf16 v[94:97], v[142:145], v[194:197], v[94:97]
	s_waitcnt lgkmcnt(1)
	v_mfma_f32_16x16x32_bf16 v[86:89], v[134:137], v[202:205], v[86:89]
	v_mfma_f32_16x16x32_bf16 v[78:81], v[142:145], v[202:205], v[78:81]
	v_mfma_f32_16x16x32_bf16 v[126:129], v[138:141], v[182:185], v[126:129]
	v_mfma_f32_16x16x32_bf16 v[122:125], v[146:149], v[182:185], v[122:125]
	v_mfma_f32_16x16x32_bf16 v[118:121], v[138:141], v[190:193], v[118:121]
	v_mfma_f32_16x16x32_bf16 v[114:117], v[146:149], v[190:193], v[114:117]
	v_mfma_f32_16x16x32_bf16 v[102:105], v[138:141], v[198:201], v[102:105]
	v_mfma_f32_16x16x32_bf16 v[94:97], v[146:149], v[198:201], v[94:97]
	s_waitcnt lgkmcnt(0)
	v_mfma_f32_16x16x32_bf16 v[86:89], v[138:141], v[206:209], v[86:89]
	v_mfma_f32_16x16x32_bf16 v[78:81], v[146:149], v[206:209], v[78:81]
	s_setprio 0
	s_setprio 1
	v_mfma_f32_16x16x32_bf16 v[110:113], v[150:153], v[178:181], v[110:113]
	v_mfma_f32_16x16x32_bf16 v[106:109], v[170:173], v[178:181], v[106:109]
	v_mfma_f32_16x16x32_bf16 v[98:101], v[150:153], v[186:189], v[98:101]
	v_mfma_f32_16x16x32_bf16 v[90:93], v[170:173], v[186:189], v[90:93]
	v_mfma_f32_16x16x32_bf16 v[82:85], v[150:153], v[194:197], v[82:85]
	v_mfma_f32_16x16x32_bf16 v[74:77], v[170:173], v[194:197], v[74:77]
	v_mfma_f32_16x16x32_bf16 v[70:73], v[150:153], v[202:205], v[70:73]
	v_mfma_f32_16x16x32_bf16 v[66:69], v[170:173], v[202:205], v[66:69]
	v_mfma_f32_16x16x32_bf16 v[110:113], v[166:169], v[182:185], v[110:113]
	v_mfma_f32_16x16x32_bf16 v[106:109], v[174:177], v[182:185], v[106:109]
	v_mfma_f32_16x16x32_bf16 v[98:101], v[166:169], v[190:193], v[98:101]
	v_mfma_f32_16x16x32_bf16 v[90:93], v[174:177], v[190:193], v[90:93]
	v_mfma_f32_16x16x32_bf16 v[82:85], v[166:169], v[198:201], v[82:85]
	v_mfma_f32_16x16x32_bf16 v[74:77], v[174:177], v[198:201], v[74:77]
	s_setprio 2
	s_barrier
	v_mfma_f32_16x16x32_bf16 v[70:73], v[166:169], v[206:209], v[70:73]
	v_mfma_f32_16x16x32_bf16 v[66:69], v[174:177], v[206:209], v[66:69]
	s_setprio 0
	ds_read_b128 v[178:181], v163 offset:49152
	ds_read_b128 v[182:185], v163 offset:50176
	ds_read_b128 v[186:189], v163 offset:51200
	ds_read_b128 v[190:193], v163 offset:52224
	ds_read_b128 v[194:197], v163 offset:53248
	ds_read_b128 v[198:201], v163 offset:54272
	ds_read_b128 v[202:205], v163 offset:55296
	ds_read_b128 v[206:209], v163 offset:56320
	s_add_u32 s24, s22, 0x40000
	s_addc_u32 s25, s23, 0
	s_mov_b32 s83, m0
	s_mov_b32 m0, s47
	s_nop 0
	global_load_lds_dwordx4 v156, s[24:25]
	s_mov_b32 m0, s83
	s_add_u32 s22, s22, 0x44000
	s_mov_b32 s83, m0
	s_mov_b32 m0, s48
	s_nop 0
	global_load_lds_dwordx4 v158, s[24:25]
	s_mov_b32 m0, s83
	s_addc_u32 s23, s23, 0
	s_mov_b32 s24, m0
	s_mov_b32 m0, s49
	s_nop 0
	global_load_lds_dwordx4 v156, s[22:23]
	s_mov_b32 m0, s24
	s_nop 0
	s_mov_b32 s24, m0
	s_mov_b32 m0, s56
	s_nop 0
	global_load_lds_dwordx4 v158, s[22:23]
	s_mov_b32 m0, s24
	s_waitcnt vmcnt(4)
	s_waitcnt lgkmcnt(0)
	s_barrier
	s_setprio 1
	s_waitcnt lgkmcnt(7)
	v_mfma_f32_16x16x32_bf16 v[62:65], v[134:137], v[178:181], v[62:65]
	v_mfma_f32_16x16x32_bf16 v[58:61], v[142:145], v[178:181], v[58:61]
	s_waitcnt lgkmcnt(5)
	v_mfma_f32_16x16x32_bf16 v[54:57], v[134:137], v[186:189], v[54:57]
	v_mfma_f32_16x16x32_bf16 v[46:49], v[142:145], v[186:189], v[46:49]
	s_waitcnt lgkmcnt(3)
	v_mfma_f32_16x16x32_bf16 v[38:41], v[134:137], v[194:197], v[38:41]
	v_mfma_f32_16x16x32_bf16 v[30:33], v[142:145], v[194:197], v[30:33]
	s_waitcnt lgkmcnt(1)
	v_mfma_f32_16x16x32_bf16 v[22:25], v[134:137], v[202:205], v[22:25]
	v_mfma_f32_16x16x32_bf16 v[14:17], v[142:145], v[202:205], v[14:17]
	v_mfma_f32_16x16x32_bf16 v[62:65], v[138:141], v[182:185], v[62:65]
	v_mfma_f32_16x16x32_bf16 v[58:61], v[146:149], v[182:185], v[58:61]
	v_mfma_f32_16x16x32_bf16 v[54:57], v[138:141], v[190:193], v[54:57]
	v_mfma_f32_16x16x32_bf16 v[46:49], v[146:149], v[190:193], v[46:49]
	v_mfma_f32_16x16x32_bf16 v[38:41], v[138:141], v[198:201], v[38:41]
	v_mfma_f32_16x16x32_bf16 v[30:33], v[146:149], v[198:201], v[30:33]
	s_waitcnt lgkmcnt(0)
	v_mfma_f32_16x16x32_bf16 v[22:25], v[138:141], v[206:209], v[22:25]
	v_mfma_f32_16x16x32_bf16 v[14:17], v[146:149], v[206:209], v[14:17]
	s_setprio 0
	s_setprio 1
	v_mfma_f32_16x16x32_bf16 v[50:53], v[150:153], v[178:181], v[50:53]
	v_mfma_f32_16x16x32_bf16 v[42:45], v[170:173], v[178:181], v[42:45]
	v_mfma_f32_16x16x32_bf16 v[34:37], v[150:153], v[186:189], v[34:37]
	v_mfma_f32_16x16x32_bf16 v[26:29], v[170:173], v[186:189], v[26:29]
	v_mfma_f32_16x16x32_bf16 v[18:21], v[150:153], v[194:197], v[18:21]
	v_mfma_f32_16x16x32_bf16 v[10:13], v[170:173], v[194:197], v[10:13]
	v_mfma_f32_16x16x32_bf16 v[6:9], v[150:153], v[202:205], v[6:9]
	v_mfma_f32_16x16x32_bf16 v[2:5], v[170:173], v[202:205], v[2:5]
	v_mfma_f32_16x16x32_bf16 v[50:53], v[166:169], v[182:185], v[50:53]
	v_mfma_f32_16x16x32_bf16 v[42:45], v[174:177], v[182:185], v[42:45]
	v_mfma_f32_16x16x32_bf16 v[34:37], v[166:169], v[190:193], v[34:37]
	v_mfma_f32_16x16x32_bf16 v[26:29], v[174:177], v[190:193], v[26:29]
	v_mfma_f32_16x16x32_bf16 v[18:21], v[166:169], v[198:201], v[18:21]
	v_mfma_f32_16x16x32_bf16 v[10:13], v[174:177], v[198:201], v[10:13]
	s_setprio 2
	s_barrier
	v_mfma_f32_16x16x32_bf16 v[6:9], v[166:169], v[206:209], v[6:9]
	v_mfma_f32_16x16x32_bf16 v[2:5], v[174:177], v[206:209], v[2:5]
	s_setprio 0
	s_add_i32 s82, s82, 2
	s_add_u32 s78, s78, 0x80000
	s_addc_u32 s79, s79, 0
	s_add_u32 s20, s20, 0x400000
	s_addc_u32 s21, s21, 0
	s_add_u32 s80, s80, 0x400000
	s_addc_u32 s81, s81, 0
	s_cmpk_gt_u32 s82, 0x53
	s_cbranch_scc0 .LBB0_473
	s_and_b64 vcc, exec, s[8:9]
	s_cbranch_vccz .LBB0_476
	s_barrier
.LBB0_476:
	s_ashr_i32 s11, s18, 31
	s_lshr_b32 s11, s11, 28
	s_add_i32 s11, s18, s11
	s_ashr_i32 s11, s11, 4
	v_lshl_or_b32 v134, s75, 8, v160
	s_mul_hi_i32 s13, s11, 0x12000
	s_mul_i32 s11, s11, 0x12000
	s_add_u32 s20, s57, s11
	v_ashrrev_i32_e32 v135, 31, v134
	v_lshl_add_u32 v154, s18, 8, v159
	s_addc_u32 s21, s64, s13
	v_lshlrev_b64 v[144:145], 2, v[134:135]
	v_ashrrev_i32_e32 v155, 31, v154
	v_lshl_add_u64 v[146:147], s[20:21], 0, v[144:145]
	v_lshl_add_u64 v[152:153], s[40:41], 0, v[144:145]
	v_lshlrev_b64 v[144:145], 13, v[154:155]
	v_lshl_add_u64 v[144:145], v[152:153], 0, v[144:145]
	global_load_dwordx4 v[136:139], v[146:147], off offset:16
	global_load_dwordx4 v[140:143], v[146:147], off
	global_load_dwordx4 v[166:169], v[146:147], off offset:528
	global_load_dwordx4 v[170:173], v[146:147], off offset:512
	global_load_dwordx4 v[174:177], v[144:145], off
	global_load_dwordx4 v[178:181], v[144:145], off offset:16
	global_load_dwordx4 v[182:185], v[144:145], off offset:528
	global_load_dwordx4 v[186:189], v[144:145], off offset:512
	v_or_b32_e32 v144, 16, v154
	v_ashrrev_i32_e32 v145, 31, v144
	v_lshlrev_b64 v[146:147], 13, v[144:145]
	v_lshl_add_u64 v[146:147], v[152:153], 0, v[146:147]
	global_load_dwordx4 v[190:193], v[146:147], off
	global_load_dwordx4 v[194:197], v[146:147], off offset:16
	global_load_dwordx4 v[198:201], v[146:147], off offset:512
	global_load_dwordx4 v[202:205], v[146:147], off offset:528
	v_or_b32_e32 v238, 32, v154
	v_ashrrev_i32_e32 v239, 31, v238
	v_lshlrev_b64 v[146:147], 13, v[238:239]
	v_lshl_add_u64 v[146:147], v[152:153], 0, v[146:147]
	global_load_dwordx4 v[206:209], v[146:147], off
	global_load_dwordx4 v[210:213], v[146:147], off offset:16
	global_load_dwordx4 v[214:217], v[146:147], off offset:512
	global_load_dwordx4 v[218:221], v[146:147], off offset:528
	v_or_b32_e32 v240, 48, v154
	v_ashrrev_i32_e32 v241, 31, v240
	v_lshlrev_b64 v[146:147], 13, v[240:241]
	v_lshl_add_u64 v[146:147], v[152:153], 0, v[146:147]
	global_load_dwordx4 v[222:225], v[146:147], off
	global_load_dwordx4 v[226:229], v[146:147], off offset:16
	global_load_dwordx4 v[230:233], v[146:147], off offset:528
	global_load_dwordx4 v[234:237], v[146:147], off offset:512
	v_lshlrev_b64 v[148:149], 12, v[154:155]
	v_lshlrev_b64 v[144:145], 12, v[144:145]
	v_lshlrev_b64 v[134:135], 1, v[134:135]
	v_lshl_add_u64 v[148:149], s[6:7], 0, v[148:149]
	v_lshl_add_u64 v[144:145], s[6:7], 0, v[144:145]
	v_lshl_add_u64 v[242:243], v[148:149], 0, v[134:135]
	v_lshl_add_u64 v[244:245], v[144:145], 0, v[134:135]
	s_andn2_b64 vcc, exec, s[2:3]
	s_mov_b64 s[2:3], -1
	s_waitcnt vmcnt(19)
	v_pk_mul_f32 v[144:145], v[138:139], 0.5 op_sel_hi:[1,0]
	s_waitcnt vmcnt(18)
	v_pk_mul_f32 v[148:149], v[142:143], 0.5 op_sel_hi:[1,0]
	v_pk_mul_f32 v[150:151], v[140:141], 0.5 op_sel_hi:[1,0]
	v_pk_mul_f32 v[146:147], v[136:137], 0.5 op_sel_hi:[1,0]
	s_waitcnt vmcnt(16)
	v_pk_mul_f32 v[140:141], v[172:173], 0.5 op_sel_hi:[1,0]
	v_pk_mul_f32 v[142:143], v[170:171], 0.5 op_sel_hi:[1,0]
	v_pk_mul_f32 v[136:137], v[168:169], 0.5 op_sel_hi:[1,0]
	v_pk_mul_f32 v[138:139], v[166:167], 0.5 op_sel_hi:[1,0]
	s_waitcnt vmcnt(15)
	v_pk_fma_f32 v[128:129], v[128:129], v[148:149], v[176:177]
	v_pk_fma_f32 v[126:127], v[126:127], v[150:151], v[174:175]
	s_waitcnt vmcnt(14)
	v_pk_fma_f32 v[124:125], v[124:125], v[144:145], v[180:181]
	v_pk_fma_f32 v[122:123], v[122:123], v[146:147], v[178:179]
	s_waitcnt vmcnt(12)
	v_pk_fma_f32 v[112:113], v[112:113], v[140:141], v[188:189]
	v_pk_fma_f32 v[110:111], v[110:111], v[142:143], v[186:187]
	v_pk_fma_f32 v[166:167], v[108:109], v[136:137], v[184:185]
	v_pk_fma_f32 v[168:169], v[106:107], v[138:139], v[182:183]
	s_waitcnt vmcnt(11)
	v_pk_fma_f32 v[120:121], v[120:121], v[148:149], v[192:193]
	v_pk_fma_f32 v[118:119], v[118:119], v[150:151], v[190:191]
	s_waitcnt vmcnt(10)
	v_pk_fma_f32 v[170:171], v[116:117], v[144:145], v[196:197]
	v_pk_fma_f32 v[116:117], v[114:115], v[146:147], v[194:195]
	v_cvt_pk_f16_f32 v106, v126, v127
	v_cvt_pk_f16_f32 v107, v128, v129
	v_cvt_pk_f16_f32 v108, v122, v123
	v_cvt_pk_f16_f32 v109, v124, v125
	s_waitcnt vmcnt(9)
	v_pk_fma_f32 v[100:101], v[100:101], v[140:141], v[200:201]
	v_cvt_pk_f16_f32 v110, v110, v111
	v_cvt_pk_f16_f32 v111, v112, v113
	v_cvt_pk_f16_f32 v112, v168, v169
	v_cvt_pk_f16_f32 v113, v166, v167
	v_cvt_pk_f16_f32 v114, v118, v119
	v_cvt_pk_f16_f32 v115, v120, v121
	v_cvt_pk_f16_f32 v116, v116, v117
	v_cvt_pk_f16_f32 v117, v170, v171
	global_store_dwordx4 v[242:243], v[106:109], off
	global_store_dwordx4 v[242:243], v[110:113], off offset:256
	global_store_dwordx4 v[244:245], v[114:117], off
	v_pk_fma_f32 v[98:99], v[98:99], v[142:143], v[198:199]
	s_waitcnt vmcnt(11)
	v_pk_fma_f32 v[106:107], v[92:93], v[136:137], v[204:205]
	v_pk_fma_f32 v[92:93], v[90:91], v[138:139], v[202:203]
	v_cvt_pk_f16_f32 v90, v98, v99
	v_cvt_pk_f16_f32 v91, v100, v101
	v_cvt_pk_f16_f32 v92, v92, v93
	v_cvt_pk_f16_f32 v93, v106, v107
	global_store_dwordx4 v[244:245], v[90:93], off offset:256
	s_waitcnt vmcnt(10)
	v_pk_fma_f32 v[94:95], v[94:95], v[146:147], v[210:211]
	v_pk_fma_f32 v[96:97], v[96:97], v[144:145], v[212:213]
	v_pk_fma_f32 v[92:93], v[104:105], v[148:149], v[208:209]
	v_pk_fma_f32 v[90:91], v[102:103], v[150:151], v[206:207]
	s_waitcnt vmcnt(9)
	v_pk_fma_f32 v[84:85], v[84:85], v[140:141], v[216:217]
	v_cvt_pk_f16_f32 v90, v90, v91
	v_cvt_pk_f16_f32 v91, v92, v93
	v_cvt_pk_f16_f32 v92, v94, v95
	v_lshlrev_b64 v[94:95], 12, v[238:239]
	v_lshl_add_u64 v[94:95], s[6:7], 0, v[94:95]
	v_cvt_pk_f16_f32 v93, v96, v97
	v_lshl_add_u64 v[94:95], v[94:95], 0, v[134:135]
	global_store_dwordx4 v[94:95], v[90:93], off
	v_pk_fma_f32 v[82:83], v[82:83], v[142:143], v[214:215]
	s_waitcnt vmcnt(7)
	v_pk_fma_f32 v[78:79], v[78:79], v[146:147], v[226:227]
	v_pk_fma_f32 v[90:91], v[76:77], v[136:137], v[220:221]
	v_pk_fma_f32 v[76:77], v[74:75], v[138:139], v[218:219]
	v_cvt_pk_f16_f32 v74, v82, v83
	v_cvt_pk_f16_f32 v75, v84, v85
	v_cvt_pk_f16_f32 v76, v76, v77
	v_cvt_pk_f16_f32 v77, v90, v91
	global_store_dwordx4 v[94:95], v[74:77], off offset:256
	v_pk_fma_f32 v[80:81], v[80:81], v[144:145], v[228:229]
	s_waitcnt vmcnt(6)
	v_pk_fma_f32 v[72:73], v[72:73], v[140:141], v[236:237]
	v_pk_fma_f32 v[76:77], v[88:89], v[148:149], v[224:225]
	v_pk_fma_f32 v[74:75], v[86:87], v[150:151], v[222:223]
	v_pk_fma_f32 v[70:71], v[70:71], v[142:143], v[234:235]
	v_cvt_pk_f16_f32 v74, v74, v75
	v_cvt_pk_f16_f32 v75, v76, v77
	v_cvt_pk_f16_f32 v76, v78, v79
	v_lshlrev_b64 v[78:79], 12, v[240:241]
	v_lshl_add_u64 v[78:79], s[6:7], 0, v[78:79]
	v_cvt_pk_f16_f32 v77, v80, v81
	v_lshl_add_u64 v[78:79], v[78:79], 0, v[134:135]
	global_store_dwordx4 v[78:79], v[74:77], off
	v_add_u32_e32 v166, 0x80, v154
	v_ashrrev_i32_e32 v167, 31, v166
	v_pk_fma_f32 v[74:75], v[68:69], v[136:137], v[232:233]
	v_pk_fma_f32 v[68:69], v[66:67], v[138:139], v[230:231]
	v_cvt_pk_f16_f32 v66, v70, v71
	v_cvt_pk_f16_f32 v67, v72, v73
	v_cvt_pk_f16_f32 v68, v68, v69
	v_cvt_pk_f16_f32 v69, v74, v75
	global_store_dwordx4 v[78:79], v[66:69], off offset:256
	v_add_u32_e32 v168, 0x90, v154
	v_ashrrev_i32_e32 v169, 31, v168
	v_lshlrev_b64 v[66:67], 13, v[166:167]
	v_lshl_add_u64 v[78:79], v[152:153], 0, v[66:67]
	global_load_dwordx4 v[66:69], v[78:79], off
	global_load_dwordx4 v[70:73], v[78:79], off offset:16
	global_load_dwordx4 v[74:77], v[78:79], off offset:512
	s_nop 0
	global_load_dwordx4 v[78:81], v[78:79], off offset:528
	v_lshlrev_b64 v[82:83], 13, v[168:169]
	v_lshl_add_u64 v[94:95], v[152:153], 0, v[82:83]
	global_load_dwordx4 v[82:85], v[94:95], off
	global_load_dwordx4 v[86:89], v[94:95], off offset:16
	global_load_dwordx4 v[90:93], v[94:95], off offset:512
	s_nop 0
	global_load_dwordx4 v[94:97], v[94:95], off offset:528
	v_add_u32_e32 v170, 0xa0, v154
	v_ashrrev_i32_e32 v171, 31, v170
	v_lshlrev_b64 v[98:99], 13, v[170:171]
	v_lshl_add_u64 v[110:111], v[152:153], 0, v[98:99]
	global_load_dwordx4 v[98:101], v[110:111], off
	global_load_dwordx4 v[102:105], v[110:111], off offset:16
	global_load_dwordx4 v[106:109], v[110:111], off offset:512
	s_nop 0
	global_load_dwordx4 v[110:113], v[110:111], off offset:528
	v_add_u32_e32 v154, 0xb0, v154
	v_ashrrev_i32_e32 v155, 31, v154
	v_lshlrev_b64 v[114:115], 13, v[154:155]
	v_lshl_add_u64 v[126:127], v[152:153], 0, v[114:115]
	global_load_dwordx4 v[114:117], v[126:127], off
	global_load_dwordx4 v[118:121], v[126:127], off offset:16
	global_load_dwordx4 v[122:125], v[126:127], off offset:512
	s_nop 0
	global_load_dwordx4 v[126:129], v[126:127], off offset:528
	s_waitcnt vmcnt(15)
	v_pk_fma_f32 v[62:63], v[62:63], v[150:151], v[66:67]
	s_waitcnt vmcnt(14)
	v_pk_fma_f32 v[66:67], v[60:61], v[144:145], v[72:73]
	v_pk_fma_f32 v[60:61], v[58:59], v[146:147], v[70:71]
	v_cvt_pk_f16_f32 v58, v62, v63
	v_lshlrev_b64 v[62:63], 12, v[166:167]
	v_pk_fma_f32 v[64:65], v[64:65], v[148:149], v[68:69]
	v_lshl_add_u64 v[62:63], s[6:7], 0, v[62:63]
	v_cvt_pk_f16_f32 v59, v64, v65
	v_cvt_pk_f16_f32 v60, v60, v61
	v_cvt_pk_f16_f32 v61, v66, v67
	v_lshl_add_u64 v[62:63], v[62:63], 0, v[134:135]
	global_store_dwordx4 v[62:63], v[58:61], off
	s_waitcnt vmcnt(14)
	v_pk_fma_f32 v[52:53], v[52:53], v[140:141], v[76:77]
	v_pk_fma_f32 v[50:51], v[50:51], v[142:143], v[74:75]
	s_waitcnt vmcnt(13)
	v_pk_fma_f32 v[58:59], v[44:45], v[136:137], v[80:81]
	v_pk_fma_f32 v[44:45], v[42:43], v[138:139], v[78:79]
	v_cvt_pk_f16_f32 v42, v50, v51
	v_cvt_pk_f16_f32 v43, v52, v53
	v_cvt_pk_f16_f32 v44, v44, v45
	v_cvt_pk_f16_f32 v45, v58, v59
	global_store_dwordx4 v[62:63], v[42:45], off offset:256
	s_waitcnt vmcnt(12)
	v_pk_fma_f32 v[46:47], v[46:47], v[146:147], v[86:87]
	v_pk_fma_f32 v[48:49], v[48:49], v[144:145], v[88:89]
	v_pk_fma_f32 v[44:45], v[56:57], v[148:149], v[84:85]
	v_pk_fma_f32 v[42:43], v[54:55], v[150:151], v[82:83]
	s_waitcnt vmcnt(11)
	v_pk_fma_f32 v[36:37], v[36:37], v[140:141], v[92:93]
	v_cvt_pk_f16_f32 v42, v42, v43
	v_cvt_pk_f16_f32 v43, v44, v45
	v_cvt_pk_f16_f32 v44, v46, v47
	v_lshlrev_b64 v[46:47], 12, v[168:169]
	v_lshl_add_u64 v[46:47], s[6:7], 0, v[46:47]
	v_cvt_pk_f16_f32 v45, v48, v49
	v_lshl_add_u64 v[46:47], v[46:47], 0, v[134:135]
	global_store_dwordx4 v[46:47], v[42:45], off
	v_pk_fma_f32 v[34:35], v[34:35], v[142:143], v[90:91]
	s_waitcnt vmcnt(9)
	v_pk_fma_f32 v[30:31], v[30:31], v[146:147], v[102:103]
	v_pk_fma_f32 v[42:43], v[28:29], v[136:137], v[96:97]
	v_pk_fma_f32 v[28:29], v[26:27], v[138:139], v[94:95]
	v_cvt_pk_f16_f32 v26, v34, v35
	v_cvt_pk_f16_f32 v27, v36, v37
	v_cvt_pk_f16_f32 v28, v28, v29
	v_cvt_pk_f16_f32 v29, v42, v43
	global_store_dwordx4 v[46:47], v[26:29], off offset:256
	v_pk_fma_f32 v[32:33], v[32:33], v[144:145], v[104:105]
	s_waitcnt vmcnt(9)
	v_pk_fma_f32 v[20:21], v[20:21], v[140:141], v[108:109]
	v_pk_fma_f32 v[28:29], v[40:41], v[148:149], v[100:101]
	v_pk_fma_f32 v[26:27], v[38:39], v[150:151], v[98:99]
	v_pk_fma_f32 v[18:19], v[18:19], v[142:143], v[106:107]
	v_cvt_pk_f16_f32 v26, v26, v27
	v_cvt_pk_f16_f32 v27, v28, v29
	v_cvt_pk_f16_f32 v28, v30, v31
	v_lshlrev_b64 v[30:31], 12, v[170:171]
	v_lshl_add_u64 v[30:31], s[6:7], 0, v[30:31]
	v_cvt_pk_f16_f32 v29, v32, v33
	v_lshl_add_u64 v[30:31], v[30:31], 0, v[134:135]
	global_store_dwordx4 v[30:31], v[26:29], off
	s_waitcnt vmcnt(7)
	v_pk_fma_f32 v[14:15], v[14:15], v[146:147], v[118:119]
	v_pk_fma_f32 v[16:17], v[16:17], v[144:145], v[120:121]
	v_pk_fma_f32 v[26:27], v[12:13], v[136:137], v[112:113]
	v_pk_fma_f32 v[12:13], v[10:11], v[138:139], v[110:111]
	v_cvt_pk_f16_f32 v10, v18, v19
	v_cvt_pk_f16_f32 v11, v20, v21
	v_cvt_pk_f16_f32 v12, v12, v13
	v_cvt_pk_f16_f32 v13, v26, v27
	global_store_dwordx4 v[30:31], v[10:13], off offset:256
	s_waitcnt vmcnt(7)
	v_pk_fma_f32 v[8:9], v[8:9], v[140:141], v[124:125]
	v_pk_fma_f32 v[6:7], v[6:7], v[142:143], v[122:123]
	v_pk_fma_f32 v[12:13], v[24:25], v[148:149], v[116:117]
	v_pk_fma_f32 v[10:11], v[22:23], v[150:151], v[114:115]
	s_nop 0
	v_cvt_pk_f16_f32 v10, v10, v11
	v_cvt_pk_f16_f32 v11, v12, v13
	v_cvt_pk_f16_f32 v12, v14, v15
	v_lshlrev_b64 v[14:15], 12, v[154:155]
	v_lshl_add_u64 v[14:15], s[6:7], 0, v[14:15]
	v_cvt_pk_f16_f32 v13, v16, v17
	v_lshl_add_u64 v[14:15], v[14:15], 0, v[134:135]
	global_store_dwordx4 v[14:15], v[10:13], off
	s_waitcnt vmcnt(7)
	s_nop 0
	v_pk_fma_f32 v[10:11], v[4:5], v[136:137], v[128:129]
	v_pk_fma_f32 v[4:5], v[2:3], v[138:139], v[126:127]
	v_cvt_pk_f16_f32 v2, v6, v7
	v_cvt_pk_f16_f32 v3, v8, v9
	v_cvt_pk_f16_f32 v4, v4, v5
	v_cvt_pk_f16_f32 v5, v10, v11
	global_store_dwordx4 v[14:15], v[2:5], off offset:256
	s_cbranch_vccnz .LBB0_465
	s_andn2_b64 vcc, exec, s[4:5]
	s_cbranch_vccnz .LBB0_464
	s_mov_b32 s99, 1
	s_branch .LBB0_464

.LBB0_653:
	s_ashr_i32 s23, s22, 31
	s_lshl_b64 s[24:25], s[22:23], 20
	s_add_u32 s24, s35, s24
	s_addc_u32 s25, s36, s25
	s_and_b64 s[26:27], s[2:3], exec
	s_cselect_b32 s7, s25, s11
	s_cselect_b32 s9, s24, s10
	s_ashr_i32 s21, s20, 31
	s_lshl_b64 s[26:27], s[20:21], 20
	s_add_u32 s26, s37, s26
	s_addc_u32 s27, s40, s27
	s_and_b64 s[28:29], s[2:3], exec
	s_cselect_b32 s21, s27, s5
	s_cselect_b32 s23, s26, s4
	s_add_u32 s30, s4, 0x100
	s_addc_u32 s31, s5, 0
	s_add_u32 s4, s10, 0x80080
	s_addc_u32 s5, s11, 0
	s_add_u32 s33, s10, 0x100
	v_mov_b32_e32 v2, 0
	s_addc_u32 s73, s11, 0
	s_mov_b32 s74, -2
	v_mov_b32_e32 v3, v2
	v_mov_b32_e32 v4, v2
	v_mov_b32_e32 v5, v2
	v_mov_b32_e32 v6, v2
	v_mov_b32_e32 v7, v2
	s_waitcnt vmcnt(25)
	v_mov_b32_e32 v8, v2
	s_waitcnt vmcnt(24)
	v_mov_b32_e32 v9, v2
	s_waitcnt vmcnt(15)
	v_mov_b32_e32 v18, v2
	s_waitcnt vmcnt(14)
	v_mov_b32_e32 v19, v2
	s_waitcnt vmcnt(13)
	v_mov_b32_e32 v20, v2
	s_waitcnt vmcnt(12)
	v_mov_b32_e32 v21, v2
	s_waitcnt vmcnt(11)
	v_mov_b32_e32 v22, v2
	s_waitcnt vmcnt(10)
	v_mov_b32_e32 v23, v2
	s_waitcnt vmcnt(9)
	v_mov_b32_e32 v24, v2
	s_waitcnt vmcnt(8)
	v_mov_b32_e32 v25, v2
	v_mov_b32_e32 v34, v2
	v_mov_b32_e32 v35, v2
	v_mov_b32_e32 v36, v2
	v_mov_b32_e32 v37, v2
	v_mov_b32_e32 v38, v2
	v_mov_b32_e32 v39, v2
	v_mov_b32_e32 v40, v2
	v_mov_b32_e32 v41, v2
	v_mov_b32_e32 v50, v2
	v_mov_b32_e32 v51, v2
	v_mov_b32_e32 v52, v2
	v_mov_b32_e32 v53, v2
	v_mov_b32_e32 v54, v2
	v_mov_b32_e32 v55, v2
	v_mov_b32_e32 v56, v2
	v_mov_b32_e32 v57, v2
	v_mov_b32_e32 v10, v2
	v_mov_b32_e32 v11, v2
	v_mov_b32_e32 v12, v2
	v_mov_b32_e32 v13, v2
	v_mov_b32_e32 v14, v2
	v_mov_b32_e32 v15, v2
	v_mov_b32_e32 v16, v2
	v_mov_b32_e32 v17, v2
	s_waitcnt vmcnt(7)
	v_mov_b32_e32 v26, v2
	s_waitcnt vmcnt(6)
	v_mov_b32_e32 v27, v2
	s_waitcnt vmcnt(5)
	v_mov_b32_e32 v28, v2
	s_waitcnt vmcnt(4)
	v_mov_b32_e32 v29, v2
	s_waitcnt vmcnt(3)
	v_mov_b32_e32 v30, v2
	s_waitcnt vmcnt(2)
	v_mov_b32_e32 v31, v2
	s_waitcnt vmcnt(1)
	v_mov_b32_e32 v32, v2
	s_waitcnt vmcnt(0)
	v_mov_b32_e32 v33, v2
	v_mov_b32_e32 v42, v2
	v_mov_b32_e32 v43, v2
	v_mov_b32_e32 v44, v2
	v_mov_b32_e32 v45, v2
	v_mov_b32_e32 v46, v2
	v_mov_b32_e32 v47, v2
	v_mov_b32_e32 v48, v2
	v_mov_b32_e32 v49, v2
	v_mov_b32_e32 v58, v2
	v_mov_b32_e32 v59, v2
	v_mov_b32_e32 v60, v2
	v_mov_b32_e32 v61, v2
	v_mov_b32_e32 v62, v2
	v_mov_b32_e32 v63, v2
	v_mov_b32_e32 v64, v2
	v_mov_b32_e32 v65, v2
	v_mov_b32_e32 v66, v2
	v_mov_b32_e32 v67, v2
	v_mov_b32_e32 v68, v2
	v_mov_b32_e32 v69, v2
	v_mov_b32_e32 v70, v2
	v_mov_b32_e32 v71, v2
	v_mov_b32_e32 v72, v2
	v_mov_b32_e32 v73, v2
	v_mov_b32_e32 v82, v2
	v_mov_b32_e32 v83, v2
	v_mov_b32_e32 v84, v2
	v_mov_b32_e32 v85, v2
	v_mov_b32_e32 v86, v2
	v_mov_b32_e32 v87, v2
	v_mov_b32_e32 v88, v2
	v_mov_b32_e32 v89, v2
	v_mov_b32_e32 v98, v2
	v_mov_b32_e32 v99, v2
	v_mov_b32_e32 v100, v2
	v_mov_b32_e32 v101, v2
	v_mov_b32_e32 v102, v2
	v_mov_b32_e32 v103, v2
	v_mov_b32_e32 v104, v2
	v_mov_b32_e32 v105, v2
	v_mov_b32_e32 v114, v2
	v_mov_b32_e32 v115, v2
	v_mov_b32_e32 v116, v2
	v_mov_b32_e32 v117, v2
	v_mov_b32_e32 v118, v2
	v_mov_b32_e32 v119, v2
	v_mov_b32_e32 v120, v2
	v_mov_b32_e32 v121, v2
	v_mov_b32_e32 v74, v2
	v_mov_b32_e32 v75, v2
	v_mov_b32_e32 v76, v2
	v_mov_b32_e32 v77, v2
	v_mov_b32_e32 v78, v2
	v_mov_b32_e32 v79, v2
	v_mov_b32_e32 v80, v2
	v_mov_b32_e32 v81, v2
	v_mov_b32_e32 v90, v2
	v_mov_b32_e32 v91, v2
	v_mov_b32_e32 v92, v2
	v_mov_b32_e32 v93, v2
	v_mov_b32_e32 v94, v2
	v_mov_b32_e32 v95, v2
	v_mov_b32_e32 v96, v2
	v_mov_b32_e32 v97, v2
	v_mov_b32_e32 v106, v2
	v_mov_b32_e32 v107, v2
	v_mov_b32_e32 v108, v2
	v_mov_b32_e32 v109, v2
	v_mov_b32_e32 v110, v2
	v_mov_b32_e32 v111, v2
	v_mov_b32_e32 v112, v2
	v_mov_b32_e32 v113, v2
	v_mov_b32_e32 v122, v2
	v_mov_b32_e32 v123, v2
	v_mov_b32_e32 v124, v2
	v_mov_b32_e32 v125, v2
	v_mov_b32_e32 v126, v2
	v_mov_b32_e32 v127, v2
	v_mov_b32_e32 v128, v2
	v_mov_b32_e32 v129, v2
	s_cmp_eq_u32 s99, 0
	s_cbranch_scc1 .Lro_skip_11
	s_barrier
	s_mov_b32 s99, 0
.Lro_skip_11:
.LBB0_654:
	ds_read_b128 v[130:133], v161
	ds_read_b128 v[138:141], v161 offset:1024
	ds_read_b128 v[142:145], v161 offset:2048
	ds_read_b128 v[146:149], v161 offset:3072
	ds_read_b128 v[150:153], v162
	ds_read_b128 v[168:171], v162 offset:1024
	ds_read_b128 v[172:175], v162 offset:2048
	ds_read_b128 v[176:179], v162 offset:3072
	s_cmp_eq_u32 s74, 28
	s_cselect_b32 s11, s21, s31
	s_cselect_b32 s10, s23, s30
	s_cselect_b32 s29, s7, s73
	s_cselect_b32 s28, s9, s33
	ds_read_b128 v[180:183], v163
	ds_read_b128 v[184:187], v163 offset:1024
	ds_read_b128 v[188:191], v163 offset:2048
	ds_read_b128 v[192:195], v163 offset:3072
	ds_read_b128 v[196:199], v163 offset:4096
	ds_read_b128 v[200:203], v163 offset:5120
	ds_read_b128 v[204:207], v163 offset:6144
	ds_read_b128 v[208:211], v163 offset:7168
	s_add_u32 s76, s4, 0xfff80000
	s_addc_u32 s77, s5, -1
	s_mov_b32 s75, m0
	s_mov_b32 m0, s80
	s_nop 0
	global_load_lds_dwordx4 v1, s[76:77]
	s_mov_b32 m0, s75
	s_nop 0
	s_mov_b32 s75, m0
	s_mov_b32 m0, s82
	s_nop 0
	global_load_lds_dwordx4 v157, s[76:77]
	s_mov_b32 m0, s75
	s_nop 0
	s_mov_b32 s75, m0
	s_mov_b32 m0, s81
	s_nop 0
	global_load_lds_dwordx4 v1, s[4:5]
	s_mov_b32 m0, s75
	s_nop 0
	s_mov_b32 s75, m0
	s_mov_b32 m0, s83
	s_nop 0
	global_load_lds_dwordx4 v157, s[4:5]
	s_mov_b32 m0, s75
	s_waitcnt vmcnt(8)
	s_waitcnt lgkmcnt(0)
	s_barrier
	s_setprio 1
	s_waitcnt lgkmcnt(7)
	v_mfma_f32_16x16x32_bf16 v[126:129], v[130:133], v[180:183], v[126:129]
	v_mfma_f32_16x16x32_bf16 v[122:125], v[142:145], v[180:183], v[122:125]
	s_waitcnt lgkmcnt(5)
	v_mfma_f32_16x16x32_bf16 v[110:113], v[130:133], v[188:191], v[110:113]
	v_mfma_f32_16x16x32_bf16 v[106:109], v[142:145], v[188:191], v[106:109]
	s_waitcnt lgkmcnt(3)
	v_mfma_f32_16x16x32_bf16 v[94:97], v[130:133], v[196:199], v[94:97]
	v_mfma_f32_16x16x32_bf16 v[90:93], v[142:145], v[196:199], v[90:93]
	s_waitcnt lgkmcnt(1)
	v_mfma_f32_16x16x32_bf16 v[78:81], v[130:133], v[204:207], v[78:81]
	v_mfma_f32_16x16x32_bf16 v[74:77], v[142:145], v[204:207], v[74:77]
	v_mfma_f32_16x16x32_bf16 v[126:129], v[138:141], v[184:187], v[126:129]
	v_mfma_f32_16x16x32_bf16 v[122:125], v[146:149], v[184:187], v[122:125]
	v_mfma_f32_16x16x32_bf16 v[110:113], v[138:141], v[192:195], v[110:113]
	v_mfma_f32_16x16x32_bf16 v[106:109], v[146:149], v[192:195], v[106:109]
	v_mfma_f32_16x16x32_bf16 v[94:97], v[138:141], v[200:203], v[94:97]
	v_mfma_f32_16x16x32_bf16 v[90:93], v[146:149], v[200:203], v[90:93]
	s_waitcnt lgkmcnt(0)
	v_mfma_f32_16x16x32_bf16 v[78:81], v[138:141], v[208:211], v[78:81]
	v_mfma_f32_16x16x32_bf16 v[74:77], v[146:149], v[208:211], v[74:77]
	s_setprio 0
	s_setprio 1
	v_mfma_f32_16x16x32_bf16 v[118:121], v[150:153], v[180:183], v[118:121]
	v_mfma_f32_16x16x32_bf16 v[114:117], v[172:175], v[180:183], v[114:117]
	v_mfma_f32_16x16x32_bf16 v[102:105], v[150:153], v[188:191], v[102:105]
	v_mfma_f32_16x16x32_bf16 v[98:101], v[172:175], v[188:191], v[98:101]
	v_mfma_f32_16x16x32_bf16 v[86:89], v[150:153], v[196:199], v[86:89]
	v_mfma_f32_16x16x32_bf16 v[82:85], v[172:175], v[196:199], v[82:85]
	v_mfma_f32_16x16x32_bf16 v[70:73], v[150:153], v[204:207], v[70:73]
	v_mfma_f32_16x16x32_bf16 v[66:69], v[172:175], v[204:207], v[66:69]
	v_mfma_f32_16x16x32_bf16 v[118:121], v[168:171], v[184:187], v[118:121]
	v_mfma_f32_16x16x32_bf16 v[114:117], v[176:179], v[184:187], v[114:117]
	v_mfma_f32_16x16x32_bf16 v[102:105], v[168:171], v[192:195], v[102:105]
	v_mfma_f32_16x16x32_bf16 v[98:101], v[176:179], v[192:195], v[98:101]
	v_mfma_f32_16x16x32_bf16 v[86:89], v[168:171], v[200:203], v[86:89]
	v_mfma_f32_16x16x32_bf16 v[82:85], v[176:179], v[200:203], v[82:85]
	s_setprio 2
	s_barrier
	v_mfma_f32_16x16x32_bf16 v[70:73], v[168:171], v[208:211], v[70:73]
	v_mfma_f32_16x16x32_bf16 v[66:69], v[176:179], v[208:211], v[66:69]
	s_setprio 0
	ds_read_b128 v[180:183], v163 offset:16384
	ds_read_b128 v[184:187], v163 offset:17408
	ds_read_b128 v[188:191], v163 offset:18432
	ds_read_b128 v[192:195], v163 offset:19456
	ds_read_b128 v[196:199], v163 offset:20480
	ds_read_b128 v[200:203], v163 offset:21504
	ds_read_b128 v[204:207], v163 offset:22528
	ds_read_b128 v[208:211], v163 offset:23552
	s_mov_b32 s75, m0
	s_mov_b32 m0, s43
	s_nop 0
	global_load_lds_dwordx4 v156, s[10:11]
	s_mov_b32 m0, s75
	s_add_u32 s76, s10, 0x80000
	s_mov_b32 s75, m0
	s_mov_b32 m0, s46
	s_nop 0
	global_load_lds_dwordx4 v158, s[10:11]
	s_mov_b32 m0, s75
	s_addc_u32 s77, s11, 0
	s_mov_b32 s75, m0
	s_mov_b32 m0, s47
	s_nop 0
	global_load_lds_dwordx4 v156, s[76:77]
	s_mov_b32 m0, s75
	s_nop 0
	s_mov_b32 s75, m0
	s_mov_b32 m0, s48
	s_nop 0
	global_load_lds_dwordx4 v158, s[76:77]
	s_mov_b32 m0, s75
	s_waitcnt vmcnt(4)
	s_waitcnt lgkmcnt(0)
	s_barrier
	s_setprio 1
	s_waitcnt lgkmcnt(7)
	v_mfma_f32_16x16x32_bf16 v[62:65], v[130:133], v[180:183], v[62:65]
	v_mfma_f32_16x16x32_bf16 v[58:61], v[142:145], v[180:183], v[58:61]
	s_waitcnt lgkmcnt(5)
	v_mfma_f32_16x16x32_bf16 v[46:49], v[130:133], v[188:191], v[46:49]
	v_mfma_f32_16x16x32_bf16 v[42:45], v[142:145], v[188:191], v[42:45]
	s_waitcnt lgkmcnt(3)
	v_mfma_f32_16x16x32_bf16 v[30:33], v[130:133], v[196:199], v[30:33]
	v_mfma_f32_16x16x32_bf16 v[26:29], v[142:145], v[196:199], v[26:29]
	s_waitcnt lgkmcnt(1)
	v_mfma_f32_16x16x32_bf16 v[14:17], v[130:133], v[204:207], v[14:17]
	v_mfma_f32_16x16x32_bf16 v[10:13], v[142:145], v[204:207], v[10:13]
	v_mfma_f32_16x16x32_bf16 v[62:65], v[138:141], v[184:187], v[62:65]
	v_mfma_f32_16x16x32_bf16 v[58:61], v[146:149], v[184:187], v[58:61]
	v_mfma_f32_16x16x32_bf16 v[46:49], v[138:141], v[192:195], v[46:49]
	v_mfma_f32_16x16x32_bf16 v[42:45], v[146:149], v[192:195], v[42:45]
	v_mfma_f32_16x16x32_bf16 v[30:33], v[138:141], v[200:203], v[30:33]
	v_mfma_f32_16x16x32_bf16 v[26:29], v[146:149], v[200:203], v[26:29]
	s_waitcnt lgkmcnt(0)
	v_mfma_f32_16x16x32_bf16 v[14:17], v[138:141], v[208:211], v[14:17]
	v_mfma_f32_16x16x32_bf16 v[10:13], v[146:149], v[208:211], v[10:13]
	s_setprio 0
	s_setprio 1
	v_mfma_f32_16x16x32_bf16 v[54:57], v[150:153], v[180:183], v[54:57]
	v_mfma_f32_16x16x32_bf16 v[50:53], v[172:175], v[180:183], v[50:53]
	v_mfma_f32_16x16x32_bf16 v[38:41], v[150:153], v[188:191], v[38:41]
	v_mfma_f32_16x16x32_bf16 v[34:37], v[172:175], v[188:191], v[34:37]
	v_mfma_f32_16x16x32_bf16 v[22:25], v[150:153], v[196:199], v[22:25]
	v_mfma_f32_16x16x32_bf16 v[18:21], v[172:175], v[196:199], v[18:21]
	v_mfma_f32_16x16x32_bf16 v[6:9], v[150:153], v[204:207], v[6:9]
	v_mfma_f32_16x16x32_bf16 v[2:5], v[172:175], v[204:207], v[2:5]
	v_mfma_f32_16x16x32_bf16 v[54:57], v[168:171], v[184:187], v[54:57]
	v_mfma_f32_16x16x32_bf16 v[50:53], v[176:179], v[184:187], v[50:53]
	v_mfma_f32_16x16x32_bf16 v[38:41], v[168:171], v[192:195], v[38:41]
	v_mfma_f32_16x16x32_bf16 v[34:37], v[176:179], v[192:195], v[34:37]
	v_mfma_f32_16x16x32_bf16 v[22:25], v[168:171], v[200:203], v[22:25]
	v_mfma_f32_16x16x32_bf16 v[18:21], v[176:179], v[200:203], v[18:21]
	s_setprio 2
	s_barrier
	v_mfma_f32_16x16x32_bf16 v[6:9], v[168:171], v[208:211], v[6:9]
	v_mfma_f32_16x16x32_bf16 v[2:5], v[176:179], v[208:211], v[2:5]
	s_setprio 0
	ds_read_b128 v[130:133], v164
	ds_read_b128 v[138:141], v164 offset:1024
	ds_read_b128 v[142:145], v164 offset:2048
	ds_read_b128 v[146:149], v164 offset:3072
	ds_read_b128 v[150:153], v165
	ds_read_b128 v[168:171], v165 offset:1024
	ds_read_b128 v[172:175], v165 offset:2048
	ds_read_b128 v[176:179], v165 offset:3072
	ds_read_b128 v[180:183], v163 offset:32768
	ds_read_b128 v[184:187], v163 offset:33792
	ds_read_b128 v[188:191], v163 offset:34816
	ds_read_b128 v[192:195], v163 offset:35840
	ds_read_b128 v[196:199], v163 offset:36864
	ds_read_b128 v[200:203], v163 offset:37888
	ds_read_b128 v[204:207], v163 offset:38912
	ds_read_b128 v[208:211], v163 offset:39936
	s_mov_b32 s75, m0
	s_mov_b32 m0, s42
	s_nop 0
	global_load_lds_dwordx4 v1, s[28:29]
	s_mov_b32 m0, s75
	s_nop 0
	s_mov_b32 s75, m0
	s_mov_b32 m0, s49
	s_nop 0
	global_load_lds_dwordx4 v157, s[28:29]
	s_mov_b32 m0, s75
	s_add_u32 s28, s28, 0x80000
	s_addc_u32 s29, s29, 0
	s_mov_b32 s75, m0
	s_mov_b32 m0, s56
	s_nop 0
	global_load_lds_dwordx4 v1, s[28:29]
	s_mov_b32 m0, s75
	s_nop 0
	s_mov_b32 s75, m0
	s_mov_b32 m0, s57
	s_nop 0
	global_load_lds_dwordx4 v157, s[28:29]
	s_mov_b32 m0, s75
	s_waitcnt vmcnt(8)
	s_waitcnt lgkmcnt(0)
	s_barrier
	s_setprio 1
	s_waitcnt lgkmcnt(7)
	v_mfma_f32_16x16x32_bf16 v[126:129], v[130:133], v[180:183], v[126:129]
	v_mfma_f32_16x16x32_bf16 v[122:125], v[142:145], v[180:183], v[122:125]
	s_waitcnt lgkmcnt(5)
	v_mfma_f32_16x16x32_bf16 v[110:113], v[130:133], v[188:191], v[110:113]
	v_mfma_f32_16x16x32_bf16 v[106:109], v[142:145], v[188:191], v[106:109]
	s_waitcnt lgkmcnt(3)
	v_mfma_f32_16x16x32_bf16 v[94:97], v[130:133], v[196:199], v[94:97]
	v_mfma_f32_16x16x32_bf16 v[90:93], v[142:145], v[196:199], v[90:93]
	s_waitcnt lgkmcnt(1)
	v_mfma_f32_16x16x32_bf16 v[78:81], v[130:133], v[204:207], v[78:81]
	v_mfma_f32_16x16x32_bf16 v[74:77], v[142:145], v[204:207], v[74:77]
	v_mfma_f32_16x16x32_bf16 v[126:129], v[138:141], v[184:187], v[126:129]
	v_mfma_f32_16x16x32_bf16 v[122:125], v[146:149], v[184:187], v[122:125]
	v_mfma_f32_16x16x32_bf16 v[110:113], v[138:141], v[192:195], v[110:113]
	v_mfma_f32_16x16x32_bf16 v[106:109], v[146:149], v[192:195], v[106:109]
	v_mfma_f32_16x16x32_bf16 v[94:97], v[138:141], v[200:203], v[94:97]
	v_mfma_f32_16x16x32_bf16 v[90:93], v[146:149], v[200:203], v[90:93]
	s_waitcnt lgkmcnt(0)
	v_mfma_f32_16x16x32_bf16 v[78:81], v[138:141], v[208:211], v[78:81]
	v_mfma_f32_16x16x32_bf16 v[74:77], v[146:149], v[208:211], v[74:77]
	s_setprio 0
	s_setprio 1
	v_mfma_f32_16x16x32_bf16 v[118:121], v[150:153], v[180:183], v[118:121]
	v_mfma_f32_16x16x32_bf16 v[114:117], v[172:175], v[180:183], v[114:117]
	v_mfma_f32_16x16x32_bf16 v[102:105], v[150:153], v[188:191], v[102:105]
	v_mfma_f32_16x16x32_bf16 v[98:101], v[172:175], v[188:191], v[98:101]
	v_mfma_f32_16x16x32_bf16 v[86:89], v[150:153], v[196:199], v[86:89]
	v_mfma_f32_16x16x32_bf16 v[82:85], v[172:175], v[196:199], v[82:85]
	v_mfma_f32_16x16x32_bf16 v[70:73], v[150:153], v[204:207], v[70:73]
	v_mfma_f32_16x16x32_bf16 v[66:69], v[172:175], v[204:207], v[66:69]
	v_mfma_f32_16x16x32_bf16 v[118:121], v[168:171], v[184:187], v[118:121]
	v_mfma_f32_16x16x32_bf16 v[114:117], v[176:179], v[184:187], v[114:117]
	v_mfma_f32_16x16x32_bf16 v[102:105], v[168:171], v[192:195], v[102:105]
	v_mfma_f32_16x16x32_bf16 v[98:101], v[176:179], v[192:195], v[98:101]
	v_mfma_f32_16x16x32_bf16 v[86:89], v[168:171], v[200:203], v[86:89]
	v_mfma_f32_16x16x32_bf16 v[82:85], v[176:179], v[200:203], v[82:85]
	s_setprio 2
	s_barrier
	v_mfma_f32_16x16x32_bf16 v[70:73], v[168:171], v[208:211], v[70:73]
	v_mfma_f32_16x16x32_bf16 v[66:69], v[176:179], v[208:211], v[66:69]
	s_setprio 0
	ds_read_b128 v[180:183], v163 offset:49152
	ds_read_b128 v[184:187], v163 offset:50176
	ds_read_b128 v[188:191], v163 offset:51200
	ds_read_b128 v[192:195], v163 offset:52224
	ds_read_b128 v[196:199], v163 offset:53248
	ds_read_b128 v[200:203], v163 offset:54272
	ds_read_b128 v[204:207], v163 offset:55296
	ds_read_b128 v[208:211], v163 offset:56320
	s_add_u32 s28, s10, 0x80
	s_addc_u32 s29, s11, 0
	s_mov_b32 s75, m0
	s_mov_b32 m0, s64
	s_nop 0
	global_load_lds_dwordx4 v156, s[28:29]
	s_mov_b32 m0, s75
	s_add_u32 s10, s10, 0x80080
	s_mov_b32 s75, m0
	s_mov_b32 m0, s65
	s_nop 0
	global_load_lds_dwordx4 v158, s[28:29]
	s_mov_b32 m0, s75
	s_addc_u32 s11, s11, 0
	s_mov_b32 s28, m0
	s_mov_b32 m0, s66
	s_nop 0
	global_load_lds_dwordx4 v156, s[10:11]
	s_mov_b32 m0, s28
	s_nop 0
	s_mov_b32 s28, m0
	s_mov_b32 m0, s67
	s_nop 0
	global_load_lds_dwordx4 v158, s[10:11]
	s_mov_b32 m0, s28
	s_waitcnt vmcnt(4)
	s_waitcnt lgkmcnt(0)
	s_barrier
	s_setprio 1
	s_waitcnt lgkmcnt(7)
	v_mfma_f32_16x16x32_bf16 v[62:65], v[130:133], v[180:183], v[62:65]
	v_mfma_f32_16x16x32_bf16 v[58:61], v[142:145], v[180:183], v[58:61]
	s_waitcnt lgkmcnt(5)
	v_mfma_f32_16x16x32_bf16 v[46:49], v[130:133], v[188:191], v[46:49]
	v_mfma_f32_16x16x32_bf16 v[42:45], v[142:145], v[188:191], v[42:45]
	s_waitcnt lgkmcnt(3)
	v_mfma_f32_16x16x32_bf16 v[30:33], v[130:133], v[196:199], v[30:33]
	v_mfma_f32_16x16x32_bf16 v[26:29], v[142:145], v[196:199], v[26:29]
	s_waitcnt lgkmcnt(1)
	v_mfma_f32_16x16x32_bf16 v[14:17], v[130:133], v[204:207], v[14:17]
	v_mfma_f32_16x16x32_bf16 v[10:13], v[142:145], v[204:207], v[10:13]
	v_mfma_f32_16x16x32_bf16 v[62:65], v[138:141], v[184:187], v[62:65]
	v_mfma_f32_16x16x32_bf16 v[58:61], v[146:149], v[184:187], v[58:61]
	v_mfma_f32_16x16x32_bf16 v[46:49], v[138:141], v[192:195], v[46:49]
	v_mfma_f32_16x16x32_bf16 v[42:45], v[146:149], v[192:195], v[42:45]
	v_mfma_f32_16x16x32_bf16 v[30:33], v[138:141], v[200:203], v[30:33]
	v_mfma_f32_16x16x32_bf16 v[26:29], v[146:149], v[200:203], v[26:29]
	s_waitcnt lgkmcnt(0)
	v_mfma_f32_16x16x32_bf16 v[14:17], v[138:141], v[208:211], v[14:17]
	v_mfma_f32_16x16x32_bf16 v[10:13], v[146:149], v[208:211], v[10:13]
	s_setprio 0
	s_setprio 1
	v_mfma_f32_16x16x32_bf16 v[54:57], v[150:153], v[180:183], v[54:57]
	v_mfma_f32_16x16x32_bf16 v[50:53], v[172:175], v[180:183], v[50:53]
	v_mfma_f32_16x16x32_bf16 v[38:41], v[150:153], v[188:191], v[38:41]
	v_mfma_f32_16x16x32_bf16 v[34:37], v[172:175], v[188:191], v[34:37]
	v_mfma_f32_16x16x32_bf16 v[22:25], v[150:153], v[196:199], v[22:25]
	v_mfma_f32_16x16x32_bf16 v[18:21], v[172:175], v[196:199], v[18:21]
	v_mfma_f32_16x16x32_bf16 v[6:9], v[150:153], v[204:207], v[6:9]
	v_mfma_f32_16x16x32_bf16 v[2:5], v[172:175], v[204:207], v[2:5]
	v_mfma_f32_16x16x32_bf16 v[54:57], v[168:171], v[184:187], v[54:57]
	v_mfma_f32_16x16x32_bf16 v[50:53], v[176:179], v[184:187], v[50:53]
	v_mfma_f32_16x16x32_bf16 v[38:41], v[168:171], v[192:195], v[38:41]
	v_mfma_f32_16x16x32_bf16 v[34:37], v[176:179], v[192:195], v[34:37]
	v_mfma_f32_16x16x32_bf16 v[22:25], v[168:171], v[200:203], v[22:25]
	v_mfma_f32_16x16x32_bf16 v[18:21], v[176:179], v[200:203], v[18:21]
	s_setprio 2
	s_barrier
	v_mfma_f32_16x16x32_bf16 v[6:9], v[168:171], v[208:211], v[6:9]
	v_mfma_f32_16x16x32_bf16 v[2:5], v[176:179], v[208:211], v[2:5]
	s_setprio 0
	s_add_i32 s74, s74, 2
	s_add_u32 s30, s30, 0x100
	s_addc_u32 s31, s31, 0
	s_add_u32 s4, s4, 0x100
	s_addc_u32 s5, s5, 0
	s_add_u32 s33, s33, 0x100
	s_addc_u32 s73, s73, 0
	s_cmp_gt_u32 s74, 29
	s_cbranch_scc0 .LBB0_654
	s_and_b64 vcc, exec, s[18:19]
	s_cbranch_vccz .LBB0_657
	s_barrier

.LBB0_757:
	s_mov_b64 s[4:5], 0x2c0000
	v_lshl_add_u64 v[2:3], v[14:15], 0, s[4:5]
	s_andn2_b64 vcc, exec, s[2:3]
	s_mov_b64 s[2:3], -1
	global_store_dwordx4 v[2:3], v[10:13], off offset:256
	s_cbranch_vccnz .LBB0_646
	s_andn2_b64 vcc, exec, s[12:13]
	s_cbranch_vccnz .LBB0_645
	s_mov_b32 s99, 1
	s_branch .LBB0_645

.LBB0_1052:
	s_ashr_i32 s13, s12, 31
	s_lshl_b64 s[14:15], s[12:13], 20
	s_add_u32 s14, s28, s14
	s_addc_u32 s15, s29, s15
	s_and_b64 s[16:17], s[2:3], exec
	s_cselect_b32 s13, s15, s23
	s_cselect_b32 s67, s14, s22
	s_ashr_i32 s11, s10, 31
	s_lshl_b64 s[16:17], s[10:11], 20
	s_add_u32 s16, s30, s16
	s_addc_u32 s17, s31, s17
	s_and_b64 s[24:25], s[2:3], exec
	s_cselect_b32 s11, s17, s21
	s_cselect_b32 s73, s16, s20
	s_add_u32 s74, s20, 0x100
	s_addc_u32 s75, s21, 0
	s_add_u32 s20, s22, 0x80080
	s_addc_u32 s21, s23, 0
	s_add_u32 s76, s22, 0x100
	v_mov_b32_e32 v2, 0
	s_addc_u32 s77, s23, 0
	s_mov_b32 s78, -2
	v_mov_b32_e32 v3, v2
	v_mov_b32_e32 v4, v2
	v_mov_b32_e32 v5, v2
	v_mov_b32_e32 v6, v2
	v_mov_b32_e32 v7, v2
	s_waitcnt vmcnt(25)
	v_mov_b32_e32 v8, v2
	s_waitcnt vmcnt(24)
	v_mov_b32_e32 v9, v2
	s_waitcnt vmcnt(15)
	v_mov_b32_e32 v18, v2
	s_waitcnt vmcnt(14)
	v_mov_b32_e32 v19, v2
	s_waitcnt vmcnt(13)
	v_mov_b32_e32 v20, v2
	s_waitcnt vmcnt(12)
	v_mov_b32_e32 v21, v2
	s_waitcnt vmcnt(11)
	v_mov_b32_e32 v22, v2
	s_waitcnt vmcnt(10)
	v_mov_b32_e32 v23, v2
	s_waitcnt vmcnt(9)
	v_mov_b32_e32 v24, v2
	s_waitcnt vmcnt(8)
	v_mov_b32_e32 v25, v2
	v_mov_b32_e32 v34, v2
	v_mov_b32_e32 v35, v2
	v_mov_b32_e32 v36, v2
	v_mov_b32_e32 v37, v2
	v_mov_b32_e32 v38, v2
	v_mov_b32_e32 v39, v2
	v_mov_b32_e32 v40, v2
	v_mov_b32_e32 v41, v2
	v_mov_b32_e32 v50, v2
	v_mov_b32_e32 v51, v2
	v_mov_b32_e32 v52, v2
	v_mov_b32_e32 v53, v2
	v_mov_b32_e32 v54, v2
	v_mov_b32_e32 v55, v2
	v_mov_b32_e32 v56, v2
	v_mov_b32_e32 v57, v2
	v_mov_b32_e32 v10, v2
	v_mov_b32_e32 v11, v2
	v_mov_b32_e32 v12, v2
	v_mov_b32_e32 v13, v2
	v_mov_b32_e32 v14, v2
	v_mov_b32_e32 v15, v2
	v_mov_b32_e32 v16, v2
	v_mov_b32_e32 v17, v2
	s_waitcnt vmcnt(7)
	v_mov_b32_e32 v26, v2
	s_waitcnt vmcnt(6)
	v_mov_b32_e32 v27, v2
	s_waitcnt vmcnt(5)
	v_mov_b32_e32 v28, v2
	s_waitcnt vmcnt(4)
	v_mov_b32_e32 v29, v2
	s_waitcnt vmcnt(3)
	v_mov_b32_e32 v30, v2
	s_waitcnt vmcnt(2)
	v_mov_b32_e32 v31, v2
	s_waitcnt vmcnt(1)
	v_mov_b32_e32 v32, v2
	s_waitcnt vmcnt(0)
	v_mov_b32_e32 v33, v2
	v_mov_b32_e32 v42, v2
	v_mov_b32_e32 v43, v2
	v_mov_b32_e32 v44, v2
	v_mov_b32_e32 v45, v2
	v_mov_b32_e32 v46, v2
	v_mov_b32_e32 v47, v2
	v_mov_b32_e32 v48, v2
	v_mov_b32_e32 v49, v2
	v_mov_b32_e32 v58, v2
	v_mov_b32_e32 v59, v2
	v_mov_b32_e32 v60, v2
	v_mov_b32_e32 v61, v2
	v_mov_b32_e32 v62, v2
	v_mov_b32_e32 v63, v2
	v_mov_b32_e32 v64, v2
	v_mov_b32_e32 v65, v2
	v_mov_b32_e32 v66, v2
	v_mov_b32_e32 v67, v2
	v_mov_b32_e32 v68, v2
	v_mov_b32_e32 v69, v2
	v_mov_b32_e32 v70, v2
	v_mov_b32_e32 v71, v2
	v_mov_b32_e32 v72, v2
	v_mov_b32_e32 v73, v2
	v_mov_b32_e32 v74, v2
	v_mov_b32_e32 v75, v2
	v_mov_b32_e32 v76, v2
	v_mov_b32_e32 v77, v2
	v_mov_b32_e32 v82, v2
	v_mov_b32_e32 v83, v2
	v_mov_b32_e32 v84, v2
	v_mov_b32_e32 v85, v2
	v_mov_b32_e32 v98, v2
	v_mov_b32_e32 v99, v2
	v_mov_b32_e32 v100, v2
	v_mov_b32_e32 v101, v2
	v_mov_b32_e32 v102, v2
	v_mov_b32_e32 v103, v2
	v_mov_b32_e32 v104, v2
	v_mov_b32_e32 v105, v2
	v_mov_b32_e32 v106, v2
	v_mov_b32_e32 v107, v2
	v_mov_b32_e32 v108, v2
	v_mov_b32_e32 v109, v2
	v_mov_b32_e32 v110, v2
	v_mov_b32_e32 v111, v2
	v_mov_b32_e32 v112, v2
	v_mov_b32_e32 v113, v2
	v_mov_b32_e32 v78, v2
	v_mov_b32_e32 v79, v2
	v_mov_b32_e32 v80, v2
	v_mov_b32_e32 v81, v2
	v_mov_b32_e32 v86, v2
	v_mov_b32_e32 v87, v2
	v_mov_b32_e32 v88, v2
	v_mov_b32_e32 v89, v2
	v_mov_b32_e32 v90, v2
	v_mov_b32_e32 v91, v2
	v_mov_b32_e32 v92, v2
	v_mov_b32_e32 v93, v2
	v_mov_b32_e32 v94, v2
	v_mov_b32_e32 v95, v2
	v_mov_b32_e32 v96, v2
	v_mov_b32_e32 v97, v2
	v_mov_b32_e32 v114, v2
	v_mov_b32_e32 v115, v2
	v_mov_b32_e32 v116, v2
	v_mov_b32_e32 v117, v2
	v_mov_b32_e32 v118, v2
	v_mov_b32_e32 v119, v2
	v_mov_b32_e32 v120, v2
	v_mov_b32_e32 v121, v2
	v_mov_b32_e32 v122, v2
	v_mov_b32_e32 v123, v2
	v_mov_b32_e32 v124, v2
	v_mov_b32_e32 v125, v2
	v_mov_b32_e32 v126, v2
	v_mov_b32_e32 v127, v2
	v_mov_b32_e32 v128, v2
	v_mov_b32_e32 v129, v2
	s_cmp_eq_u32 s99, 0
	s_cbranch_scc1 .Lro_skip_10
	s_barrier
	s_mov_b32 s99, 0
.Lro_skip_10:
.LBB0_1053:
	ds_read_b128 v[130:133], v181
	ds_read_b128 v[134:137], v181 offset:1024
	ds_read_b128 v[138:141], v181 offset:2048
	ds_read_b128 v[142:145], v181 offset:3072
	ds_read_b128 v[146:149], v182
	ds_read_b128 v[150:153], v182 offset:1024
	ds_read_b128 v[154:157], v182 offset:2048
	ds_read_b128 v[158:161], v182 offset:3072
	s_cmp_eq_u32 s78, 28
	s_cselect_b32 s23, s11, s75
	s_cselect_b32 s22, s73, s74
	s_cselect_b32 s25, s13, s77
	s_cselect_b32 s24, s67, s76
	ds_read_b128 v[166:169], v183
	ds_read_b128 v[170:173], v183 offset:1024
	ds_read_b128 v[186:189], v183 offset:2048
	ds_read_b128 v[190:193], v183 offset:3072
	ds_read_b128 v[194:197], v183 offset:4096
	ds_read_b128 v[198:201], v183 offset:5120
	ds_read_b128 v[202:205], v183 offset:6144
	ds_read_b128 v[206:209], v183 offset:7168
	s_add_u32 s80, s20, 0xfff80000
	s_addc_u32 s81, s21, -1
	s_mov_b32 s79, m0
	s_mov_b32 m0, s58
	s_nop 0
	global_load_lds_dwordx4 v1, s[80:81]
	s_mov_b32 m0, s79
	s_nop 0
	s_mov_b32 s79, m0
	s_mov_b32 m0, s64
	s_nop 0
	global_load_lds_dwordx4 v177, s[80:81]
	s_mov_b32 m0, s79
	s_nop 0
	s_mov_b32 s79, m0
	s_mov_b32 m0, s59
	s_nop 0
	global_load_lds_dwordx4 v1, s[20:21]
	s_mov_b32 m0, s79
	s_nop 0
	s_mov_b32 s79, m0
	s_mov_b32 m0, s65
	s_nop 0
	global_load_lds_dwordx4 v177, s[20:21]
	s_mov_b32 m0, s79
	s_waitcnt vmcnt(8)
	s_waitcnt lgkmcnt(0)
	s_barrier
	s_setprio 1
	s_waitcnt lgkmcnt(7)
	v_mfma_f32_16x16x32_bf16 v[126:129], v[130:133], v[166:169], v[126:129]
	v_mfma_f32_16x16x32_bf16 v[122:125], v[138:141], v[166:169], v[122:125]
	s_waitcnt lgkmcnt(5)
	v_mfma_f32_16x16x32_bf16 v[118:121], v[130:133], v[186:189], v[118:121]
	v_mfma_f32_16x16x32_bf16 v[114:117], v[138:141], v[186:189], v[114:117]
	s_waitcnt lgkmcnt(3)
	v_mfma_f32_16x16x32_bf16 v[94:97], v[130:133], v[194:197], v[94:97]
	v_mfma_f32_16x16x32_bf16 v[90:93], v[138:141], v[194:197], v[90:93]
	s_waitcnt lgkmcnt(1)
	v_mfma_f32_16x16x32_bf16 v[86:89], v[130:133], v[202:205], v[86:89]
	v_mfma_f32_16x16x32_bf16 v[78:81], v[138:141], v[202:205], v[78:81]
	v_mfma_f32_16x16x32_bf16 v[126:129], v[134:137], v[170:173], v[126:129]
	v_mfma_f32_16x16x32_bf16 v[122:125], v[142:145], v[170:173], v[122:125]
	v_mfma_f32_16x16x32_bf16 v[118:121], v[134:137], v[190:193], v[118:121]
	v_mfma_f32_16x16x32_bf16 v[114:117], v[142:145], v[190:193], v[114:117]
	v_mfma_f32_16x16x32_bf16 v[94:97], v[134:137], v[198:201], v[94:97]
	v_mfma_f32_16x16x32_bf16 v[90:93], v[142:145], v[198:201], v[90:93]
	s_waitcnt lgkmcnt(0)
	v_mfma_f32_16x16x32_bf16 v[86:89], v[134:137], v[206:209], v[86:89]
	v_mfma_f32_16x16x32_bf16 v[78:81], v[142:145], v[206:209], v[78:81]
	s_setprio 0
	s_setprio 1
	v_mfma_f32_16x16x32_bf16 v[110:113], v[146:149], v[166:169], v[110:113]
	v_mfma_f32_16x16x32_bf16 v[106:109], v[154:157], v[166:169], v[106:109]
	v_mfma_f32_16x16x32_bf16 v[102:105], v[146:149], v[186:189], v[102:105]
	v_mfma_f32_16x16x32_bf16 v[98:101], v[154:157], v[186:189], v[98:101]
	v_mfma_f32_16x16x32_bf16 v[82:85], v[146:149], v[194:197], v[82:85]
	v_mfma_f32_16x16x32_bf16 v[74:77], v[154:157], v[194:197], v[74:77]
	v_mfma_f32_16x16x32_bf16 v[70:73], v[146:149], v[202:205], v[70:73]
	v_mfma_f32_16x16x32_bf16 v[66:69], v[154:157], v[202:205], v[66:69]
	v_mfma_f32_16x16x32_bf16 v[110:113], v[150:153], v[170:173], v[110:113]
	v_mfma_f32_16x16x32_bf16 v[106:109], v[158:161], v[170:173], v[106:109]
	v_mfma_f32_16x16x32_bf16 v[102:105], v[150:153], v[190:193], v[102:105]
	v_mfma_f32_16x16x32_bf16 v[98:101], v[158:161], v[190:193], v[98:101]
	v_mfma_f32_16x16x32_bf16 v[82:85], v[150:153], v[198:201], v[82:85]
	v_mfma_f32_16x16x32_bf16 v[74:77], v[158:161], v[198:201], v[74:77]
	s_setprio 2
	s_barrier
	v_mfma_f32_16x16x32_bf16 v[70:73], v[150:153], v[206:209], v[70:73]
	v_mfma_f32_16x16x32_bf16 v[66:69], v[158:161], v[206:209], v[66:69]
	s_setprio 0
	ds_read_b128 v[166:169], v183 offset:16384
	ds_read_b128 v[170:173], v183 offset:17408
	ds_read_b128 v[186:189], v183 offset:18432
	ds_read_b128 v[190:193], v183 offset:19456
	ds_read_b128 v[194:197], v183 offset:20480
	ds_read_b128 v[198:201], v183 offset:21504
	ds_read_b128 v[202:205], v183 offset:22528
	ds_read_b128 v[206:209], v183 offset:23552
	s_mov_b32 s79, m0
	s_mov_b32 m0, s35
	s_nop 0
	global_load_lds_dwordx4 v176, s[22:23]
	s_mov_b32 m0, s79
	s_add_u32 s80, s22, 0x80000
	s_mov_b32 s79, m0
	s_mov_b32 m0, s36
	s_nop 0
	global_load_lds_dwordx4 v178, s[22:23]
	s_mov_b32 m0, s79
	s_addc_u32 s81, s23, 0
	s_mov_b32 s79, m0
	s_mov_b32 m0, s37
	s_nop 0
	global_load_lds_dwordx4 v176, s[80:81]
	s_mov_b32 m0, s79
	s_nop 0
	s_mov_b32 s79, m0
	s_mov_b32 m0, s40
	s_nop 0
	global_load_lds_dwordx4 v178, s[80:81]
	s_mov_b32 m0, s79
	s_waitcnt vmcnt(4)
	s_waitcnt lgkmcnt(0)
	s_barrier
	s_setprio 1
	s_waitcnt lgkmcnt(7)
	v_mfma_f32_16x16x32_bf16 v[62:65], v[130:133], v[166:169], v[62:65]
	v_mfma_f32_16x16x32_bf16 v[58:61], v[138:141], v[166:169], v[58:61]
	s_waitcnt lgkmcnt(5)
	v_mfma_f32_16x16x32_bf16 v[46:49], v[130:133], v[186:189], v[46:49]
	v_mfma_f32_16x16x32_bf16 v[42:45], v[138:141], v[186:189], v[42:45]
	s_waitcnt lgkmcnt(3)
	v_mfma_f32_16x16x32_bf16 v[30:33], v[130:133], v[194:197], v[30:33]
	v_mfma_f32_16x16x32_bf16 v[26:29], v[138:141], v[194:197], v[26:29]
	s_waitcnt lgkmcnt(1)
	v_mfma_f32_16x16x32_bf16 v[14:17], v[130:133], v[202:205], v[14:17]
	v_mfma_f32_16x16x32_bf16 v[10:13], v[138:141], v[202:205], v[10:13]
	v_mfma_f32_16x16x32_bf16 v[62:65], v[134:137], v[170:173], v[62:65]
	v_mfma_f32_16x16x32_bf16 v[58:61], v[142:145], v[170:173], v[58:61]
	v_mfma_f32_16x16x32_bf16 v[46:49], v[134:137], v[190:193], v[46:49]
	v_mfma_f32_16x16x32_bf16 v[42:45], v[142:145], v[190:193], v[42:45]
	v_mfma_f32_16x16x32_bf16 v[30:33], v[134:137], v[198:201], v[30:33]
	v_mfma_f32_16x16x32_bf16 v[26:29], v[142:145], v[198:201], v[26:29]
	s_waitcnt lgkmcnt(0)
	v_mfma_f32_16x16x32_bf16 v[14:17], v[134:137], v[206:209], v[14:17]
	v_mfma_f32_16x16x32_bf16 v[10:13], v[142:145], v[206:209], v[10:13]
	s_setprio 0
	s_setprio 1
	v_mfma_f32_16x16x32_bf16 v[54:57], v[146:149], v[166:169], v[54:57]
	v_mfma_f32_16x16x32_bf16 v[50:53], v[154:157], v[166:169], v[50:53]
	v_mfma_f32_16x16x32_bf16 v[38:41], v[146:149], v[186:189], v[38:41]
	v_mfma_f32_16x16x32_bf16 v[34:37], v[154:157], v[186:189], v[34:37]
	v_mfma_f32_16x16x32_bf16 v[22:25], v[146:149], v[194:197], v[22:25]
	v_mfma_f32_16x16x32_bf16 v[18:21], v[154:157], v[194:197], v[18:21]
	v_mfma_f32_16x16x32_bf16 v[6:9], v[146:149], v[202:205], v[6:9]
	v_mfma_f32_16x16x32_bf16 v[2:5], v[154:157], v[202:205], v[2:5]
	v_mfma_f32_16x16x32_bf16 v[54:57], v[150:153], v[170:173], v[54:57]
	v_mfma_f32_16x16x32_bf16 v[50:53], v[158:161], v[170:173], v[50:53]
	v_mfma_f32_16x16x32_bf16 v[38:41], v[150:153], v[190:193], v[38:41]
	v_mfma_f32_16x16x32_bf16 v[34:37], v[158:161], v[190:193], v[34:37]
	v_mfma_f32_16x16x32_bf16 v[22:25], v[150:153], v[198:201], v[22:25]
	v_mfma_f32_16x16x32_bf16 v[18:21], v[158:161], v[198:201], v[18:21]
	s_setprio 2
	s_barrier
	v_mfma_f32_16x16x32_bf16 v[6:9], v[150:153], v[206:209], v[6:9]
	v_mfma_f32_16x16x32_bf16 v[2:5], v[158:161], v[206:209], v[2:5]
	s_setprio 0
	ds_read_b128 v[130:133], v184
	ds_read_b128 v[134:137], v184 offset:1024
	ds_read_b128 v[138:141], v184 offset:2048
	ds_read_b128 v[142:145], v184 offset:3072
	ds_read_b128 v[146:149], v185
	ds_read_b128 v[150:153], v185 offset:1024
	ds_read_b128 v[154:157], v185 offset:2048
	ds_read_b128 v[158:161], v185 offset:3072
	ds_read_b128 v[166:169], v183 offset:32768
	ds_read_b128 v[170:173], v183 offset:33792
	ds_read_b128 v[186:189], v183 offset:34816
	ds_read_b128 v[190:193], v183 offset:35840
	ds_read_b128 v[194:197], v183 offset:36864
	ds_read_b128 v[198:201], v183 offset:37888
	ds_read_b128 v[202:205], v183 offset:38912
	ds_read_b128 v[206:209], v183 offset:39936
	s_mov_b32 s79, m0
	s_mov_b32 m0, s34
	s_nop 0
	global_load_lds_dwordx4 v1, s[24:25]
	s_mov_b32 m0, s79
	s_nop 0
	s_mov_b32 s79, m0
	s_mov_b32 m0, s41
	s_nop 0
	global_load_lds_dwordx4 v177, s[24:25]
	s_mov_b32 m0, s79
	s_add_u32 s24, s24, 0x80000
	s_addc_u32 s25, s25, 0
	s_mov_b32 s79, m0
	s_mov_b32 m0, s42
	s_nop 0
	global_load_lds_dwordx4 v1, s[24:25]
	s_mov_b32 m0, s79
	s_nop 0
	s_mov_b32 s79, m0
	s_mov_b32 m0, s43
	s_nop 0
	global_load_lds_dwordx4 v177, s[24:25]
	s_mov_b32 m0, s79
	s_waitcnt vmcnt(8)
	s_waitcnt lgkmcnt(0)
	s_barrier
	s_setprio 1
	s_waitcnt lgkmcnt(7)
	v_mfma_f32_16x16x32_bf16 v[126:129], v[130:133], v[166:169], v[126:129]
	v_mfma_f32_16x16x32_bf16 v[122:125], v[138:141], v[166:169], v[122:125]
	s_waitcnt lgkmcnt(5)
	v_mfma_f32_16x16x32_bf16 v[118:121], v[130:133], v[186:189], v[118:121]
	v_mfma_f32_16x16x32_bf16 v[114:117], v[138:141], v[186:189], v[114:117]
	s_waitcnt lgkmcnt(3)
	v_mfma_f32_16x16x32_bf16 v[94:97], v[130:133], v[194:197], v[94:97]
	v_mfma_f32_16x16x32_bf16 v[90:93], v[138:141], v[194:197], v[90:93]
	s_waitcnt lgkmcnt(1)
	v_mfma_f32_16x16x32_bf16 v[86:89], v[130:133], v[202:205], v[86:89]
	v_mfma_f32_16x16x32_bf16 v[78:81], v[138:141], v[202:205], v[78:81]
	v_mfma_f32_16x16x32_bf16 v[126:129], v[134:137], v[170:173], v[126:129]
	v_mfma_f32_16x16x32_bf16 v[122:125], v[142:145], v[170:173], v[122:125]
	v_mfma_f32_16x16x32_bf16 v[118:121], v[134:137], v[190:193], v[118:121]
	v_mfma_f32_16x16x32_bf16 v[114:117], v[142:145], v[190:193], v[114:117]
	v_mfma_f32_16x16x32_bf16 v[94:97], v[134:137], v[198:201], v[94:97]
	v_mfma_f32_16x16x32_bf16 v[90:93], v[142:145], v[198:201], v[90:93]
	s_waitcnt lgkmcnt(0)
	v_mfma_f32_16x16x32_bf16 v[86:89], v[134:137], v[206:209], v[86:89]
	v_mfma_f32_16x16x32_bf16 v[78:81], v[142:145], v[206:209], v[78:81]
	s_setprio 0
	s_setprio 1
	v_mfma_f32_16x16x32_bf16 v[110:113], v[146:149], v[166:169], v[110:113]
	v_mfma_f32_16x16x32_bf16 v[106:109], v[154:157], v[166:169], v[106:109]
	v_mfma_f32_16x16x32_bf16 v[102:105], v[146:149], v[186:189], v[102:105]
	v_mfma_f32_16x16x32_bf16 v[98:101], v[154:157], v[186:189], v[98:101]
	v_mfma_f32_16x16x32_bf16 v[82:85], v[146:149], v[194:197], v[82:85]
	v_mfma_f32_16x16x32_bf16 v[74:77], v[154:157], v[194:197], v[74:77]
	v_mfma_f32_16x16x32_bf16 v[70:73], v[146:149], v[202:205], v[70:73]
	v_mfma_f32_16x16x32_bf16 v[66:69], v[154:157], v[202:205], v[66:69]
	v_mfma_f32_16x16x32_bf16 v[110:113], v[150:153], v[170:173], v[110:113]
	v_mfma_f32_16x16x32_bf16 v[106:109], v[158:161], v[170:173], v[106:109]
	v_mfma_f32_16x16x32_bf16 v[102:105], v[150:153], v[190:193], v[102:105]
	v_mfma_f32_16x16x32_bf16 v[98:101], v[158:161], v[190:193], v[98:101]
	v_mfma_f32_16x16x32_bf16 v[82:85], v[150:153], v[198:201], v[82:85]
	v_mfma_f32_16x16x32_bf16 v[74:77], v[158:161], v[198:201], v[74:77]
	s_setprio 2
	s_barrier
	v_mfma_f32_16x16x32_bf16 v[70:73], v[150:153], v[206:209], v[70:73]
	v_mfma_f32_16x16x32_bf16 v[66:69], v[158:161], v[206:209], v[66:69]
	s_setprio 0
	ds_read_b128 v[166:169], v183 offset:49152
	ds_read_b128 v[170:173], v183 offset:50176
	ds_read_b128 v[186:189], v183 offset:51200
	ds_read_b128 v[190:193], v183 offset:52224
	ds_read_b128 v[194:197], v183 offset:53248
	ds_read_b128 v[198:201], v183 offset:54272
	ds_read_b128 v[202:205], v183 offset:55296
	ds_read_b128 v[206:209], v183 offset:56320
	s_add_u32 s24, s22, 0x80
	s_addc_u32 s25, s23, 0
	s_mov_b32 s79, m0
	s_mov_b32 m0, s46
	s_nop 0
	global_load_lds_dwordx4 v176, s[24:25]
	s_mov_b32 m0, s79
	s_add_u32 s22, s22, 0x80080
	s_mov_b32 s79, m0
	s_mov_b32 m0, s47
	s_nop 0
	global_load_lds_dwordx4 v178, s[24:25]
	s_mov_b32 m0, s79
	s_addc_u32 s23, s23, 0
	s_mov_b32 s24, m0
	s_mov_b32 m0, s48
	s_nop 0
	global_load_lds_dwordx4 v176, s[22:23]
	s_mov_b32 m0, s24
	s_nop 0
	s_mov_b32 s24, m0
	s_mov_b32 m0, s49
	s_nop 0
	global_load_lds_dwordx4 v178, s[22:23]
	s_mov_b32 m0, s24
	s_waitcnt vmcnt(4)
	s_waitcnt lgkmcnt(0)
	s_barrier
	s_setprio 1
	s_waitcnt lgkmcnt(7)
	v_mfma_f32_16x16x32_bf16 v[62:65], v[130:133], v[166:169], v[62:65]
	v_mfma_f32_16x16x32_bf16 v[58:61], v[138:141], v[166:169], v[58:61]
	s_waitcnt lgkmcnt(5)
	v_mfma_f32_16x16x32_bf16 v[46:49], v[130:133], v[186:189], v[46:49]
	v_mfma_f32_16x16x32_bf16 v[42:45], v[138:141], v[186:189], v[42:45]
	s_waitcnt lgkmcnt(3)
	v_mfma_f32_16x16x32_bf16 v[30:33], v[130:133], v[194:197], v[30:33]
	v_mfma_f32_16x16x32_bf16 v[26:29], v[138:141], v[194:197], v[26:29]
	s_waitcnt lgkmcnt(1)
	v_mfma_f32_16x16x32_bf16 v[14:17], v[130:133], v[202:205], v[14:17]
	v_mfma_f32_16x16x32_bf16 v[10:13], v[138:141], v[202:205], v[10:13]
	v_mfma_f32_16x16x32_bf16 v[62:65], v[134:137], v[170:173], v[62:65]
	v_mfma_f32_16x16x32_bf16 v[58:61], v[142:145], v[170:173], v[58:61]
	v_mfma_f32_16x16x32_bf16 v[46:49], v[134:137], v[190:193], v[46:49]
	v_mfma_f32_16x16x32_bf16 v[42:45], v[142:145], v[190:193], v[42:45]
	v_mfma_f32_16x16x32_bf16 v[30:33], v[134:137], v[198:201], v[30:33]
	v_mfma_f32_16x16x32_bf16 v[26:29], v[142:145], v[198:201], v[26:29]
	s_waitcnt lgkmcnt(0)
	v_mfma_f32_16x16x32_bf16 v[14:17], v[134:137], v[206:209], v[14:17]
	v_mfma_f32_16x16x32_bf16 v[10:13], v[142:145], v[206:209], v[10:13]
	s_setprio 0
	s_setprio 1
	v_mfma_f32_16x16x32_bf16 v[54:57], v[146:149], v[166:169], v[54:57]
	v_mfma_f32_16x16x32_bf16 v[50:53], v[154:157], v[166:169], v[50:53]
	v_mfma_f32_16x16x32_bf16 v[38:41], v[146:149], v[186:189], v[38:41]
	v_mfma_f32_16x16x32_bf16 v[34:37], v[154:157], v[186:189], v[34:37]
	v_mfma_f32_16x16x32_bf16 v[22:25], v[146:149], v[194:197], v[22:25]
	v_mfma_f32_16x16x32_bf16 v[18:21], v[154:157], v[194:197], v[18:21]
	v_mfma_f32_16x16x32_bf16 v[6:9], v[146:149], v[202:205], v[6:9]
	v_mfma_f32_16x16x32_bf16 v[2:5], v[154:157], v[202:205], v[2:5]
	v_mfma_f32_16x16x32_bf16 v[54:57], v[150:153], v[170:173], v[54:57]
	v_mfma_f32_16x16x32_bf16 v[50:53], v[158:161], v[170:173], v[50:53]
	v_mfma_f32_16x16x32_bf16 v[38:41], v[150:153], v[190:193], v[38:41]
	v_mfma_f32_16x16x32_bf16 v[34:37], v[158:161], v[190:193], v[34:37]
	v_mfma_f32_16x16x32_bf16 v[22:25], v[150:153], v[198:201], v[22:25]
	v_mfma_f32_16x16x32_bf16 v[18:21], v[158:161], v[198:201], v[18:21]
	s_setprio 2
	s_barrier
	v_mfma_f32_16x16x32_bf16 v[6:9], v[150:153], v[206:209], v[6:9]
	v_mfma_f32_16x16x32_bf16 v[2:5], v[158:161], v[206:209], v[2:5]
	s_setprio 0
	s_add_i32 s78, s78, 2
	s_add_u32 s74, s74, 0x100
	s_addc_u32 s75, s75, 0
	s_add_u32 s20, s20, 0x100
	s_addc_u32 s21, s21, 0
	s_add_u32 s76, s76, 0x100
	s_addc_u32 s77, s77, 0
	s_cmp_gt_u32 s78, 29
	s_cbranch_scc0 .LBB0_1053
	s_and_b64 vcc, exec, s[8:9]
	s_cbranch_vccz .LBB0_1056
	s_barrier
.LBB0_1056:
	v_lshl_or_b32 v130, s19, 8, v180
	v_ashrrev_i32_e32 v131, 31, v130
	v_lshl_add_u32 v146, s18, 8, v179
	v_lshlrev_b64 v[166:167], 1, v[130:131]
	v_ashrrev_i32_e32 v147, 31, v146
	v_lshl_add_u64 v[168:169], s[6:7], 0, v[166:167]
	v_lshlrev_b64 v[170:171], 12, v[146:147]
	v_lshl_add_u64 v[132:133], v[168:169], 0, v[170:171]
	global_load_dwordx4 v[186:189], v[132:133], off
	global_load_dwordx4 v[190:193], v[132:133], off offset:256
	s_ashr_i32 s11, s18, 31
	v_or_b32_e32 v132, 16, v146
	s_lshr_b32 s11, s11, 28
	v_ashrrev_i32_e32 v133, 31, v132
	v_lshlrev_b64 v[202:203], 12, v[132:133]
	s_add_i32 s11, s18, s11
	v_lshl_add_u64 v[148:149], v[168:169], 0, v[202:203]
	s_ashr_i32 s11, s11, 4
	global_load_dwordx4 v[194:197], v[148:149], off
	s_mul_hi_i32 s13, s11, 0x12000
	s_mul_i32 s11, s11, 0x12000
	s_add_u32 s18, s56, s11
	s_addc_u32 s19, s57, s13
	v_lshl_add_u64 v[130:131], v[130:131], 2, s[18:19]
	global_load_dwordx4 v[142:145], v[130:131], off
	global_load_dwordx4 v[138:141], v[130:131], off offset:16
	global_load_dwordx4 v[134:137], v[130:131], off offset:512
	s_nop 0
	global_load_dwordx4 v[130:133], v[130:131], off offset:528
	s_nop 0
	global_load_dwordx4 v[198:201], v[148:149], off offset:256
	v_or_b32_e32 v148, 32, v146
	v_ashrrev_i32_e32 v149, 31, v148
	v_lshlrev_b64 v[174:175], 12, v[148:149]
	v_lshl_add_u64 v[148:149], v[168:169], 0, v[174:175]
	global_load_dwordx4 v[150:153], v[148:149], off
	v_or_b32_e32 v146, 48, v146
	v_ashrrev_i32_e32 v147, 31, v146
	v_lshlrev_b64 v[172:173], 12, v[146:147]
	v_lshl_add_u64 v[146:147], s[6:7], 0, v[170:171]
	v_lshl_add_u64 v[204:205], v[168:169], 0, v[172:173]
	v_lshl_add_u64 v[206:207], v[146:147], 0, v[166:167]
	global_load_dwordx4 v[158:161], v[148:149], off offset:256
	global_load_dwordx4 v[154:157], v[204:205], off
	s_nop 0
	global_load_dwordx4 v[146:149], v[204:205], off offset:256
	s_mov_b64 s[18:19], 0x80000
	s_andn2_b64 vcc, exec, s[2:3]
	s_mov_b64 s[2:3], -1
	s_waitcnt vmcnt(11)
	v_cvt_f32_f16_e32 v204, v186
	v_cvt_f32_f16_sdwa v205, v186 dst_sel:DWORD dst_unused:UNUSED_PAD src0_sel:WORD_1
	v_cvt_f32_f16_e32 v186, v187
	v_cvt_f32_f16_sdwa v187, v187 dst_sel:DWORD dst_unused:UNUSED_PAD src0_sel:WORD_1
	v_cvt_f32_f16_e32 v208, v188
	v_cvt_f32_f16_sdwa v209, v188 dst_sel:DWORD dst_unused:UNUSED_PAD src0_sel:WORD_1
	v_cvt_f32_f16_e32 v188, v189
	v_cvt_f32_f16_sdwa v189, v189 dst_sel:DWORD dst_unused:UNUSED_PAD src0_sel:WORD_1
	s_waitcnt vmcnt(10)
	v_cvt_f32_f16_e32 v210, v190
	v_cvt_f32_f16_sdwa v211, v190 dst_sel:DWORD dst_unused:UNUSED_PAD src0_sel:WORD_1
	v_cvt_f32_f16_e32 v190, v191
	v_cvt_f32_f16_sdwa v191, v191 dst_sel:DWORD dst_unused:UNUSED_PAD src0_sel:WORD_1
	v_cvt_f32_f16_e32 v212, v192
	v_cvt_f32_f16_sdwa v213, v192 dst_sel:DWORD dst_unused:UNUSED_PAD src0_sel:WORD_1
	v_cvt_f32_f16_e32 v192, v193
	v_cvt_f32_f16_sdwa v193, v193 dst_sel:DWORD dst_unused:UNUSED_PAD src0_sel:WORD_1
	s_waitcnt vmcnt(9)
	v_cvt_f32_f16_e32 v214, v194
	v_cvt_f32_f16_sdwa v215, v194 dst_sel:DWORD dst_unused:UNUSED_PAD src0_sel:WORD_1
	v_cvt_f32_f16_e32 v194, v195
	v_cvt_f32_f16_sdwa v195, v195 dst_sel:DWORD dst_unused:UNUSED_PAD src0_sel:WORD_1
	v_cvt_f32_f16_e32 v216, v196
	v_cvt_f32_f16_sdwa v217, v196 dst_sel:DWORD dst_unused:UNUSED_PAD src0_sel:WORD_1
	v_cvt_f32_f16_e32 v196, v197
	v_cvt_f32_f16_sdwa v197, v197 dst_sel:DWORD dst_unused:UNUSED_PAD src0_sel:WORD_1
	s_waitcnt vmcnt(8)
	v_pk_fma_f32 v[128:129], v[128:129], v[144:145], v[186:187]
	v_pk_fma_f32 v[126:127], v[126:127], v[142:143], v[204:205]
	s_waitcnt vmcnt(7)
	v_pk_fma_f32 v[124:125], v[124:125], v[140:141], v[188:189]
	v_pk_fma_f32 v[122:123], v[122:123], v[138:139], v[208:209]
	s_waitcnt vmcnt(6)
	v_pk_fma_f32 v[112:113], v[112:113], v[136:137], v[190:191]
	v_pk_fma_f32 v[110:111], v[110:111], v[134:135], v[210:211]
	s_waitcnt vmcnt(5)
	v_pk_fma_f32 v[186:187], v[108:109], v[132:133], v[192:193]
	v_pk_fma_f32 v[188:189], v[106:107], v[130:131], v[212:213]
	v_cvt_pk_f16_f32 v106, v126, v127
	v_cvt_pk_f16_f32 v107, v128, v129
	v_cvt_pk_f16_f32 v108, v122, v123
	v_cvt_pk_f16_f32 v109, v124, v125
	v_pk_fma_f32 v[120:121], v[120:121], v[144:145], v[194:195]
	v_pk_fma_f32 v[118:119], v[118:119], v[142:143], v[214:215]
	v_pk_fma_f32 v[190:191], v[116:117], v[140:141], v[196:197]
	v_pk_fma_f32 v[116:117], v[114:115], v[138:139], v[216:217]
	v_cvt_pk_f16_f32 v110, v110, v111
	v_cvt_pk_f16_f32 v111, v112, v113
	v_cvt_pk_f16_f32 v112, v188, v189
	v_cvt_pk_f16_f32 v113, v186, v187
	global_store_dwordx4 v[206:207], v[106:109], off
	global_store_dwordx4 v[206:207], v[110:113], off offset:256
	v_cvt_pk_f16_f32 v114, v118, v119
	v_lshl_add_u64 v[106:107], s[6:7], 0, v[202:203]
	v_cvt_pk_f16_f32 v115, v120, v121
	v_cvt_pk_f16_f32 v116, v116, v117
	v_cvt_pk_f16_f32 v117, v190, v191
	v_lshl_add_u64 v[106:107], v[106:107], 0, v[166:167]
	global_store_dwordx4 v[106:107], v[114:117], off
	s_waitcnt vmcnt(7)
	v_cvt_f32_f16_e32 v108, v198
	v_cvt_f32_f16_sdwa v109, v198 dst_sel:DWORD dst_unused:UNUSED_PAD src0_sel:WORD_1
	v_cvt_f32_f16_e32 v110, v199
	v_cvt_f32_f16_sdwa v111, v199 dst_sel:DWORD dst_unused:UNUSED_PAD src0_sel:WORD_1
	v_cvt_f32_f16_e32 v112, v200
	v_cvt_f32_f16_e32 v114, v201
	v_cvt_f32_f16_sdwa v115, v201 dst_sel:DWORD dst_unused:UNUSED_PAD src0_sel:WORD_1
	v_cvt_f32_f16_sdwa v113, v200 dst_sel:DWORD dst_unused:UNUSED_PAD src0_sel:WORD_1
	v_pk_fma_f32 v[104:105], v[104:105], v[136:137], v[110:111]
	v_pk_fma_f32 v[102:103], v[102:103], v[134:135], v[108:109]
	v_pk_fma_f32 v[108:109], v[100:101], v[132:133], v[114:115]
	v_pk_fma_f32 v[100:101], v[98:99], v[130:131], v[112:113]
	v_lshl_add_u64 v[110:111], v[170:171], 0, s[18:19]
	v_cvt_pk_f16_f32 v98, v102, v103
	v_cvt_pk_f16_f32 v99, v104, v105
	v_cvt_pk_f16_f32 v100, v100, v101
	v_cvt_pk_f16_f32 v101, v108, v109
	v_lshl_add_u64 v[112:113], v[168:169], 0, v[110:111]
	global_store_dwordx4 v[106:107], v[98:101], off offset:256
	s_waitcnt vmcnt(7)
	v_cvt_f32_f16_e32 v102, v150
	v_cvt_f32_f16_sdwa v103, v150 dst_sel:DWORD dst_unused:UNUSED_PAD src0_sel:WORD_1
	v_cvt_f32_f16_e32 v104, v151
	v_cvt_f32_f16_sdwa v105, v151 dst_sel:DWORD dst_unused:UNUSED_PAD src0_sel:WORD_1
	v_cvt_f32_f16_e32 v106, v152
	v_cvt_f32_f16_e32 v108, v153
	global_load_dwordx4 v[98:101], v[112:113], off
	v_cvt_f32_f16_sdwa v109, v153 dst_sel:DWORD dst_unused:UNUSED_PAD src0_sel:WORD_1
	v_cvt_f32_f16_sdwa v107, v152 dst_sel:DWORD dst_unused:UNUSED_PAD src0_sel:WORD_1
	v_pk_fma_f32 v[96:97], v[96:97], v[144:145], v[104:105]
	v_pk_fma_f32 v[94:95], v[94:95], v[142:143], v[102:103]
	v_pk_fma_f32 v[102:103], v[92:93], v[140:141], v[108:109]
	v_pk_fma_f32 v[92:93], v[90:91], v[138:139], v[106:107]
	v_cvt_pk_f16_f32 v90, v94, v95
	v_cvt_pk_f16_f32 v91, v96, v97
	v_cvt_pk_f16_f32 v92, v92, v93
	v_cvt_pk_f16_f32 v93, v102, v103
	v_lshl_add_u64 v[94:95], s[6:7], 0, v[174:175]
	s_waitcnt vmcnt(7)
	v_cvt_f32_f16_e32 v96, v158
	v_cvt_f32_f16_sdwa v97, v158 dst_sel:DWORD dst_unused:UNUSED_PAD src0_sel:WORD_1
	v_cvt_f32_f16_e32 v102, v159
	v_cvt_f32_f16_sdwa v103, v159 dst_sel:DWORD dst_unused:UNUSED_PAD src0_sel:WORD_1
	v_cvt_f32_f16_e32 v104, v160
	v_cvt_f32_f16_e32 v106, v161
	v_cvt_f32_f16_sdwa v107, v161 dst_sel:DWORD dst_unused:UNUSED_PAD src0_sel:WORD_1
	v_cvt_f32_f16_sdwa v105, v160 dst_sel:DWORD dst_unused:UNUSED_PAD src0_sel:WORD_1
	v_lshl_add_u64 v[94:95], v[94:95], 0, v[166:167]
	global_store_dwordx4 v[94:95], v[90:93], off
	global_load_dwordx4 v[90:93], v[112:113], off offset:256
	v_pk_fma_f32 v[84:85], v[84:85], v[136:137], v[102:103]
	v_pk_fma_f32 v[82:83], v[82:83], v[134:135], v[96:97]
	v_pk_fma_f32 v[96:97], v[76:77], v[132:133], v[106:107]
	v_pk_fma_f32 v[76:77], v[74:75], v[130:131], v[104:105]
	v_cvt_pk_f16_f32 v74, v82, v83
	v_cvt_pk_f16_f32 v75, v84, v85
	v_cvt_pk_f16_f32 v76, v76, v77
	v_cvt_pk_f16_f32 v77, v96, v97
	s_mov_b64 s[18:19], 0x90000
	global_store_dwordx4 v[94:95], v[74:77], off offset:256
	v_lshl_add_u64 v[94:95], v[170:171], 0, s[18:19]
	v_lshl_add_u64 v[84:85], v[168:169], 0, v[94:95]
	s_waitcnt vmcnt(9)
	v_cvt_f32_f16_e32 v82, v154
	v_cvt_f32_f16_sdwa v83, v154 dst_sel:DWORD dst_unused:UNUSED_PAD src0_sel:WORD_1
	global_load_dwordx4 v[74:77], v[84:85], off
	v_cvt_f32_f16_e32 v96, v155
	v_cvt_f32_f16_sdwa v97, v155 dst_sel:DWORD dst_unused:UNUSED_PAD src0_sel:WORD_1
	v_cvt_f32_f16_e32 v102, v156
	v_cvt_f32_f16_e32 v104, v157
	v_cvt_f32_f16_sdwa v105, v157 dst_sel:DWORD dst_unused:UNUSED_PAD src0_sel:WORD_1
	v_cvt_f32_f16_sdwa v103, v156 dst_sel:DWORD dst_unused:UNUSED_PAD src0_sel:WORD_1
	v_pk_fma_f32 v[82:83], v[86:87], v[142:143], v[82:83]
	v_pk_fma_f32 v[88:89], v[88:89], v[144:145], v[96:97]
	v_pk_fma_f32 v[86:87], v[80:81], v[140:141], v[104:105]
	v_pk_fma_f32 v[80:81], v[78:79], v[138:139], v[102:103]
	v_cvt_pk_f16_f32 v78, v82, v83
	v_lshl_add_u64 v[82:83], s[6:7], 0, v[172:173]
	v_cvt_pk_f16_f32 v79, v88, v89
	v_cvt_pk_f16_f32 v80, v80, v81
	v_cvt_pk_f16_f32 v81, v86, v87
	v_lshl_add_u64 v[82:83], v[82:83], 0, v[166:167]
	global_store_dwordx4 v[82:83], v[78:81], off
	s_waitcnt vmcnt(10)
	v_cvt_f32_f16_e32 v86, v146
	global_load_dwordx4 v[78:81], v[84:85], off offset:256
	v_cvt_f32_f16_sdwa v87, v146 dst_sel:DWORD dst_unused:UNUSED_PAD src0_sel:WORD_1
	v_cvt_f32_f16_e32 v84, v147
	v_cvt_f32_f16_sdwa v85, v147 dst_sel:DWORD dst_unused:UNUSED_PAD src0_sel:WORD_1
	v_cvt_f32_f16_e32 v88, v148
	v_cvt_f32_f16_e32 v96, v149
	v_cvt_f32_f16_sdwa v97, v149 dst_sel:DWORD dst_unused:UNUSED_PAD src0_sel:WORD_1
	v_cvt_f32_f16_sdwa v89, v148 dst_sel:DWORD dst_unused:UNUSED_PAD src0_sel:WORD_1
	v_pk_fma_f32 v[72:73], v[72:73], v[136:137], v[84:85]
	v_pk_fma_f32 v[70:71], v[70:71], v[134:135], v[86:87]
	v_pk_fma_f32 v[84:85], v[68:69], v[132:133], v[96:97]
	v_pk_fma_f32 v[68:69], v[66:67], v[130:131], v[88:89]
	s_mov_b64 s[18:19], 0xa0000
	v_cvt_pk_f16_f32 v66, v70, v71
	v_cvt_pk_f16_f32 v67, v72, v73
	v_cvt_pk_f16_f32 v68, v68, v69
	v_lshl_add_u64 v[96:97], v[170:171], 0, s[18:19]
	v_cvt_pk_f16_f32 v69, v84, v85
	v_lshl_add_u64 v[86:87], v[168:169], 0, v[96:97]
	global_store_dwordx4 v[82:83], v[66:69], off offset:256
	global_load_dwordx4 v[70:73], v[86:87], off
	s_nop 0
	global_load_dwordx4 v[82:85], v[86:87], off offset:256
	s_mov_b64 s[18:19], 0xb0000
	v_lshl_add_u64 v[102:103], v[170:171], 0, s[18:19]
	v_lshl_add_u64 v[66:67], v[168:169], 0, v[102:103]
	global_load_dwordx4 v[86:89], v[66:67], off
	s_nop 0
	global_load_dwordx4 v[66:69], v[66:67], off offset:256
	s_waitcnt vmcnt(11)
	v_cvt_f32_f16_e32 v104, v98
	v_cvt_f32_f16_sdwa v105, v98 dst_sel:DWORD dst_unused:UNUSED_PAD src0_sel:WORD_1
	v_cvt_f32_f16_e32 v98, v99
	v_cvt_f32_f16_sdwa v99, v99 dst_sel:DWORD dst_unused:UNUSED_PAD src0_sel:WORD_1
	v_cvt_f32_f16_e32 v106, v100
	v_cvt_f32_f16_e32 v108, v101
	v_cvt_f32_f16_sdwa v109, v101 dst_sel:DWORD dst_unused:UNUSED_PAD src0_sel:WORD_1
	v_cvt_f32_f16_sdwa v107, v100 dst_sel:DWORD dst_unused:UNUSED_PAD src0_sel:WORD_1
	v_pk_fma_f32 v[62:63], v[62:63], v[142:143], v[104:105]
	v_pk_fma_f32 v[64:65], v[64:65], v[144:145], v[98:99]
	v_pk_fma_f32 v[98:99], v[60:61], v[140:141], v[108:109]
	v_pk_fma_f32 v[60:61], v[58:59], v[138:139], v[106:107]
	v_cvt_pk_f16_f32 v58, v62, v63
	v_lshl_add_u64 v[62:63], s[6:7], 0, v[110:111]
	v_cvt_pk_f16_f32 v59, v64, v65
	v_cvt_pk_f16_f32 v60, v60, v61
	v_cvt_pk_f16_f32 v61, v98, v99
	v_lshl_add_u64 v[62:63], v[62:63], 0, v[166:167]
	global_store_dwordx4 v[62:63], v[58:61], off
	s_waitcnt vmcnt(10)
	v_cvt_f32_f16_e32 v64, v92
	v_cvt_f32_f16_e32 v58, v90
	v_cvt_f32_f16_sdwa v59, v90 dst_sel:DWORD dst_unused:UNUSED_PAD src0_sel:WORD_1
	v_cvt_f32_f16_e32 v60, v91
	v_cvt_f32_f16_sdwa v61, v91 dst_sel:DWORD dst_unused:UNUSED_PAD src0_sel:WORD_1
	v_cvt_f32_f16_e32 v90, v93
	v_cvt_f32_f16_sdwa v91, v93 dst_sel:DWORD dst_unused:UNUSED_PAD src0_sel:WORD_1
	v_cvt_f32_f16_sdwa v65, v92 dst_sel:DWORD dst_unused:UNUSED_PAD src0_sel:WORD_1
	v_pk_fma_f32 v[56:57], v[56:57], v[136:137], v[60:61]
	v_pk_fma_f32 v[54:55], v[54:55], v[134:135], v[58:59]
	v_pk_fma_f32 v[58:59], v[52:53], v[132:133], v[90:91]
	v_pk_fma_f32 v[52:53], v[50:51], v[130:131], v[64:65]
	v_cvt_pk_f16_f32 v50, v54, v55
	v_cvt_pk_f16_f32 v51, v56, v57
	v_cvt_pk_f16_f32 v52, v52, v53
	v_cvt_pk_f16_f32 v53, v58, v59
	global_store_dwordx4 v[62:63], v[50:53], off offset:256
	s_waitcnt vmcnt(9)
	v_cvt_f32_f16_e32 v54, v76
	v_cvt_f32_f16_e32 v56, v77
	v_cvt_f32_f16_e32 v50, v74
	v_cvt_f32_f16_sdwa v51, v74 dst_sel:DWORD dst_unused:UNUSED_PAD src0_sel:WORD_1
	v_cvt_f32_f16_e32 v52, v75
	v_cvt_f32_f16_sdwa v53, v75 dst_sel:DWORD dst_unused:UNUSED_PAD src0_sel:WORD_1
	v_cvt_f32_f16_sdwa v57, v77 dst_sel:DWORD dst_unused:UNUSED_PAD src0_sel:WORD_1
	v_cvt_f32_f16_sdwa v55, v76 dst_sel:DWORD dst_unused:UNUSED_PAD src0_sel:WORD_1
	v_pk_fma_f32 v[46:47], v[46:47], v[142:143], v[50:51]
	v_pk_fma_f32 v[48:49], v[48:49], v[144:145], v[52:53]
	v_pk_fma_f32 v[50:51], v[44:45], v[140:141], v[56:57]
	v_pk_fma_f32 v[44:45], v[42:43], v[138:139], v[54:55]
	v_cvt_pk_f16_f32 v42, v46, v47
	v_lshl_add_u64 v[46:47], s[6:7], 0, v[94:95]
	v_cvt_pk_f16_f32 v43, v48, v49
	v_cvt_pk_f16_f32 v44, v44, v45
	v_cvt_pk_f16_f32 v45, v50, v51
	v_lshl_add_u64 v[46:47], v[46:47], 0, v[166:167]
	global_store_dwordx4 v[46:47], v[42:45], off
	s_waitcnt vmcnt(8)
	v_cvt_f32_f16_e32 v48, v80
	v_cvt_f32_f16_e32 v50, v81
	v_cvt_f32_f16_e32 v42, v78
	v_cvt_f32_f16_sdwa v43, v78 dst_sel:DWORD dst_unused:UNUSED_PAD src0_sel:WORD_1
	v_cvt_f32_f16_e32 v44, v79
	v_cvt_f32_f16_sdwa v45, v79 dst_sel:DWORD dst_unused:UNUSED_PAD src0_sel:WORD_1
	v_cvt_f32_f16_sdwa v51, v81 dst_sel:DWORD dst_unused:UNUSED_PAD src0_sel:WORD_1
	v_cvt_f32_f16_sdwa v49, v80 dst_sel:DWORD dst_unused:UNUSED_PAD src0_sel:WORD_1
	v_pk_fma_f32 v[38:39], v[38:39], v[134:135], v[42:43]
	v_pk_fma_f32 v[40:41], v[40:41], v[136:137], v[44:45]
	v_pk_fma_f32 v[42:43], v[36:37], v[132:133], v[50:51]
	v_pk_fma_f32 v[36:37], v[34:35], v[130:131], v[48:49]
	v_cvt_pk_f16_f32 v34, v38, v39
	v_cvt_pk_f16_f32 v35, v40, v41
	v_cvt_pk_f16_f32 v36, v36, v37
	v_cvt_pk_f16_f32 v37, v42, v43
	global_store_dwordx4 v[46:47], v[34:37], off offset:256
	s_waitcnt vmcnt(7)
	v_cvt_f32_f16_e32 v38, v72
	v_cvt_f32_f16_e32 v40, v73
	v_cvt_f32_f16_e32 v34, v70
	v_cvt_f32_f16_sdwa v35, v70 dst_sel:DWORD dst_unused:UNUSED_PAD src0_sel:WORD_1
	v_cvt_f32_f16_e32 v36, v71
	v_cvt_f32_f16_sdwa v37, v71 dst_sel:DWORD dst_unused:UNUSED_PAD src0_sel:WORD_1
	v_cvt_f32_f16_sdwa v41, v73 dst_sel:DWORD dst_unused:UNUSED_PAD src0_sel:WORD_1
	v_cvt_f32_f16_sdwa v39, v72 dst_sel:DWORD dst_unused:UNUSED_PAD src0_sel:WORD_1
	v_pk_fma_f32 v[30:31], v[30:31], v[142:143], v[34:35]
	v_pk_fma_f32 v[32:33], v[32:33], v[144:145], v[36:37]
	v_pk_fma_f32 v[34:35], v[28:29], v[140:141], v[40:41]
	v_pk_fma_f32 v[28:29], v[26:27], v[138:139], v[38:39]
	v_cvt_pk_f16_f32 v26, v30, v31
	v_lshl_add_u64 v[30:31], s[6:7], 0, v[96:97]
	v_cvt_pk_f16_f32 v27, v32, v33
	v_cvt_pk_f16_f32 v28, v28, v29
	v_cvt_pk_f16_f32 v29, v34, v35
	v_lshl_add_u64 v[30:31], v[30:31], 0, v[166:167]
	global_store_dwordx4 v[30:31], v[26:29], off
	s_waitcnt vmcnt(7)
	v_cvt_f32_f16_e32 v32, v84
	v_cvt_f32_f16_e32 v34, v85
	v_cvt_f32_f16_e32 v26, v82
	v_cvt_f32_f16_sdwa v27, v82 dst_sel:DWORD dst_unused:UNUSED_PAD src0_sel:WORD_1
	v_cvt_f32_f16_e32 v28, v83
	v_cvt_f32_f16_sdwa v29, v83 dst_sel:DWORD dst_unused:UNUSED_PAD src0_sel:WORD_1
	v_cvt_f32_f16_sdwa v35, v85 dst_sel:DWORD dst_unused:UNUSED_PAD src0_sel:WORD_1
	v_cvt_f32_f16_sdwa v33, v84 dst_sel:DWORD dst_unused:UNUSED_PAD src0_sel:WORD_1
	v_pk_fma_f32 v[22:23], v[22:23], v[134:135], v[26:27]
	v_pk_fma_f32 v[24:25], v[24:25], v[136:137], v[28:29]
	v_pk_fma_f32 v[26:27], v[20:21], v[132:133], v[34:35]
	v_pk_fma_f32 v[20:21], v[18:19], v[130:131], v[32:33]
	v_cvt_pk_f16_f32 v18, v22, v23
	v_cvt_pk_f16_f32 v19, v24, v25
	v_cvt_pk_f16_f32 v20, v20, v21
	v_cvt_pk_f16_f32 v21, v26, v27
	global_store_dwordx4 v[30:31], v[18:21], off offset:256
	s_waitcnt vmcnt(7)
	v_cvt_f32_f16_e32 v22, v88
	v_cvt_f32_f16_e32 v24, v89
	v_cvt_f32_f16_e32 v18, v86
	v_cvt_f32_f16_sdwa v19, v86 dst_sel:DWORD dst_unused:UNUSED_PAD src0_sel:WORD_1
	v_cvt_f32_f16_e32 v20, v87
	v_cvt_f32_f16_sdwa v21, v87 dst_sel:DWORD dst_unused:UNUSED_PAD src0_sel:WORD_1
	v_cvt_f32_f16_sdwa v25, v89 dst_sel:DWORD dst_unused:UNUSED_PAD src0_sel:WORD_1
	v_cvt_f32_f16_sdwa v23, v88 dst_sel:DWORD dst_unused:UNUSED_PAD src0_sel:WORD_1
	v_pk_fma_f32 v[14:15], v[14:15], v[142:143], v[18:19]
	v_pk_fma_f32 v[16:17], v[16:17], v[144:145], v[20:21]
	v_pk_fma_f32 v[18:19], v[12:13], v[140:141], v[24:25]
	v_pk_fma_f32 v[12:13], v[10:11], v[138:139], v[22:23]
	v_cvt_pk_f16_f32 v10, v14, v15
	v_lshl_add_u64 v[14:15], s[6:7], 0, v[102:103]
	v_cvt_pk_f16_f32 v11, v16, v17
	v_cvt_pk_f16_f32 v12, v12, v13
	v_cvt_pk_f16_f32 v13, v18, v19
	v_lshl_add_u64 v[14:15], v[14:15], 0, v[166:167]
	global_store_dwordx4 v[14:15], v[10:13], off
	s_waitcnt vmcnt(7)
	v_cvt_f32_f16_e32 v16, v68
	v_cvt_f32_f16_e32 v18, v69
	v_cvt_f32_f16_e32 v10, v66
	v_cvt_f32_f16_sdwa v11, v66 dst_sel:DWORD dst_unused:UNUSED_PAD src0_sel:WORD_1
	v_cvt_f32_f16_e32 v12, v67
	v_cvt_f32_f16_sdwa v13, v67 dst_sel:DWORD dst_unused:UNUSED_PAD src0_sel:WORD_1
	v_cvt_f32_f16_sdwa v19, v69 dst_sel:DWORD dst_unused:UNUSED_PAD src0_sel:WORD_1
	v_cvt_f32_f16_sdwa v17, v68 dst_sel:DWORD dst_unused:UNUSED_PAD src0_sel:WORD_1
	v_pk_fma_f32 v[6:7], v[6:7], v[134:135], v[10:11]
	v_pk_fma_f32 v[8:9], v[8:9], v[136:137], v[12:13]
	v_pk_fma_f32 v[10:11], v[4:5], v[132:133], v[18:19]
	v_pk_fma_f32 v[4:5], v[2:3], v[130:131], v[16:17]
	v_cvt_pk_f16_f32 v2, v6, v7
	v_cvt_pk_f16_f32 v3, v8, v9
	v_cvt_pk_f16_f32 v4, v4, v5
	v_cvt_pk_f16_f32 v5, v10, v11
	global_store_dwordx4 v[14:15], v[2:5], off offset:256
	s_cbranch_vccnz .LBB0_1045
	s_andn2_b64 vcc, exec, s[4:5]
	s_cbranch_vccnz .LBB0_1044
	s_mov_b32 s99, 1
	s_branch .LBB0_1044

.LBB0_1223:
	s_ashr_i32 s11, s10, 31
	s_lshl_b64 s[12:13], s[10:11], 20
	s_add_u32 s12, s26, s12
	s_addc_u32 s13, s27, s13
	s_and_b64 s[14:15], s[2:3], exec
	s_cselect_b32 s11, s13, s21
	s_cselect_b32 s66, s12, s20
	s_ashr_i32 s9, s8, 31
	s_lshl_b64 s[14:15], s[8:9], 20
	s_add_u32 s14, s28, s14
	s_addc_u32 s15, s29, s15
	s_and_b64 s[22:23], s[2:3], exec
	s_cselect_b32 s9, s15, s19
	s_cselect_b32 s67, s14, s18
	s_add_u32 s73, s18, 0x100
	s_addc_u32 s74, s19, 0
	s_add_u32 s18, s20, 0x80080
	s_addc_u32 s19, s21, 0
	s_add_u32 s75, s20, 0x100
	v_mov_b32_e32 v2, 0
	s_addc_u32 s76, s21, 0
	s_mov_b32 s77, -2
	v_mov_b32_e32 v3, v2
	v_mov_b32_e32 v4, v2
	v_mov_b32_e32 v5, v2
	v_mov_b32_e32 v6, v2
	v_mov_b32_e32 v7, v2
	v_mov_b32_e32 v8, v2
	v_mov_b32_e32 v9, v2
	v_mov_b32_e32 v18, v2
	v_mov_b32_e32 v19, v2
	v_mov_b32_e32 v20, v2
	v_mov_b32_e32 v21, v2
	v_mov_b32_e32 v22, v2
	v_mov_b32_e32 v23, v2
	v_mov_b32_e32 v24, v2
	v_mov_b32_e32 v25, v2
	v_mov_b32_e32 v34, v2
	v_mov_b32_e32 v35, v2
	v_mov_b32_e32 v36, v2
	v_mov_b32_e32 v37, v2
	v_mov_b32_e32 v38, v2
	v_mov_b32_e32 v39, v2
	v_mov_b32_e32 v40, v2
	v_mov_b32_e32 v41, v2
	v_mov_b32_e32 v50, v2
	v_mov_b32_e32 v51, v2
	v_mov_b32_e32 v52, v2
	v_mov_b32_e32 v53, v2
	v_mov_b32_e32 v54, v2
	v_mov_b32_e32 v55, v2
	v_mov_b32_e32 v56, v2
	v_mov_b32_e32 v57, v2
	v_mov_b32_e32 v10, v2
	v_mov_b32_e32 v11, v2
	v_mov_b32_e32 v12, v2
	v_mov_b32_e32 v13, v2
	v_mov_b32_e32 v14, v2
	v_mov_b32_e32 v15, v2
	v_mov_b32_e32 v16, v2
	v_mov_b32_e32 v17, v2
	v_mov_b32_e32 v26, v2
	v_mov_b32_e32 v27, v2
	v_mov_b32_e32 v28, v2
	v_mov_b32_e32 v29, v2
	v_mov_b32_e32 v30, v2
	v_mov_b32_e32 v31, v2
	v_mov_b32_e32 v32, v2
	v_mov_b32_e32 v33, v2
	v_mov_b32_e32 v42, v2
	v_mov_b32_e32 v43, v2
	v_mov_b32_e32 v44, v2
	v_mov_b32_e32 v45, v2
	v_mov_b32_e32 v46, v2
	v_mov_b32_e32 v47, v2
	v_mov_b32_e32 v48, v2
	v_mov_b32_e32 v49, v2
	v_mov_b32_e32 v58, v2
	v_mov_b32_e32 v59, v2
	v_mov_b32_e32 v60, v2
	v_mov_b32_e32 v61, v2
	v_mov_b32_e32 v62, v2
	v_mov_b32_e32 v63, v2
	v_mov_b32_e32 v64, v2
	v_mov_b32_e32 v65, v2
	v_mov_b32_e32 v66, v2
	v_mov_b32_e32 v67, v2
	v_mov_b32_e32 v68, v2
	v_mov_b32_e32 v69, v2
	v_mov_b32_e32 v70, v2
	v_mov_b32_e32 v71, v2
	v_mov_b32_e32 v72, v2
	v_mov_b32_e32 v73, v2
	v_mov_b32_e32 v82, v2
	v_mov_b32_e32 v83, v2
	v_mov_b32_e32 v84, v2
	v_mov_b32_e32 v85, v2
	v_mov_b32_e32 v86, v2
	v_mov_b32_e32 v87, v2
	v_mov_b32_e32 v88, v2
	v_mov_b32_e32 v89, v2
	v_mov_b32_e32 v98, v2
	v_mov_b32_e32 v99, v2
	v_mov_b32_e32 v100, v2
	v_mov_b32_e32 v101, v2
	v_mov_b32_e32 v102, v2
	v_mov_b32_e32 v103, v2
	v_mov_b32_e32 v104, v2
	v_mov_b32_e32 v105, v2
	v_mov_b32_e32 v114, v2
	v_mov_b32_e32 v115, v2
	v_mov_b32_e32 v116, v2
	v_mov_b32_e32 v117, v2
	v_mov_b32_e32 v118, v2
	v_mov_b32_e32 v119, v2
	v_mov_b32_e32 v120, v2
	v_mov_b32_e32 v121, v2
	v_mov_b32_e32 v74, v2
	v_mov_b32_e32 v75, v2
	v_mov_b32_e32 v76, v2
	v_mov_b32_e32 v77, v2
	v_mov_b32_e32 v78, v2
	v_mov_b32_e32 v79, v2
	v_mov_b32_e32 v80, v2
	v_mov_b32_e32 v81, v2
	v_mov_b32_e32 v90, v2
	v_mov_b32_e32 v91, v2
	v_mov_b32_e32 v92, v2
	v_mov_b32_e32 v93, v2
	v_mov_b32_e32 v94, v2
	v_mov_b32_e32 v95, v2
	v_mov_b32_e32 v96, v2
	v_mov_b32_e32 v97, v2
	v_mov_b32_e32 v106, v2
	v_mov_b32_e32 v107, v2
	v_mov_b32_e32 v108, v2
	v_mov_b32_e32 v109, v2
	v_mov_b32_e32 v110, v2
	v_mov_b32_e32 v111, v2
	v_mov_b32_e32 v112, v2
	v_mov_b32_e32 v113, v2
	v_mov_b32_e32 v122, v2
	v_mov_b32_e32 v123, v2
	v_mov_b32_e32 v124, v2
	v_mov_b32_e32 v125, v2
	v_mov_b32_e32 v126, v2
	v_mov_b32_e32 v127, v2
	v_mov_b32_e32 v128, v2
	v_mov_b32_e32 v129, v2
	s_cmp_eq_u32 s99, 0
	s_cbranch_scc1 .Lro_skip_9
	s_barrier
	s_mov_b32 s99, 0
.Lro_skip_9:
.LBB0_1224:
	ds_read_b128 v[148:151], v143
	ds_read_b128 v[152:155], v143 offset:1024
	ds_read_b128 v[156:159], v143 offset:2048
	ds_read_b128 v[160:163], v143 offset:3072
	ds_read_b128 v[164:167], v144
	ds_read_b128 v[168:171], v144 offset:1024
	ds_read_b128 v[172:175], v144 offset:2048
	ds_read_b128 v[176:179], v144 offset:3072
	s_cmp_eq_u32 s77, 28
	s_cselect_b32 s21, s9, s74
	s_cselect_b32 s20, s67, s73
	s_cselect_b32 s23, s11, s76
	s_cselect_b32 s22, s66, s75
	ds_read_b128 v[180:183], v145
	ds_read_b128 v[184:187], v145 offset:1024
	ds_read_b128 v[188:191], v145 offset:2048
	ds_read_b128 v[192:195], v145 offset:3072
	ds_read_b128 v[196:199], v145 offset:4096
	ds_read_b128 v[200:203], v145 offset:5120
	ds_read_b128 v[204:207], v145 offset:6144
	ds_read_b128 v[208:211], v145 offset:7168
	s_add_u32 s78, s18, 0xfff80000
	s_addc_u32 s79, s19, -1
	s_mov_b32 s80, m0
	s_mov_b32 m0, s56
	s_nop 0
	global_load_lds_dwordx4 v138, s[78:79]
	s_mov_b32 m0, s80
	s_nop 0
	s_mov_b32 s80, m0
	s_mov_b32 m0, s59
	s_nop 0
	global_load_lds_dwordx4 v140, s[78:79]
	s_mov_b32 m0, s80
	s_mov_b32 s78, m0
	s_mov_b32 m0, s57
	s_nop 0
	global_load_lds_dwordx4 v138, s[18:19]
	s_mov_b32 m0, s78
	s_nop 0
	s_mov_b32 s78, m0
	s_mov_b32 m0, s64
	s_nop 0
	global_load_lds_dwordx4 v140, s[18:19]
	s_mov_b32 m0, s78
	s_waitcnt vmcnt(8)
	s_waitcnt lgkmcnt(0)
	s_barrier
	s_setprio 1
	s_waitcnt lgkmcnt(7)
	v_mfma_f32_16x16x32_bf16 v[126:129], v[148:151], v[180:183], v[126:129]
	v_mfma_f32_16x16x32_bf16 v[122:125], v[156:159], v[180:183], v[122:125]
	s_waitcnt lgkmcnt(5)
	v_mfma_f32_16x16x32_bf16 v[110:113], v[148:151], v[188:191], v[110:113]
	v_mfma_f32_16x16x32_bf16 v[106:109], v[156:159], v[188:191], v[106:109]
	s_waitcnt lgkmcnt(3)
	v_mfma_f32_16x16x32_bf16 v[94:97], v[148:151], v[196:199], v[94:97]
	v_mfma_f32_16x16x32_bf16 v[90:93], v[156:159], v[196:199], v[90:93]
	s_waitcnt lgkmcnt(1)
	v_mfma_f32_16x16x32_bf16 v[78:81], v[148:151], v[204:207], v[78:81]
	v_mfma_f32_16x16x32_bf16 v[74:77], v[156:159], v[204:207], v[74:77]
	v_mfma_f32_16x16x32_bf16 v[126:129], v[152:155], v[184:187], v[126:129]
	v_mfma_f32_16x16x32_bf16 v[122:125], v[160:163], v[184:187], v[122:125]
	v_mfma_f32_16x16x32_bf16 v[110:113], v[152:155], v[192:195], v[110:113]
	v_mfma_f32_16x16x32_bf16 v[106:109], v[160:163], v[192:195], v[106:109]
	v_mfma_f32_16x16x32_bf16 v[94:97], v[152:155], v[200:203], v[94:97]
	v_mfma_f32_16x16x32_bf16 v[90:93], v[160:163], v[200:203], v[90:93]
	s_waitcnt lgkmcnt(0)
	v_mfma_f32_16x16x32_bf16 v[78:81], v[152:155], v[208:211], v[78:81]
	v_mfma_f32_16x16x32_bf16 v[74:77], v[160:163], v[208:211], v[74:77]
	s_setprio 0
	s_setprio 1
	v_mfma_f32_16x16x32_bf16 v[118:121], v[164:167], v[180:183], v[118:121]
	v_mfma_f32_16x16x32_bf16 v[114:117], v[172:175], v[180:183], v[114:117]
	v_mfma_f32_16x16x32_bf16 v[102:105], v[164:167], v[188:191], v[102:105]
	v_mfma_f32_16x16x32_bf16 v[98:101], v[172:175], v[188:191], v[98:101]
	v_mfma_f32_16x16x32_bf16 v[86:89], v[164:167], v[196:199], v[86:89]
	v_mfma_f32_16x16x32_bf16 v[82:85], v[172:175], v[196:199], v[82:85]
	v_mfma_f32_16x16x32_bf16 v[70:73], v[164:167], v[204:207], v[70:73]
	v_mfma_f32_16x16x32_bf16 v[66:69], v[172:175], v[204:207], v[66:69]
	v_mfma_f32_16x16x32_bf16 v[118:121], v[168:171], v[184:187], v[118:121]
	v_mfma_f32_16x16x32_bf16 v[114:117], v[176:179], v[184:187], v[114:117]
	v_mfma_f32_16x16x32_bf16 v[102:105], v[168:171], v[192:195], v[102:105]
	v_mfma_f32_16x16x32_bf16 v[98:101], v[176:179], v[192:195], v[98:101]
	v_mfma_f32_16x16x32_bf16 v[86:89], v[168:171], v[200:203], v[86:89]
	v_mfma_f32_16x16x32_bf16 v[82:85], v[176:179], v[200:203], v[82:85]
	s_setprio 2
	s_barrier
	v_mfma_f32_16x16x32_bf16 v[70:73], v[168:171], v[208:211], v[70:73]
	v_mfma_f32_16x16x32_bf16 v[66:69], v[176:179], v[208:211], v[66:69]
	s_setprio 0
	ds_read_b128 v[180:183], v145 offset:16384
	ds_read_b128 v[184:187], v145 offset:17408
	ds_read_b128 v[188:191], v145 offset:18432
	ds_read_b128 v[192:195], v145 offset:19456
	ds_read_b128 v[196:199], v145 offset:20480
	ds_read_b128 v[200:203], v145 offset:21504
	ds_read_b128 v[204:207], v145 offset:22528
	ds_read_b128 v[208:211], v145 offset:23552
	s_mov_b32 s78, m0
	s_mov_b32 m0, s35
	s_nop 0
	global_load_lds_dwordx4 v139, s[20:21]
	s_mov_b32 m0, s78
	s_nop 0
	s_mov_b32 s78, m0
	s_mov_b32 m0, s36
	s_nop 0
	global_load_lds_dwordx4 v141, s[20:21]
	s_mov_b32 m0, s78
	s_add_u32 s78, s20, 0x80000
	s_addc_u32 s79, s21, 0
	s_mov_b32 s80, m0
	s_mov_b32 m0, s37
	s_nop 0
	global_load_lds_dwordx4 v139, s[78:79]
	s_mov_b32 m0, s80
	s_nop 0
	s_mov_b32 s80, m0
	s_mov_b32 m0, s40
	s_nop 0
	global_load_lds_dwordx4 v141, s[78:79]
	s_mov_b32 m0, s80
	s_waitcnt vmcnt(4)
	s_waitcnt lgkmcnt(0)
	s_barrier
	s_setprio 1
	s_waitcnt lgkmcnt(7)
	v_mfma_f32_16x16x32_bf16 v[62:65], v[148:151], v[180:183], v[62:65]
	v_mfma_f32_16x16x32_bf16 v[58:61], v[156:159], v[180:183], v[58:61]
	s_waitcnt lgkmcnt(5)
	v_mfma_f32_16x16x32_bf16 v[46:49], v[148:151], v[188:191], v[46:49]
	v_mfma_f32_16x16x32_bf16 v[42:45], v[156:159], v[188:191], v[42:45]
	s_waitcnt lgkmcnt(3)
	v_mfma_f32_16x16x32_bf16 v[30:33], v[148:151], v[196:199], v[30:33]
	v_mfma_f32_16x16x32_bf16 v[26:29], v[156:159], v[196:199], v[26:29]
	s_waitcnt lgkmcnt(1)
	v_mfma_f32_16x16x32_bf16 v[14:17], v[148:151], v[204:207], v[14:17]
	v_mfma_f32_16x16x32_bf16 v[10:13], v[156:159], v[204:207], v[10:13]
	v_mfma_f32_16x16x32_bf16 v[62:65], v[152:155], v[184:187], v[62:65]
	v_mfma_f32_16x16x32_bf16 v[58:61], v[160:163], v[184:187], v[58:61]
	v_mfma_f32_16x16x32_bf16 v[46:49], v[152:155], v[192:195], v[46:49]
	v_mfma_f32_16x16x32_bf16 v[42:45], v[160:163], v[192:195], v[42:45]
	v_mfma_f32_16x16x32_bf16 v[30:33], v[152:155], v[200:203], v[30:33]
	v_mfma_f32_16x16x32_bf16 v[26:29], v[160:163], v[200:203], v[26:29]
	s_waitcnt lgkmcnt(0)
	v_mfma_f32_16x16x32_bf16 v[14:17], v[152:155], v[208:211], v[14:17]
	v_mfma_f32_16x16x32_bf16 v[10:13], v[160:163], v[208:211], v[10:13]
	s_setprio 0
	s_setprio 1
	v_mfma_f32_16x16x32_bf16 v[54:57], v[164:167], v[180:183], v[54:57]
	v_mfma_f32_16x16x32_bf16 v[50:53], v[172:175], v[180:183], v[50:53]
	v_mfma_f32_16x16x32_bf16 v[38:41], v[164:167], v[188:191], v[38:41]
	v_mfma_f32_16x16x32_bf16 v[34:37], v[172:175], v[188:191], v[34:37]
	v_mfma_f32_16x16x32_bf16 v[22:25], v[164:167], v[196:199], v[22:25]
	v_mfma_f32_16x16x32_bf16 v[18:21], v[172:175], v[196:199], v[18:21]
	v_mfma_f32_16x16x32_bf16 v[6:9], v[164:167], v[204:207], v[6:9]
	v_mfma_f32_16x16x32_bf16 v[2:5], v[172:175], v[204:207], v[2:5]
	v_mfma_f32_16x16x32_bf16 v[54:57], v[168:171], v[184:187], v[54:57]
	v_mfma_f32_16x16x32_bf16 v[50:53], v[176:179], v[184:187], v[50:53]
	v_mfma_f32_16x16x32_bf16 v[38:41], v[168:171], v[192:195], v[38:41]
	v_mfma_f32_16x16x32_bf16 v[34:37], v[176:179], v[192:195], v[34:37]
	v_mfma_f32_16x16x32_bf16 v[22:25], v[168:171], v[200:203], v[22:25]
	v_mfma_f32_16x16x32_bf16 v[18:21], v[176:179], v[200:203], v[18:21]
	s_setprio 2
	s_barrier
	v_mfma_f32_16x16x32_bf16 v[6:9], v[168:171], v[208:211], v[6:9]
	v_mfma_f32_16x16x32_bf16 v[2:5], v[176:179], v[208:211], v[2:5]
	s_setprio 0
	ds_read_b128 v[148:151], v146
	ds_read_b128 v[152:155], v146 offset:1024
	ds_read_b128 v[156:159], v146 offset:2048
	ds_read_b128 v[160:163], v146 offset:3072
	ds_read_b128 v[164:167], v147
	ds_read_b128 v[168:171], v147 offset:1024
	ds_read_b128 v[172:175], v147 offset:2048
	ds_read_b128 v[176:179], v147 offset:3072
	ds_read_b128 v[180:183], v145 offset:32768
	ds_read_b128 v[184:187], v145 offset:33792
	ds_read_b128 v[188:191], v145 offset:34816
	ds_read_b128 v[192:195], v145 offset:35840
	ds_read_b128 v[196:199], v145 offset:36864
	ds_read_b128 v[200:203], v145 offset:37888
	ds_read_b128 v[204:207], v145 offset:38912
	ds_read_b128 v[208:211], v145 offset:39936
	s_mov_b32 s78, m0
	s_mov_b32 m0, s31
	s_nop 0
	global_load_lds_dwordx4 v138, s[22:23]
	s_mov_b32 m0, s78
	s_nop 0
	s_mov_b32 s78, m0
	s_mov_b32 m0, s41
	s_nop 0
	global_load_lds_dwordx4 v140, s[22:23]
	s_mov_b32 m0, s78
	s_add_u32 s22, s22, 0x80000
	s_addc_u32 s23, s23, 0
	s_mov_b32 s78, m0
	s_mov_b32 m0, s42
	s_nop 0
	global_load_lds_dwordx4 v138, s[22:23]
	s_mov_b32 m0, s78
	s_nop 0
	s_mov_b32 s78, m0
	s_mov_b32 m0, s43
	s_nop 0
	global_load_lds_dwordx4 v140, s[22:23]
	s_mov_b32 m0, s78
	s_waitcnt vmcnt(8)
	s_waitcnt lgkmcnt(0)
	s_barrier
	s_setprio 1
	s_waitcnt lgkmcnt(7)
	v_mfma_f32_16x16x32_bf16 v[126:129], v[148:151], v[180:183], v[126:129]
	v_mfma_f32_16x16x32_bf16 v[122:125], v[156:159], v[180:183], v[122:125]
	s_waitcnt lgkmcnt(5)
	v_mfma_f32_16x16x32_bf16 v[110:113], v[148:151], v[188:191], v[110:113]
	v_mfma_f32_16x16x32_bf16 v[106:109], v[156:159], v[188:191], v[106:109]
	s_waitcnt lgkmcnt(3)
	v_mfma_f32_16x16x32_bf16 v[94:97], v[148:151], v[196:199], v[94:97]
	v_mfma_f32_16x16x32_bf16 v[90:93], v[156:159], v[196:199], v[90:93]
	s_waitcnt lgkmcnt(1)
	v_mfma_f32_16x16x32_bf16 v[78:81], v[148:151], v[204:207], v[78:81]
	v_mfma_f32_16x16x32_bf16 v[74:77], v[156:159], v[204:207], v[74:77]
	v_mfma_f32_16x16x32_bf16 v[126:129], v[152:155], v[184:187], v[126:129]
	v_mfma_f32_16x16x32_bf16 v[122:125], v[160:163], v[184:187], v[122:125]
	v_mfma_f32_16x16x32_bf16 v[110:113], v[152:155], v[192:195], v[110:113]
	v_mfma_f32_16x16x32_bf16 v[106:109], v[160:163], v[192:195], v[106:109]
	v_mfma_f32_16x16x32_bf16 v[94:97], v[152:155], v[200:203], v[94:97]
	v_mfma_f32_16x16x32_bf16 v[90:93], v[160:163], v[200:203], v[90:93]
	s_waitcnt lgkmcnt(0)
	v_mfma_f32_16x16x32_bf16 v[78:81], v[152:155], v[208:211], v[78:81]
	v_mfma_f32_16x16x32_bf16 v[74:77], v[160:163], v[208:211], v[74:77]
	s_setprio 0
	s_setprio 1
	v_mfma_f32_16x16x32_bf16 v[118:121], v[164:167], v[180:183], v[118:121]
	v_mfma_f32_16x16x32_bf16 v[114:117], v[172:175], v[180:183], v[114:117]
	v_mfma_f32_16x16x32_bf16 v[102:105], v[164:167], v[188:191], v[102:105]
	v_mfma_f32_16x16x32_bf16 v[98:101], v[172:175], v[188:191], v[98:101]
	v_mfma_f32_16x16x32_bf16 v[86:89], v[164:167], v[196:199], v[86:89]
	v_mfma_f32_16x16x32_bf16 v[82:85], v[172:175], v[196:199], v[82:85]
	v_mfma_f32_16x16x32_bf16 v[70:73], v[164:167], v[204:207], v[70:73]
	v_mfma_f32_16x16x32_bf16 v[66:69], v[172:175], v[204:207], v[66:69]
	v_mfma_f32_16x16x32_bf16 v[118:121], v[168:171], v[184:187], v[118:121]
	v_mfma_f32_16x16x32_bf16 v[114:117], v[176:179], v[184:187], v[114:117]
	v_mfma_f32_16x16x32_bf16 v[102:105], v[168:171], v[192:195], v[102:105]
	v_mfma_f32_16x16x32_bf16 v[98:101], v[176:179], v[192:195], v[98:101]
	v_mfma_f32_16x16x32_bf16 v[86:89], v[168:171], v[200:203], v[86:89]
	v_mfma_f32_16x16x32_bf16 v[82:85], v[176:179], v[200:203], v[82:85]
	s_setprio 2
	s_barrier
	v_mfma_f32_16x16x32_bf16 v[70:73], v[168:171], v[208:211], v[70:73]
	v_mfma_f32_16x16x32_bf16 v[66:69], v[176:179], v[208:211], v[66:69]
	s_setprio 0
	ds_read_b128 v[180:183], v145 offset:49152
	ds_read_b128 v[184:187], v145 offset:50176
	ds_read_b128 v[188:191], v145 offset:51200
	ds_read_b128 v[192:195], v145 offset:52224
	ds_read_b128 v[196:199], v145 offset:53248
	ds_read_b128 v[200:203], v145 offset:54272
	ds_read_b128 v[204:207], v145 offset:55296
	ds_read_b128 v[208:211], v145 offset:56320
	s_add_u32 s22, s20, 0x80
	s_addc_u32 s23, s21, 0
	s_mov_b32 s78, m0
	s_mov_b32 m0, s46
	s_nop 0
	global_load_lds_dwordx4 v139, s[22:23]
	s_mov_b32 m0, s78
	s_add_u32 s20, s20, 0x80080
	s_mov_b32 s78, m0
	s_mov_b32 m0, s47
	s_nop 0
	global_load_lds_dwordx4 v141, s[22:23]
	s_mov_b32 m0, s78
	s_addc_u32 s21, s21, 0
	s_mov_b32 s22, m0
	s_mov_b32 m0, s48
	s_nop 0
	global_load_lds_dwordx4 v139, s[20:21]
	s_mov_b32 m0, s22
	s_nop 0
	s_mov_b32 s22, m0
	s_mov_b32 m0, s49
	s_nop 0
	global_load_lds_dwordx4 v141, s[20:21]
	s_mov_b32 m0, s22
	s_waitcnt vmcnt(4)
	s_waitcnt lgkmcnt(0)
	s_barrier
	s_setprio 1
	s_waitcnt lgkmcnt(7)
	v_mfma_f32_16x16x32_bf16 v[62:65], v[148:151], v[180:183], v[62:65]
	v_mfma_f32_16x16x32_bf16 v[58:61], v[156:159], v[180:183], v[58:61]
	s_waitcnt lgkmcnt(5)
	v_mfma_f32_16x16x32_bf16 v[46:49], v[148:151], v[188:191], v[46:49]
	v_mfma_f32_16x16x32_bf16 v[42:45], v[156:159], v[188:191], v[42:45]
	s_waitcnt lgkmcnt(3)
	v_mfma_f32_16x16x32_bf16 v[30:33], v[148:151], v[196:199], v[30:33]
	v_mfma_f32_16x16x32_bf16 v[26:29], v[156:159], v[196:199], v[26:29]
	s_waitcnt lgkmcnt(1)
	v_mfma_f32_16x16x32_bf16 v[14:17], v[148:151], v[204:207], v[14:17]
	v_mfma_f32_16x16x32_bf16 v[10:13], v[156:159], v[204:207], v[10:13]
	v_mfma_f32_16x16x32_bf16 v[62:65], v[152:155], v[184:187], v[62:65]
	v_mfma_f32_16x16x32_bf16 v[58:61], v[160:163], v[184:187], v[58:61]
	v_mfma_f32_16x16x32_bf16 v[46:49], v[152:155], v[192:195], v[46:49]
	v_mfma_f32_16x16x32_bf16 v[42:45], v[160:163], v[192:195], v[42:45]
	v_mfma_f32_16x16x32_bf16 v[30:33], v[152:155], v[200:203], v[30:33]
	v_mfma_f32_16x16x32_bf16 v[26:29], v[160:163], v[200:203], v[26:29]
	s_waitcnt lgkmcnt(0)
	v_mfma_f32_16x16x32_bf16 v[14:17], v[152:155], v[208:211], v[14:17]
	v_mfma_f32_16x16x32_bf16 v[10:13], v[160:163], v[208:211], v[10:13]
	s_setprio 0
	s_setprio 1
	v_mfma_f32_16x16x32_bf16 v[54:57], v[164:167], v[180:183], v[54:57]
	v_mfma_f32_16x16x32_bf16 v[50:53], v[172:175], v[180:183], v[50:53]
	v_mfma_f32_16x16x32_bf16 v[38:41], v[164:167], v[188:191], v[38:41]
	v_mfma_f32_16x16x32_bf16 v[34:37], v[172:175], v[188:191], v[34:37]
	v_mfma_f32_16x16x32_bf16 v[22:25], v[164:167], v[196:199], v[22:25]
	v_mfma_f32_16x16x32_bf16 v[18:21], v[172:175], v[196:199], v[18:21]
	v_mfma_f32_16x16x32_bf16 v[6:9], v[164:167], v[204:207], v[6:9]
	v_mfma_f32_16x16x32_bf16 v[2:5], v[172:175], v[204:207], v[2:5]
	v_mfma_f32_16x16x32_bf16 v[54:57], v[168:171], v[184:187], v[54:57]
	v_mfma_f32_16x16x32_bf16 v[50:53], v[176:179], v[184:187], v[50:53]
	v_mfma_f32_16x16x32_bf16 v[38:41], v[168:171], v[192:195], v[38:41]
	v_mfma_f32_16x16x32_bf16 v[34:37], v[176:179], v[192:195], v[34:37]
	v_mfma_f32_16x16x32_bf16 v[22:25], v[168:171], v[200:203], v[22:25]
	v_mfma_f32_16x16x32_bf16 v[18:21], v[176:179], v[200:203], v[18:21]
	s_setprio 2
	s_barrier
	v_mfma_f32_16x16x32_bf16 v[6:9], v[168:171], v[208:211], v[6:9]
	v_mfma_f32_16x16x32_bf16 v[2:5], v[176:179], v[208:211], v[2:5]
	s_setprio 0
	s_add_i32 s77, s77, 2
	s_add_u32 s73, s73, 0x100
	s_addc_u32 s74, s74, 0
	s_add_u32 s18, s18, 0x100
	s_addc_u32 s19, s19, 0
	s_add_u32 s75, s75, 0x100
	s_addc_u32 s76, s76, 0
	s_cmp_gt_u32 s77, 29
	s_cbranch_scc0 .LBB0_1224
	s_and_b64 vcc, exec, s[6:7]
	s_cbranch_vccz .LBB0_1227
	s_barrier
.LBB0_1227:
	v_exp_f32_e32 v150, v126
	v_exp_f32_e32 v152, v122
	v_exp_f32_e32 v151, v127
	v_exp_f32_e32 v156, v124
	v_exp_f32_e32 v157, v125
	v_exp_f32_e32 v153, v123
	v_exp_f32_e32 v154, v128
	v_exp_f32_e32 v155, v129
	s_lshl_b32 s9, s17, 1
	v_pk_add_f32 v[150:151], v[150:151], 1.0 op_sel_hi:[1,0]
	v_pk_add_f32 v[156:157], v[156:157], 1.0 op_sel_hi:[1,0]
	v_pk_add_f32 v[152:153], v[152:153], 1.0 op_sel_hi:[1,0]
	v_lshl_add_u32 v136, s16, 8, v142
	s_or_b32 s16, s9, s58
	v_rcp_f32_e32 v150, v150
	v_rcp_f32_e32 v152, v152
	v_rcp_f32_e32 v151, v151
	v_rcp_f32_e32 v153, v153
	v_rcp_f32_e32 v156, v156
	v_rcp_f32_e32 v157, v157
	s_ashr_i32 s17, s16, 31
	v_pk_add_f32 v[154:155], v[154:155], 1.0 op_sel_hi:[1,0]
	s_lshl_b64 s[16:17], s[16:17], 14
	v_ashrrev_i32_e32 v137, 31, v136
	v_rcp_f32_e32 v154, v154
	v_rcp_f32_e32 v155, v155
	v_lshl_add_u64 v[148:149], s[16:17], 0, v[136:137]
	v_pk_mul_f32 v[118:119], v[126:127], v[118:119]
	v_pk_mul_f32 v[116:117], v[124:125], v[116:117]
	v_pk_mul_f32 v[114:115], v[122:123], v[114:115]
	v_lshlrev_b64 v[148:149], 7, v[148:149]
	v_pk_mul_f32 v[118:119], v[150:151], v[118:119]
	v_pk_mul_f32 v[122:123], v[156:157], v[116:117]
	v_pk_mul_f32 v[116:117], v[152:153], v[114:115]
	v_lshl_add_u64 v[148:149], v[130:131], 0, v[148:149]
	v_pk_mul_f32 v[120:121], v[128:129], v[120:121]
	v_cvt_pk_bf16_f32 v114, v118, v119
	v_cvt_pk_bf16_f32 v116, v116, v117
	v_cvt_pk_bf16_f32 v117, v122, v123
	v_exp_f32_e32 v118, v106
	v_exp_f32_e32 v122, v108
	v_exp_f32_e32 v123, v109
	v_exp_f32_e32 v119, v107
	v_pk_mul_f32 v[120:121], v[154:155], v[120:121]
	v_pk_mul_f32 v[100:101], v[108:109], v[100:101]
	v_cvt_pk_bf16_f32 v115, v120, v121
	global_store_dwordx4 v[148:149], v[114:117], off
	v_exp_f32_e32 v120, v112
	v_exp_f32_e32 v121, v113
	v_exp_f32_e32 v116, v110
	v_exp_f32_e32 v117, v111
	v_pk_add_f32 v[122:123], v[122:123], 1.0 op_sel_hi:[1,0]
	v_pk_add_f32 v[118:119], v[118:119], 1.0 op_sel_hi:[1,0]
	v_rcp_f32_e32 v122, v122
	v_pk_add_f32 v[116:117], v[116:117], 1.0 op_sel_hi:[1,0]
	v_rcp_f32_e32 v118, v118
	v_rcp_f32_e32 v119, v119
	v_rcp_f32_e32 v123, v123
	v_or_b32_e32 v114, 16, v136
	v_pk_add_f32 v[120:121], v[120:121], 1.0 op_sel_hi:[1,0]
	v_rcp_f32_e32 v116, v116
	v_rcp_f32_e32 v117, v117
	v_ashrrev_i32_e32 v115, 31, v114
	v_rcp_f32_e32 v120, v120
	v_rcp_f32_e32 v121, v121
	v_lshl_add_u64 v[114:115], s[16:17], 0, v[114:115]
	v_pk_mul_f32 v[98:99], v[106:107], v[98:99]
	v_lshlrev_b64 v[114:115], 7, v[114:115]
	v_pk_mul_f32 v[102:103], v[110:111], v[102:103]
	v_pk_mul_f32 v[106:107], v[122:123], v[100:101]
	v_pk_mul_f32 v[100:101], v[118:119], v[98:99]
	v_lshl_add_u64 v[114:115], v[130:131], 0, v[114:115]
	v_pk_mul_f32 v[104:105], v[112:113], v[104:105]
	v_pk_mul_f32 v[102:103], v[116:117], v[102:103]
	v_cvt_pk_bf16_f32 v100, v100, v101
	v_cvt_pk_bf16_f32 v101, v106, v107
	v_pk_mul_f32 v[104:105], v[120:121], v[104:105]
	v_cvt_pk_bf16_f32 v98, v102, v103
	v_exp_f32_e32 v102, v90
	v_cvt_pk_bf16_f32 v99, v104, v105
	global_store_dwordx4 v[114:115], v[98:101], off
	v_exp_f32_e32 v106, v92
	v_exp_f32_e32 v107, v93
	v_exp_f32_e32 v100, v94
	v_exp_f32_e32 v101, v95
	v_exp_f32_e32 v103, v91
	v_exp_f32_e32 v104, v96
	v_exp_f32_e32 v105, v97
	v_pk_add_f32 v[100:101], v[100:101], 1.0 op_sel_hi:[1,0]
	v_pk_add_f32 v[106:107], v[106:107], 1.0 op_sel_hi:[1,0]
	v_pk_add_f32 v[102:103], v[102:103], 1.0 op_sel_hi:[1,0]
	v_rcp_f32_e32 v100, v100
	v_rcp_f32_e32 v102, v102
	v_rcp_f32_e32 v101, v101
	v_rcp_f32_e32 v103, v103
	v_rcp_f32_e32 v106, v106
	v_rcp_f32_e32 v107, v107
	v_or_b32_e32 v98, 32, v136
	v_pk_add_f32 v[104:105], v[104:105], 1.0 op_sel_hi:[1,0]
	v_ashrrev_i32_e32 v99, 31, v98
	v_rcp_f32_e32 v104, v104
	v_rcp_f32_e32 v105, v105
	v_lshl_add_u64 v[98:99], s[16:17], 0, v[98:99]
	v_pk_mul_f32 v[86:87], v[94:95], v[86:87]
	v_pk_mul_f32 v[84:85], v[92:93], v[84:85]
	v_pk_mul_f32 v[82:83], v[90:91], v[82:83]
	v_lshlrev_b64 v[98:99], 7, v[98:99]
	v_pk_mul_f32 v[86:87], v[100:101], v[86:87]
	v_pk_mul_f32 v[90:91], v[106:107], v[84:85]
	v_pk_mul_f32 v[84:85], v[102:103], v[82:83]
	v_lshl_add_u64 v[98:99], v[130:131], 0, v[98:99]
	v_pk_mul_f32 v[88:89], v[96:97], v[88:89]
	v_cvt_pk_bf16_f32 v82, v86, v87
	v_cvt_pk_bf16_f32 v84, v84, v85
	v_cvt_pk_bf16_f32 v85, v90, v91
	v_exp_f32_e32 v86, v74
	v_exp_f32_e32 v90, v76
	v_exp_f32_e32 v91, v77
	v_exp_f32_e32 v87, v75
	v_pk_mul_f32 v[88:89], v[104:105], v[88:89]
	v_pk_mul_f32 v[68:69], v[76:77], v[68:69]
	v_cvt_pk_bf16_f32 v83, v88, v89
	global_store_dwordx4 v[98:99], v[82:85], off
	v_exp_f32_e32 v88, v80
	v_exp_f32_e32 v89, v81
	v_exp_f32_e32 v84, v78
	v_exp_f32_e32 v85, v79
	v_pk_add_f32 v[90:91], v[90:91], 1.0 op_sel_hi:[1,0]
	v_pk_add_f32 v[86:87], v[86:87], 1.0 op_sel_hi:[1,0]
	v_rcp_f32_e32 v90, v90
	v_pk_add_f32 v[84:85], v[84:85], 1.0 op_sel_hi:[1,0]
	v_rcp_f32_e32 v86, v86
	v_rcp_f32_e32 v87, v87
	v_rcp_f32_e32 v91, v91
	v_or_b32_e32 v82, 48, v136
	v_pk_add_f32 v[88:89], v[88:89], 1.0 op_sel_hi:[1,0]
	v_rcp_f32_e32 v84, v84
	v_rcp_f32_e32 v85, v85
	v_ashrrev_i32_e32 v83, 31, v82
	v_rcp_f32_e32 v88, v88
	v_rcp_f32_e32 v89, v89
	v_lshl_add_u64 v[82:83], s[16:17], 0, v[82:83]
	v_pk_mul_f32 v[66:67], v[74:75], v[66:67]
	v_lshlrev_b64 v[82:83], 7, v[82:83]
	v_pk_mul_f32 v[70:71], v[78:79], v[70:71]
	v_pk_mul_f32 v[74:75], v[90:91], v[68:69]
	v_pk_mul_f32 v[68:69], v[86:87], v[66:67]
	v_lshl_add_u64 v[82:83], v[130:131], 0, v[82:83]
	v_pk_mul_f32 v[72:73], v[80:81], v[72:73]
	v_pk_mul_f32 v[70:71], v[84:85], v[70:71]
	v_cvt_pk_bf16_f32 v68, v68, v69
	v_cvt_pk_bf16_f32 v69, v74, v75
	v_pk_mul_f32 v[72:73], v[88:89], v[72:73]
	v_cvt_pk_bf16_f32 v66, v70, v71
	v_exp_f32_e32 v70, v58
	v_cvt_pk_bf16_f32 v67, v72, v73
	global_store_dwordx4 v[82:83], v[66:69], off
	v_exp_f32_e32 v74, v60
	v_exp_f32_e32 v75, v61
	v_exp_f32_e32 v68, v62
	v_exp_f32_e32 v69, v63
	v_exp_f32_e32 v71, v59
	v_exp_f32_e32 v72, v64
	v_exp_f32_e32 v73, v65
	v_pk_add_f32 v[68:69], v[68:69], 1.0 op_sel_hi:[1,0]
	v_pk_add_f32 v[74:75], v[74:75], 1.0 op_sel_hi:[1,0]
	v_pk_add_f32 v[70:71], v[70:71], 1.0 op_sel_hi:[1,0]
	v_rcp_f32_e32 v68, v68
	v_rcp_f32_e32 v70, v70
	v_rcp_f32_e32 v69, v69
	v_rcp_f32_e32 v71, v71
	v_rcp_f32_e32 v74, v74
	v_rcp_f32_e32 v75, v75
	v_add_u32_e32 v66, 0x80, v136
	v_pk_add_f32 v[72:73], v[72:73], 1.0 op_sel_hi:[1,0]
	v_ashrrev_i32_e32 v67, 31, v66
	v_rcp_f32_e32 v72, v72
	v_rcp_f32_e32 v73, v73
	v_lshl_add_u64 v[66:67], s[16:17], 0, v[66:67]
	v_pk_mul_f32 v[54:55], v[62:63], v[54:55]
	v_pk_mul_f32 v[52:53], v[60:61], v[52:53]
	v_pk_mul_f32 v[50:51], v[58:59], v[50:51]
	v_lshlrev_b64 v[66:67], 7, v[66:67]
	v_pk_mul_f32 v[54:55], v[68:69], v[54:55]
	v_pk_mul_f32 v[58:59], v[74:75], v[52:53]
	v_pk_mul_f32 v[52:53], v[70:71], v[50:51]
	v_lshl_add_u64 v[66:67], v[130:131], 0, v[66:67]
	v_pk_mul_f32 v[56:57], v[64:65], v[56:57]
	v_cvt_pk_bf16_f32 v50, v54, v55
	v_cvt_pk_bf16_f32 v52, v52, v53
	v_cvt_pk_bf16_f32 v53, v58, v59
	v_exp_f32_e32 v54, v42
	v_exp_f32_e32 v58, v44
	v_exp_f32_e32 v59, v45
	v_exp_f32_e32 v55, v43
	v_pk_mul_f32 v[56:57], v[72:73], v[56:57]
	v_pk_mul_f32 v[36:37], v[44:45], v[36:37]
	v_cvt_pk_bf16_f32 v51, v56, v57
	global_store_dwordx4 v[66:67], v[50:53], off
	v_exp_f32_e32 v56, v48
	v_exp_f32_e32 v57, v49
	v_exp_f32_e32 v52, v46
	v_exp_f32_e32 v53, v47
	v_pk_add_f32 v[58:59], v[58:59], 1.0 op_sel_hi:[1,0]
	v_pk_add_f32 v[54:55], v[54:55], 1.0 op_sel_hi:[1,0]
	v_rcp_f32_e32 v58, v58
	v_pk_add_f32 v[52:53], v[52:53], 1.0 op_sel_hi:[1,0]
	v_rcp_f32_e32 v54, v54
	v_rcp_f32_e32 v55, v55
	v_rcp_f32_e32 v59, v59
	v_add_u32_e32 v50, 0x90, v136
	v_pk_add_f32 v[56:57], v[56:57], 1.0 op_sel_hi:[1,0]
	v_rcp_f32_e32 v52, v52
	v_rcp_f32_e32 v53, v53
	v_ashrrev_i32_e32 v51, 31, v50
	v_rcp_f32_e32 v56, v56
	v_rcp_f32_e32 v57, v57
	v_lshl_add_u64 v[50:51], s[16:17], 0, v[50:51]
	v_pk_mul_f32 v[34:35], v[42:43], v[34:35]
	v_lshlrev_b64 v[50:51], 7, v[50:51]
	v_pk_mul_f32 v[38:39], v[46:47], v[38:39]
	v_pk_mul_f32 v[42:43], v[58:59], v[36:37]
	v_pk_mul_f32 v[36:37], v[54:55], v[34:35]
	v_lshl_add_u64 v[50:51], v[130:131], 0, v[50:51]
	v_pk_mul_f32 v[40:41], v[48:49], v[40:41]
	v_pk_mul_f32 v[38:39], v[52:53], v[38:39]
	v_cvt_pk_bf16_f32 v36, v36, v37
	v_cvt_pk_bf16_f32 v37, v42, v43
	v_pk_mul_f32 v[40:41], v[56:57], v[40:41]
	v_cvt_pk_bf16_f32 v34, v38, v39
	v_exp_f32_e32 v38, v26
	v_cvt_pk_bf16_f32 v35, v40, v41
	global_store_dwordx4 v[50:51], v[34:37], off
	v_exp_f32_e32 v42, v28
	v_exp_f32_e32 v43, v29
	v_exp_f32_e32 v36, v30
	v_exp_f32_e32 v37, v31
	v_exp_f32_e32 v39, v27
	v_exp_f32_e32 v40, v32
	v_exp_f32_e32 v41, v33
	v_pk_add_f32 v[36:37], v[36:37], 1.0 op_sel_hi:[1,0]
	v_pk_add_f32 v[42:43], v[42:43], 1.0 op_sel_hi:[1,0]
	v_pk_add_f32 v[38:39], v[38:39], 1.0 op_sel_hi:[1,0]
	v_pk_add_f32 v[40:41], v[40:41], 1.0 op_sel_hi:[1,0]
	v_rcp_f32_e32 v36, v36
	v_rcp_f32_e32 v38, v38
	v_rcp_f32_e32 v37, v37
	v_rcp_f32_e32 v39, v39
	v_rcp_f32_e32 v42, v42
	v_rcp_f32_e32 v43, v43
	v_add_u32_e32 v34, 0xa0, v136
	v_rcp_f32_e32 v40, v40
	v_rcp_f32_e32 v41, v41
	v_ashrrev_i32_e32 v35, 31, v34
	v_lshl_add_u64 v[34:35], s[16:17], 0, v[34:35]
	v_pk_mul_f32 v[22:23], v[30:31], v[22:23]
	v_pk_mul_f32 v[20:21], v[28:29], v[20:21]
	v_pk_mul_f32 v[18:19], v[26:27], v[18:19]
	v_lshlrev_b64 v[34:35], 7, v[34:35]
	v_pk_mul_f32 v[24:25], v[32:33], v[24:25]
	v_pk_mul_f32 v[22:23], v[36:37], v[22:23]
	v_pk_mul_f32 v[26:27], v[42:43], v[20:21]
	v_pk_mul_f32 v[20:21], v[38:39], v[18:19]
	v_lshl_add_u64 v[34:35], v[130:131], 0, v[34:35]
	v_pk_mul_f32 v[24:25], v[40:41], v[24:25]
	v_cvt_pk_bf16_f32 v18, v22, v23
	v_cvt_pk_bf16_f32 v20, v20, v21
	v_cvt_pk_bf16_f32 v21, v26, v27
	v_exp_f32_e32 v22, v10
	v_exp_f32_e32 v26, v12
	v_exp_f32_e32 v27, v13
	v_exp_f32_e32 v23, v11
	v_cvt_pk_bf16_f32 v19, v24, v25
	global_store_dwordx4 v[34:35], v[18:21], off
	v_exp_f32_e32 v24, v16
	v_exp_f32_e32 v25, v17
	v_exp_f32_e32 v20, v14
	v_exp_f32_e32 v21, v15
	v_pk_add_f32 v[26:27], v[26:27], 1.0 op_sel_hi:[1,0]
	v_pk_add_f32 v[22:23], v[22:23], 1.0 op_sel_hi:[1,0]
	v_add_u32_e32 v18, 0xb0, v136
	v_pk_add_f32 v[24:25], v[24:25], 1.0 op_sel_hi:[1,0]
	v_pk_add_f32 v[20:21], v[20:21], 1.0 op_sel_hi:[1,0]
	v_rcp_f32_e32 v22, v22
	v_rcp_f32_e32 v23, v23
	v_rcp_f32_e32 v26, v26
	v_rcp_f32_e32 v27, v27
	v_ashrrev_i32_e32 v19, 31, v18
	v_rcp_f32_e32 v20, v20
	v_rcp_f32_e32 v21, v21
	v_rcp_f32_e32 v24, v24
	v_rcp_f32_e32 v25, v25
	v_lshl_add_u64 v[18:19], s[16:17], 0, v[18:19]
	v_lshlrev_b64 v[18:19], 7, v[18:19]
	v_pk_mul_f32 v[4:5], v[12:13], v[4:5]
	v_pk_mul_f32 v[2:3], v[10:11], v[2:3]
	v_lshl_add_u64 v[18:19], v[130:131], 0, v[18:19]
	v_pk_mul_f32 v[8:9], v[16:17], v[8:9]
	v_pk_mul_f32 v[6:7], v[14:15], v[6:7]
	v_pk_mul_f32 v[10:11], v[26:27], v[4:5]
	v_pk_mul_f32 v[4:5], v[22:23], v[2:3]
	s_andn2_b64 vcc, exec, s[2:3]
	s_mov_b64 s[2:3], -1
	v_pk_mul_f32 v[8:9], v[24:25], v[8:9]
	v_pk_mul_f32 v[6:7], v[20:21], v[6:7]
	v_cvt_pk_bf16_f32 v3, v8, v9
	v_cvt_pk_bf16_f32 v4, v4, v5
	v_cvt_pk_bf16_f32 v5, v10, v11
	s_nop 0
	v_cvt_pk_bf16_f32 v2, v6, v7
	global_store_dwordx4 v[18:19], v[2:5], off
	s_cbranch_vccnz .LBB0_1220
	s_andn2_b64 vcc, exec, s[4:5]
	s_cbranch_vccnz .LBB0_1219
	s_mov_b32 s99, 1
	s_branch .LBB0_1219

.LBB0_1356:
	s_ashr_i32 s13, s12, 31
	s_lshl_b64 s[14:15], s[12:13], 15
	s_add_u32 s14, s28, s14
	s_addc_u32 s15, s29, s15
	s_and_b64 s[16:17], s[2:3], exec
	s_cselect_b32 s13, s15, s23
	s_cselect_b32 s67, s14, s22
	s_ashr_i32 s11, s10, 31
	s_lshl_b64 s[16:17], s[10:11], 15
	s_add_u32 s16, s30, s16
	s_addc_u32 s17, s31, s17
	s_and_b64 s[24:25], s[2:3], exec
	s_cselect_b32 s11, s17, s21
	s_cselect_b32 s73, s16, s20
	s_add_u32 s74, s20, 0x80000
	s_addc_u32 s75, s21, 0
	s_add_u32 s20, s22, 0x204000
	s_addc_u32 s21, s23, 0
	s_add_u32 s76, s22, 0x400000
	v_mov_b32_e32 v2, 0
	s_addc_u32 s77, s23, 0
	s_mov_b32 s78, -2
	v_mov_b32_e32 v3, v2
	v_mov_b32_e32 v4, v2
	v_mov_b32_e32 v5, v2
	v_mov_b32_e32 v6, v2
	v_mov_b32_e32 v7, v2
	s_waitcnt vmcnt(25)
	v_mov_b32_e32 v8, v2
	s_waitcnt vmcnt(24)
	v_mov_b32_e32 v9, v2
	s_waitcnt vmcnt(15)
	v_mov_b32_e32 v18, v2
	s_waitcnt vmcnt(14)
	v_mov_b32_e32 v19, v2
	s_waitcnt vmcnt(13)
	v_mov_b32_e32 v20, v2
	s_waitcnt vmcnt(12)
	v_mov_b32_e32 v21, v2
	s_waitcnt vmcnt(11)
	v_mov_b32_e32 v22, v2
	s_waitcnt vmcnt(10)
	v_mov_b32_e32 v23, v2
	s_waitcnt vmcnt(9)
	v_mov_b32_e32 v24, v2
	s_waitcnt vmcnt(8)
	v_mov_b32_e32 v25, v2
	v_mov_b32_e32 v34, v2
	v_mov_b32_e32 v35, v2
	v_mov_b32_e32 v36, v2
	v_mov_b32_e32 v37, v2
	v_mov_b32_e32 v38, v2
	v_mov_b32_e32 v39, v2
	v_mov_b32_e32 v40, v2
	v_mov_b32_e32 v41, v2
	v_mov_b32_e32 v50, v2
	v_mov_b32_e32 v51, v2
	v_mov_b32_e32 v52, v2
	v_mov_b32_e32 v53, v2
	v_mov_b32_e32 v54, v2
	v_mov_b32_e32 v55, v2
	v_mov_b32_e32 v56, v2
	v_mov_b32_e32 v57, v2
	v_mov_b32_e32 v10, v2
	v_mov_b32_e32 v11, v2
	v_mov_b32_e32 v12, v2
	v_mov_b32_e32 v13, v2
	v_mov_b32_e32 v14, v2
	v_mov_b32_e32 v15, v2
	v_mov_b32_e32 v16, v2
	v_mov_b32_e32 v17, v2
	s_waitcnt vmcnt(7)
	v_mov_b32_e32 v26, v2
	s_waitcnt vmcnt(6)
	v_mov_b32_e32 v27, v2
	s_waitcnt vmcnt(5)
	v_mov_b32_e32 v28, v2
	s_waitcnt vmcnt(4)
	v_mov_b32_e32 v29, v2
	s_waitcnt vmcnt(3)
	v_mov_b32_e32 v30, v2
	s_waitcnt vmcnt(2)
	v_mov_b32_e32 v31, v2
	s_waitcnt vmcnt(1)
	v_mov_b32_e32 v32, v2
	s_waitcnt vmcnt(0)
	v_mov_b32_e32 v33, v2
	v_mov_b32_e32 v42, v2
	v_mov_b32_e32 v43, v2
	v_mov_b32_e32 v44, v2
	v_mov_b32_e32 v45, v2
	v_mov_b32_e32 v46, v2
	v_mov_b32_e32 v47, v2
	v_mov_b32_e32 v48, v2
	v_mov_b32_e32 v49, v2
	v_mov_b32_e32 v58, v2
	v_mov_b32_e32 v59, v2
	v_mov_b32_e32 v60, v2
	v_mov_b32_e32 v61, v2
	v_mov_b32_e32 v62, v2
	v_mov_b32_e32 v63, v2
	v_mov_b32_e32 v64, v2
	v_mov_b32_e32 v65, v2
	v_mov_b32_e32 v66, v2
	v_mov_b32_e32 v67, v2
	v_mov_b32_e32 v68, v2
	v_mov_b32_e32 v69, v2
	v_mov_b32_e32 v70, v2
	v_mov_b32_e32 v71, v2
	v_mov_b32_e32 v72, v2
	v_mov_b32_e32 v73, v2
	v_mov_b32_e32 v74, v2
	v_mov_b32_e32 v75, v2
	v_mov_b32_e32 v76, v2
	v_mov_b32_e32 v77, v2
	v_mov_b32_e32 v82, v2
	v_mov_b32_e32 v83, v2
	v_mov_b32_e32 v84, v2
	v_mov_b32_e32 v85, v2
	v_mov_b32_e32 v98, v2
	v_mov_b32_e32 v99, v2
	v_mov_b32_e32 v100, v2
	v_mov_b32_e32 v101, v2
	v_mov_b32_e32 v102, v2
	v_mov_b32_e32 v103, v2
	v_mov_b32_e32 v104, v2
	v_mov_b32_e32 v105, v2
	v_mov_b32_e32 v106, v2
	v_mov_b32_e32 v107, v2
	v_mov_b32_e32 v108, v2
	v_mov_b32_e32 v109, v2
	v_mov_b32_e32 v114, v2
	v_mov_b32_e32 v115, v2
	v_mov_b32_e32 v116, v2
	v_mov_b32_e32 v117, v2
	v_mov_b32_e32 v78, v2
	v_mov_b32_e32 v79, v2
	v_mov_b32_e32 v80, v2
	v_mov_b32_e32 v81, v2
	v_mov_b32_e32 v86, v2
	v_mov_b32_e32 v87, v2
	v_mov_b32_e32 v88, v2
	v_mov_b32_e32 v89, v2
	v_mov_b32_e32 v90, v2
	v_mov_b32_e32 v91, v2
	v_mov_b32_e32 v92, v2
	v_mov_b32_e32 v93, v2
	v_mov_b32_e32 v94, v2
	v_mov_b32_e32 v95, v2
	v_mov_b32_e32 v96, v2
	v_mov_b32_e32 v97, v2
	v_mov_b32_e32 v110, v2
	v_mov_b32_e32 v111, v2
	v_mov_b32_e32 v112, v2
	v_mov_b32_e32 v113, v2
	v_mov_b32_e32 v118, v2
	v_mov_b32_e32 v119, v2
	v_mov_b32_e32 v120, v2
	v_mov_b32_e32 v121, v2
	v_mov_b32_e32 v122, v2
	v_mov_b32_e32 v123, v2
	v_mov_b32_e32 v124, v2
	v_mov_b32_e32 v125, v2
	v_mov_b32_e32 v126, v2
	v_mov_b32_e32 v127, v2
	v_mov_b32_e32 v128, v2
	v_mov_b32_e32 v129, v2
	s_cmp_eq_u32 s99, 0
	s_cbranch_scc1 .Lro_skip_8
	s_barrier
	s_mov_b32 s99, 0
.Lro_skip_8:
.LBB0_1357:
	ds_read_b128 v[130:133], v181
	ds_read_b128 v[134:137], v181 offset:1024
	ds_read_b128 v[138:141], v181 offset:2048
	ds_read_b128 v[142:145], v181 offset:3072
	ds_read_b128 v[150:153], v182
	ds_read_b128 v[154:157], v182 offset:1024
	ds_read_b128 v[158:161], v182 offset:2048
	ds_read_b128 v[162:165], v182 offset:3072
	s_cmpk_eq_i32 s78, 0x52
	s_cselect_b32 s23, s11, s75
	s_cselect_b32 s22, s73, s74
	s_cselect_b32 s25, s13, s77
	s_cselect_b32 s24, s67, s76
	ds_read_b128 v[166:169], v183
	ds_read_b128 v[170:173], v183 offset:1024
	ds_read_b128 v[186:189], v183 offset:2048
	ds_read_b128 v[190:193], v183 offset:3072
	ds_read_b128 v[194:197], v183 offset:4096
	ds_read_b128 v[198:201], v183 offset:5120
	ds_read_b128 v[202:205], v183 offset:6144
	ds_read_b128 v[206:209], v183 offset:7168
	s_add_u32 s80, s20, 0xffffc000
	s_addc_u32 s81, s21, -1
	s_mov_b32 s79, m0
	s_mov_b32 m0, s58
	s_nop 0
	global_load_lds_dwordx4 v1, s[80:81]
	s_mov_b32 m0, s79
	s_nop 0
	s_mov_b32 s79, m0
	s_mov_b32 m0, s64
	s_nop 0
	global_load_lds_dwordx4 v177, s[80:81]
	s_mov_b32 m0, s79
	s_nop 0
	s_mov_b32 s79, m0
	s_mov_b32 m0, s59
	s_nop 0
	global_load_lds_dwordx4 v1, s[20:21]
	s_mov_b32 m0, s79
	s_nop 0
	s_mov_b32 s79, m0
	s_mov_b32 m0, s65
	s_nop 0
	global_load_lds_dwordx4 v177, s[20:21]
	s_mov_b32 m0, s79
	s_waitcnt vmcnt(8)
	s_waitcnt lgkmcnt(0)
	s_barrier
	s_setprio 1
	s_waitcnt lgkmcnt(7)
	v_mfma_f32_16x16x32_bf16 v[126:129], v[130:133], v[166:169], v[126:129]
	v_mfma_f32_16x16x32_bf16 v[122:125], v[138:141], v[166:169], v[122:125]
	s_waitcnt lgkmcnt(5)
	v_mfma_f32_16x16x32_bf16 v[118:121], v[130:133], v[186:189], v[118:121]
	v_mfma_f32_16x16x32_bf16 v[110:113], v[138:141], v[186:189], v[110:113]
	s_waitcnt lgkmcnt(3)
	v_mfma_f32_16x16x32_bf16 v[94:97], v[130:133], v[194:197], v[94:97]
	v_mfma_f32_16x16x32_bf16 v[90:93], v[138:141], v[194:197], v[90:93]
	s_waitcnt lgkmcnt(1)
	v_mfma_f32_16x16x32_bf16 v[86:89], v[130:133], v[202:205], v[86:89]
	v_mfma_f32_16x16x32_bf16 v[78:81], v[138:141], v[202:205], v[78:81]
	v_mfma_f32_16x16x32_bf16 v[126:129], v[134:137], v[170:173], v[126:129]
	v_mfma_f32_16x16x32_bf16 v[122:125], v[142:145], v[170:173], v[122:125]
	v_mfma_f32_16x16x32_bf16 v[118:121], v[134:137], v[190:193], v[118:121]
	v_mfma_f32_16x16x32_bf16 v[110:113], v[142:145], v[190:193], v[110:113]
	v_mfma_f32_16x16x32_bf16 v[94:97], v[134:137], v[198:201], v[94:97]
	v_mfma_f32_16x16x32_bf16 v[90:93], v[142:145], v[198:201], v[90:93]
	s_waitcnt lgkmcnt(0)
	v_mfma_f32_16x16x32_bf16 v[86:89], v[134:137], v[206:209], v[86:89]
	v_mfma_f32_16x16x32_bf16 v[78:81], v[142:145], v[206:209], v[78:81]
	s_setprio 0
	s_setprio 1
	v_mfma_f32_16x16x32_bf16 v[114:117], v[150:153], v[166:169], v[114:117]
	v_mfma_f32_16x16x32_bf16 v[106:109], v[158:161], v[166:169], v[106:109]
	v_mfma_f32_16x16x32_bf16 v[102:105], v[150:153], v[186:189], v[102:105]
	v_mfma_f32_16x16x32_bf16 v[98:101], v[158:161], v[186:189], v[98:101]
	v_mfma_f32_16x16x32_bf16 v[82:85], v[150:153], v[194:197], v[82:85]
	v_mfma_f32_16x16x32_bf16 v[74:77], v[158:161], v[194:197], v[74:77]
	v_mfma_f32_16x16x32_bf16 v[70:73], v[150:153], v[202:205], v[70:73]
	v_mfma_f32_16x16x32_bf16 v[66:69], v[158:161], v[202:205], v[66:69]
	v_mfma_f32_16x16x32_bf16 v[114:117], v[154:157], v[170:173], v[114:117]
	v_mfma_f32_16x16x32_bf16 v[106:109], v[162:165], v[170:173], v[106:109]
	v_mfma_f32_16x16x32_bf16 v[102:105], v[154:157], v[190:193], v[102:105]
	v_mfma_f32_16x16x32_bf16 v[98:101], v[162:165], v[190:193], v[98:101]
	v_mfma_f32_16x16x32_bf16 v[82:85], v[154:157], v[198:201], v[82:85]
	v_mfma_f32_16x16x32_bf16 v[74:77], v[162:165], v[198:201], v[74:77]
	s_setprio 2
	s_barrier
	v_mfma_f32_16x16x32_bf16 v[70:73], v[154:157], v[206:209], v[70:73]
	v_mfma_f32_16x16x32_bf16 v[66:69], v[162:165], v[206:209], v[66:69]
	s_setprio 0
	ds_read_b128 v[166:169], v183 offset:16384
	ds_read_b128 v[170:173], v183 offset:17408
	ds_read_b128 v[186:189], v183 offset:18432
	ds_read_b128 v[190:193], v183 offset:19456
	ds_read_b128 v[194:197], v183 offset:20480
	ds_read_b128 v[198:201], v183 offset:21504
	ds_read_b128 v[202:205], v183 offset:22528
	ds_read_b128 v[206:209], v183 offset:23552
	s_mov_b32 s79, m0
	s_mov_b32 m0, s35
	s_nop 0
	global_load_lds_dwordx4 v176, s[22:23]
	s_mov_b32 m0, s79
	s_add_u32 s80, s22, 0x4000
	s_mov_b32 s79, m0
	s_mov_b32 m0, s36
	s_nop 0
	global_load_lds_dwordx4 v178, s[22:23]
	s_mov_b32 m0, s79
	s_addc_u32 s81, s23, 0
	s_mov_b32 s79, m0
	s_mov_b32 m0, s37
	s_nop 0
	global_load_lds_dwordx4 v176, s[80:81]
	s_mov_b32 m0, s79
	s_nop 0
	s_mov_b32 s79, m0
	s_mov_b32 m0, s40
	s_nop 0
	global_load_lds_dwordx4 v178, s[80:81]
	s_mov_b32 m0, s79
	s_waitcnt vmcnt(4)
	s_waitcnt lgkmcnt(0)
	s_barrier
	s_setprio 1
	s_waitcnt lgkmcnt(7)
	v_mfma_f32_16x16x32_bf16 v[62:65], v[130:133], v[166:169], v[62:65]
	v_mfma_f32_16x16x32_bf16 v[58:61], v[138:141], v[166:169], v[58:61]
	s_waitcnt lgkmcnt(5)
	v_mfma_f32_16x16x32_bf16 v[46:49], v[130:133], v[186:189], v[46:49]
	v_mfma_f32_16x16x32_bf16 v[42:45], v[138:141], v[186:189], v[42:45]
	s_waitcnt lgkmcnt(3)
	v_mfma_f32_16x16x32_bf16 v[30:33], v[130:133], v[194:197], v[30:33]
	v_mfma_f32_16x16x32_bf16 v[26:29], v[138:141], v[194:197], v[26:29]
	s_waitcnt lgkmcnt(1)
	v_mfma_f32_16x16x32_bf16 v[14:17], v[130:133], v[202:205], v[14:17]
	v_mfma_f32_16x16x32_bf16 v[10:13], v[138:141], v[202:205], v[10:13]
	v_mfma_f32_16x16x32_bf16 v[62:65], v[134:137], v[170:173], v[62:65]
	v_mfma_f32_16x16x32_bf16 v[58:61], v[142:145], v[170:173], v[58:61]
	v_mfma_f32_16x16x32_bf16 v[46:49], v[134:137], v[190:193], v[46:49]
	v_mfma_f32_16x16x32_bf16 v[42:45], v[142:145], v[190:193], v[42:45]
	v_mfma_f32_16x16x32_bf16 v[30:33], v[134:137], v[198:201], v[30:33]
	v_mfma_f32_16x16x32_bf16 v[26:29], v[142:145], v[198:201], v[26:29]
	s_waitcnt lgkmcnt(0)
	v_mfma_f32_16x16x32_bf16 v[14:17], v[134:137], v[206:209], v[14:17]
	v_mfma_f32_16x16x32_bf16 v[10:13], v[142:145], v[206:209], v[10:13]
	s_setprio 0
	s_setprio 1
	v_mfma_f32_16x16x32_bf16 v[54:57], v[150:153], v[166:169], v[54:57]
	v_mfma_f32_16x16x32_bf16 v[50:53], v[158:161], v[166:169], v[50:53]
	v_mfma_f32_16x16x32_bf16 v[38:41], v[150:153], v[186:189], v[38:41]
	v_mfma_f32_16x16x32_bf16 v[34:37], v[158:161], v[186:189], v[34:37]
	v_mfma_f32_16x16x32_bf16 v[22:25], v[150:153], v[194:197], v[22:25]
	v_mfma_f32_16x16x32_bf16 v[18:21], v[158:161], v[194:197], v[18:21]
	v_mfma_f32_16x16x32_bf16 v[6:9], v[150:153], v[202:205], v[6:9]
	v_mfma_f32_16x16x32_bf16 v[2:5], v[158:161], v[202:205], v[2:5]
	v_mfma_f32_16x16x32_bf16 v[54:57], v[154:157], v[170:173], v[54:57]
	v_mfma_f32_16x16x32_bf16 v[50:53], v[162:165], v[170:173], v[50:53]
	v_mfma_f32_16x16x32_bf16 v[38:41], v[154:157], v[190:193], v[38:41]
	v_mfma_f32_16x16x32_bf16 v[34:37], v[162:165], v[190:193], v[34:37]
	v_mfma_f32_16x16x32_bf16 v[22:25], v[154:157], v[198:201], v[22:25]
	v_mfma_f32_16x16x32_bf16 v[18:21], v[162:165], v[198:201], v[18:21]
	s_setprio 2
	s_barrier
	v_mfma_f32_16x16x32_bf16 v[6:9], v[154:157], v[206:209], v[6:9]
	v_mfma_f32_16x16x32_bf16 v[2:5], v[162:165], v[206:209], v[2:5]
	s_setprio 0
	ds_read_b128 v[130:133], v184
	ds_read_b128 v[134:137], v184 offset:1024
	ds_read_b128 v[138:141], v184 offset:2048
	ds_read_b128 v[142:145], v184 offset:3072
	ds_read_b128 v[150:153], v185
	ds_read_b128 v[154:157], v185 offset:1024
	ds_read_b128 v[158:161], v185 offset:2048
	ds_read_b128 v[162:165], v185 offset:3072
	ds_read_b128 v[166:169], v183 offset:32768
	ds_read_b128 v[170:173], v183 offset:33792
	ds_read_b128 v[186:189], v183 offset:34816
	ds_read_b128 v[190:193], v183 offset:35840
	ds_read_b128 v[194:197], v183 offset:36864
	ds_read_b128 v[198:201], v183 offset:37888
	ds_read_b128 v[202:205], v183 offset:38912
	ds_read_b128 v[206:209], v183 offset:39936
	s_mov_b32 s79, m0
	s_mov_b32 m0, s34
	s_nop 0
	global_load_lds_dwordx4 v1, s[24:25]
	s_mov_b32 m0, s79
	s_nop 0
	s_mov_b32 s79, m0
	s_mov_b32 m0, s41
	s_nop 0
	global_load_lds_dwordx4 v177, s[24:25]
	s_mov_b32 m0, s79
	s_add_u32 s24, s24, 0x4000
	s_addc_u32 s25, s25, 0
	s_mov_b32 s79, m0
	s_mov_b32 m0, s42
	s_nop 0
	global_load_lds_dwordx4 v1, s[24:25]
	s_mov_b32 m0, s79
	s_nop 0
	s_mov_b32 s79, m0
	s_mov_b32 m0, s43
	s_nop 0
	global_load_lds_dwordx4 v177, s[24:25]
	s_mov_b32 m0, s79
	s_waitcnt vmcnt(8)
	s_waitcnt lgkmcnt(0)
	s_barrier
	s_setprio 1
	s_waitcnt lgkmcnt(7)
	v_mfma_f32_16x16x32_bf16 v[126:129], v[130:133], v[166:169], v[126:129]
	v_mfma_f32_16x16x32_bf16 v[122:125], v[138:141], v[166:169], v[122:125]
	s_waitcnt lgkmcnt(5)
	v_mfma_f32_16x16x32_bf16 v[118:121], v[130:133], v[186:189], v[118:121]
	v_mfma_f32_16x16x32_bf16 v[110:113], v[138:141], v[186:189], v[110:113]
	s_waitcnt lgkmcnt(3)
	v_mfma_f32_16x16x32_bf16 v[94:97], v[130:133], v[194:197], v[94:97]
	v_mfma_f32_16x16x32_bf16 v[90:93], v[138:141], v[194:197], v[90:93]
	s_waitcnt lgkmcnt(1)
	v_mfma_f32_16x16x32_bf16 v[86:89], v[130:133], v[202:205], v[86:89]
	v_mfma_f32_16x16x32_bf16 v[78:81], v[138:141], v[202:205], v[78:81]
	v_mfma_f32_16x16x32_bf16 v[126:129], v[134:137], v[170:173], v[126:129]
	v_mfma_f32_16x16x32_bf16 v[122:125], v[142:145], v[170:173], v[122:125]
	v_mfma_f32_16x16x32_bf16 v[118:121], v[134:137], v[190:193], v[118:121]
	v_mfma_f32_16x16x32_bf16 v[110:113], v[142:145], v[190:193], v[110:113]
	v_mfma_f32_16x16x32_bf16 v[94:97], v[134:137], v[198:201], v[94:97]
	v_mfma_f32_16x16x32_bf16 v[90:93], v[142:145], v[198:201], v[90:93]
	s_waitcnt lgkmcnt(0)
	v_mfma_f32_16x16x32_bf16 v[86:89], v[134:137], v[206:209], v[86:89]
	v_mfma_f32_16x16x32_bf16 v[78:81], v[142:145], v[206:209], v[78:81]
	s_setprio 0
	s_setprio 1
	v_mfma_f32_16x16x32_bf16 v[114:117], v[150:153], v[166:169], v[114:117]
	v_mfma_f32_16x16x32_bf16 v[106:109], v[158:161], v[166:169], v[106:109]
	v_mfma_f32_16x16x32_bf16 v[102:105], v[150:153], v[186:189], v[102:105]
	v_mfma_f32_16x16x32_bf16 v[98:101], v[158:161], v[186:189], v[98:101]
	v_mfma_f32_16x16x32_bf16 v[82:85], v[150:153], v[194:197], v[82:85]
	v_mfma_f32_16x16x32_bf16 v[74:77], v[158:161], v[194:197], v[74:77]
	v_mfma_f32_16x16x32_bf16 v[70:73], v[150:153], v[202:205], v[70:73]
	v_mfma_f32_16x16x32_bf16 v[66:69], v[158:161], v[202:205], v[66:69]
	v_mfma_f32_16x16x32_bf16 v[114:117], v[154:157], v[170:173], v[114:117]
	v_mfma_f32_16x16x32_bf16 v[106:109], v[162:165], v[170:173], v[106:109]
	v_mfma_f32_16x16x32_bf16 v[102:105], v[154:157], v[190:193], v[102:105]
	v_mfma_f32_16x16x32_bf16 v[98:101], v[162:165], v[190:193], v[98:101]
	v_mfma_f32_16x16x32_bf16 v[82:85], v[154:157], v[198:201], v[82:85]
	v_mfma_f32_16x16x32_bf16 v[74:77], v[162:165], v[198:201], v[74:77]
	s_setprio 2
	s_barrier
	v_mfma_f32_16x16x32_bf16 v[70:73], v[154:157], v[206:209], v[70:73]
	v_mfma_f32_16x16x32_bf16 v[66:69], v[162:165], v[206:209], v[66:69]
	s_setprio 0
	ds_read_b128 v[166:169], v183 offset:49152
	ds_read_b128 v[170:173], v183 offset:50176
	ds_read_b128 v[186:189], v183 offset:51200
	ds_read_b128 v[190:193], v183 offset:52224
	ds_read_b128 v[194:197], v183 offset:53248
	ds_read_b128 v[198:201], v183 offset:54272
	ds_read_b128 v[202:205], v183 offset:55296
	ds_read_b128 v[206:209], v183 offset:56320
	s_add_u32 s24, s22, 0x40000
	s_addc_u32 s25, s23, 0
	s_mov_b32 s79, m0
	s_mov_b32 m0, s46
	s_nop 0
	global_load_lds_dwordx4 v176, s[24:25]
	s_mov_b32 m0, s79
	s_add_u32 s22, s22, 0x44000
	s_mov_b32 s79, m0
	s_mov_b32 m0, s47
	s_nop 0
	global_load_lds_dwordx4 v178, s[24:25]
	s_mov_b32 m0, s79
	s_addc_u32 s23, s23, 0
	s_mov_b32 s24, m0
	s_mov_b32 m0, s48
	s_nop 0
	global_load_lds_dwordx4 v176, s[22:23]
	s_mov_b32 m0, s24
	s_nop 0
	s_mov_b32 s24, m0
	s_mov_b32 m0, s49
	s_nop 0
	global_load_lds_dwordx4 v178, s[22:23]
	s_mov_b32 m0, s24
	s_waitcnt vmcnt(4)
	s_waitcnt lgkmcnt(0)
	s_barrier
	s_setprio 1
	s_waitcnt lgkmcnt(7)
	v_mfma_f32_16x16x32_bf16 v[62:65], v[130:133], v[166:169], v[62:65]
	v_mfma_f32_16x16x32_bf16 v[58:61], v[138:141], v[166:169], v[58:61]
	s_waitcnt lgkmcnt(5)
	v_mfma_f32_16x16x32_bf16 v[46:49], v[130:133], v[186:189], v[46:49]
	v_mfma_f32_16x16x32_bf16 v[42:45], v[138:141], v[186:189], v[42:45]
	s_waitcnt lgkmcnt(3)
	v_mfma_f32_16x16x32_bf16 v[30:33], v[130:133], v[194:197], v[30:33]
	v_mfma_f32_16x16x32_bf16 v[26:29], v[138:141], v[194:197], v[26:29]
	s_waitcnt lgkmcnt(1)
	v_mfma_f32_16x16x32_bf16 v[14:17], v[130:133], v[202:205], v[14:17]
	v_mfma_f32_16x16x32_bf16 v[10:13], v[138:141], v[202:205], v[10:13]
	v_mfma_f32_16x16x32_bf16 v[62:65], v[134:137], v[170:173], v[62:65]
	v_mfma_f32_16x16x32_bf16 v[58:61], v[142:145], v[170:173], v[58:61]
	v_mfma_f32_16x16x32_bf16 v[46:49], v[134:137], v[190:193], v[46:49]
	v_mfma_f32_16x16x32_bf16 v[42:45], v[142:145], v[190:193], v[42:45]
	v_mfma_f32_16x16x32_bf16 v[30:33], v[134:137], v[198:201], v[30:33]
	v_mfma_f32_16x16x32_bf16 v[26:29], v[142:145], v[198:201], v[26:29]
	s_waitcnt lgkmcnt(0)
	v_mfma_f32_16x16x32_bf16 v[14:17], v[134:137], v[206:209], v[14:17]
	v_mfma_f32_16x16x32_bf16 v[10:13], v[142:145], v[206:209], v[10:13]
	s_setprio 0
	s_setprio 1
	v_mfma_f32_16x16x32_bf16 v[54:57], v[150:153], v[166:169], v[54:57]
	v_mfma_f32_16x16x32_bf16 v[50:53], v[158:161], v[166:169], v[50:53]
	v_mfma_f32_16x16x32_bf16 v[38:41], v[150:153], v[186:189], v[38:41]
	v_mfma_f32_16x16x32_bf16 v[34:37], v[158:161], v[186:189], v[34:37]
	v_mfma_f32_16x16x32_bf16 v[22:25], v[150:153], v[194:197], v[22:25]
	v_mfma_f32_16x16x32_bf16 v[18:21], v[158:161], v[194:197], v[18:21]
	v_mfma_f32_16x16x32_bf16 v[6:9], v[150:153], v[202:205], v[6:9]
	v_mfma_f32_16x16x32_bf16 v[2:5], v[158:161], v[202:205], v[2:5]
	v_mfma_f32_16x16x32_bf16 v[54:57], v[154:157], v[170:173], v[54:57]
	v_mfma_f32_16x16x32_bf16 v[50:53], v[162:165], v[170:173], v[50:53]
	v_mfma_f32_16x16x32_bf16 v[38:41], v[154:157], v[190:193], v[38:41]
	v_mfma_f32_16x16x32_bf16 v[34:37], v[162:165], v[190:193], v[34:37]
	v_mfma_f32_16x16x32_bf16 v[22:25], v[154:157], v[198:201], v[22:25]
	v_mfma_f32_16x16x32_bf16 v[18:21], v[162:165], v[198:201], v[18:21]
	s_setprio 2
	s_barrier
	v_mfma_f32_16x16x32_bf16 v[6:9], v[154:157], v[206:209], v[6:9]
	v_mfma_f32_16x16x32_bf16 v[2:5], v[162:165], v[206:209], v[2:5]
	s_setprio 0
	s_add_i32 s78, s78, 2
	s_add_u32 s74, s74, 0x80000
	s_addc_u32 s75, s75, 0
	s_add_u32 s20, s20, 0x400000
	s_addc_u32 s21, s21, 0
	s_add_u32 s76, s76, 0x400000
	s_addc_u32 s77, s77, 0
	s_cmpk_gt_u32 s78, 0x53
	s_cbranch_scc0 .LBB0_1357
	s_and_b64 vcc, exec, s[8:9]
	s_cbranch_vccz .LBB0_1360
	s_barrier
.LBB0_1360:
	v_lshl_or_b32 v130, s19, 8, v180
	v_ashrrev_i32_e32 v131, 31, v130
	v_lshl_add_u32 v132, s18, 8, v179
	v_lshlrev_b64 v[150:151], 1, v[130:131]
	v_ashrrev_i32_e32 v133, 31, v132
	v_lshl_add_u64 v[168:169], s[6:7], 0, v[150:151]
	v_lshlrev_b64 v[170:171], 12, v[132:133]
	v_lshl_add_u64 v[134:135], v[168:169], 0, v[170:171]
	s_ashr_i32 s11, s18, 31
	global_load_dwordx4 v[152:155], v[134:135], off
	global_load_dwordx4 v[156:159], v[134:135], off offset:256
	s_lshr_b32 s11, s11, 28
	v_or_b32_e32 v134, 16, v132
	s_add_i32 s11, s18, s11
	v_ashrrev_i32_e32 v135, 31, v134
	v_lshlrev_b64 v[206:207], 12, v[134:135]
	s_ashr_i32 s11, s11, 4
	v_lshl_add_u64 v[134:135], v[168:169], 0, v[206:207]
	s_mul_hi_i32 s13, s11, 0x12000
	s_mul_i32 s11, s11, 0x12000
	global_load_dwordx4 v[186:189], v[134:135], off
	s_add_u32 s18, s56, s11
	s_addc_u32 s19, s57, s13
	v_lshl_add_u64 v[130:131], v[130:131], 2, s[18:19]
	global_load_dwordx4 v[160:163], v[130:131], off
	global_load_dwordx4 v[190:193], v[130:131], off offset:16
	global_load_dwordx4 v[194:197], v[130:131], off offset:512
	global_load_dwordx4 v[198:201], v[130:131], off offset:528
	global_load_dwordx4 v[202:205], v[134:135], off offset:256
	v_or_b32_e32 v130, 32, v132
	v_or_b32_e32 v132, 48, v132
	v_ashrrev_i32_e32 v131, 31, v130
	v_ashrrev_i32_e32 v133, 31, v132
	v_lshlrev_b64 v[174:175], 12, v[130:131]
	v_lshlrev_b64 v[172:173], 12, v[132:133]
	v_lshl_add_u64 v[130:131], s[6:7], 0, v[170:171]
	v_lshl_add_u64 v[132:133], v[168:169], 0, v[174:175]
	v_lshl_add_u64 v[164:165], v[168:169], 0, v[172:173]
	v_lshl_add_u64 v[208:209], v[130:131], 0, v[150:151]
	global_load_dwordx4 v[142:145], v[132:133], off
	global_load_dwordx4 v[138:141], v[132:133], off offset:256
	global_load_dwordx4 v[134:137], v[164:165], off
	s_nop 0
	global_load_dwordx4 v[130:133], v[164:165], off offset:256
	s_mov_b64 s[18:19], 0x80000
	s_andn2_b64 vcc, exec, s[2:3]
	s_mov_b64 s[2:3], -1
	s_waitcnt vmcnt(11)
	v_cvt_f32_f16_e32 v210, v152
	v_cvt_f32_f16_sdwa v211, v152 dst_sel:DWORD dst_unused:UNUSED_PAD src0_sel:WORD_1
	v_cvt_f32_f16_e32 v212, v153
	v_cvt_f32_f16_sdwa v213, v153 dst_sel:DWORD dst_unused:UNUSED_PAD src0_sel:WORD_1
	v_cvt_f32_f16_e32 v214, v154
	v_cvt_f32_f16_sdwa v215, v154 dst_sel:DWORD dst_unused:UNUSED_PAD src0_sel:WORD_1
	v_cvt_f32_f16_e32 v216, v155
	v_cvt_f32_f16_sdwa v217, v155 dst_sel:DWORD dst_unused:UNUSED_PAD src0_sel:WORD_1
	s_waitcnt vmcnt(10)
	v_cvt_f32_f16_e32 v218, v156
	v_cvt_f32_f16_sdwa v219, v156 dst_sel:DWORD dst_unused:UNUSED_PAD src0_sel:WORD_1
	v_cvt_f32_f16_e32 v220, v157
	v_cvt_f32_f16_sdwa v221, v157 dst_sel:DWORD dst_unused:UNUSED_PAD src0_sel:WORD_1
	v_cvt_f32_f16_e32 v222, v158
	v_cvt_f32_f16_sdwa v223, v158 dst_sel:DWORD dst_unused:UNUSED_PAD src0_sel:WORD_1
	v_cvt_f32_f16_e32 v224, v159
	v_cvt_f32_f16_sdwa v225, v159 dst_sel:DWORD dst_unused:UNUSED_PAD src0_sel:WORD_1
	s_waitcnt vmcnt(9)
	v_cvt_f32_f16_e32 v226, v186
	v_cvt_f32_f16_sdwa v227, v186 dst_sel:DWORD dst_unused:UNUSED_PAD src0_sel:WORD_1
	v_cvt_f32_f16_e32 v186, v187
	v_cvt_f32_f16_sdwa v187, v187 dst_sel:DWORD dst_unused:UNUSED_PAD src0_sel:WORD_1
	v_cvt_f32_f16_e32 v228, v188
	v_cvt_f32_f16_sdwa v229, v188 dst_sel:DWORD dst_unused:UNUSED_PAD src0_sel:WORD_1
	v_cvt_f32_f16_e32 v230, v189
	v_cvt_f32_f16_sdwa v231, v189 dst_sel:DWORD dst_unused:UNUSED_PAD src0_sel:WORD_1
	s_waitcnt vmcnt(8)
	v_pk_mul_f32 v[164:165], v[162:163], 0.5 op_sel_hi:[1,0]
	v_pk_mul_f32 v[166:167], v[160:161], 0.5 op_sel_hi:[1,0]
	s_waitcnt vmcnt(7)
	v_pk_mul_f32 v[160:161], v[192:193], 0.5 op_sel_hi:[1,0]
	v_pk_mul_f32 v[162:163], v[190:191], 0.5 op_sel_hi:[1,0]
	s_waitcnt vmcnt(6)
	v_pk_mul_f32 v[156:157], v[196:197], 0.5 op_sel_hi:[1,0]
	v_pk_mul_f32 v[158:159], v[194:195], 0.5 op_sel_hi:[1,0]
	s_waitcnt vmcnt(5)
	v_pk_mul_f32 v[152:153], v[200:201], 0.5 op_sel_hi:[1,0]
	v_pk_mul_f32 v[154:155], v[198:199], 0.5 op_sel_hi:[1,0]
	v_pk_fma_f32 v[128:129], v[128:129], v[164:165], v[212:213]
	v_pk_fma_f32 v[126:127], v[126:127], v[166:167], v[210:211]
	v_pk_fma_f32 v[124:125], v[124:125], v[160:161], v[216:217]
	v_pk_fma_f32 v[122:123], v[122:123], v[162:163], v[214:215]
	v_pk_fma_f32 v[116:117], v[116:117], v[156:157], v[220:221]
	v_pk_fma_f32 v[114:115], v[114:115], v[158:159], v[218:219]
	v_pk_fma_f32 v[190:191], v[108:109], v[152:153], v[224:225]
	v_pk_fma_f32 v[192:193], v[106:107], v[154:155], v[222:223]
	v_cvt_pk_f16_f32 v106, v126, v127
	v_cvt_pk_f16_f32 v107, v128, v129
	v_cvt_pk_f16_f32 v108, v122, v123
	v_cvt_pk_f16_f32 v109, v124, v125
	v_cvt_pk_f16_f32 v114, v114, v115
	v_cvt_pk_f16_f32 v115, v116, v117
	v_cvt_pk_f16_f32 v116, v192, v193
	v_cvt_pk_f16_f32 v117, v190, v191
	global_store_dwordx4 v[208:209], v[106:109], off
	global_store_dwordx4 v[208:209], v[114:117], off offset:256
	v_pk_fma_f32 v[110:111], v[110:111], v[162:163], v[228:229]
	v_pk_fma_f32 v[108:109], v[120:121], v[164:165], v[186:187]
	v_pk_fma_f32 v[106:107], v[118:119], v[166:167], v[226:227]
	v_pk_fma_f32 v[112:113], v[112:113], v[160:161], v[230:231]
	v_cvt_pk_f16_f32 v106, v106, v107
	v_cvt_pk_f16_f32 v107, v108, v109
	v_cvt_pk_f16_f32 v108, v110, v111
	v_lshl_add_u64 v[110:111], s[6:7], 0, v[206:207]
	v_cvt_pk_f16_f32 v109, v112, v113
	v_lshl_add_u64 v[110:111], v[110:111], 0, v[150:151]
	global_store_dwordx4 v[110:111], v[106:109], off
	s_waitcnt vmcnt(7)
	v_cvt_f32_f16_e32 v112, v204
	v_cvt_f32_f16_e32 v114, v205
	v_cvt_f32_f16_e32 v106, v202
	v_cvt_f32_f16_sdwa v107, v202 dst_sel:DWORD dst_unused:UNUSED_PAD src0_sel:WORD_1
	v_cvt_f32_f16_e32 v108, v203
	v_cvt_f32_f16_sdwa v109, v203 dst_sel:DWORD dst_unused:UNUSED_PAD src0_sel:WORD_1
	v_cvt_f32_f16_sdwa v115, v205 dst_sel:DWORD dst_unused:UNUSED_PAD src0_sel:WORD_1
	v_cvt_f32_f16_sdwa v113, v204 dst_sel:DWORD dst_unused:UNUSED_PAD src0_sel:WORD_1
	v_pk_fma_f32 v[102:103], v[102:103], v[158:159], v[106:107]
	v_pk_fma_f32 v[104:105], v[104:105], v[156:157], v[108:109]
	v_pk_fma_f32 v[106:107], v[100:101], v[152:153], v[114:115]
	v_pk_fma_f32 v[100:101], v[98:99], v[154:155], v[112:113]
	v_cvt_pk_f16_f32 v98, v102, v103
	v_cvt_pk_f16_f32 v99, v104, v105
	v_cvt_pk_f16_f32 v100, v100, v101
	v_cvt_pk_f16_f32 v101, v106, v107
	global_store_dwordx4 v[110:111], v[98:101], off offset:256
	v_lshl_add_u64 v[110:111], v[170:171], 0, s[18:19]
	v_lshl_add_u64 v[112:113], v[168:169], 0, v[110:111]
	s_waitcnt vmcnt(7)
	v_cvt_f32_f16_e32 v102, v142
	v_cvt_f32_f16_sdwa v103, v142 dst_sel:DWORD dst_unused:UNUSED_PAD src0_sel:WORD_1
	v_cvt_f32_f16_e32 v104, v143
	v_cvt_f32_f16_sdwa v105, v143 dst_sel:DWORD dst_unused:UNUSED_PAD src0_sel:WORD_1
	v_cvt_f32_f16_e32 v106, v144
	v_cvt_f32_f16_e32 v108, v145
	global_load_dwordx4 v[98:101], v[112:113], off
	v_cvt_f32_f16_sdwa v109, v145 dst_sel:DWORD dst_unused:UNUSED_PAD src0_sel:WORD_1
	v_cvt_f32_f16_sdwa v107, v144 dst_sel:DWORD dst_unused:UNUSED_PAD src0_sel:WORD_1
	v_pk_fma_f32 v[96:97], v[96:97], v[164:165], v[104:105]
	v_pk_fma_f32 v[94:95], v[94:95], v[166:167], v[102:103]
	v_pk_fma_f32 v[102:103], v[92:93], v[160:161], v[108:109]
	v_pk_fma_f32 v[92:93], v[90:91], v[162:163], v[106:107]
	v_cvt_pk_f16_f32 v90, v94, v95
	v_cvt_pk_f16_f32 v91, v96, v97
	v_cvt_pk_f16_f32 v92, v92, v93
	v_cvt_pk_f16_f32 v93, v102, v103
	v_lshl_add_u64 v[94:95], s[6:7], 0, v[174:175]
	s_waitcnt vmcnt(7)
	v_cvt_f32_f16_e32 v96, v138
	v_cvt_f32_f16_sdwa v97, v138 dst_sel:DWORD dst_unused:UNUSED_PAD src0_sel:WORD_1
	v_cvt_f32_f16_e32 v102, v139
	v_cvt_f32_f16_sdwa v103, v139 dst_sel:DWORD dst_unused:UNUSED_PAD src0_sel:WORD_1
	v_cvt_f32_f16_e32 v104, v140
	v_cvt_f32_f16_e32 v106, v141
	v_cvt_f32_f16_sdwa v107, v141 dst_sel:DWORD dst_unused:UNUSED_PAD src0_sel:WORD_1
	v_cvt_f32_f16_sdwa v105, v140 dst_sel:DWORD dst_unused:UNUSED_PAD src0_sel:WORD_1
	v_lshl_add_u64 v[94:95], v[94:95], 0, v[150:151]
	global_store_dwordx4 v[94:95], v[90:93], off
	global_load_dwordx4 v[90:93], v[112:113], off offset:256
	v_pk_fma_f32 v[84:85], v[84:85], v[156:157], v[102:103]
	v_pk_fma_f32 v[82:83], v[82:83], v[158:159], v[96:97]
	v_pk_fma_f32 v[96:97], v[76:77], v[152:153], v[106:107]
	v_pk_fma_f32 v[76:77], v[74:75], v[154:155], v[104:105]
	v_cvt_pk_f16_f32 v74, v82, v83
	v_cvt_pk_f16_f32 v75, v84, v85
	v_cvt_pk_f16_f32 v76, v76, v77
	v_cvt_pk_f16_f32 v77, v96, v97
	s_mov_b64 s[18:19], 0x90000
	global_store_dwordx4 v[94:95], v[74:77], off offset:256
	v_lshl_add_u64 v[94:95], v[170:171], 0, s[18:19]
	v_lshl_add_u64 v[84:85], v[168:169], 0, v[94:95]
	s_waitcnt vmcnt(9)
	v_cvt_f32_f16_e32 v82, v134
	v_cvt_f32_f16_sdwa v83, v134 dst_sel:DWORD dst_unused:UNUSED_PAD src0_sel:WORD_1
	global_load_dwordx4 v[74:77], v[84:85], off
	v_cvt_f32_f16_e32 v96, v135
	v_cvt_f32_f16_sdwa v97, v135 dst_sel:DWORD dst_unused:UNUSED_PAD src0_sel:WORD_1
	v_cvt_f32_f16_e32 v102, v136
	v_cvt_f32_f16_e32 v104, v137
	v_cvt_f32_f16_sdwa v105, v137 dst_sel:DWORD dst_unused:UNUSED_PAD src0_sel:WORD_1
	v_cvt_f32_f16_sdwa v103, v136 dst_sel:DWORD dst_unused:UNUSED_PAD src0_sel:WORD_1
	v_pk_fma_f32 v[82:83], v[86:87], v[166:167], v[82:83]
	v_pk_fma_f32 v[88:89], v[88:89], v[164:165], v[96:97]
	v_pk_fma_f32 v[86:87], v[80:81], v[160:161], v[104:105]
	v_pk_fma_f32 v[80:81], v[78:79], v[162:163], v[102:103]
	v_cvt_pk_f16_f32 v78, v82, v83
	v_lshl_add_u64 v[82:83], s[6:7], 0, v[172:173]
	v_cvt_pk_f16_f32 v79, v88, v89
	v_cvt_pk_f16_f32 v80, v80, v81
	v_cvt_pk_f16_f32 v81, v86, v87
	v_lshl_add_u64 v[82:83], v[82:83], 0, v[150:151]
	global_store_dwordx4 v[82:83], v[78:81], off
	s_waitcnt vmcnt(10)
	v_cvt_f32_f16_e32 v86, v130
	global_load_dwordx4 v[78:81], v[84:85], off offset:256
	v_cvt_f32_f16_sdwa v87, v130 dst_sel:DWORD dst_unused:UNUSED_PAD src0_sel:WORD_1
	v_cvt_f32_f16_e32 v84, v131
	v_cvt_f32_f16_sdwa v85, v131 dst_sel:DWORD dst_unused:UNUSED_PAD src0_sel:WORD_1
	v_cvt_f32_f16_e32 v88, v132
	v_cvt_f32_f16_e32 v96, v133
	v_cvt_f32_f16_sdwa v97, v133 dst_sel:DWORD dst_unused:UNUSED_PAD src0_sel:WORD_1
	v_cvt_f32_f16_sdwa v89, v132 dst_sel:DWORD dst_unused:UNUSED_PAD src0_sel:WORD_1
	v_pk_fma_f32 v[72:73], v[72:73], v[156:157], v[84:85]
	v_pk_fma_f32 v[70:71], v[70:71], v[158:159], v[86:87]
	v_pk_fma_f32 v[84:85], v[68:69], v[152:153], v[96:97]
	v_pk_fma_f32 v[68:69], v[66:67], v[154:155], v[88:89]
	s_mov_b64 s[18:19], 0xa0000
	v_cvt_pk_f16_f32 v66, v70, v71
	v_cvt_pk_f16_f32 v67, v72, v73
	v_cvt_pk_f16_f32 v68, v68, v69
	v_lshl_add_u64 v[96:97], v[170:171], 0, s[18:19]
	v_cvt_pk_f16_f32 v69, v84, v85
	v_lshl_add_u64 v[86:87], v[168:169], 0, v[96:97]
	global_store_dwordx4 v[82:83], v[66:69], off offset:256
	global_load_dwordx4 v[70:73], v[86:87], off
	s_nop 0
	global_load_dwordx4 v[82:85], v[86:87], off offset:256
	s_mov_b64 s[18:19], 0xb0000
	v_lshl_add_u64 v[102:103], v[170:171], 0, s[18:19]
	v_lshl_add_u64 v[66:67], v[168:169], 0, v[102:103]
	global_load_dwordx4 v[86:89], v[66:67], off
	s_nop 0
	global_load_dwordx4 v[66:69], v[66:67], off offset:256
	s_waitcnt vmcnt(11)
	v_cvt_f32_f16_e32 v104, v98
	v_cvt_f32_f16_sdwa v105, v98 dst_sel:DWORD dst_unused:UNUSED_PAD src0_sel:WORD_1
	v_cvt_f32_f16_e32 v98, v99
	v_cvt_f32_f16_sdwa v99, v99 dst_sel:DWORD dst_unused:UNUSED_PAD src0_sel:WORD_1
	v_cvt_f32_f16_e32 v106, v100
	v_cvt_f32_f16_e32 v108, v101
	v_cvt_f32_f16_sdwa v109, v101 dst_sel:DWORD dst_unused:UNUSED_PAD src0_sel:WORD_1
	v_cvt_f32_f16_sdwa v107, v100 dst_sel:DWORD dst_unused:UNUSED_PAD src0_sel:WORD_1
	v_pk_fma_f32 v[62:63], v[62:63], v[166:167], v[104:105]
	v_pk_fma_f32 v[64:65], v[64:65], v[164:165], v[98:99]
	v_pk_fma_f32 v[98:99], v[60:61], v[160:161], v[108:109]
	v_pk_fma_f32 v[60:61], v[58:59], v[162:163], v[106:107]
	v_cvt_pk_f16_f32 v58, v62, v63
	v_lshl_add_u64 v[62:63], s[6:7], 0, v[110:111]
	v_cvt_pk_f16_f32 v59, v64, v65
	v_cvt_pk_f16_f32 v60, v60, v61
	v_cvt_pk_f16_f32 v61, v98, v99
	v_lshl_add_u64 v[62:63], v[62:63], 0, v[150:151]
	global_store_dwordx4 v[62:63], v[58:61], off
	s_waitcnt vmcnt(10)
	v_cvt_f32_f16_e32 v64, v92
	v_cvt_f32_f16_e32 v58, v90
	v_cvt_f32_f16_sdwa v59, v90 dst_sel:DWORD dst_unused:UNUSED_PAD src0_sel:WORD_1
	v_cvt_f32_f16_e32 v60, v91
	v_cvt_f32_f16_sdwa v61, v91 dst_sel:DWORD dst_unused:UNUSED_PAD src0_sel:WORD_1
	v_cvt_f32_f16_e32 v90, v93
	v_cvt_f32_f16_sdwa v91, v93 dst_sel:DWORD dst_unused:UNUSED_PAD src0_sel:WORD_1
	v_cvt_f32_f16_sdwa v65, v92 dst_sel:DWORD dst_unused:UNUSED_PAD src0_sel:WORD_1
	v_pk_fma_f32 v[56:57], v[56:57], v[156:157], v[60:61]
	v_pk_fma_f32 v[54:55], v[54:55], v[158:159], v[58:59]
	v_pk_fma_f32 v[58:59], v[52:53], v[152:153], v[90:91]
	v_pk_fma_f32 v[52:53], v[50:51], v[154:155], v[64:65]
	v_cvt_pk_f16_f32 v50, v54, v55
	v_cvt_pk_f16_f32 v51, v56, v57
	v_cvt_pk_f16_f32 v52, v52, v53
	v_cvt_pk_f16_f32 v53, v58, v59
	global_store_dwordx4 v[62:63], v[50:53], off offset:256
	s_waitcnt vmcnt(9)
	v_cvt_f32_f16_e32 v54, v76
	v_cvt_f32_f16_e32 v56, v77
	v_cvt_f32_f16_e32 v50, v74
	v_cvt_f32_f16_sdwa v51, v74 dst_sel:DWORD dst_unused:UNUSED_PAD src0_sel:WORD_1
	v_cvt_f32_f16_e32 v52, v75
	v_cvt_f32_f16_sdwa v53, v75 dst_sel:DWORD dst_unused:UNUSED_PAD src0_sel:WORD_1
	v_cvt_f32_f16_sdwa v57, v77 dst_sel:DWORD dst_unused:UNUSED_PAD src0_sel:WORD_1
	v_cvt_f32_f16_sdwa v55, v76 dst_sel:DWORD dst_unused:UNUSED_PAD src0_sel:WORD_1
	v_pk_fma_f32 v[46:47], v[46:47], v[166:167], v[50:51]
	v_pk_fma_f32 v[48:49], v[48:49], v[164:165], v[52:53]
	v_pk_fma_f32 v[50:51], v[44:45], v[160:161], v[56:57]
	v_pk_fma_f32 v[44:45], v[42:43], v[162:163], v[54:55]
	v_cvt_pk_f16_f32 v42, v46, v47
	v_lshl_add_u64 v[46:47], s[6:7], 0, v[94:95]
	v_cvt_pk_f16_f32 v43, v48, v49
	v_cvt_pk_f16_f32 v44, v44, v45
	v_cvt_pk_f16_f32 v45, v50, v51
	v_lshl_add_u64 v[46:47], v[46:47], 0, v[150:151]
	global_store_dwordx4 v[46:47], v[42:45], off
	s_waitcnt vmcnt(8)
	v_cvt_f32_f16_e32 v48, v80
	v_cvt_f32_f16_e32 v50, v81
	v_cvt_f32_f16_e32 v42, v78
	v_cvt_f32_f16_sdwa v43, v78 dst_sel:DWORD dst_unused:UNUSED_PAD src0_sel:WORD_1
	v_cvt_f32_f16_e32 v44, v79
	v_cvt_f32_f16_sdwa v45, v79 dst_sel:DWORD dst_unused:UNUSED_PAD src0_sel:WORD_1
	v_cvt_f32_f16_sdwa v51, v81 dst_sel:DWORD dst_unused:UNUSED_PAD src0_sel:WORD_1
	v_cvt_f32_f16_sdwa v49, v80 dst_sel:DWORD dst_unused:UNUSED_PAD src0_sel:WORD_1
	v_pk_fma_f32 v[38:39], v[38:39], v[158:159], v[42:43]
	v_pk_fma_f32 v[40:41], v[40:41], v[156:157], v[44:45]
	v_pk_fma_f32 v[42:43], v[36:37], v[152:153], v[50:51]
	v_pk_fma_f32 v[36:37], v[34:35], v[154:155], v[48:49]
	v_cvt_pk_f16_f32 v34, v38, v39
	v_cvt_pk_f16_f32 v35, v40, v41
	v_cvt_pk_f16_f32 v36, v36, v37
	v_cvt_pk_f16_f32 v37, v42, v43
	global_store_dwordx4 v[46:47], v[34:37], off offset:256
	s_waitcnt vmcnt(7)
	v_cvt_f32_f16_e32 v38, v72
	v_cvt_f32_f16_e32 v40, v73
	v_cvt_f32_f16_e32 v34, v70
	v_cvt_f32_f16_sdwa v35, v70 dst_sel:DWORD dst_unused:UNUSED_PAD src0_sel:WORD_1
	v_cvt_f32_f16_e32 v36, v71
	v_cvt_f32_f16_sdwa v37, v71 dst_sel:DWORD dst_unused:UNUSED_PAD src0_sel:WORD_1
	v_cvt_f32_f16_sdwa v41, v73 dst_sel:DWORD dst_unused:UNUSED_PAD src0_sel:WORD_1
	v_cvt_f32_f16_sdwa v39, v72 dst_sel:DWORD dst_unused:UNUSED_PAD src0_sel:WORD_1
	v_pk_fma_f32 v[30:31], v[30:31], v[166:167], v[34:35]
	v_pk_fma_f32 v[32:33], v[32:33], v[164:165], v[36:37]
	v_pk_fma_f32 v[34:35], v[28:29], v[160:161], v[40:41]
	v_pk_fma_f32 v[28:29], v[26:27], v[162:163], v[38:39]
	v_cvt_pk_f16_f32 v26, v30, v31
	v_lshl_add_u64 v[30:31], s[6:7], 0, v[96:97]
	v_cvt_pk_f16_f32 v27, v32, v33
	v_cvt_pk_f16_f32 v28, v28, v29
	v_cvt_pk_f16_f32 v29, v34, v35
	v_lshl_add_u64 v[30:31], v[30:31], 0, v[150:151]
	global_store_dwordx4 v[30:31], v[26:29], off
	s_waitcnt vmcnt(7)
	v_cvt_f32_f16_e32 v32, v84
	v_cvt_f32_f16_e32 v34, v85
	v_cvt_f32_f16_e32 v26, v82
	v_cvt_f32_f16_sdwa v27, v82 dst_sel:DWORD dst_unused:UNUSED_PAD src0_sel:WORD_1
	v_cvt_f32_f16_e32 v28, v83
	v_cvt_f32_f16_sdwa v29, v83 dst_sel:DWORD dst_unused:UNUSED_PAD src0_sel:WORD_1
	v_cvt_f32_f16_sdwa v35, v85 dst_sel:DWORD dst_unused:UNUSED_PAD src0_sel:WORD_1
	v_cvt_f32_f16_sdwa v33, v84 dst_sel:DWORD dst_unused:UNUSED_PAD src0_sel:WORD_1
	v_pk_fma_f32 v[22:23], v[22:23], v[158:159], v[26:27]
	v_pk_fma_f32 v[24:25], v[24:25], v[156:157], v[28:29]
	v_pk_fma_f32 v[26:27], v[20:21], v[152:153], v[34:35]
	v_pk_fma_f32 v[20:21], v[18:19], v[154:155], v[32:33]
	v_cvt_pk_f16_f32 v18, v22, v23
	v_cvt_pk_f16_f32 v19, v24, v25
	v_cvt_pk_f16_f32 v20, v20, v21
	v_cvt_pk_f16_f32 v21, v26, v27
	global_store_dwordx4 v[30:31], v[18:21], off offset:256
	s_waitcnt vmcnt(7)
	v_cvt_f32_f16_e32 v22, v88
	v_cvt_f32_f16_e32 v24, v89
	v_cvt_f32_f16_e32 v18, v86
	v_cvt_f32_f16_sdwa v19, v86 dst_sel:DWORD dst_unused:UNUSED_PAD src0_sel:WORD_1
	v_cvt_f32_f16_e32 v20, v87
	v_cvt_f32_f16_sdwa v21, v87 dst_sel:DWORD dst_unused:UNUSED_PAD src0_sel:WORD_1
	v_cvt_f32_f16_sdwa v25, v89 dst_sel:DWORD dst_unused:UNUSED_PAD src0_sel:WORD_1
	v_cvt_f32_f16_sdwa v23, v88 dst_sel:DWORD dst_unused:UNUSED_PAD src0_sel:WORD_1
	v_pk_fma_f32 v[14:15], v[14:15], v[166:167], v[18:19]
	v_pk_fma_f32 v[16:17], v[16:17], v[164:165], v[20:21]
	v_pk_fma_f32 v[18:19], v[12:13], v[160:161], v[24:25]
	v_pk_fma_f32 v[12:13], v[10:11], v[162:163], v[22:23]
	v_cvt_pk_f16_f32 v10, v14, v15
	v_lshl_add_u64 v[14:15], s[6:7], 0, v[102:103]
	v_cvt_pk_f16_f32 v11, v16, v17
	v_cvt_pk_f16_f32 v12, v12, v13
	v_cvt_pk_f16_f32 v13, v18, v19
	v_lshl_add_u64 v[14:15], v[14:15], 0, v[150:151]
	global_store_dwordx4 v[14:15], v[10:13], off
	s_waitcnt vmcnt(7)
	v_cvt_f32_f16_e32 v16, v68
	v_cvt_f32_f16_e32 v18, v69
	v_cvt_f32_f16_e32 v10, v66
	v_cvt_f32_f16_sdwa v11, v66 dst_sel:DWORD dst_unused:UNUSED_PAD src0_sel:WORD_1
	v_cvt_f32_f16_e32 v12, v67
	v_cvt_f32_f16_sdwa v13, v67 dst_sel:DWORD dst_unused:UNUSED_PAD src0_sel:WORD_1
	v_cvt_f32_f16_sdwa v19, v69 dst_sel:DWORD dst_unused:UNUSED_PAD src0_sel:WORD_1
	v_cvt_f32_f16_sdwa v17, v68 dst_sel:DWORD dst_unused:UNUSED_PAD src0_sel:WORD_1
	v_pk_fma_f32 v[6:7], v[6:7], v[158:159], v[10:11]
	v_pk_fma_f32 v[8:9], v[8:9], v[156:157], v[12:13]
	v_pk_fma_f32 v[10:11], v[4:5], v[152:153], v[18:19]
	v_pk_fma_f32 v[4:5], v[2:3], v[154:155], v[16:17]
	v_cvt_pk_f16_f32 v2, v6, v7
	v_cvt_pk_f16_f32 v3, v8, v9
	v_cvt_pk_f16_f32 v4, v4, v5
	v_cvt_pk_f16_f32 v5, v10, v11
	global_store_dwordx4 v[14:15], v[2:5], off offset:256
	s_cbranch_vccnz .LBB0_1349
	s_andn2_b64 vcc, exec, s[4:5]
	s_cbranch_vccnz .LBB0_1348
	s_mov_b32 s99, 1
	s_branch .LBB0_1348

.LBB0_1537:
	s_ashr_i32 s23, s22, 31
	s_lshl_b64 s[24:25], s[22:23], 20
	s_add_u32 s24, s41, s24
	s_addc_u32 s25, s42, s25
	s_and_b64 s[26:27], s[4:5], exec
	s_cselect_b32 s7, s25, s35
	s_cselect_b32 s23, s24, s34
	s_ashr_i32 s21, s20, 31
	s_lshl_b64 s[26:27], s[20:21], 20
	s_add_u32 s26, s43, s26
	s_addc_u32 s27, s46, s27
	s_and_b64 s[36:37], s[4:5], exec
	s_cselect_b32 s21, s27, s31
	s_cselect_b32 s29, s26, s30
	s_add_u32 s79, s30, 0x100
	s_addc_u32 s80, s31, 0
	s_add_u32 s30, s34, 0x80080
	s_addc_u32 s31, s35, 0
	s_add_u32 s81, s34, 0x100
	v_mov_b32_e32 v2, 0
	s_addc_u32 s82, s35, 0
	s_mov_b32 s83, -2
	v_mov_b32_e32 v3, v2
	v_mov_b32_e32 v4, v2
	v_mov_b32_e32 v5, v2
	v_mov_b32_e32 v6, v2
	v_mov_b32_e32 v7, v2
	s_waitcnt vmcnt(25)
	v_mov_b32_e32 v8, v2
	s_waitcnt vmcnt(24)
	v_mov_b32_e32 v9, v2
	s_waitcnt vmcnt(4)
	v_mov_b32_e32 v18, v2
	s_waitcnt vmcnt(14)
	v_mov_b32_e32 v19, v2
	s_waitcnt vmcnt(13)
	v_mov_b32_e32 v20, v2
	s_waitcnt vmcnt(12)
	v_mov_b32_e32 v21, v2
	s_waitcnt vmcnt(2)
	v_mov_b32_e32 v22, v2
	s_waitcnt vmcnt(10)
	v_mov_b32_e32 v23, v2
	s_waitcnt vmcnt(9)
	v_mov_b32_e32 v24, v2
	s_waitcnt vmcnt(8)
	v_mov_b32_e32 v25, v2
	v_mov_b32_e32 v34, v2
	v_mov_b32_e32 v35, v2
	v_mov_b32_e32 v36, v2
	v_mov_b32_e32 v37, v2
	v_mov_b32_e32 v38, v2
	v_mov_b32_e32 v39, v2
	v_mov_b32_e32 v40, v2
	v_mov_b32_e32 v41, v2
	v_mov_b32_e32 v66, v2
	v_mov_b32_e32 v67, v2
	v_mov_b32_e32 v68, v2
	v_mov_b32_e32 v69, v2
	v_mov_b32_e32 v70, v2
	v_mov_b32_e32 v71, v2
	v_mov_b32_e32 v72, v2
	v_mov_b32_e32 v73, v2
	v_mov_b32_e32 v10, v2
	v_mov_b32_e32 v11, v2
	v_mov_b32_e32 v12, v2
	v_mov_b32_e32 v13, v2
	v_mov_b32_e32 v14, v2
	v_mov_b32_e32 v15, v2
	v_mov_b32_e32 v16, v2
	v_mov_b32_e32 v17, v2
	s_waitcnt vmcnt(7)
	v_mov_b32_e32 v26, v2
	s_waitcnt vmcnt(6)
	v_mov_b32_e32 v27, v2
	s_waitcnt vmcnt(5)
	v_mov_b32_e32 v28, v2
	s_waitcnt vmcnt(4)
	v_mov_b32_e32 v29, v2
	s_waitcnt vmcnt(3)
	v_mov_b32_e32 v30, v2
	s_waitcnt vmcnt(2)
	v_mov_b32_e32 v31, v2
	s_waitcnt vmcnt(1)
	v_mov_b32_e32 v32, v2
	s_waitcnt vmcnt(0)
	v_mov_b32_e32 v33, v2
	v_mov_b32_e32 v42, v2
	v_mov_b32_e32 v43, v2
	v_mov_b32_e32 v44, v2
	v_mov_b32_e32 v45, v2
	v_mov_b32_e32 v50, v2
	v_mov_b32_e32 v51, v2
	v_mov_b32_e32 v52, v2
	v_mov_b32_e32 v53, v2
	v_mov_b32_e32 v74, v2
	v_mov_b32_e32 v75, v2
	v_mov_b32_e32 v76, v2
	v_mov_b32_e32 v77, v2
	v_mov_b32_e32 v78, v2
	v_mov_b32_e32 v79, v2
	v_mov_b32_e32 v80, v2
	v_mov_b32_e32 v81, v2
	v_mov_b32_e32 v82, v2
	v_mov_b32_e32 v83, v2
	v_mov_b32_e32 v84, v2
	v_mov_b32_e32 v85, v2
	v_mov_b32_e32 v86, v2
	v_mov_b32_e32 v87, v2
	v_mov_b32_e32 v88, v2
	v_mov_b32_e32 v89, v2
	v_mov_b32_e32 v98, v2
	v_mov_b32_e32 v99, v2
	v_mov_b32_e32 v100, v2
	v_mov_b32_e32 v101, v2
	v_mov_b32_e32 v102, v2
	v_mov_b32_e32 v103, v2
	v_mov_b32_e32 v104, v2
	v_mov_b32_e32 v105, v2
	v_mov_b32_e32 v114, v2
	v_mov_b32_e32 v115, v2
	v_mov_b32_e32 v116, v2
	v_mov_b32_e32 v117, v2
	v_mov_b32_e32 v118, v2
	v_mov_b32_e32 v119, v2
	v_mov_b32_e32 v120, v2
	v_mov_b32_e32 v121, v2
	v_mov_b32_e32 v130, v2
	v_mov_b32_e32 v131, v2
	v_mov_b32_e32 v132, v2
	v_mov_b32_e32 v133, v2
	v_mov_b32_e32 v134, v2
	v_mov_b32_e32 v135, v2
	v_mov_b32_e32 v136, v2
	v_mov_b32_e32 v137, v2
	v_mov_b32_e32 v90, v2
	v_mov_b32_e32 v91, v2
	v_mov_b32_e32 v92, v2
	v_mov_b32_e32 v93, v2
	v_mov_b32_e32 v94, v2
	v_mov_b32_e32 v95, v2
	v_mov_b32_e32 v96, v2
	v_mov_b32_e32 v97, v2
	v_mov_b32_e32 v106, v2
	v_mov_b32_e32 v107, v2
	v_mov_b32_e32 v108, v2
	v_mov_b32_e32 v109, v2
	v_mov_b32_e32 v110, v2
	v_mov_b32_e32 v111, v2
	v_mov_b32_e32 v112, v2
	v_mov_b32_e32 v113, v2
	v_mov_b32_e32 v122, v2
	v_mov_b32_e32 v123, v2
	v_mov_b32_e32 v124, v2
	v_mov_b32_e32 v125, v2
	v_mov_b32_e32 v126, v2
	v_mov_b32_e32 v127, v2
	v_mov_b32_e32 v128, v2
	v_mov_b32_e32 v129, v2
	v_mov_b32_e32 v138, v2
	v_mov_b32_e32 v139, v2
	v_mov_b32_e32 v140, v2
	v_mov_b32_e32 v141, v2
	v_mov_b32_e32 v142, v2
	v_mov_b32_e32 v143, v2
	v_mov_b32_e32 v144, v2
	v_mov_b32_e32 v145, v2
	s_cmp_eq_u32 s99, 0
	s_cbranch_scc1 .Lro_skip_7
	s_barrier
	s_mov_b32 s99, 0
.Lro_skip_7:
.LBB0_1538:
	ds_read_b128 v[46:49], v182
	ds_read_b128 v[54:57], v182 offset:1024
	ds_read_b128 v[58:61], v182 offset:2048
	ds_read_b128 v[62:65], v182 offset:3072
	ds_read_b128 v[146:149], v183
	ds_read_b128 v[150:153], v183 offset:1024
	ds_read_b128 v[154:157], v183 offset:2048
	ds_read_b128 v[158:161], v183 offset:3072
	s_cmp_eq_u32 s83, 28
	s_cselect_b32 s35, s21, s80
	s_cselect_b32 s34, s29, s79
	s_cselect_b32 s37, s7, s82
	s_cselect_b32 s36, s23, s81
	ds_read_b128 v[170:173], v184
	ds_read_b128 v[188:191], v184 offset:1024
	ds_read_b128 v[192:195], v184 offset:2048
	ds_read_b128 v[196:199], v184 offset:3072
	ds_read_b128 v[200:203], v184 offset:4096
	ds_read_b128 v[204:207], v184 offset:5120
	ds_read_b128 v[208:211], v184 offset:6144
	ds_read_b128 v[212:215], v184 offset:7168
	s_add_u32 s86, s30, 0xfff80000
	s_addc_u32 s87, s31, -1
	s_mov_b32 s92, m0
	s_mov_b32 m0, s73
	s_nop 0
	global_load_lds_dwordx4 v176, s[86:87]
	s_mov_b32 m0, s92
	s_nop 0
	s_mov_b32 s92, m0
	s_mov_b32 m0, s75
	s_nop 0
	global_load_lds_dwordx4 v178, s[86:87]
	s_mov_b32 m0, s92
	s_mov_b32 s86, m0
	s_mov_b32 m0, s74
	s_nop 0
	global_load_lds_dwordx4 v176, s[30:31]
	s_mov_b32 m0, s86
	s_nop 0
	s_mov_b32 s86, m0
	s_mov_b32 m0, s76
	s_nop 0
	global_load_lds_dwordx4 v178, s[30:31]
	s_mov_b32 m0, s86
	s_waitcnt vmcnt(8)
	s_waitcnt lgkmcnt(0)
	s_barrier
	s_setprio 1
	s_waitcnt lgkmcnt(7)
	v_mfma_f32_16x16x32_bf16 v[142:145], v[46:49], v[170:173], v[142:145]
	v_mfma_f32_16x16x32_bf16 v[138:141], v[58:61], v[170:173], v[138:141]
	s_waitcnt lgkmcnt(5)
	v_mfma_f32_16x16x32_bf16 v[126:129], v[46:49], v[192:195], v[126:129]
	v_mfma_f32_16x16x32_bf16 v[122:125], v[58:61], v[192:195], v[122:125]
	s_waitcnt lgkmcnt(3)
	v_mfma_f32_16x16x32_bf16 v[110:113], v[46:49], v[200:203], v[110:113]
	v_mfma_f32_16x16x32_bf16 v[106:109], v[58:61], v[200:203], v[106:109]
	s_waitcnt lgkmcnt(1)
	v_mfma_f32_16x16x32_bf16 v[94:97], v[46:49], v[208:211], v[94:97]
	v_mfma_f32_16x16x32_bf16 v[90:93], v[58:61], v[208:211], v[90:93]
	v_mfma_f32_16x16x32_bf16 v[142:145], v[54:57], v[188:191], v[142:145]
	v_mfma_f32_16x16x32_bf16 v[138:141], v[62:65], v[188:191], v[138:141]
	v_mfma_f32_16x16x32_bf16 v[126:129], v[54:57], v[196:199], v[126:129]
	v_mfma_f32_16x16x32_bf16 v[122:125], v[62:65], v[196:199], v[122:125]
	v_mfma_f32_16x16x32_bf16 v[110:113], v[54:57], v[204:207], v[110:113]
	v_mfma_f32_16x16x32_bf16 v[106:109], v[62:65], v[204:207], v[106:109]
	s_waitcnt lgkmcnt(0)
	v_mfma_f32_16x16x32_bf16 v[94:97], v[54:57], v[212:215], v[94:97]
	v_mfma_f32_16x16x32_bf16 v[90:93], v[62:65], v[212:215], v[90:93]
	s_setprio 0
	s_setprio 1
	v_mfma_f32_16x16x32_bf16 v[134:137], v[146:149], v[170:173], v[134:137]
	v_mfma_f32_16x16x32_bf16 v[130:133], v[154:157], v[170:173], v[130:133]
	v_mfma_f32_16x16x32_bf16 v[118:121], v[146:149], v[192:195], v[118:121]
	v_mfma_f32_16x16x32_bf16 v[114:117], v[154:157], v[192:195], v[114:117]
	v_mfma_f32_16x16x32_bf16 v[102:105], v[146:149], v[200:203], v[102:105]
	v_mfma_f32_16x16x32_bf16 v[98:101], v[154:157], v[200:203], v[98:101]
	v_mfma_f32_16x16x32_bf16 v[86:89], v[146:149], v[208:211], v[86:89]
	v_mfma_f32_16x16x32_bf16 v[82:85], v[154:157], v[208:211], v[82:85]
	v_mfma_f32_16x16x32_bf16 v[134:137], v[150:153], v[188:191], v[134:137]
	v_mfma_f32_16x16x32_bf16 v[130:133], v[158:161], v[188:191], v[130:133]
	v_mfma_f32_16x16x32_bf16 v[118:121], v[150:153], v[196:199], v[118:121]
	v_mfma_f32_16x16x32_bf16 v[114:117], v[158:161], v[196:199], v[114:117]
	v_mfma_f32_16x16x32_bf16 v[102:105], v[150:153], v[204:207], v[102:105]
	v_mfma_f32_16x16x32_bf16 v[98:101], v[158:161], v[204:207], v[98:101]
	s_setprio 2
	s_barrier
	v_mfma_f32_16x16x32_bf16 v[86:89], v[150:153], v[212:215], v[86:89]
	v_mfma_f32_16x16x32_bf16 v[82:85], v[158:161], v[212:215], v[82:85]
	s_setprio 0
	ds_read_b128 v[170:173], v184 offset:16384
	ds_read_b128 v[188:191], v184 offset:17408
	ds_read_b128 v[192:195], v184 offset:18432
	ds_read_b128 v[196:199], v184 offset:19456
	ds_read_b128 v[200:203], v184 offset:20480
	ds_read_b128 v[204:207], v184 offset:21504
	ds_read_b128 v[208:211], v184 offset:22528
	ds_read_b128 v[212:215], v184 offset:23552
	s_mov_b32 s86, m0
	s_mov_b32 m0, s49
	s_nop 0
	global_load_lds_dwordx4 v177, s[34:35]
	s_mov_b32 m0, s86
	s_nop 0
	s_mov_b32 s86, m0
	s_mov_b32 m0, s56
	s_nop 0
	global_load_lds_dwordx4 v179, s[34:35]
	s_mov_b32 m0, s86
	s_add_u32 s86, s34, 0x80000
	s_addc_u32 s87, s35, 0
	s_mov_b32 s92, m0
	s_mov_b32 m0, s57
	s_nop 0
	global_load_lds_dwordx4 v177, s[86:87]
	s_mov_b32 m0, s92
	s_nop 0
	s_mov_b32 s92, m0
	s_mov_b32 m0, s58
	s_nop 0
	global_load_lds_dwordx4 v179, s[86:87]
	s_mov_b32 m0, s92
	s_waitcnt vmcnt(4)
	s_waitcnt lgkmcnt(0)
	s_barrier
	s_setprio 1
	s_waitcnt lgkmcnt(7)
	v_mfma_f32_16x16x32_bf16 v[78:81], v[46:49], v[170:173], v[78:81]
	v_mfma_f32_16x16x32_bf16 v[74:77], v[58:61], v[170:173], v[74:77]
	s_waitcnt lgkmcnt(5)
	v_mfma_f32_16x16x32_bf16 v[50:53], v[46:49], v[192:195], v[50:53]
	v_mfma_f32_16x16x32_bf16 v[42:45], v[58:61], v[192:195], v[42:45]
	s_waitcnt lgkmcnt(3)
	v_mfma_f32_16x16x32_bf16 v[30:33], v[46:49], v[200:203], v[30:33]
	v_mfma_f32_16x16x32_bf16 v[26:29], v[58:61], v[200:203], v[26:29]
	s_waitcnt lgkmcnt(1)
	v_mfma_f32_16x16x32_bf16 v[14:17], v[46:49], v[208:211], v[14:17]
	v_mfma_f32_16x16x32_bf16 v[10:13], v[58:61], v[208:211], v[10:13]
	v_mfma_f32_16x16x32_bf16 v[78:81], v[54:57], v[188:191], v[78:81]
	v_mfma_f32_16x16x32_bf16 v[74:77], v[62:65], v[188:191], v[74:77]
	v_mfma_f32_16x16x32_bf16 v[50:53], v[54:57], v[196:199], v[50:53]
	v_mfma_f32_16x16x32_bf16 v[42:45], v[62:65], v[196:199], v[42:45]
	v_mfma_f32_16x16x32_bf16 v[30:33], v[54:57], v[204:207], v[30:33]
	v_mfma_f32_16x16x32_bf16 v[26:29], v[62:65], v[204:207], v[26:29]
	s_waitcnt lgkmcnt(0)
	v_mfma_f32_16x16x32_bf16 v[14:17], v[54:57], v[212:215], v[14:17]
	v_mfma_f32_16x16x32_bf16 v[10:13], v[62:65], v[212:215], v[10:13]
	s_setprio 0
	s_setprio 1
	v_mfma_f32_16x16x32_bf16 v[38:41], v[146:149], v[192:195], v[38:41]
	v_mfma_f32_16x16x32_bf16 v[34:37], v[154:157], v[192:195], v[34:37]
	v_mfma_f32_16x16x32_bf16 v[22:25], v[146:149], v[200:203], v[22:25]
	v_mfma_f32_16x16x32_bf16 v[18:21], v[154:157], v[200:203], v[18:21]
	v_mfma_f32_16x16x32_bf16 v[6:9], v[146:149], v[208:211], v[6:9]
	v_mfma_f32_16x16x32_bf16 v[2:5], v[154:157], v[208:211], v[2:5]
	v_mfma_f32_16x16x32_bf16 v[46:49], v[146:149], v[170:173], v[70:73]
	v_mfma_f32_16x16x32_bf16 v[54:57], v[154:157], v[170:173], v[66:69]
	v_mfma_f32_16x16x32_bf16 v[38:41], v[150:153], v[196:199], v[38:41]
	v_mfma_f32_16x16x32_bf16 v[34:37], v[158:161], v[196:199], v[34:37]
	v_mfma_f32_16x16x32_bf16 v[22:25], v[150:153], v[204:207], v[22:25]
	v_mfma_f32_16x16x32_bf16 v[18:21], v[158:161], v[204:207], v[18:21]
	v_mfma_f32_16x16x32_bf16 v[6:9], v[150:153], v[212:215], v[6:9]
	v_mfma_f32_16x16x32_bf16 v[2:5], v[158:161], v[212:215], v[2:5]
	s_setprio 2
	s_barrier
	v_mfma_f32_16x16x32_bf16 v[46:49], v[150:153], v[188:191], v[46:49]
	v_mfma_f32_16x16x32_bf16 v[54:57], v[158:161], v[188:191], v[54:57]
	s_setprio 0
	ds_read_b128 v[58:61], v185
	ds_read_b128 v[62:65], v185 offset:1024
	ds_read_b128 v[66:69], v185 offset:2048
	ds_read_b128 v[70:73], v185 offset:3072
	ds_read_b128 v[146:149], v186
	ds_read_b128 v[150:153], v186 offset:1024
	ds_read_b128 v[154:157], v186 offset:2048
	ds_read_b128 v[158:161], v186 offset:3072
	ds_read_b128 v[170:173], v184 offset:32768
	ds_read_b128 v[188:191], v184 offset:33792
	ds_read_b128 v[192:195], v184 offset:34816
	ds_read_b128 v[196:199], v184 offset:35840
	ds_read_b128 v[200:203], v184 offset:36864
	ds_read_b128 v[204:207], v184 offset:37888
	ds_read_b128 v[208:211], v184 offset:38912
	ds_read_b128 v[212:215], v184 offset:39936
	s_mov_b32 s86, m0
	s_mov_b32 m0, s48
	s_nop 0
	global_load_lds_dwordx4 v176, s[36:37]
	s_mov_b32 m0, s86
	s_nop 0
	s_mov_b32 s86, m0
	s_mov_b32 m0, s59
	s_nop 0
	global_load_lds_dwordx4 v178, s[36:37]
	s_mov_b32 m0, s86
	s_add_u32 s36, s36, 0x80000
	s_addc_u32 s37, s37, 0
	s_mov_b32 s86, m0
	s_mov_b32 m0, s62
	s_nop 0
	global_load_lds_dwordx4 v176, s[36:37]
	s_mov_b32 m0, s86
	s_nop 0
	s_mov_b32 s86, m0
	s_mov_b32 m0, s63
	s_nop 0
	global_load_lds_dwordx4 v178, s[36:37]
	s_mov_b32 m0, s86
	s_waitcnt vmcnt(8)
	s_waitcnt lgkmcnt(0)
	s_barrier
	s_setprio 1
	s_waitcnt lgkmcnt(7)
	v_mfma_f32_16x16x32_bf16 v[142:145], v[58:61], v[170:173], v[142:145]
	v_mfma_f32_16x16x32_bf16 v[138:141], v[66:69], v[170:173], v[138:141]
	s_waitcnt lgkmcnt(5)
	v_mfma_f32_16x16x32_bf16 v[126:129], v[58:61], v[192:195], v[126:129]
	v_mfma_f32_16x16x32_bf16 v[122:125], v[66:69], v[192:195], v[122:125]
	s_waitcnt lgkmcnt(3)
	v_mfma_f32_16x16x32_bf16 v[110:113], v[58:61], v[200:203], v[110:113]
	v_mfma_f32_16x16x32_bf16 v[106:109], v[66:69], v[200:203], v[106:109]
	s_waitcnt lgkmcnt(1)
	v_mfma_f32_16x16x32_bf16 v[94:97], v[58:61], v[208:211], v[94:97]
	v_mfma_f32_16x16x32_bf16 v[90:93], v[66:69], v[208:211], v[90:93]
	v_mfma_f32_16x16x32_bf16 v[142:145], v[62:65], v[188:191], v[142:145]
	v_mfma_f32_16x16x32_bf16 v[138:141], v[70:73], v[188:191], v[138:141]
	v_mfma_f32_16x16x32_bf16 v[126:129], v[62:65], v[196:199], v[126:129]
	v_mfma_f32_16x16x32_bf16 v[122:125], v[70:73], v[196:199], v[122:125]
	v_mfma_f32_16x16x32_bf16 v[110:113], v[62:65], v[204:207], v[110:113]
	v_mfma_f32_16x16x32_bf16 v[106:109], v[70:73], v[204:207], v[106:109]
	s_waitcnt lgkmcnt(0)
	v_mfma_f32_16x16x32_bf16 v[94:97], v[62:65], v[212:215], v[94:97]
	v_mfma_f32_16x16x32_bf16 v[90:93], v[70:73], v[212:215], v[90:93]
	s_setprio 0
	s_setprio 1
	v_mfma_f32_16x16x32_bf16 v[134:137], v[146:149], v[170:173], v[134:137]
	v_mfma_f32_16x16x32_bf16 v[130:133], v[154:157], v[170:173], v[130:133]
	v_mfma_f32_16x16x32_bf16 v[118:121], v[146:149], v[192:195], v[118:121]
	v_mfma_f32_16x16x32_bf16 v[114:117], v[154:157], v[192:195], v[114:117]
	v_mfma_f32_16x16x32_bf16 v[102:105], v[146:149], v[200:203], v[102:105]
	v_mfma_f32_16x16x32_bf16 v[98:101], v[154:157], v[200:203], v[98:101]
	v_mfma_f32_16x16x32_bf16 v[86:89], v[146:149], v[208:211], v[86:89]
	v_mfma_f32_16x16x32_bf16 v[82:85], v[154:157], v[208:211], v[82:85]
	v_mfma_f32_16x16x32_bf16 v[134:137], v[150:153], v[188:191], v[134:137]
	v_mfma_f32_16x16x32_bf16 v[130:133], v[158:161], v[188:191], v[130:133]
	v_mfma_f32_16x16x32_bf16 v[118:121], v[150:153], v[196:199], v[118:121]
	v_mfma_f32_16x16x32_bf16 v[114:117], v[158:161], v[196:199], v[114:117]
	v_mfma_f32_16x16x32_bf16 v[102:105], v[150:153], v[204:207], v[102:105]
	v_mfma_f32_16x16x32_bf16 v[98:101], v[158:161], v[204:207], v[98:101]
	s_setprio 2
	s_barrier
	v_mfma_f32_16x16x32_bf16 v[86:89], v[150:153], v[212:215], v[86:89]
	v_mfma_f32_16x16x32_bf16 v[82:85], v[158:161], v[212:215], v[82:85]
	s_setprio 0
	ds_read_b128 v[170:173], v184 offset:49152
	ds_read_b128 v[188:191], v184 offset:50176
	ds_read_b128 v[192:195], v184 offset:51200
	ds_read_b128 v[196:199], v184 offset:52224
	ds_read_b128 v[200:203], v184 offset:53248
	ds_read_b128 v[204:207], v184 offset:54272
	ds_read_b128 v[208:211], v184 offset:55296
	ds_read_b128 v[212:215], v184 offset:56320
	s_add_u32 s36, s34, 0x80
	s_addc_u32 s37, s35, 0
	s_mov_b32 s86, m0
	s_mov_b32 m0, s64
	s_nop 0
	global_load_lds_dwordx4 v177, s[36:37]
	s_mov_b32 m0, s86
	s_add_u32 s34, s34, 0x80080
	s_mov_b32 s86, m0
	s_mov_b32 m0, s65
	s_nop 0
	global_load_lds_dwordx4 v179, s[36:37]
	s_mov_b32 m0, s86
	s_addc_u32 s35, s35, 0
	s_mov_b32 s36, m0
	s_mov_b32 m0, s66
	s_nop 0
	global_load_lds_dwordx4 v177, s[34:35]
	s_mov_b32 m0, s36
	s_nop 0
	s_mov_b32 s36, m0
	s_mov_b32 m0, s67
	s_nop 0
	global_load_lds_dwordx4 v179, s[34:35]
	s_mov_b32 m0, s36
	s_waitcnt vmcnt(4)
	s_waitcnt lgkmcnt(0)
	s_barrier
	s_setprio 1
	s_waitcnt lgkmcnt(7)
	v_mfma_f32_16x16x32_bf16 v[78:81], v[58:61], v[170:173], v[78:81]
	v_mfma_f32_16x16x32_bf16 v[74:77], v[66:69], v[170:173], v[74:77]
	s_waitcnt lgkmcnt(5)
	v_mfma_f32_16x16x32_bf16 v[50:53], v[58:61], v[192:195], v[50:53]
	v_mfma_f32_16x16x32_bf16 v[42:45], v[66:69], v[192:195], v[42:45]
	s_waitcnt lgkmcnt(3)
	v_mfma_f32_16x16x32_bf16 v[30:33], v[58:61], v[200:203], v[30:33]
	v_mfma_f32_16x16x32_bf16 v[26:29], v[66:69], v[200:203], v[26:29]
	s_waitcnt lgkmcnt(1)
	v_mfma_f32_16x16x32_bf16 v[14:17], v[58:61], v[208:211], v[14:17]
	v_mfma_f32_16x16x32_bf16 v[10:13], v[66:69], v[208:211], v[10:13]
	v_mfma_f32_16x16x32_bf16 v[78:81], v[62:65], v[188:191], v[78:81]
	v_mfma_f32_16x16x32_bf16 v[74:77], v[70:73], v[188:191], v[74:77]
	v_mfma_f32_16x16x32_bf16 v[50:53], v[62:65], v[196:199], v[50:53]
	v_mfma_f32_16x16x32_bf16 v[42:45], v[70:73], v[196:199], v[42:45]
	v_mfma_f32_16x16x32_bf16 v[30:33], v[62:65], v[204:207], v[30:33]
	v_mfma_f32_16x16x32_bf16 v[26:29], v[70:73], v[204:207], v[26:29]
	s_waitcnt lgkmcnt(0)
	v_mfma_f32_16x16x32_bf16 v[14:17], v[62:65], v[212:215], v[14:17]
	v_mfma_f32_16x16x32_bf16 v[10:13], v[70:73], v[212:215], v[10:13]
	s_setprio 0
	s_setprio 1
	v_mfma_f32_16x16x32_bf16 v[46:49], v[146:149], v[170:173], v[46:49]
	v_mfma_f32_16x16x32_bf16 v[70:73], v[150:153], v[188:191], v[46:49]
	v_mfma_f32_16x16x32_bf16 v[46:49], v[154:157], v[170:173], v[54:57]
	v_mfma_f32_16x16x32_bf16 v[38:41], v[146:149], v[192:195], v[38:41]
	v_mfma_f32_16x16x32_bf16 v[34:37], v[154:157], v[192:195], v[34:37]
	v_mfma_f32_16x16x32_bf16 v[22:25], v[146:149], v[200:203], v[22:25]
	v_mfma_f32_16x16x32_bf16 v[18:21], v[154:157], v[200:203], v[18:21]
	v_mfma_f32_16x16x32_bf16 v[6:9], v[146:149], v[208:211], v[6:9]
	v_mfma_f32_16x16x32_bf16 v[2:5], v[154:157], v[208:211], v[2:5]
	v_mfma_f32_16x16x32_bf16 v[66:69], v[158:161], v[188:191], v[46:49]
	v_mfma_f32_16x16x32_bf16 v[38:41], v[150:153], v[196:199], v[38:41]
	v_mfma_f32_16x16x32_bf16 v[34:37], v[158:161], v[196:199], v[34:37]
	v_mfma_f32_16x16x32_bf16 v[22:25], v[150:153], v[204:207], v[22:25]
	v_mfma_f32_16x16x32_bf16 v[18:21], v[158:161], v[204:207], v[18:21]
	s_setprio 2
	s_barrier
	v_mfma_f32_16x16x32_bf16 v[6:9], v[150:153], v[212:215], v[6:9]
	v_mfma_f32_16x16x32_bf16 v[2:5], v[158:161], v[212:215], v[2:5]
	s_setprio 0
	s_add_i32 s83, s83, 2
	s_add_u32 s79, s79, 0x100
	s_addc_u32 s80, s80, 0
	s_add_u32 s30, s30, 0x100
	s_addc_u32 s31, s31, 0
	s_add_u32 s81, s81, 0x100
	s_addc_u32 s82, s82, 0
	s_cmp_gt_u32 s83, 29
	s_cbranch_scc0 .LBB0_1538
	s_and_b64 vcc, exec, s[16:17]
	s_cbranch_vccz .LBB0_1541
	s_barrier

.LBB0_1589:
	s_andn2_b64 vcc, exec, s[4:5]
	s_mov_b64 s[4:5], -1
	v_cvt_pk_bf16_f32 v6, v6, v7
	v_cvt_pk_bf16_f32 v7, v8, v9
	v_cvt_pk_bf16_f32 v8, v2, v3
	v_cvt_pk_bf16_f32 v9, v4, v5
	global_store_dwordx4 v[10:11], v[6:9], off offset:256
	s_cbranch_vccnz .LBB0_1530
	s_andn2_b64 vcc, exec, s[10:11]
	s_cbranch_vccnz .LBB0_1529
	s_mov_b32 s99, 1
	s_branch .LBB0_1529

.LBB0_1784:
	s_ashr_i32 s11, s10, 31
	s_lshl_b64 s[12:13], s[10:11], 20
	s_add_u32 s12, s26, s12
	s_addc_u32 s13, s27, s13
	s_and_b64 s[14:15], s[2:3], exec
	s_cselect_b32 s11, s13, s21
	s_cselect_b32 s64, s12, s20
	s_ashr_i32 s9, s8, 31
	s_lshl_b64 s[14:15], s[8:9], 20
	s_add_u32 s14, s28, s14
	s_addc_u32 s15, s29, s15
	s_and_b64 s[22:23], s[2:3], exec
	s_cselect_b32 s9, s15, s19
	s_cselect_b32 s65, s14, s18
	s_add_u32 s66, s18, 0x100
	s_addc_u32 s67, s19, 0
	s_add_u32 s18, s20, 0x80080
	s_addc_u32 s19, s21, 0
	s_add_u32 s70, s20, 0x100
	v_mov_b32_e32 v2, 0
	s_addc_u32 s71, s21, 0
	s_mov_b32 s73, -2
	v_mov_b32_e32 v3, v2
	v_mov_b32_e32 v4, v2
	v_mov_b32_e32 v5, v2
	v_mov_b32_e32 v6, v2
	v_mov_b32_e32 v7, v2
	v_mov_b32_e32 v8, v2
	v_mov_b32_e32 v9, v2
	v_mov_b32_e32 v18, v2
	v_mov_b32_e32 v19, v2
	v_mov_b32_e32 v20, v2
	v_mov_b32_e32 v21, v2
	v_mov_b32_e32 v22, v2
	v_mov_b32_e32 v23, v2
	v_mov_b32_e32 v24, v2
	v_mov_b32_e32 v25, v2
	v_mov_b32_e32 v34, v2
	v_mov_b32_e32 v35, v2
	v_mov_b32_e32 v36, v2
	v_mov_b32_e32 v37, v2
	v_mov_b32_e32 v38, v2
	v_mov_b32_e32 v39, v2
	v_mov_b32_e32 v40, v2
	v_mov_b32_e32 v41, v2
	v_mov_b32_e32 v50, v2
	v_mov_b32_e32 v51, v2
	v_mov_b32_e32 v52, v2
	v_mov_b32_e32 v53, v2
	v_mov_b32_e32 v54, v2
	v_mov_b32_e32 v55, v2
	v_mov_b32_e32 v56, v2
	v_mov_b32_e32 v57, v2
	v_mov_b32_e32 v10, v2
	v_mov_b32_e32 v11, v2
	v_mov_b32_e32 v12, v2
	v_mov_b32_e32 v13, v2
	v_mov_b32_e32 v14, v2
	v_mov_b32_e32 v15, v2
	v_mov_b32_e32 v16, v2
	v_mov_b32_e32 v17, v2
	v_mov_b32_e32 v26, v2
	v_mov_b32_e32 v27, v2
	v_mov_b32_e32 v28, v2
	v_mov_b32_e32 v29, v2
	v_mov_b32_e32 v30, v2
	v_mov_b32_e32 v31, v2
	v_mov_b32_e32 v32, v2
	v_mov_b32_e32 v33, v2
	v_mov_b32_e32 v42, v2
	v_mov_b32_e32 v43, v2
	v_mov_b32_e32 v44, v2
	v_mov_b32_e32 v45, v2
	v_mov_b32_e32 v46, v2
	v_mov_b32_e32 v47, v2
	v_mov_b32_e32 v48, v2
	v_mov_b32_e32 v49, v2
	v_mov_b32_e32 v58, v2
	v_mov_b32_e32 v59, v2
	v_mov_b32_e32 v60, v2
	v_mov_b32_e32 v61, v2
	v_mov_b32_e32 v62, v2
	v_mov_b32_e32 v63, v2
	v_mov_b32_e32 v64, v2
	v_mov_b32_e32 v65, v2
	v_mov_b32_e32 v66, v2
	v_mov_b32_e32 v67, v2
	v_mov_b32_e32 v68, v2
	v_mov_b32_e32 v69, v2
	v_mov_b32_e32 v70, v2
	v_mov_b32_e32 v71, v2
	v_mov_b32_e32 v72, v2
	v_mov_b32_e32 v73, v2
	v_mov_b32_e32 v82, v2
	v_mov_b32_e32 v83, v2
	v_mov_b32_e32 v84, v2
	v_mov_b32_e32 v85, v2
	v_mov_b32_e32 v86, v2
	v_mov_b32_e32 v87, v2
	v_mov_b32_e32 v88, v2
	v_mov_b32_e32 v89, v2
	v_mov_b32_e32 v98, v2
	v_mov_b32_e32 v99, v2
	v_mov_b32_e32 v100, v2
	v_mov_b32_e32 v101, v2
	v_mov_b32_e32 v102, v2
	v_mov_b32_e32 v103, v2
	v_mov_b32_e32 v104, v2
	v_mov_b32_e32 v105, v2
	v_mov_b32_e32 v114, v2
	v_mov_b32_e32 v115, v2
	v_mov_b32_e32 v116, v2
	v_mov_b32_e32 v117, v2
	v_mov_b32_e32 v118, v2
	v_mov_b32_e32 v119, v2
	v_mov_b32_e32 v120, v2
	v_mov_b32_e32 v121, v2
	v_mov_b32_e32 v74, v2
	v_mov_b32_e32 v75, v2
	v_mov_b32_e32 v76, v2
	v_mov_b32_e32 v77, v2
	v_mov_b32_e32 v78, v2
	v_mov_b32_e32 v79, v2
	v_mov_b32_e32 v80, v2
	v_mov_b32_e32 v81, v2
	v_mov_b32_e32 v90, v2
	v_mov_b32_e32 v91, v2
	v_mov_b32_e32 v92, v2
	v_mov_b32_e32 v93, v2
	v_mov_b32_e32 v94, v2
	v_mov_b32_e32 v95, v2
	v_mov_b32_e32 v96, v2
	v_mov_b32_e32 v97, v2
	v_mov_b32_e32 v106, v2
	v_mov_b32_e32 v107, v2
	v_mov_b32_e32 v108, v2
	v_mov_b32_e32 v109, v2
	v_mov_b32_e32 v110, v2
	v_mov_b32_e32 v111, v2
	v_mov_b32_e32 v112, v2
	v_mov_b32_e32 v113, v2
	v_mov_b32_e32 v122, v2
	v_mov_b32_e32 v123, v2
	v_mov_b32_e32 v124, v2
	v_mov_b32_e32 v125, v2
	v_mov_b32_e32 v126, v2
	v_mov_b32_e32 v127, v2
	v_mov_b32_e32 v128, v2
	v_mov_b32_e32 v129, v2
	s_cmp_eq_u32 s99, 0
	s_cbranch_scc1 .Lro_skip_6
	s_barrier
	s_mov_b32 s99, 0
.Lro_skip_6:
.LBB0_1785:
	ds_read_b128 v[148:151], v143
	ds_read_b128 v[152:155], v143 offset:1024
	ds_read_b128 v[156:159], v143 offset:2048
	ds_read_b128 v[160:163], v143 offset:3072
	ds_read_b128 v[164:167], v144
	ds_read_b128 v[168:171], v144 offset:1024
	ds_read_b128 v[172:175], v144 offset:2048
	ds_read_b128 v[176:179], v144 offset:3072
	s_cmp_eq_u32 s73, 28
	s_cselect_b32 s21, s9, s67
	s_cselect_b32 s20, s65, s66
	s_cselect_b32 s23, s11, s71
	s_cselect_b32 s22, s64, s70
	ds_read_b128 v[180:183], v145
	ds_read_b128 v[184:187], v145 offset:1024
	ds_read_b128 v[188:191], v145 offset:2048
	ds_read_b128 v[192:195], v145 offset:3072
	ds_read_b128 v[196:199], v145 offset:4096
	ds_read_b128 v[200:203], v145 offset:5120
	ds_read_b128 v[204:207], v145 offset:6144
	ds_read_b128 v[208:211], v145 offset:7168
	s_add_u32 s74, s18, 0xfff80000
	s_addc_u32 s75, s19, -1
	s_mov_b32 s76, m0
	s_mov_b32 m0, s56
	s_nop 0
	global_load_lds_dwordx4 v138, s[74:75]
	s_mov_b32 m0, s76
	s_nop 0
	s_mov_b32 s76, m0
	s_mov_b32 m0, s59
	s_nop 0
	global_load_lds_dwordx4 v140, s[74:75]
	s_mov_b32 m0, s76
	s_mov_b32 s74, m0
	s_mov_b32 m0, s57
	s_nop 0
	global_load_lds_dwordx4 v138, s[18:19]
	s_mov_b32 m0, s74
	s_nop 0
	s_mov_b32 s74, m0
	s_mov_b32 m0, s62
	s_nop 0
	global_load_lds_dwordx4 v140, s[18:19]
	s_mov_b32 m0, s74
	s_waitcnt vmcnt(8)
	s_waitcnt lgkmcnt(0)
	s_barrier
	s_setprio 1
	s_waitcnt lgkmcnt(7)
	v_mfma_f32_16x16x32_bf16 v[126:129], v[148:151], v[180:183], v[126:129]
	v_mfma_f32_16x16x32_bf16 v[122:125], v[156:159], v[180:183], v[122:125]
	s_waitcnt lgkmcnt(5)
	v_mfma_f32_16x16x32_bf16 v[110:113], v[148:151], v[188:191], v[110:113]
	v_mfma_f32_16x16x32_bf16 v[106:109], v[156:159], v[188:191], v[106:109]
	s_waitcnt lgkmcnt(3)
	v_mfma_f32_16x16x32_bf16 v[94:97], v[148:151], v[196:199], v[94:97]
	v_mfma_f32_16x16x32_bf16 v[90:93], v[156:159], v[196:199], v[90:93]
	s_waitcnt lgkmcnt(1)
	v_mfma_f32_16x16x32_bf16 v[78:81], v[148:151], v[204:207], v[78:81]
	v_mfma_f32_16x16x32_bf16 v[74:77], v[156:159], v[204:207], v[74:77]
	v_mfma_f32_16x16x32_bf16 v[126:129], v[152:155], v[184:187], v[126:129]
	v_mfma_f32_16x16x32_bf16 v[122:125], v[160:163], v[184:187], v[122:125]
	v_mfma_f32_16x16x32_bf16 v[110:113], v[152:155], v[192:195], v[110:113]
	v_mfma_f32_16x16x32_bf16 v[106:109], v[160:163], v[192:195], v[106:109]
	v_mfma_f32_16x16x32_bf16 v[94:97], v[152:155], v[200:203], v[94:97]
	v_mfma_f32_16x16x32_bf16 v[90:93], v[160:163], v[200:203], v[90:93]
	s_waitcnt lgkmcnt(0)
	v_mfma_f32_16x16x32_bf16 v[78:81], v[152:155], v[208:211], v[78:81]
	v_mfma_f32_16x16x32_bf16 v[74:77], v[160:163], v[208:211], v[74:77]
	s_setprio 0
	s_setprio 1
	v_mfma_f32_16x16x32_bf16 v[118:121], v[164:167], v[180:183], v[118:121]
	v_mfma_f32_16x16x32_bf16 v[114:117], v[172:175], v[180:183], v[114:117]
	v_mfma_f32_16x16x32_bf16 v[102:105], v[164:167], v[188:191], v[102:105]
	v_mfma_f32_16x16x32_bf16 v[98:101], v[172:175], v[188:191], v[98:101]
	v_mfma_f32_16x16x32_bf16 v[86:89], v[164:167], v[196:199], v[86:89]
	v_mfma_f32_16x16x32_bf16 v[82:85], v[172:175], v[196:199], v[82:85]
	v_mfma_f32_16x16x32_bf16 v[70:73], v[164:167], v[204:207], v[70:73]
	v_mfma_f32_16x16x32_bf16 v[66:69], v[172:175], v[204:207], v[66:69]
	v_mfma_f32_16x16x32_bf16 v[118:121], v[168:171], v[184:187], v[118:121]
	v_mfma_f32_16x16x32_bf16 v[114:117], v[176:179], v[184:187], v[114:117]
	v_mfma_f32_16x16x32_bf16 v[102:105], v[168:171], v[192:195], v[102:105]
	v_mfma_f32_16x16x32_bf16 v[98:101], v[176:179], v[192:195], v[98:101]
	v_mfma_f32_16x16x32_bf16 v[86:89], v[168:171], v[200:203], v[86:89]
	v_mfma_f32_16x16x32_bf16 v[82:85], v[176:179], v[200:203], v[82:85]
	s_setprio 2
	s_barrier
	v_mfma_f32_16x16x32_bf16 v[70:73], v[168:171], v[208:211], v[70:73]
	v_mfma_f32_16x16x32_bf16 v[66:69], v[176:179], v[208:211], v[66:69]
	s_setprio 0
	ds_read_b128 v[180:183], v145 offset:16384
	ds_read_b128 v[184:187], v145 offset:17408
	ds_read_b128 v[188:191], v145 offset:18432
	ds_read_b128 v[192:195], v145 offset:19456
	ds_read_b128 v[196:199], v145 offset:20480
	ds_read_b128 v[200:203], v145 offset:21504
	ds_read_b128 v[204:207], v145 offset:22528
	ds_read_b128 v[208:211], v145 offset:23552
	s_mov_b32 s74, m0
	s_mov_b32 m0, s35
	s_nop 0
	global_load_lds_dwordx4 v139, s[20:21]
	s_mov_b32 m0, s74
	s_nop 0
	s_mov_b32 s74, m0
	s_mov_b32 m0, s36
	s_nop 0
	global_load_lds_dwordx4 v141, s[20:21]
	s_mov_b32 m0, s74
	s_add_u32 s74, s20, 0x80000
	s_addc_u32 s75, s21, 0
	s_mov_b32 s76, m0
	s_mov_b32 m0, s37
	s_nop 0
	global_load_lds_dwordx4 v139, s[74:75]
	s_mov_b32 m0, s76
	s_nop 0
	s_mov_b32 s76, m0
	s_mov_b32 m0, s40
	s_nop 0
	global_load_lds_dwordx4 v141, s[74:75]
	s_mov_b32 m0, s76
	s_waitcnt vmcnt(4)
	s_waitcnt lgkmcnt(0)
	s_barrier
	s_setprio 1
	s_waitcnt lgkmcnt(7)
	v_mfma_f32_16x16x32_bf16 v[62:65], v[148:151], v[180:183], v[62:65]
	v_mfma_f32_16x16x32_bf16 v[58:61], v[156:159], v[180:183], v[58:61]
	s_waitcnt lgkmcnt(5)
	v_mfma_f32_16x16x32_bf16 v[46:49], v[148:151], v[188:191], v[46:49]
	v_mfma_f32_16x16x32_bf16 v[42:45], v[156:159], v[188:191], v[42:45]
	s_waitcnt lgkmcnt(3)
	v_mfma_f32_16x16x32_bf16 v[30:33], v[148:151], v[196:199], v[30:33]
	v_mfma_f32_16x16x32_bf16 v[26:29], v[156:159], v[196:199], v[26:29]
	s_waitcnt lgkmcnt(1)
	v_mfma_f32_16x16x32_bf16 v[14:17], v[148:151], v[204:207], v[14:17]
	v_mfma_f32_16x16x32_bf16 v[10:13], v[156:159], v[204:207], v[10:13]
	v_mfma_f32_16x16x32_bf16 v[62:65], v[152:155], v[184:187], v[62:65]
	v_mfma_f32_16x16x32_bf16 v[58:61], v[160:163], v[184:187], v[58:61]
	v_mfma_f32_16x16x32_bf16 v[46:49], v[152:155], v[192:195], v[46:49]
	v_mfma_f32_16x16x32_bf16 v[42:45], v[160:163], v[192:195], v[42:45]
	v_mfma_f32_16x16x32_bf16 v[30:33], v[152:155], v[200:203], v[30:33]
	v_mfma_f32_16x16x32_bf16 v[26:29], v[160:163], v[200:203], v[26:29]
	s_waitcnt lgkmcnt(0)
	v_mfma_f32_16x16x32_bf16 v[14:17], v[152:155], v[208:211], v[14:17]
	v_mfma_f32_16x16x32_bf16 v[10:13], v[160:163], v[208:211], v[10:13]
	s_setprio 0
	s_setprio 1
	v_mfma_f32_16x16x32_bf16 v[54:57], v[164:167], v[180:183], v[54:57]
	v_mfma_f32_16x16x32_bf16 v[50:53], v[172:175], v[180:183], v[50:53]
	v_mfma_f32_16x16x32_bf16 v[38:41], v[164:167], v[188:191], v[38:41]
	v_mfma_f32_16x16x32_bf16 v[34:37], v[172:175], v[188:191], v[34:37]
	v_mfma_f32_16x16x32_bf16 v[22:25], v[164:167], v[196:199], v[22:25]
	v_mfma_f32_16x16x32_bf16 v[18:21], v[172:175], v[196:199], v[18:21]
	v_mfma_f32_16x16x32_bf16 v[6:9], v[164:167], v[204:207], v[6:9]
	v_mfma_f32_16x16x32_bf16 v[2:5], v[172:175], v[204:207], v[2:5]
	v_mfma_f32_16x16x32_bf16 v[54:57], v[168:171], v[184:187], v[54:57]
	v_mfma_f32_16x16x32_bf16 v[50:53], v[176:179], v[184:187], v[50:53]
	v_mfma_f32_16x16x32_bf16 v[38:41], v[168:171], v[192:195], v[38:41]
	v_mfma_f32_16x16x32_bf16 v[34:37], v[176:179], v[192:195], v[34:37]
	v_mfma_f32_16x16x32_bf16 v[22:25], v[168:171], v[200:203], v[22:25]
	v_mfma_f32_16x16x32_bf16 v[18:21], v[176:179], v[200:203], v[18:21]
	s_setprio 2
	s_barrier
	v_mfma_f32_16x16x32_bf16 v[6:9], v[168:171], v[208:211], v[6:9]
	v_mfma_f32_16x16x32_bf16 v[2:5], v[176:179], v[208:211], v[2:5]
	s_setprio 0
	ds_read_b128 v[148:151], v146
	ds_read_b128 v[152:155], v146 offset:1024
	ds_read_b128 v[156:159], v146 offset:2048
	ds_read_b128 v[160:163], v146 offset:3072
	ds_read_b128 v[164:167], v147
	ds_read_b128 v[168:171], v147 offset:1024
	ds_read_b128 v[172:175], v147 offset:2048
	ds_read_b128 v[176:179], v147 offset:3072
	ds_read_b128 v[180:183], v145 offset:32768
	ds_read_b128 v[184:187], v145 offset:33792
	ds_read_b128 v[188:191], v145 offset:34816
	ds_read_b128 v[192:195], v145 offset:35840
	ds_read_b128 v[196:199], v145 offset:36864
	ds_read_b128 v[200:203], v145 offset:37888
	ds_read_b128 v[204:207], v145 offset:38912
	ds_read_b128 v[208:211], v145 offset:39936
	s_mov_b32 s74, m0
	s_mov_b32 m0, s31
	s_nop 0
	global_load_lds_dwordx4 v138, s[22:23]
	s_mov_b32 m0, s74
	s_nop 0
	s_mov_b32 s74, m0
	s_mov_b32 m0, s41
	s_nop 0
	global_load_lds_dwordx4 v140, s[22:23]
	s_mov_b32 m0, s74
	s_add_u32 s22, s22, 0x80000
	s_addc_u32 s23, s23, 0
	s_mov_b32 s74, m0
	s_mov_b32 m0, s42
	s_nop 0
	global_load_lds_dwordx4 v138, s[22:23]
	s_mov_b32 m0, s74
	s_nop 0
	s_mov_b32 s74, m0
	s_mov_b32 m0, s43
	s_nop 0
	global_load_lds_dwordx4 v140, s[22:23]
	s_mov_b32 m0, s74
	s_waitcnt vmcnt(8)
	s_waitcnt lgkmcnt(0)
	s_barrier
	s_setprio 1
	s_waitcnt lgkmcnt(7)
	v_mfma_f32_16x16x32_bf16 v[126:129], v[148:151], v[180:183], v[126:129]
	v_mfma_f32_16x16x32_bf16 v[122:125], v[156:159], v[180:183], v[122:125]
	s_waitcnt lgkmcnt(5)
	v_mfma_f32_16x16x32_bf16 v[110:113], v[148:151], v[188:191], v[110:113]
	v_mfma_f32_16x16x32_bf16 v[106:109], v[156:159], v[188:191], v[106:109]
	s_waitcnt lgkmcnt(3)
	v_mfma_f32_16x16x32_bf16 v[94:97], v[148:151], v[196:199], v[94:97]
	v_mfma_f32_16x16x32_bf16 v[90:93], v[156:159], v[196:199], v[90:93]
	s_waitcnt lgkmcnt(1)
	v_mfma_f32_16x16x32_bf16 v[78:81], v[148:151], v[204:207], v[78:81]
	v_mfma_f32_16x16x32_bf16 v[74:77], v[156:159], v[204:207], v[74:77]
	v_mfma_f32_16x16x32_bf16 v[126:129], v[152:155], v[184:187], v[126:129]
	v_mfma_f32_16x16x32_bf16 v[122:125], v[160:163], v[184:187], v[122:125]
	v_mfma_f32_16x16x32_bf16 v[110:113], v[152:155], v[192:195], v[110:113]
	v_mfma_f32_16x16x32_bf16 v[106:109], v[160:163], v[192:195], v[106:109]
	v_mfma_f32_16x16x32_bf16 v[94:97], v[152:155], v[200:203], v[94:97]
	v_mfma_f32_16x16x32_bf16 v[90:93], v[160:163], v[200:203], v[90:93]
	s_waitcnt lgkmcnt(0)
	v_mfma_f32_16x16x32_bf16 v[78:81], v[152:155], v[208:211], v[78:81]
	v_mfma_f32_16x16x32_bf16 v[74:77], v[160:163], v[208:211], v[74:77]
	s_setprio 0
	s_setprio 1
	v_mfma_f32_16x16x32_bf16 v[118:121], v[164:167], v[180:183], v[118:121]
	v_mfma_f32_16x16x32_bf16 v[114:117], v[172:175], v[180:183], v[114:117]
	v_mfma_f32_16x16x32_bf16 v[102:105], v[164:167], v[188:191], v[102:105]
	v_mfma_f32_16x16x32_bf16 v[98:101], v[172:175], v[188:191], v[98:101]
	v_mfma_f32_16x16x32_bf16 v[86:89], v[164:167], v[196:199], v[86:89]
	v_mfma_f32_16x16x32_bf16 v[82:85], v[172:175], v[196:199], v[82:85]
	v_mfma_f32_16x16x32_bf16 v[70:73], v[164:167], v[204:207], v[70:73]
	v_mfma_f32_16x16x32_bf16 v[66:69], v[172:175], v[204:207], v[66:69]
	v_mfma_f32_16x16x32_bf16 v[118:121], v[168:171], v[184:187], v[118:121]
	v_mfma_f32_16x16x32_bf16 v[114:117], v[176:179], v[184:187], v[114:117]
	v_mfma_f32_16x16x32_bf16 v[102:105], v[168:171], v[192:195], v[102:105]
	v_mfma_f32_16x16x32_bf16 v[98:101], v[176:179], v[192:195], v[98:101]
	v_mfma_f32_16x16x32_bf16 v[86:89], v[168:171], v[200:203], v[86:89]
	v_mfma_f32_16x16x32_bf16 v[82:85], v[176:179], v[200:203], v[82:85]
	s_setprio 2
	s_barrier
	v_mfma_f32_16x16x32_bf16 v[70:73], v[168:171], v[208:211], v[70:73]
	v_mfma_f32_16x16x32_bf16 v[66:69], v[176:179], v[208:211], v[66:69]
	s_setprio 0
	ds_read_b128 v[180:183], v145 offset:49152
	ds_read_b128 v[184:187], v145 offset:50176
	ds_read_b128 v[188:191], v145 offset:51200
	ds_read_b128 v[192:195], v145 offset:52224
	ds_read_b128 v[196:199], v145 offset:53248
	ds_read_b128 v[200:203], v145 offset:54272
	ds_read_b128 v[204:207], v145 offset:55296
	ds_read_b128 v[208:211], v145 offset:56320
	s_add_u32 s22, s20, 0x80
	s_addc_u32 s23, s21, 0
	s_mov_b32 s74, m0
	s_mov_b32 m0, s46
	s_nop 0
	global_load_lds_dwordx4 v139, s[22:23]
	s_mov_b32 m0, s74
	s_add_u32 s20, s20, 0x80080
	s_mov_b32 s74, m0
	s_mov_b32 m0, s47
	s_nop 0
	global_load_lds_dwordx4 v141, s[22:23]
	s_mov_b32 m0, s74
	s_addc_u32 s21, s21, 0
	s_mov_b32 s22, m0
	s_mov_b32 m0, s48
	s_nop 0
	global_load_lds_dwordx4 v139, s[20:21]
	s_mov_b32 m0, s22
	s_nop 0
	s_mov_b32 s22, m0
	s_mov_b32 m0, s49
	s_nop 0
	global_load_lds_dwordx4 v141, s[20:21]
	s_mov_b32 m0, s22
	s_waitcnt vmcnt(4)
	s_waitcnt lgkmcnt(0)
	s_barrier
	s_setprio 1
	s_waitcnt lgkmcnt(7)
	v_mfma_f32_16x16x32_bf16 v[62:65], v[148:151], v[180:183], v[62:65]
	v_mfma_f32_16x16x32_bf16 v[58:61], v[156:159], v[180:183], v[58:61]
	s_waitcnt lgkmcnt(5)
	v_mfma_f32_16x16x32_bf16 v[46:49], v[148:151], v[188:191], v[46:49]
	v_mfma_f32_16x16x32_bf16 v[42:45], v[156:159], v[188:191], v[42:45]
	s_waitcnt lgkmcnt(3)
	v_mfma_f32_16x16x32_bf16 v[30:33], v[148:151], v[196:199], v[30:33]
	v_mfma_f32_16x16x32_bf16 v[26:29], v[156:159], v[196:199], v[26:29]
	s_waitcnt lgkmcnt(1)
	v_mfma_f32_16x16x32_bf16 v[14:17], v[148:151], v[204:207], v[14:17]
	v_mfma_f32_16x16x32_bf16 v[10:13], v[156:159], v[204:207], v[10:13]
	v_mfma_f32_16x16x32_bf16 v[62:65], v[152:155], v[184:187], v[62:65]
	v_mfma_f32_16x16x32_bf16 v[58:61], v[160:163], v[184:187], v[58:61]
	v_mfma_f32_16x16x32_bf16 v[46:49], v[152:155], v[192:195], v[46:49]
	v_mfma_f32_16x16x32_bf16 v[42:45], v[160:163], v[192:195], v[42:45]
	v_mfma_f32_16x16x32_bf16 v[30:33], v[152:155], v[200:203], v[30:33]
	v_mfma_f32_16x16x32_bf16 v[26:29], v[160:163], v[200:203], v[26:29]
	s_waitcnt lgkmcnt(0)
	v_mfma_f32_16x16x32_bf16 v[14:17], v[152:155], v[208:211], v[14:17]
	v_mfma_f32_16x16x32_bf16 v[10:13], v[160:163], v[208:211], v[10:13]
	s_setprio 0
	s_setprio 1
	v_mfma_f32_16x16x32_bf16 v[54:57], v[164:167], v[180:183], v[54:57]
	v_mfma_f32_16x16x32_bf16 v[50:53], v[172:175], v[180:183], v[50:53]
	v_mfma_f32_16x16x32_bf16 v[38:41], v[164:167], v[188:191], v[38:41]
	v_mfma_f32_16x16x32_bf16 v[34:37], v[172:175], v[188:191], v[34:37]
	v_mfma_f32_16x16x32_bf16 v[22:25], v[164:167], v[196:199], v[22:25]
	v_mfma_f32_16x16x32_bf16 v[18:21], v[172:175], v[196:199], v[18:21]
	v_mfma_f32_16x16x32_bf16 v[6:9], v[164:167], v[204:207], v[6:9]
	v_mfma_f32_16x16x32_bf16 v[2:5], v[172:175], v[204:207], v[2:5]
	v_mfma_f32_16x16x32_bf16 v[54:57], v[168:171], v[184:187], v[54:57]
	v_mfma_f32_16x16x32_bf16 v[50:53], v[176:179], v[184:187], v[50:53]
	v_mfma_f32_16x16x32_bf16 v[38:41], v[168:171], v[192:195], v[38:41]
	v_mfma_f32_16x16x32_bf16 v[34:37], v[176:179], v[192:195], v[34:37]
	v_mfma_f32_16x16x32_bf16 v[22:25], v[168:171], v[200:203], v[22:25]
	v_mfma_f32_16x16x32_bf16 v[18:21], v[176:179], v[200:203], v[18:21]
	s_setprio 2
	s_barrier
	v_mfma_f32_16x16x32_bf16 v[6:9], v[168:171], v[208:211], v[6:9]
	v_mfma_f32_16x16x32_bf16 v[2:5], v[176:179], v[208:211], v[2:5]
	s_setprio 0
	s_add_i32 s73, s73, 2
	s_add_u32 s66, s66, 0x100
	s_addc_u32 s67, s67, 0
	s_add_u32 s18, s18, 0x100
	s_addc_u32 s19, s19, 0
	s_add_u32 s70, s70, 0x100
	s_addc_u32 s71, s71, 0
	s_cmp_gt_u32 s73, 29
	s_cbranch_scc0 .LBB0_1785
	s_and_b64 vcc, exec, s[6:7]
	s_cbranch_vccz .LBB0_1788
	s_barrier

.LBB0_1951:
	s_ashr_i32 s13, s12, 31
	s_lshl_b64 s[14:15], s[12:13], 15
	s_add_u32 s14, s28, s14
	s_addc_u32 s15, s29, s15
	s_and_b64 s[16:17], s[2:3], exec
	s_cselect_b32 s13, s15, s23
	s_cselect_b32 s65, s14, s22
	s_ashr_i32 s11, s10, 31
	s_lshl_b64 s[16:17], s[10:11], 15
	s_add_u32 s16, s30, s16
	s_addc_u32 s17, s31, s17
	s_and_b64 s[24:25], s[2:3], exec
	s_cselect_b32 s11, s17, s21
	s_cselect_b32 s66, s16, s20
	s_add_u32 s67, s20, 0x80000
	s_addc_u32 s70, s21, 0
	s_add_u32 s20, s22, 0x204000
	s_addc_u32 s21, s23, 0
	s_add_u32 s71, s22, 0x400000
	v_mov_b32_e32 v2, 0
	s_addc_u32 s73, s23, 0
	s_mov_b32 s74, -2
	v_mov_b32_e32 v3, v2
	v_mov_b32_e32 v4, v2
	v_mov_b32_e32 v5, v2
	v_mov_b32_e32 v6, v2
	v_mov_b32_e32 v7, v2
	s_waitcnt vmcnt(25)
	v_mov_b32_e32 v8, v2
	s_waitcnt vmcnt(24)
	v_mov_b32_e32 v9, v2
	s_waitcnt vmcnt(4)
	v_mov_b32_e32 v18, v2
	v_mov_b32_e32 v19, v2
	v_mov_b32_e32 v20, v2
	v_mov_b32_e32 v21, v2
	s_waitcnt vmcnt(2)
	v_mov_b32_e32 v22, v2
	v_mov_b32_e32 v23, v2
	v_mov_b32_e32 v24, v2
	v_mov_b32_e32 v25, v2
	v_mov_b32_e32 v34, v2
	v_mov_b32_e32 v35, v2
	v_mov_b32_e32 v36, v2
	v_mov_b32_e32 v37, v2
	v_mov_b32_e32 v38, v2
	v_mov_b32_e32 v39, v2
	v_mov_b32_e32 v40, v2
	v_mov_b32_e32 v41, v2
	v_mov_b32_e32 v50, v2
	v_mov_b32_e32 v51, v2
	v_mov_b32_e32 v52, v2
	v_mov_b32_e32 v53, v2
	v_mov_b32_e32 v54, v2
	v_mov_b32_e32 v55, v2
	v_mov_b32_e32 v56, v2
	v_mov_b32_e32 v57, v2
	v_mov_b32_e32 v10, v2
	v_mov_b32_e32 v11, v2
	v_mov_b32_e32 v12, v2
	v_mov_b32_e32 v13, v2
	v_mov_b32_e32 v14, v2
	v_mov_b32_e32 v15, v2
	v_mov_b32_e32 v16, v2
	v_mov_b32_e32 v17, v2
	v_mov_b32_e32 v26, v2
	v_mov_b32_e32 v27, v2
	v_mov_b32_e32 v28, v2
	v_mov_b32_e32 v29, v2
	v_mov_b32_e32 v30, v2
	v_mov_b32_e32 v31, v2
	s_waitcnt vmcnt(1)
	v_mov_b32_e32 v32, v2
	s_waitcnt vmcnt(0)
	v_mov_b32_e32 v33, v2
	v_mov_b32_e32 v42, v2
	v_mov_b32_e32 v43, v2
	v_mov_b32_e32 v44, v2
	v_mov_b32_e32 v45, v2
	v_mov_b32_e32 v46, v2
	v_mov_b32_e32 v47, v2
	v_mov_b32_e32 v48, v2
	v_mov_b32_e32 v49, v2
	v_mov_b32_e32 v58, v2
	v_mov_b32_e32 v59, v2
	v_mov_b32_e32 v60, v2
	v_mov_b32_e32 v61, v2
	v_mov_b32_e32 v62, v2
	v_mov_b32_e32 v63, v2
	v_mov_b32_e32 v64, v2
	v_mov_b32_e32 v65, v2
	v_mov_b32_e32 v66, v2
	v_mov_b32_e32 v67, v2
	v_mov_b32_e32 v68, v2
	v_mov_b32_e32 v69, v2
	v_mov_b32_e32 v70, v2
	v_mov_b32_e32 v71, v2
	v_mov_b32_e32 v72, v2
	v_mov_b32_e32 v73, v2
	v_mov_b32_e32 v74, v2
	v_mov_b32_e32 v75, v2
	v_mov_b32_e32 v76, v2
	v_mov_b32_e32 v77, v2
	v_mov_b32_e32 v82, v2
	v_mov_b32_e32 v83, v2
	v_mov_b32_e32 v84, v2
	v_mov_b32_e32 v85, v2
	v_mov_b32_e32 v98, v2
	v_mov_b32_e32 v99, v2
	v_mov_b32_e32 v100, v2
	v_mov_b32_e32 v101, v2
	v_mov_b32_e32 v102, v2
	v_mov_b32_e32 v103, v2
	v_mov_b32_e32 v104, v2
	v_mov_b32_e32 v105, v2
	v_mov_b32_e32 v106, v2
	v_mov_b32_e32 v107, v2
	v_mov_b32_e32 v108, v2
	v_mov_b32_e32 v109, v2
	v_mov_b32_e32 v114, v2
	v_mov_b32_e32 v115, v2
	v_mov_b32_e32 v116, v2
	v_mov_b32_e32 v117, v2
	v_mov_b32_e32 v78, v2
	v_mov_b32_e32 v79, v2
	v_mov_b32_e32 v80, v2
	v_mov_b32_e32 v81, v2
	v_mov_b32_e32 v86, v2
	v_mov_b32_e32 v87, v2
	v_mov_b32_e32 v88, v2
	v_mov_b32_e32 v89, v2
	v_mov_b32_e32 v90, v2
	v_mov_b32_e32 v91, v2
	v_mov_b32_e32 v92, v2
	v_mov_b32_e32 v93, v2
	v_mov_b32_e32 v94, v2
	v_mov_b32_e32 v95, v2
	v_mov_b32_e32 v96, v2
	v_mov_b32_e32 v97, v2
	v_mov_b32_e32 v110, v2
	v_mov_b32_e32 v111, v2
	v_mov_b32_e32 v112, v2
	v_mov_b32_e32 v113, v2
	v_mov_b32_e32 v118, v2
	v_mov_b32_e32 v119, v2
	v_mov_b32_e32 v120, v2
	v_mov_b32_e32 v121, v2
	v_mov_b32_e32 v122, v2
	v_mov_b32_e32 v123, v2
	v_mov_b32_e32 v124, v2
	v_mov_b32_e32 v125, v2
	v_mov_b32_e32 v126, v2
	v_mov_b32_e32 v127, v2
	v_mov_b32_e32 v128, v2
	v_mov_b32_e32 v129, v2
	s_cmp_eq_u32 s99, 0
	s_cbranch_scc1 .Lro_skip_5
	s_barrier
	s_mov_b32 s99, 0
.Lro_skip_5:
.LBB0_1952:
	ds_read_b128 v[130:133], v181
	ds_read_b128 v[134:137], v181 offset:1024
	ds_read_b128 v[138:141], v181 offset:2048
	ds_read_b128 v[142:145], v181 offset:3072
	ds_read_b128 v[150:153], v182
	ds_read_b128 v[154:157], v182 offset:1024
	ds_read_b128 v[158:161], v182 offset:2048
	ds_read_b128 v[162:165], v182 offset:3072
	s_cmpk_eq_i32 s74, 0x52
	s_cselect_b32 s23, s11, s70
	s_cselect_b32 s22, s66, s67
	s_cselect_b32 s25, s13, s73
	s_cselect_b32 s24, s65, s71
	ds_read_b128 v[166:169], v183
	ds_read_b128 v[170:173], v183 offset:1024
	ds_read_b128 v[186:189], v183 offset:2048
	ds_read_b128 v[190:193], v183 offset:3072
	ds_read_b128 v[194:197], v183 offset:4096
	ds_read_b128 v[198:201], v183 offset:5120
	ds_read_b128 v[202:205], v183 offset:6144
	ds_read_b128 v[206:209], v183 offset:7168
	s_add_u32 s76, s20, 0xffffc000
	s_addc_u32 s77, s21, -1
	s_mov_b32 s75, m0
	s_mov_b32 m0, s58
	s_nop 0
	global_load_lds_dwordx4 v1, s[76:77]
	s_mov_b32 m0, s75
	s_nop 0
	s_mov_b32 s75, m0
	s_mov_b32 m0, s62
	s_nop 0
	global_load_lds_dwordx4 v177, s[76:77]
	s_mov_b32 m0, s75
	s_nop 0
	s_mov_b32 s75, m0
	s_mov_b32 m0, s59
	s_nop 0
	global_load_lds_dwordx4 v1, s[20:21]
	s_mov_b32 m0, s75
	s_nop 0
	s_mov_b32 s75, m0
	s_mov_b32 m0, s63
	s_nop 0
	global_load_lds_dwordx4 v177, s[20:21]
	s_mov_b32 m0, s75
	s_waitcnt vmcnt(8)
	s_waitcnt lgkmcnt(0)
	s_barrier
	s_setprio 1
	s_waitcnt lgkmcnt(7)
	v_mfma_f32_16x16x32_bf16 v[126:129], v[130:133], v[166:169], v[126:129]
	v_mfma_f32_16x16x32_bf16 v[122:125], v[138:141], v[166:169], v[122:125]
	s_waitcnt lgkmcnt(5)
	v_mfma_f32_16x16x32_bf16 v[118:121], v[130:133], v[186:189], v[118:121]
	v_mfma_f32_16x16x32_bf16 v[110:113], v[138:141], v[186:189], v[110:113]
	s_waitcnt lgkmcnt(3)
	v_mfma_f32_16x16x32_bf16 v[94:97], v[130:133], v[194:197], v[94:97]
	v_mfma_f32_16x16x32_bf16 v[90:93], v[138:141], v[194:197], v[90:93]
	s_waitcnt lgkmcnt(1)
	v_mfma_f32_16x16x32_bf16 v[86:89], v[130:133], v[202:205], v[86:89]
	v_mfma_f32_16x16x32_bf16 v[78:81], v[138:141], v[202:205], v[78:81]
	v_mfma_f32_16x16x32_bf16 v[126:129], v[134:137], v[170:173], v[126:129]
	v_mfma_f32_16x16x32_bf16 v[122:125], v[142:145], v[170:173], v[122:125]
	v_mfma_f32_16x16x32_bf16 v[118:121], v[134:137], v[190:193], v[118:121]
	v_mfma_f32_16x16x32_bf16 v[110:113], v[142:145], v[190:193], v[110:113]
	v_mfma_f32_16x16x32_bf16 v[94:97], v[134:137], v[198:201], v[94:97]
	v_mfma_f32_16x16x32_bf16 v[90:93], v[142:145], v[198:201], v[90:93]
	s_waitcnt lgkmcnt(0)
	v_mfma_f32_16x16x32_bf16 v[86:89], v[134:137], v[206:209], v[86:89]
	v_mfma_f32_16x16x32_bf16 v[78:81], v[142:145], v[206:209], v[78:81]
	s_setprio 0
	s_setprio 1
	v_mfma_f32_16x16x32_bf16 v[114:117], v[150:153], v[166:169], v[114:117]
	v_mfma_f32_16x16x32_bf16 v[106:109], v[158:161], v[166:169], v[106:109]
	v_mfma_f32_16x16x32_bf16 v[102:105], v[150:153], v[186:189], v[102:105]
	v_mfma_f32_16x16x32_bf16 v[98:101], v[158:161], v[186:189], v[98:101]
	v_mfma_f32_16x16x32_bf16 v[82:85], v[150:153], v[194:197], v[82:85]
	v_mfma_f32_16x16x32_bf16 v[74:77], v[158:161], v[194:197], v[74:77]
	v_mfma_f32_16x16x32_bf16 v[70:73], v[150:153], v[202:205], v[70:73]
	v_mfma_f32_16x16x32_bf16 v[66:69], v[158:161], v[202:205], v[66:69]
	v_mfma_f32_16x16x32_bf16 v[114:117], v[154:157], v[170:173], v[114:117]
	v_mfma_f32_16x16x32_bf16 v[106:109], v[162:165], v[170:173], v[106:109]
	v_mfma_f32_16x16x32_bf16 v[102:105], v[154:157], v[190:193], v[102:105]
	v_mfma_f32_16x16x32_bf16 v[98:101], v[162:165], v[190:193], v[98:101]
	v_mfma_f32_16x16x32_bf16 v[82:85], v[154:157], v[198:201], v[82:85]
	v_mfma_f32_16x16x32_bf16 v[74:77], v[162:165], v[198:201], v[74:77]
	s_setprio 2
	s_barrier
	v_mfma_f32_16x16x32_bf16 v[70:73], v[154:157], v[206:209], v[70:73]
	v_mfma_f32_16x16x32_bf16 v[66:69], v[162:165], v[206:209], v[66:69]
	s_setprio 0
	ds_read_b128 v[166:169], v183 offset:16384
	ds_read_b128 v[170:173], v183 offset:17408
	ds_read_b128 v[186:189], v183 offset:18432
	ds_read_b128 v[190:193], v183 offset:19456
	ds_read_b128 v[194:197], v183 offset:20480
	ds_read_b128 v[198:201], v183 offset:21504
	ds_read_b128 v[202:205], v183 offset:22528
	ds_read_b128 v[206:209], v183 offset:23552
	s_mov_b32 s75, m0
	s_mov_b32 m0, s35
	s_nop 0
	global_load_lds_dwordx4 v176, s[22:23]
	s_mov_b32 m0, s75
	s_add_u32 s76, s22, 0x4000
	s_mov_b32 s75, m0
	s_mov_b32 m0, s36
	s_nop 0
	global_load_lds_dwordx4 v178, s[22:23]
	s_mov_b32 m0, s75
	s_addc_u32 s77, s23, 0
	s_mov_b32 s75, m0
	s_mov_b32 m0, s37
	s_nop 0
	global_load_lds_dwordx4 v176, s[76:77]
	s_mov_b32 m0, s75
	s_nop 0
	s_mov_b32 s75, m0
	s_mov_b32 m0, s40
	s_nop 0
	global_load_lds_dwordx4 v178, s[76:77]
	s_mov_b32 m0, s75
	s_waitcnt vmcnt(4)
	s_waitcnt lgkmcnt(0)
	s_barrier
	s_setprio 1
	s_waitcnt lgkmcnt(7)
	v_mfma_f32_16x16x32_bf16 v[62:65], v[130:133], v[166:169], v[62:65]
	v_mfma_f32_16x16x32_bf16 v[58:61], v[138:141], v[166:169], v[58:61]
	s_waitcnt lgkmcnt(5)
	v_mfma_f32_16x16x32_bf16 v[46:49], v[130:133], v[186:189], v[46:49]
	v_mfma_f32_16x16x32_bf16 v[42:45], v[138:141], v[186:189], v[42:45]
	s_waitcnt lgkmcnt(3)
	v_mfma_f32_16x16x32_bf16 v[30:33], v[130:133], v[194:197], v[30:33]
	v_mfma_f32_16x16x32_bf16 v[26:29], v[138:141], v[194:197], v[26:29]
	s_waitcnt lgkmcnt(1)
	v_mfma_f32_16x16x32_bf16 v[14:17], v[130:133], v[202:205], v[14:17]
	v_mfma_f32_16x16x32_bf16 v[10:13], v[138:141], v[202:205], v[10:13]
	v_mfma_f32_16x16x32_bf16 v[62:65], v[134:137], v[170:173], v[62:65]
	v_mfma_f32_16x16x32_bf16 v[58:61], v[142:145], v[170:173], v[58:61]
	v_mfma_f32_16x16x32_bf16 v[46:49], v[134:137], v[190:193], v[46:49]
	v_mfma_f32_16x16x32_bf16 v[42:45], v[142:145], v[190:193], v[42:45]
	v_mfma_f32_16x16x32_bf16 v[30:33], v[134:137], v[198:201], v[30:33]
	v_mfma_f32_16x16x32_bf16 v[26:29], v[142:145], v[198:201], v[26:29]
	s_waitcnt lgkmcnt(0)
	v_mfma_f32_16x16x32_bf16 v[14:17], v[134:137], v[206:209], v[14:17]
	v_mfma_f32_16x16x32_bf16 v[10:13], v[142:145], v[206:209], v[10:13]
	s_setprio 0
	s_setprio 1
	v_mfma_f32_16x16x32_bf16 v[54:57], v[150:153], v[166:169], v[54:57]
	v_mfma_f32_16x16x32_bf16 v[50:53], v[158:161], v[166:169], v[50:53]
	v_mfma_f32_16x16x32_bf16 v[38:41], v[150:153], v[186:189], v[38:41]
	v_mfma_f32_16x16x32_bf16 v[34:37], v[158:161], v[186:189], v[34:37]
	v_mfma_f32_16x16x32_bf16 v[22:25], v[150:153], v[194:197], v[22:25]
	v_mfma_f32_16x16x32_bf16 v[18:21], v[158:161], v[194:197], v[18:21]
	v_mfma_f32_16x16x32_bf16 v[6:9], v[150:153], v[202:205], v[6:9]
	v_mfma_f32_16x16x32_bf16 v[2:5], v[158:161], v[202:205], v[2:5]
	v_mfma_f32_16x16x32_bf16 v[54:57], v[154:157], v[170:173], v[54:57]
	v_mfma_f32_16x16x32_bf16 v[50:53], v[162:165], v[170:173], v[50:53]
	v_mfma_f32_16x16x32_bf16 v[38:41], v[154:157], v[190:193], v[38:41]
	v_mfma_f32_16x16x32_bf16 v[34:37], v[162:165], v[190:193], v[34:37]
	v_mfma_f32_16x16x32_bf16 v[22:25], v[154:157], v[198:201], v[22:25]
	v_mfma_f32_16x16x32_bf16 v[18:21], v[162:165], v[198:201], v[18:21]
	s_setprio 2
	s_barrier
	v_mfma_f32_16x16x32_bf16 v[6:9], v[154:157], v[206:209], v[6:9]
	v_mfma_f32_16x16x32_bf16 v[2:5], v[162:165], v[206:209], v[2:5]
	s_setprio 0
	ds_read_b128 v[130:133], v184
	ds_read_b128 v[134:137], v184 offset:1024
	ds_read_b128 v[138:141], v184 offset:2048
	ds_read_b128 v[142:145], v184 offset:3072
	ds_read_b128 v[150:153], v185
	ds_read_b128 v[154:157], v185 offset:1024
	ds_read_b128 v[158:161], v185 offset:2048
	ds_read_b128 v[162:165], v185 offset:3072
	ds_read_b128 v[166:169], v183 offset:32768
	ds_read_b128 v[170:173], v183 offset:33792
	ds_read_b128 v[186:189], v183 offset:34816
	ds_read_b128 v[190:193], v183 offset:35840
	ds_read_b128 v[194:197], v183 offset:36864
	ds_read_b128 v[198:201], v183 offset:37888
	ds_read_b128 v[202:205], v183 offset:38912
	ds_read_b128 v[206:209], v183 offset:39936
	s_mov_b32 s75, m0
	s_mov_b32 m0, s34
	s_nop 0
	global_load_lds_dwordx4 v1, s[24:25]
	s_mov_b32 m0, s75
	s_nop 0
	s_mov_b32 s75, m0
	s_mov_b32 m0, s41
	s_nop 0
	global_load_lds_dwordx4 v177, s[24:25]
	s_mov_b32 m0, s75
	s_add_u32 s24, s24, 0x4000
	s_addc_u32 s25, s25, 0
	s_mov_b32 s75, m0
	s_mov_b32 m0, s42
	s_nop 0
	global_load_lds_dwordx4 v1, s[24:25]
	s_mov_b32 m0, s75
	s_nop 0
	s_mov_b32 s75, m0
	s_mov_b32 m0, s43
	s_nop 0
	global_load_lds_dwordx4 v177, s[24:25]
	s_mov_b32 m0, s75
	s_waitcnt vmcnt(8)
	s_waitcnt lgkmcnt(0)
	s_barrier
	s_setprio 1
	s_waitcnt lgkmcnt(7)
	v_mfma_f32_16x16x32_bf16 v[126:129], v[130:133], v[166:169], v[126:129]
	v_mfma_f32_16x16x32_bf16 v[122:125], v[138:141], v[166:169], v[122:125]
	s_waitcnt lgkmcnt(5)
	v_mfma_f32_16x16x32_bf16 v[118:121], v[130:133], v[186:189], v[118:121]
	v_mfma_f32_16x16x32_bf16 v[110:113], v[138:141], v[186:189], v[110:113]
	s_waitcnt lgkmcnt(3)
	v_mfma_f32_16x16x32_bf16 v[94:97], v[130:133], v[194:197], v[94:97]
	v_mfma_f32_16x16x32_bf16 v[90:93], v[138:141], v[194:197], v[90:93]
	s_waitcnt lgkmcnt(1)
	v_mfma_f32_16x16x32_bf16 v[86:89], v[130:133], v[202:205], v[86:89]
	v_mfma_f32_16x16x32_bf16 v[78:81], v[138:141], v[202:205], v[78:81]
	v_mfma_f32_16x16x32_bf16 v[126:129], v[134:137], v[170:173], v[126:129]
	v_mfma_f32_16x16x32_bf16 v[122:125], v[142:145], v[170:173], v[122:125]
	v_mfma_f32_16x16x32_bf16 v[118:121], v[134:137], v[190:193], v[118:121]
	v_mfma_f32_16x16x32_bf16 v[110:113], v[142:145], v[190:193], v[110:113]
	v_mfma_f32_16x16x32_bf16 v[94:97], v[134:137], v[198:201], v[94:97]
	v_mfma_f32_16x16x32_bf16 v[90:93], v[142:145], v[198:201], v[90:93]
	s_waitcnt lgkmcnt(0)
	v_mfma_f32_16x16x32_bf16 v[86:89], v[134:137], v[206:209], v[86:89]
	v_mfma_f32_16x16x32_bf16 v[78:81], v[142:145], v[206:209], v[78:81]
	s_setprio 0
	s_setprio 1
	v_mfma_f32_16x16x32_bf16 v[114:117], v[150:153], v[166:169], v[114:117]
	v_mfma_f32_16x16x32_bf16 v[106:109], v[158:161], v[166:169], v[106:109]
	v_mfma_f32_16x16x32_bf16 v[102:105], v[150:153], v[186:189], v[102:105]
	v_mfma_f32_16x16x32_bf16 v[98:101], v[158:161], v[186:189], v[98:101]
	v_mfma_f32_16x16x32_bf16 v[82:85], v[150:153], v[194:197], v[82:85]
	v_mfma_f32_16x16x32_bf16 v[74:77], v[158:161], v[194:197], v[74:77]
	v_mfma_f32_16x16x32_bf16 v[70:73], v[150:153], v[202:205], v[70:73]
	v_mfma_f32_16x16x32_bf16 v[66:69], v[158:161], v[202:205], v[66:69]
	v_mfma_f32_16x16x32_bf16 v[114:117], v[154:157], v[170:173], v[114:117]
	v_mfma_f32_16x16x32_bf16 v[106:109], v[162:165], v[170:173], v[106:109]
	v_mfma_f32_16x16x32_bf16 v[102:105], v[154:157], v[190:193], v[102:105]
	v_mfma_f32_16x16x32_bf16 v[98:101], v[162:165], v[190:193], v[98:101]
	v_mfma_f32_16x16x32_bf16 v[82:85], v[154:157], v[198:201], v[82:85]
	v_mfma_f32_16x16x32_bf16 v[74:77], v[162:165], v[198:201], v[74:77]
	s_setprio 2
	s_barrier
	v_mfma_f32_16x16x32_bf16 v[70:73], v[154:157], v[206:209], v[70:73]
	v_mfma_f32_16x16x32_bf16 v[66:69], v[162:165], v[206:209], v[66:69]
	s_setprio 0
	ds_read_b128 v[166:169], v183 offset:49152
	ds_read_b128 v[170:173], v183 offset:50176
	ds_read_b128 v[186:189], v183 offset:51200
	ds_read_b128 v[190:193], v183 offset:52224
	ds_read_b128 v[194:197], v183 offset:53248
	ds_read_b128 v[198:201], v183 offset:54272
	ds_read_b128 v[202:205], v183 offset:55296
	ds_read_b128 v[206:209], v183 offset:56320
	s_add_u32 s24, s22, 0x40000
	s_addc_u32 s25, s23, 0
	s_mov_b32 s75, m0
	s_mov_b32 m0, s46
	s_nop 0
	global_load_lds_dwordx4 v176, s[24:25]
	s_mov_b32 m0, s75
	s_add_u32 s22, s22, 0x44000
	s_mov_b32 s75, m0
	s_mov_b32 m0, s47
	s_nop 0
	global_load_lds_dwordx4 v178, s[24:25]
	s_mov_b32 m0, s75
	s_addc_u32 s23, s23, 0
	s_mov_b32 s24, m0
	s_mov_b32 m0, s48
	s_nop 0
	global_load_lds_dwordx4 v176, s[22:23]
	s_mov_b32 m0, s24
	s_nop 0
	s_mov_b32 s24, m0
	s_mov_b32 m0, s49
	s_nop 0
	global_load_lds_dwordx4 v178, s[22:23]
	s_mov_b32 m0, s24
	s_waitcnt vmcnt(4)
	s_waitcnt lgkmcnt(0)
	s_barrier
	s_setprio 1
	s_waitcnt lgkmcnt(7)
	v_mfma_f32_16x16x32_bf16 v[62:65], v[130:133], v[166:169], v[62:65]
	v_mfma_f32_16x16x32_bf16 v[58:61], v[138:141], v[166:169], v[58:61]
	s_waitcnt lgkmcnt(5)
	v_mfma_f32_16x16x32_bf16 v[46:49], v[130:133], v[186:189], v[46:49]
	v_mfma_f32_16x16x32_bf16 v[42:45], v[138:141], v[186:189], v[42:45]
	s_waitcnt lgkmcnt(3)
	v_mfma_f32_16x16x32_bf16 v[30:33], v[130:133], v[194:197], v[30:33]
	v_mfma_f32_16x16x32_bf16 v[26:29], v[138:141], v[194:197], v[26:29]
	s_waitcnt lgkmcnt(1)
	v_mfma_f32_16x16x32_bf16 v[14:17], v[130:133], v[202:205], v[14:17]
	v_mfma_f32_16x16x32_bf16 v[10:13], v[138:141], v[202:205], v[10:13]
	v_mfma_f32_16x16x32_bf16 v[62:65], v[134:137], v[170:173], v[62:65]
	v_mfma_f32_16x16x32_bf16 v[58:61], v[142:145], v[170:173], v[58:61]
	v_mfma_f32_16x16x32_bf16 v[46:49], v[134:137], v[190:193], v[46:49]
	v_mfma_f32_16x16x32_bf16 v[42:45], v[142:145], v[190:193], v[42:45]
	v_mfma_f32_16x16x32_bf16 v[30:33], v[134:137], v[198:201], v[30:33]
	v_mfma_f32_16x16x32_bf16 v[26:29], v[142:145], v[198:201], v[26:29]
	s_waitcnt lgkmcnt(0)
	v_mfma_f32_16x16x32_bf16 v[14:17], v[134:137], v[206:209], v[14:17]
	v_mfma_f32_16x16x32_bf16 v[10:13], v[142:145], v[206:209], v[10:13]
	s_setprio 0
	s_setprio 1
	v_mfma_f32_16x16x32_bf16 v[54:57], v[150:153], v[166:169], v[54:57]
	v_mfma_f32_16x16x32_bf16 v[50:53], v[158:161], v[166:169], v[50:53]
	v_mfma_f32_16x16x32_bf16 v[38:41], v[150:153], v[186:189], v[38:41]
	v_mfma_f32_16x16x32_bf16 v[34:37], v[158:161], v[186:189], v[34:37]
	v_mfma_f32_16x16x32_bf16 v[22:25], v[150:153], v[194:197], v[22:25]
	v_mfma_f32_16x16x32_bf16 v[18:21], v[158:161], v[194:197], v[18:21]
	v_mfma_f32_16x16x32_bf16 v[6:9], v[150:153], v[202:205], v[6:9]
	v_mfma_f32_16x16x32_bf16 v[2:5], v[158:161], v[202:205], v[2:5]
	v_mfma_f32_16x16x32_bf16 v[54:57], v[154:157], v[170:173], v[54:57]
	v_mfma_f32_16x16x32_bf16 v[50:53], v[162:165], v[170:173], v[50:53]
	v_mfma_f32_16x16x32_bf16 v[38:41], v[154:157], v[190:193], v[38:41]
	v_mfma_f32_16x16x32_bf16 v[34:37], v[162:165], v[190:193], v[34:37]
	v_mfma_f32_16x16x32_bf16 v[22:25], v[154:157], v[198:201], v[22:25]
	v_mfma_f32_16x16x32_bf16 v[18:21], v[162:165], v[198:201], v[18:21]
	s_setprio 2
	s_barrier
	v_mfma_f32_16x16x32_bf16 v[6:9], v[154:157], v[206:209], v[6:9]
	v_mfma_f32_16x16x32_bf16 v[2:5], v[162:165], v[206:209], v[2:5]
	s_setprio 0
	s_add_i32 s74, s74, 2
	s_add_u32 s67, s67, 0x80000
	s_addc_u32 s70, s70, 0
	s_add_u32 s20, s20, 0x400000
	s_addc_u32 s21, s21, 0
	s_add_u32 s71, s71, 0x400000
	s_addc_u32 s73, s73, 0
	s_cmpk_gt_u32 s74, 0x53
	s_cbranch_scc0 .LBB0_1952
	s_and_b64 vcc, exec, s[8:9]
	s_cbranch_vccz .LBB0_1955
	s_barrier

.LBB0_2145:
	s_ashr_i32 s25, s24, 31
	s_lshl_b64 s[26:27], s[24:25], 20
	s_add_u32 s26, s33, s26
	s_addc_u32 s27, s42, s27
	s_and_b64 s[28:29], s[2:3], exec
	s_cselect_b32 s5, s27, s37
	s_cselect_b32 s25, s26, s36
	s_ashr_i32 s23, s22, 31
	s_lshl_b64 s[28:29], s[22:23], 20
	s_add_u32 s28, s43, s28
	s_addc_u32 s29, s46, s29
	s_and_b64 s[40:41], s[2:3], exec
	s_cselect_b32 s23, s29, s35
	s_cselect_b32 s31, s28, s34
	s_add_u32 s77, s34, 0x100
	s_addc_u32 s78, s35, 0
	s_add_u32 s34, s36, 0x80080
	s_addc_u32 s35, s37, 0
	s_add_u32 s79, s36, 0x100
	v_mov_b32_e32 v2, 0
	s_addc_u32 s80, s37, 0
	s_mov_b32 s81, -2
	v_mov_b32_e32 v3, v2
	v_mov_b32_e32 v4, v2
	v_mov_b32_e32 v5, v2
	v_mov_b32_e32 v6, v2
	v_mov_b32_e32 v7, v2
	s_waitcnt vmcnt(25)
	v_mov_b32_e32 v8, v2
	s_waitcnt vmcnt(24)
	v_mov_b32_e32 v9, v2
	s_waitcnt vmcnt(4)
	v_mov_b32_e32 v18, v2
	v_mov_b32_e32 v19, v2
	v_mov_b32_e32 v20, v2
	v_mov_b32_e32 v21, v2
	s_waitcnt vmcnt(2)
	v_mov_b32_e32 v22, v2
	v_mov_b32_e32 v23, v2
	v_mov_b32_e32 v24, v2
	v_mov_b32_e32 v25, v2
	v_mov_b32_e32 v34, v2
	v_mov_b32_e32 v35, v2
	v_mov_b32_e32 v36, v2
	v_mov_b32_e32 v37, v2
	v_mov_b32_e32 v38, v2
	v_mov_b32_e32 v39, v2
	v_mov_b32_e32 v40, v2
	v_mov_b32_e32 v41, v2
	v_mov_b32_e32 v66, v2
	v_mov_b32_e32 v67, v2
	v_mov_b32_e32 v68, v2
	v_mov_b32_e32 v69, v2
	v_mov_b32_e32 v70, v2
	v_mov_b32_e32 v71, v2
	v_mov_b32_e32 v72, v2
	v_mov_b32_e32 v73, v2
	v_mov_b32_e32 v10, v2
	v_mov_b32_e32 v11, v2
	v_mov_b32_e32 v12, v2
	v_mov_b32_e32 v13, v2
	v_mov_b32_e32 v14, v2
	v_mov_b32_e32 v15, v2
	v_mov_b32_e32 v16, v2
	v_mov_b32_e32 v17, v2
	v_mov_b32_e32 v26, v2
	v_mov_b32_e32 v27, v2
	v_mov_b32_e32 v28, v2
	v_mov_b32_e32 v29, v2
	v_mov_b32_e32 v30, v2
	v_mov_b32_e32 v31, v2
	s_waitcnt vmcnt(1)
	v_mov_b32_e32 v32, v2
	s_waitcnt vmcnt(0)
	v_mov_b32_e32 v33, v2
	v_mov_b32_e32 v50, v2
	v_mov_b32_e32 v51, v2
	v_mov_b32_e32 v52, v2
	v_mov_b32_e32 v53, v2
	v_mov_b32_e32 v54, v2
	v_mov_b32_e32 v55, v2
	v_mov_b32_e32 v56, v2
	v_mov_b32_e32 v57, v2
	v_mov_b32_e32 v74, v2
	v_mov_b32_e32 v75, v2
	v_mov_b32_e32 v76, v2
	v_mov_b32_e32 v77, v2
	v_mov_b32_e32 v78, v2
	v_mov_b32_e32 v79, v2
	v_mov_b32_e32 v80, v2
	v_mov_b32_e32 v81, v2
	v_mov_b32_e32 v82, v2
	v_mov_b32_e32 v83, v2
	v_mov_b32_e32 v84, v2
	v_mov_b32_e32 v85, v2
	v_mov_b32_e32 v86, v2
	v_mov_b32_e32 v87, v2
	v_mov_b32_e32 v88, v2
	v_mov_b32_e32 v89, v2
	v_mov_b32_e32 v98, v2
	v_mov_b32_e32 v99, v2
	v_mov_b32_e32 v100, v2
	v_mov_b32_e32 v101, v2
	v_mov_b32_e32 v102, v2
	v_mov_b32_e32 v103, v2
	v_mov_b32_e32 v104, v2
	v_mov_b32_e32 v105, v2
	v_mov_b32_e32 v114, v2
	v_mov_b32_e32 v115, v2
	v_mov_b32_e32 v116, v2
	v_mov_b32_e32 v117, v2
	v_mov_b32_e32 v118, v2
	v_mov_b32_e32 v119, v2
	v_mov_b32_e32 v120, v2
	v_mov_b32_e32 v121, v2
	v_mov_b32_e32 v130, v2
	v_mov_b32_e32 v131, v2
	v_mov_b32_e32 v132, v2
	v_mov_b32_e32 v133, v2
	v_mov_b32_e32 v134, v2
	v_mov_b32_e32 v135, v2
	v_mov_b32_e32 v136, v2
	v_mov_b32_e32 v137, v2
	v_mov_b32_e32 v90, v2
	v_mov_b32_e32 v91, v2
	v_mov_b32_e32 v92, v2
	v_mov_b32_e32 v93, v2
	v_mov_b32_e32 v94, v2
	v_mov_b32_e32 v95, v2
	v_mov_b32_e32 v96, v2
	v_mov_b32_e32 v97, v2
	v_mov_b32_e32 v106, v2
	v_mov_b32_e32 v107, v2
	v_mov_b32_e32 v108, v2
	v_mov_b32_e32 v109, v2
	v_mov_b32_e32 v110, v2
	v_mov_b32_e32 v111, v2
	v_mov_b32_e32 v112, v2
	v_mov_b32_e32 v113, v2
	v_mov_b32_e32 v122, v2
	v_mov_b32_e32 v123, v2
	v_mov_b32_e32 v124, v2
	v_mov_b32_e32 v125, v2
	v_mov_b32_e32 v126, v2
	v_mov_b32_e32 v127, v2
	v_mov_b32_e32 v128, v2
	v_mov_b32_e32 v129, v2
	v_mov_b32_e32 v138, v2
	v_mov_b32_e32 v139, v2
	v_mov_b32_e32 v140, v2
	v_mov_b32_e32 v141, v2
	v_mov_b32_e32 v142, v2
	v_mov_b32_e32 v143, v2
	v_mov_b32_e32 v144, v2
	v_mov_b32_e32 v145, v2
	s_cmp_eq_u32 s99, 0
	s_cbranch_scc1 .Lro_skip_4
	s_barrier
	s_mov_b32 s99, 0
.Lro_skip_4:
.LBB0_2146:
	ds_read_b128 v[42:45], v181
	ds_read_b128 v[46:49], v181 offset:1024
	ds_read_b128 v[58:61], v181 offset:2048
	ds_read_b128 v[62:65], v181 offset:3072
	ds_read_b128 v[146:149], v182
	ds_read_b128 v[150:153], v182 offset:1024
	ds_read_b128 v[154:157], v182 offset:2048
	ds_read_b128 v[158:161], v182 offset:3072
	s_cmp_eq_u32 s81, 28
	s_cselect_b32 s37, s23, s78
	s_cselect_b32 s36, s31, s77
	s_cselect_b32 s41, s5, s80
	s_cselect_b32 s40, s25, s79
	ds_read_b128 v[170:173], v183
	ds_read_b128 v[188:191], v183 offset:1024
	ds_read_b128 v[192:195], v183 offset:2048
	ds_read_b128 v[196:199], v183 offset:3072
	ds_read_b128 v[200:203], v183 offset:4096
	ds_read_b128 v[204:207], v183 offset:5120
	ds_read_b128 v[208:211], v183 offset:6144
	ds_read_b128 v[212:215], v183 offset:7168
	s_add_u32 s82, s34, 0xfff80000
	s_addc_u32 s83, s35, -1
	s_mov_b32 s86, m0
	s_mov_b32 m0, s70
	s_nop 0
	global_load_lds_dwordx4 v1, s[82:83]
	s_mov_b32 m0, s86
	s_nop 0
	s_mov_b32 s86, m0
	s_mov_b32 m0, s73
	s_nop 0
	global_load_lds_dwordx4 v177, s[82:83]
	s_mov_b32 m0, s86
	s_mov_b32 s82, m0
	s_mov_b32 m0, s71
	s_nop 0
	global_load_lds_dwordx4 v1, s[34:35]
	s_mov_b32 m0, s82
	s_nop 0
	s_mov_b32 s82, m0
	s_mov_b32 m0, s74
	s_nop 0
	global_load_lds_dwordx4 v177, s[34:35]
	s_mov_b32 m0, s82
	s_waitcnt vmcnt(8)
	s_waitcnt lgkmcnt(0)
	s_barrier
	s_setprio 1
	s_waitcnt lgkmcnt(7)
	v_mfma_f32_16x16x32_bf16 v[142:145], v[42:45], v[170:173], v[142:145]
	v_mfma_f32_16x16x32_bf16 v[138:141], v[58:61], v[170:173], v[138:141]
	s_waitcnt lgkmcnt(5)
	v_mfma_f32_16x16x32_bf16 v[126:129], v[42:45], v[192:195], v[126:129]
	v_mfma_f32_16x16x32_bf16 v[122:125], v[58:61], v[192:195], v[122:125]
	s_waitcnt lgkmcnt(3)
	v_mfma_f32_16x16x32_bf16 v[110:113], v[42:45], v[200:203], v[110:113]
	v_mfma_f32_16x16x32_bf16 v[106:109], v[58:61], v[200:203], v[106:109]
	s_waitcnt lgkmcnt(1)
	v_mfma_f32_16x16x32_bf16 v[94:97], v[42:45], v[208:211], v[94:97]
	v_mfma_f32_16x16x32_bf16 v[90:93], v[58:61], v[208:211], v[90:93]
	v_mfma_f32_16x16x32_bf16 v[142:145], v[46:49], v[188:191], v[142:145]
	v_mfma_f32_16x16x32_bf16 v[138:141], v[62:65], v[188:191], v[138:141]
	v_mfma_f32_16x16x32_bf16 v[126:129], v[46:49], v[196:199], v[126:129]
	v_mfma_f32_16x16x32_bf16 v[122:125], v[62:65], v[196:199], v[122:125]
	v_mfma_f32_16x16x32_bf16 v[110:113], v[46:49], v[204:207], v[110:113]
	v_mfma_f32_16x16x32_bf16 v[106:109], v[62:65], v[204:207], v[106:109]
	s_waitcnt lgkmcnt(0)
	v_mfma_f32_16x16x32_bf16 v[94:97], v[46:49], v[212:215], v[94:97]
	v_mfma_f32_16x16x32_bf16 v[90:93], v[62:65], v[212:215], v[90:93]
	s_setprio 0
	s_setprio 1
	v_mfma_f32_16x16x32_bf16 v[134:137], v[146:149], v[170:173], v[134:137]
	v_mfma_f32_16x16x32_bf16 v[130:133], v[154:157], v[170:173], v[130:133]
	v_mfma_f32_16x16x32_bf16 v[118:121], v[146:149], v[192:195], v[118:121]
	v_mfma_f32_16x16x32_bf16 v[114:117], v[154:157], v[192:195], v[114:117]
	v_mfma_f32_16x16x32_bf16 v[102:105], v[146:149], v[200:203], v[102:105]
	v_mfma_f32_16x16x32_bf16 v[98:101], v[154:157], v[200:203], v[98:101]
	v_mfma_f32_16x16x32_bf16 v[86:89], v[146:149], v[208:211], v[86:89]
	v_mfma_f32_16x16x32_bf16 v[82:85], v[154:157], v[208:211], v[82:85]
	v_mfma_f32_16x16x32_bf16 v[134:137], v[150:153], v[188:191], v[134:137]
	v_mfma_f32_16x16x32_bf16 v[130:133], v[158:161], v[188:191], v[130:133]
	v_mfma_f32_16x16x32_bf16 v[118:121], v[150:153], v[196:199], v[118:121]
	v_mfma_f32_16x16x32_bf16 v[114:117], v[158:161], v[196:199], v[114:117]
	v_mfma_f32_16x16x32_bf16 v[102:105], v[150:153], v[204:207], v[102:105]
	v_mfma_f32_16x16x32_bf16 v[98:101], v[158:161], v[204:207], v[98:101]
	s_setprio 2
	s_barrier
	v_mfma_f32_16x16x32_bf16 v[86:89], v[150:153], v[212:215], v[86:89]
	v_mfma_f32_16x16x32_bf16 v[82:85], v[158:161], v[212:215], v[82:85]
	s_setprio 0
	ds_read_b128 v[170:173], v183 offset:16384
	ds_read_b128 v[188:191], v183 offset:17408
	ds_read_b128 v[192:195], v183 offset:18432
	ds_read_b128 v[196:199], v183 offset:19456
	ds_read_b128 v[200:203], v183 offset:20480
	ds_read_b128 v[204:207], v183 offset:21504
	ds_read_b128 v[208:211], v183 offset:22528
	ds_read_b128 v[212:215], v183 offset:23552
	s_mov_b32 s82, m0
	s_mov_b32 m0, s49
	s_nop 0
	global_load_lds_dwordx4 v176, s[36:37]
	s_mov_b32 m0, s82
	s_nop 0
	s_mov_b32 s82, m0
	s_mov_b32 m0, s56
	s_nop 0
	global_load_lds_dwordx4 v178, s[36:37]
	s_mov_b32 m0, s82
	s_add_u32 s82, s36, 0x80000
	s_addc_u32 s83, s37, 0
	s_mov_b32 s86, m0
	s_mov_b32 m0, s57
	s_nop 0
	global_load_lds_dwordx4 v176, s[82:83]
	s_mov_b32 m0, s86
	s_nop 0
	s_mov_b32 s86, m0
	s_mov_b32 m0, s58
	s_nop 0
	global_load_lds_dwordx4 v178, s[82:83]
	s_mov_b32 m0, s86
	s_waitcnt vmcnt(4)
	s_waitcnt lgkmcnt(0)
	s_barrier
	s_setprio 1
	s_waitcnt lgkmcnt(7)
	v_mfma_f32_16x16x32_bf16 v[78:81], v[42:45], v[170:173], v[78:81]
	v_mfma_f32_16x16x32_bf16 v[74:77], v[58:61], v[170:173], v[74:77]
	s_waitcnt lgkmcnt(5)
	v_mfma_f32_16x16x32_bf16 v[54:57], v[42:45], v[192:195], v[54:57]
	v_mfma_f32_16x16x32_bf16 v[50:53], v[58:61], v[192:195], v[50:53]
	s_waitcnt lgkmcnt(3)
	v_mfma_f32_16x16x32_bf16 v[30:33], v[42:45], v[200:203], v[30:33]
	v_mfma_f32_16x16x32_bf16 v[26:29], v[58:61], v[200:203], v[26:29]
	s_waitcnt lgkmcnt(1)
	v_mfma_f32_16x16x32_bf16 v[14:17], v[42:45], v[208:211], v[14:17]
	v_mfma_f32_16x16x32_bf16 v[10:13], v[58:61], v[208:211], v[10:13]
	v_mfma_f32_16x16x32_bf16 v[78:81], v[46:49], v[188:191], v[78:81]
	v_mfma_f32_16x16x32_bf16 v[74:77], v[62:65], v[188:191], v[74:77]
	v_mfma_f32_16x16x32_bf16 v[54:57], v[46:49], v[196:199], v[54:57]
	v_mfma_f32_16x16x32_bf16 v[50:53], v[62:65], v[196:199], v[50:53]
	v_mfma_f32_16x16x32_bf16 v[30:33], v[46:49], v[204:207], v[30:33]
	v_mfma_f32_16x16x32_bf16 v[26:29], v[62:65], v[204:207], v[26:29]
	s_waitcnt lgkmcnt(0)
	v_mfma_f32_16x16x32_bf16 v[14:17], v[46:49], v[212:215], v[14:17]
	v_mfma_f32_16x16x32_bf16 v[10:13], v[62:65], v[212:215], v[10:13]
	s_setprio 0
	s_setprio 1
	v_mfma_f32_16x16x32_bf16 v[38:41], v[146:149], v[192:195], v[38:41]
	v_mfma_f32_16x16x32_bf16 v[34:37], v[154:157], v[192:195], v[34:37]
	v_mfma_f32_16x16x32_bf16 v[22:25], v[146:149], v[200:203], v[22:25]
	v_mfma_f32_16x16x32_bf16 v[18:21], v[154:157], v[200:203], v[18:21]
	v_mfma_f32_16x16x32_bf16 v[6:9], v[146:149], v[208:211], v[6:9]
	v_mfma_f32_16x16x32_bf16 v[2:5], v[154:157], v[208:211], v[2:5]
	v_mfma_f32_16x16x32_bf16 v[42:45], v[146:149], v[170:173], v[70:73]
	v_mfma_f32_16x16x32_bf16 v[46:49], v[154:157], v[170:173], v[66:69]
	v_mfma_f32_16x16x32_bf16 v[38:41], v[150:153], v[196:199], v[38:41]
	v_mfma_f32_16x16x32_bf16 v[34:37], v[158:161], v[196:199], v[34:37]
	v_mfma_f32_16x16x32_bf16 v[22:25], v[150:153], v[204:207], v[22:25]
	v_mfma_f32_16x16x32_bf16 v[18:21], v[158:161], v[204:207], v[18:21]
	v_mfma_f32_16x16x32_bf16 v[6:9], v[150:153], v[212:215], v[6:9]
	v_mfma_f32_16x16x32_bf16 v[2:5], v[158:161], v[212:215], v[2:5]
	s_setprio 2
	s_barrier
	v_mfma_f32_16x16x32_bf16 v[42:45], v[150:153], v[188:191], v[42:45]
	v_mfma_f32_16x16x32_bf16 v[46:49], v[158:161], v[188:191], v[46:49]
	s_setprio 0
	ds_read_b128 v[58:61], v184
	ds_read_b128 v[62:65], v184 offset:1024
	ds_read_b128 v[66:69], v184 offset:2048
	ds_read_b128 v[70:73], v184 offset:3072
	ds_read_b128 v[146:149], v185
	ds_read_b128 v[150:153], v185 offset:1024
	ds_read_b128 v[154:157], v185 offset:2048
	ds_read_b128 v[158:161], v185 offset:3072
	ds_read_b128 v[170:173], v183 offset:32768
	ds_read_b128 v[188:191], v183 offset:33792
	ds_read_b128 v[192:195], v183 offset:34816
	ds_read_b128 v[196:199], v183 offset:35840
	ds_read_b128 v[200:203], v183 offset:36864
	ds_read_b128 v[204:207], v183 offset:37888
	ds_read_b128 v[208:211], v183 offset:38912
	ds_read_b128 v[212:215], v183 offset:39936
	s_mov_b32 s82, m0
	s_mov_b32 m0, s48
	s_nop 0
	global_load_lds_dwordx4 v1, s[40:41]
	s_mov_b32 m0, s82
	s_nop 0
	s_mov_b32 s82, m0
	s_mov_b32 m0, s59
	s_nop 0
	global_load_lds_dwordx4 v177, s[40:41]
	s_mov_b32 m0, s82
	s_add_u32 s40, s40, 0x80000
	s_addc_u32 s41, s41, 0
	s_mov_b32 s82, m0
	s_mov_b32 m0, s62
	s_nop 0
	global_load_lds_dwordx4 v1, s[40:41]
	s_mov_b32 m0, s82
	s_nop 0
	s_mov_b32 s82, m0
	s_mov_b32 m0, s63
	s_nop 0
	global_load_lds_dwordx4 v177, s[40:41]
	s_mov_b32 m0, s82
	s_waitcnt vmcnt(8)
	s_waitcnt lgkmcnt(0)
	s_barrier
	s_setprio 1
	s_waitcnt lgkmcnt(7)
	v_mfma_f32_16x16x32_bf16 v[142:145], v[58:61], v[170:173], v[142:145]
	v_mfma_f32_16x16x32_bf16 v[138:141], v[66:69], v[170:173], v[138:141]
	s_waitcnt lgkmcnt(5)
	v_mfma_f32_16x16x32_bf16 v[126:129], v[58:61], v[192:195], v[126:129]
	v_mfma_f32_16x16x32_bf16 v[122:125], v[66:69], v[192:195], v[122:125]
	s_waitcnt lgkmcnt(3)
	v_mfma_f32_16x16x32_bf16 v[110:113], v[58:61], v[200:203], v[110:113]
	v_mfma_f32_16x16x32_bf16 v[106:109], v[66:69], v[200:203], v[106:109]
	s_waitcnt lgkmcnt(1)
	v_mfma_f32_16x16x32_bf16 v[94:97], v[58:61], v[208:211], v[94:97]
	v_mfma_f32_16x16x32_bf16 v[90:93], v[66:69], v[208:211], v[90:93]
	v_mfma_f32_16x16x32_bf16 v[142:145], v[62:65], v[188:191], v[142:145]
	v_mfma_f32_16x16x32_bf16 v[138:141], v[70:73], v[188:191], v[138:141]
	v_mfma_f32_16x16x32_bf16 v[126:129], v[62:65], v[196:199], v[126:129]
	v_mfma_f32_16x16x32_bf16 v[122:125], v[70:73], v[196:199], v[122:125]
	v_mfma_f32_16x16x32_bf16 v[110:113], v[62:65], v[204:207], v[110:113]
	v_mfma_f32_16x16x32_bf16 v[106:109], v[70:73], v[204:207], v[106:109]
	s_waitcnt lgkmcnt(0)
	v_mfma_f32_16x16x32_bf16 v[94:97], v[62:65], v[212:215], v[94:97]
	v_mfma_f32_16x16x32_bf16 v[90:93], v[70:73], v[212:215], v[90:93]
	s_setprio 0
	s_setprio 1
	v_mfma_f32_16x16x32_bf16 v[134:137], v[146:149], v[170:173], v[134:137]
	v_mfma_f32_16x16x32_bf16 v[130:133], v[154:157], v[170:173], v[130:133]
	v_mfma_f32_16x16x32_bf16 v[118:121], v[146:149], v[192:195], v[118:121]
	v_mfma_f32_16x16x32_bf16 v[114:117], v[154:157], v[192:195], v[114:117]
	v_mfma_f32_16x16x32_bf16 v[102:105], v[146:149], v[200:203], v[102:105]
	v_mfma_f32_16x16x32_bf16 v[98:101], v[154:157], v[200:203], v[98:101]
	v_mfma_f32_16x16x32_bf16 v[86:89], v[146:149], v[208:211], v[86:89]
	v_mfma_f32_16x16x32_bf16 v[82:85], v[154:157], v[208:211], v[82:85]
	v_mfma_f32_16x16x32_bf16 v[134:137], v[150:153], v[188:191], v[134:137]
	v_mfma_f32_16x16x32_bf16 v[130:133], v[158:161], v[188:191], v[130:133]
	v_mfma_f32_16x16x32_bf16 v[118:121], v[150:153], v[196:199], v[118:121]
	v_mfma_f32_16x16x32_bf16 v[114:117], v[158:161], v[196:199], v[114:117]
	v_mfma_f32_16x16x32_bf16 v[102:105], v[150:153], v[204:207], v[102:105]
	v_mfma_f32_16x16x32_bf16 v[98:101], v[158:161], v[204:207], v[98:101]
	s_setprio 2
	s_barrier
	v_mfma_f32_16x16x32_bf16 v[86:89], v[150:153], v[212:215], v[86:89]
	v_mfma_f32_16x16x32_bf16 v[82:85], v[158:161], v[212:215], v[82:85]
	s_setprio 0
	ds_read_b128 v[170:173], v183 offset:49152
	ds_read_b128 v[188:191], v183 offset:50176
	ds_read_b128 v[192:195], v183 offset:51200
	ds_read_b128 v[196:199], v183 offset:52224
	ds_read_b128 v[200:203], v183 offset:53248
	ds_read_b128 v[204:207], v183 offset:54272
	ds_read_b128 v[208:211], v183 offset:55296
	ds_read_b128 v[212:215], v183 offset:56320
	s_add_u32 s40, s36, 0x80
	s_addc_u32 s41, s37, 0
	s_mov_b32 s82, m0
	s_mov_b32 m0, s64
	s_nop 0
	global_load_lds_dwordx4 v176, s[40:41]
	s_mov_b32 m0, s82
	s_add_u32 s36, s36, 0x80080
	s_mov_b32 s82, m0
	s_mov_b32 m0, s65
	s_nop 0
	global_load_lds_dwordx4 v178, s[40:41]
	s_mov_b32 m0, s82
	s_addc_u32 s37, s37, 0
	s_mov_b32 s40, m0
	s_mov_b32 m0, s66
	s_nop 0
	global_load_lds_dwordx4 v176, s[36:37]
	s_mov_b32 m0, s40
	s_nop 0
	s_mov_b32 s40, m0
	s_mov_b32 m0, s67
	s_nop 0
	global_load_lds_dwordx4 v178, s[36:37]
	s_mov_b32 m0, s40
	s_waitcnt vmcnt(4)
	s_waitcnt lgkmcnt(0)
	s_barrier
	s_setprio 1
	s_waitcnt lgkmcnt(7)
	v_mfma_f32_16x16x32_bf16 v[78:81], v[58:61], v[170:173], v[78:81]
	v_mfma_f32_16x16x32_bf16 v[74:77], v[66:69], v[170:173], v[74:77]
	s_waitcnt lgkmcnt(5)
	v_mfma_f32_16x16x32_bf16 v[54:57], v[58:61], v[192:195], v[54:57]
	v_mfma_f32_16x16x32_bf16 v[50:53], v[66:69], v[192:195], v[50:53]
	s_waitcnt lgkmcnt(3)
	v_mfma_f32_16x16x32_bf16 v[30:33], v[58:61], v[200:203], v[30:33]
	v_mfma_f32_16x16x32_bf16 v[26:29], v[66:69], v[200:203], v[26:29]
	s_waitcnt lgkmcnt(1)
	v_mfma_f32_16x16x32_bf16 v[14:17], v[58:61], v[208:211], v[14:17]
	v_mfma_f32_16x16x32_bf16 v[10:13], v[66:69], v[208:211], v[10:13]
	v_mfma_f32_16x16x32_bf16 v[78:81], v[62:65], v[188:191], v[78:81]
	v_mfma_f32_16x16x32_bf16 v[74:77], v[70:73], v[188:191], v[74:77]
	v_mfma_f32_16x16x32_bf16 v[54:57], v[62:65], v[196:199], v[54:57]
	v_mfma_f32_16x16x32_bf16 v[50:53], v[70:73], v[196:199], v[50:53]
	v_mfma_f32_16x16x32_bf16 v[30:33], v[62:65], v[204:207], v[30:33]
	v_mfma_f32_16x16x32_bf16 v[26:29], v[70:73], v[204:207], v[26:29]
	s_waitcnt lgkmcnt(0)
	v_mfma_f32_16x16x32_bf16 v[14:17], v[62:65], v[212:215], v[14:17]
	v_mfma_f32_16x16x32_bf16 v[10:13], v[70:73], v[212:215], v[10:13]
	s_setprio 0
	s_setprio 1
	v_mfma_f32_16x16x32_bf16 v[42:45], v[146:149], v[170:173], v[42:45]
	v_mfma_f32_16x16x32_bf16 v[70:73], v[150:153], v[188:191], v[42:45]
	v_mfma_f32_16x16x32_bf16 v[42:45], v[154:157], v[170:173], v[46:49]
	v_mfma_f32_16x16x32_bf16 v[38:41], v[146:149], v[192:195], v[38:41]
	v_mfma_f32_16x16x32_bf16 v[34:37], v[154:157], v[192:195], v[34:37]
	v_mfma_f32_16x16x32_bf16 v[22:25], v[146:149], v[200:203], v[22:25]
	v_mfma_f32_16x16x32_bf16 v[18:21], v[154:157], v[200:203], v[18:21]
	v_mfma_f32_16x16x32_bf16 v[6:9], v[146:149], v[208:211], v[6:9]
	v_mfma_f32_16x16x32_bf16 v[2:5], v[154:157], v[208:211], v[2:5]
	v_mfma_f32_16x16x32_bf16 v[66:69], v[158:161], v[188:191], v[42:45]
	v_mfma_f32_16x16x32_bf16 v[38:41], v[150:153], v[196:199], v[38:41]
	v_mfma_f32_16x16x32_bf16 v[34:37], v[158:161], v[196:199], v[34:37]
	v_mfma_f32_16x16x32_bf16 v[22:25], v[150:153], v[204:207], v[22:25]
	v_mfma_f32_16x16x32_bf16 v[18:21], v[158:161], v[204:207], v[18:21]
	s_setprio 2
	s_barrier
	v_mfma_f32_16x16x32_bf16 v[6:9], v[150:153], v[212:215], v[6:9]
	v_mfma_f32_16x16x32_bf16 v[2:5], v[158:161], v[212:215], v[2:5]
	s_setprio 0
	s_add_i32 s81, s81, 2
	s_add_u32 s77, s77, 0x100
	s_addc_u32 s78, s78, 0
	s_add_u32 s34, s34, 0x100
	s_addc_u32 s35, s35, 0
	s_add_u32 s79, s79, 0x100
	s_addc_u32 s80, s80, 0
	s_cmp_gt_u32 s81, 29
	s_cbranch_scc0 .LBB0_2146
	s_and_b64 vcc, exec, s[14:15]
	s_cbranch_vccz .LBB0_2149
	s_barrier

.LBB0_2197:
	s_nop 0
	v_pk_mul_f32 v[12:13], v[4:5], s[20:21] op_sel_hi:[1,0]
	v_pk_mul_f32 v[4:5], v[2:3], s[20:21] op_sel_hi:[1,0]
	s_andn2_b64 vcc, exec, s[2:3]
	s_mov_b64 s[2:3], -1
	v_pk_mul_f32 v[8:9], v[8:9], s[20:21] op_sel_hi:[1,0]
	v_pk_mul_f32 v[6:7], v[6:7], s[20:21] op_sel_hi:[1,0]
	v_cvt_pk_bf16_f32 v3, v8, v9
	v_cvt_pk_bf16_f32 v4, v4, v5
	v_cvt_pk_bf16_f32 v5, v12, v13
	s_nop 0
	v_cvt_pk_bf16_f32 v2, v6, v7
	global_store_dwordx4 v[10:11], v[2:5], off offset:256
	s_cbranch_vccnz .LBB0_2138
	s_andn2_b64 vcc, exec, s[6:7]
	s_cbranch_vccnz .LBB0_2137
	s_mov_b32 s99, 1
	s_branch .LBB0_2137

.LBB0_2409:
	s_ashr_i32 s17, s16, 31
	s_lshl_b64 s[18:19], s[16:17], 20
	s_add_u32 s18, s33, s18
	s_addc_u32 s19, s34, s19
	s_and_b64 s[20:21], s[2:3], exec
	s_cselect_b32 s17, s19, s27
	s_cselect_b32 s71, s18, s26
	s_ashr_i32 s15, s14, 31
	s_lshl_b64 s[20:21], s[14:15], 20
	s_add_u32 s20, s35, s20
	s_addc_u32 s21, s36, s21
	s_and_b64 s[28:29], s[2:3], exec
	s_cselect_b32 s15, s21, s25
	s_cselect_b32 s73, s20, s24
	s_add_u32 s74, s24, 0x100
	s_addc_u32 s75, s25, 0
	s_add_u32 s24, s26, 0x80080
	s_addc_u32 s25, s27, 0
	s_add_u32 s76, s26, 0x100
	v_mov_b32_e32 v2, 0
	s_addc_u32 s77, s27, 0
	s_mov_b32 s78, -2
	v_mov_b32_e32 v3, v2
	v_mov_b32_e32 v4, v2
	v_mov_b32_e32 v5, v2
	v_mov_b32_e32 v6, v2
	v_mov_b32_e32 v7, v2
	s_waitcnt vmcnt(25)
	v_mov_b32_e32 v8, v2
	s_waitcnt vmcnt(24)
	v_mov_b32_e32 v9, v2
	s_waitcnt vmcnt(4)
	v_mov_b32_e32 v18, v2
	v_mov_b32_e32 v19, v2
	v_mov_b32_e32 v20, v2
	v_mov_b32_e32 v21, v2
	s_waitcnt vmcnt(2)
	v_mov_b32_e32 v22, v2
	v_mov_b32_e32 v23, v2
	v_mov_b32_e32 v24, v2
	v_mov_b32_e32 v25, v2
	v_mov_b32_e32 v34, v2
	v_mov_b32_e32 v35, v2
	v_mov_b32_e32 v36, v2
	v_mov_b32_e32 v37, v2
	v_mov_b32_e32 v38, v2
	v_mov_b32_e32 v39, v2
	v_mov_b32_e32 v40, v2
	v_mov_b32_e32 v41, v2
	v_mov_b32_e32 v50, v2
	v_mov_b32_e32 v51, v2
	v_mov_b32_e32 v52, v2
	v_mov_b32_e32 v53, v2
	v_mov_b32_e32 v54, v2
	v_mov_b32_e32 v55, v2
	v_mov_b32_e32 v56, v2
	v_mov_b32_e32 v57, v2
	v_mov_b32_e32 v10, v2
	v_mov_b32_e32 v11, v2
	v_mov_b32_e32 v12, v2
	v_mov_b32_e32 v13, v2
	v_mov_b32_e32 v14, v2
	v_mov_b32_e32 v15, v2
	v_mov_b32_e32 v16, v2
	v_mov_b32_e32 v17, v2
	v_mov_b32_e32 v26, v2
	v_mov_b32_e32 v27, v2
	v_mov_b32_e32 v28, v2
	v_mov_b32_e32 v29, v2
	v_mov_b32_e32 v30, v2
	v_mov_b32_e32 v31, v2
	s_waitcnt vmcnt(1)
	v_mov_b32_e32 v32, v2
	s_waitcnt vmcnt(0)
	v_mov_b32_e32 v33, v2
	v_mov_b32_e32 v42, v2
	v_mov_b32_e32 v43, v2
	v_mov_b32_e32 v44, v2
	v_mov_b32_e32 v45, v2
	v_mov_b32_e32 v46, v2
	v_mov_b32_e32 v47, v2
	v_mov_b32_e32 v48, v2
	v_mov_b32_e32 v49, v2
	v_mov_b32_e32 v58, v2
	v_mov_b32_e32 v59, v2
	v_mov_b32_e32 v60, v2
	v_mov_b32_e32 v61, v2
	v_mov_b32_e32 v62, v2
	v_mov_b32_e32 v63, v2
	v_mov_b32_e32 v64, v2
	v_mov_b32_e32 v65, v2
	v_mov_b32_e32 v66, v2
	v_mov_b32_e32 v67, v2
	v_mov_b32_e32 v68, v2
	v_mov_b32_e32 v69, v2
	v_mov_b32_e32 v70, v2
	v_mov_b32_e32 v71, v2
	v_mov_b32_e32 v72, v2
	v_mov_b32_e32 v73, v2
	v_mov_b32_e32 v74, v2
	v_mov_b32_e32 v75, v2
	v_mov_b32_e32 v76, v2
	v_mov_b32_e32 v77, v2
	v_mov_b32_e32 v82, v2
	v_mov_b32_e32 v83, v2
	v_mov_b32_e32 v84, v2
	v_mov_b32_e32 v85, v2
	v_mov_b32_e32 v98, v2
	v_mov_b32_e32 v99, v2
	v_mov_b32_e32 v100, v2
	v_mov_b32_e32 v101, v2
	v_mov_b32_e32 v102, v2
	v_mov_b32_e32 v103, v2
	v_mov_b32_e32 v104, v2
	v_mov_b32_e32 v105, v2
	v_mov_b32_e32 v106, v2
	v_mov_b32_e32 v107, v2
	v_mov_b32_e32 v108, v2
	v_mov_b32_e32 v109, v2
	v_mov_b32_e32 v110, v2
	v_mov_b32_e32 v111, v2
	v_mov_b32_e32 v112, v2
	v_mov_b32_e32 v113, v2
	v_mov_b32_e32 v78, v2
	v_mov_b32_e32 v79, v2
	v_mov_b32_e32 v80, v2
	v_mov_b32_e32 v81, v2
	v_mov_b32_e32 v86, v2
	v_mov_b32_e32 v87, v2
	v_mov_b32_e32 v88, v2
	v_mov_b32_e32 v89, v2
	v_mov_b32_e32 v90, v2
	v_mov_b32_e32 v91, v2
	v_mov_b32_e32 v92, v2
	v_mov_b32_e32 v93, v2
	v_mov_b32_e32 v94, v2
	v_mov_b32_e32 v95, v2
	v_mov_b32_e32 v96, v2
	v_mov_b32_e32 v97, v2
	v_mov_b32_e32 v114, v2
	v_mov_b32_e32 v115, v2
	v_mov_b32_e32 v116, v2
	v_mov_b32_e32 v117, v2
	v_mov_b32_e32 v118, v2
	v_mov_b32_e32 v119, v2
	v_mov_b32_e32 v120, v2
	v_mov_b32_e32 v121, v2
	v_mov_b32_e32 v122, v2
	v_mov_b32_e32 v123, v2
	v_mov_b32_e32 v124, v2
	v_mov_b32_e32 v125, v2
	v_mov_b32_e32 v126, v2
	v_mov_b32_e32 v127, v2
	v_mov_b32_e32 v128, v2
	v_mov_b32_e32 v129, v2
	s_cmp_eq_u32 s99, 0
	s_cbranch_scc1 .Lro_skip_3
	s_barrier
	s_mov_b32 s99, 0
.Lro_skip_3:
.LBB0_2410:
	ds_read_b128 v[130:133], v181
	ds_read_b128 v[134:137], v181 offset:1024
	ds_read_b128 v[138:141], v181 offset:2048
	ds_read_b128 v[142:145], v181 offset:3072
	ds_read_b128 v[146:149], v182
	ds_read_b128 v[150:153], v182 offset:1024
	ds_read_b128 v[154:157], v182 offset:2048
	ds_read_b128 v[158:161], v182 offset:3072
	s_cmp_eq_u32 s78, 28
	s_cselect_b32 s27, s15, s75
	s_cselect_b32 s26, s73, s74
	s_cselect_b32 s29, s17, s77
	s_cselect_b32 s28, s71, s76
	ds_read_b128 v[166:169], v183
	ds_read_b128 v[170:173], v183 offset:1024
	ds_read_b128 v[186:189], v183 offset:2048
	ds_read_b128 v[190:193], v183 offset:3072
	ds_read_b128 v[194:197], v183 offset:4096
	ds_read_b128 v[198:201], v183 offset:5120
	ds_read_b128 v[202:205], v183 offset:6144
	ds_read_b128 v[206:209], v183 offset:7168
	s_add_u32 s80, s24, 0xfff80000
	s_addc_u32 s81, s25, -1
	s_mov_b32 s79, m0
	s_mov_b32 m0, s64
	s_nop 0
	global_load_lds_dwordx4 v1, s[80:81]
	s_mov_b32 m0, s79
	s_nop 0
	s_mov_b32 s79, m0
	s_mov_b32 m0, s66
	s_nop 0
	global_load_lds_dwordx4 v177, s[80:81]
	s_mov_b32 m0, s79
	s_nop 0
	s_mov_b32 s79, m0
	s_mov_b32 m0, s65
	s_nop 0
	global_load_lds_dwordx4 v1, s[24:25]
	s_mov_b32 m0, s79
	s_nop 0
	s_mov_b32 s79, m0
	s_mov_b32 m0, s67
	s_nop 0
	global_load_lds_dwordx4 v177, s[24:25]
	s_mov_b32 m0, s79
	s_waitcnt vmcnt(8)
	s_waitcnt lgkmcnt(0)
	s_barrier
	s_setprio 1
	s_waitcnt lgkmcnt(7)
	v_mfma_f32_16x16x32_bf16 v[126:129], v[130:133], v[166:169], v[126:129]
	v_mfma_f32_16x16x32_bf16 v[122:125], v[138:141], v[166:169], v[122:125]
	s_waitcnt lgkmcnt(5)
	v_mfma_f32_16x16x32_bf16 v[118:121], v[130:133], v[186:189], v[118:121]
	v_mfma_f32_16x16x32_bf16 v[114:117], v[138:141], v[186:189], v[114:117]
	s_waitcnt lgkmcnt(3)
	v_mfma_f32_16x16x32_bf16 v[94:97], v[130:133], v[194:197], v[94:97]
	v_mfma_f32_16x16x32_bf16 v[90:93], v[138:141], v[194:197], v[90:93]
	s_waitcnt lgkmcnt(1)
	v_mfma_f32_16x16x32_bf16 v[86:89], v[130:133], v[202:205], v[86:89]
	v_mfma_f32_16x16x32_bf16 v[78:81], v[138:141], v[202:205], v[78:81]
	v_mfma_f32_16x16x32_bf16 v[126:129], v[134:137], v[170:173], v[126:129]
	v_mfma_f32_16x16x32_bf16 v[122:125], v[142:145], v[170:173], v[122:125]
	v_mfma_f32_16x16x32_bf16 v[118:121], v[134:137], v[190:193], v[118:121]
	v_mfma_f32_16x16x32_bf16 v[114:117], v[142:145], v[190:193], v[114:117]
	v_mfma_f32_16x16x32_bf16 v[94:97], v[134:137], v[198:201], v[94:97]
	v_mfma_f32_16x16x32_bf16 v[90:93], v[142:145], v[198:201], v[90:93]
	s_waitcnt lgkmcnt(0)
	v_mfma_f32_16x16x32_bf16 v[86:89], v[134:137], v[206:209], v[86:89]
	v_mfma_f32_16x16x32_bf16 v[78:81], v[142:145], v[206:209], v[78:81]
	s_setprio 0
	s_setprio 1
	v_mfma_f32_16x16x32_bf16 v[110:113], v[146:149], v[166:169], v[110:113]
	v_mfma_f32_16x16x32_bf16 v[106:109], v[154:157], v[166:169], v[106:109]
	v_mfma_f32_16x16x32_bf16 v[102:105], v[146:149], v[186:189], v[102:105]
	v_mfma_f32_16x16x32_bf16 v[98:101], v[154:157], v[186:189], v[98:101]
	v_mfma_f32_16x16x32_bf16 v[82:85], v[146:149], v[194:197], v[82:85]
	v_mfma_f32_16x16x32_bf16 v[74:77], v[154:157], v[194:197], v[74:77]
	v_mfma_f32_16x16x32_bf16 v[70:73], v[146:149], v[202:205], v[70:73]
	v_mfma_f32_16x16x32_bf16 v[66:69], v[154:157], v[202:205], v[66:69]
	v_mfma_f32_16x16x32_bf16 v[110:113], v[150:153], v[170:173], v[110:113]
	v_mfma_f32_16x16x32_bf16 v[106:109], v[158:161], v[170:173], v[106:109]
	v_mfma_f32_16x16x32_bf16 v[102:105], v[150:153], v[190:193], v[102:105]
	v_mfma_f32_16x16x32_bf16 v[98:101], v[158:161], v[190:193], v[98:101]
	v_mfma_f32_16x16x32_bf16 v[82:85], v[150:153], v[198:201], v[82:85]
	v_mfma_f32_16x16x32_bf16 v[74:77], v[158:161], v[198:201], v[74:77]
	s_setprio 2
	s_barrier
	v_mfma_f32_16x16x32_bf16 v[70:73], v[150:153], v[206:209], v[70:73]
	v_mfma_f32_16x16x32_bf16 v[66:69], v[158:161], v[206:209], v[66:69]
	s_setprio 0
	ds_read_b128 v[166:169], v183 offset:16384
	ds_read_b128 v[170:173], v183 offset:17408
	ds_read_b128 v[186:189], v183 offset:18432
	ds_read_b128 v[190:193], v183 offset:19456
	ds_read_b128 v[194:197], v183 offset:20480
	ds_read_b128 v[198:201], v183 offset:21504
	ds_read_b128 v[202:205], v183 offset:22528
	ds_read_b128 v[206:209], v183 offset:23552
	s_mov_b32 s79, m0
	s_mov_b32 m0, s41
	s_nop 0
	global_load_lds_dwordx4 v176, s[26:27]
	s_mov_b32 m0, s79
	s_add_u32 s80, s26, 0x80000
	s_mov_b32 s79, m0
	s_mov_b32 m0, s42
	s_nop 0
	global_load_lds_dwordx4 v178, s[26:27]
	s_mov_b32 m0, s79
	s_addc_u32 s81, s27, 0
	s_mov_b32 s79, m0
	s_mov_b32 m0, s43
	s_nop 0
	global_load_lds_dwordx4 v176, s[80:81]
	s_mov_b32 m0, s79
	s_nop 0
	s_mov_b32 s79, m0
	s_mov_b32 m0, s46
	s_nop 0
	global_load_lds_dwordx4 v178, s[80:81]
	s_mov_b32 m0, s79
	s_waitcnt vmcnt(4)
	s_waitcnt lgkmcnt(0)
	s_barrier
	s_setprio 1
	s_waitcnt lgkmcnt(7)
	v_mfma_f32_16x16x32_bf16 v[62:65], v[130:133], v[166:169], v[62:65]
	v_mfma_f32_16x16x32_bf16 v[58:61], v[138:141], v[166:169], v[58:61]
	s_waitcnt lgkmcnt(5)
	v_mfma_f32_16x16x32_bf16 v[46:49], v[130:133], v[186:189], v[46:49]
	v_mfma_f32_16x16x32_bf16 v[42:45], v[138:141], v[186:189], v[42:45]
	s_waitcnt lgkmcnt(3)
	v_mfma_f32_16x16x32_bf16 v[30:33], v[130:133], v[194:197], v[30:33]
	v_mfma_f32_16x16x32_bf16 v[26:29], v[138:141], v[194:197], v[26:29]
	s_waitcnt lgkmcnt(1)
	v_mfma_f32_16x16x32_bf16 v[14:17], v[130:133], v[202:205], v[14:17]
	v_mfma_f32_16x16x32_bf16 v[10:13], v[138:141], v[202:205], v[10:13]
	v_mfma_f32_16x16x32_bf16 v[62:65], v[134:137], v[170:173], v[62:65]
	v_mfma_f32_16x16x32_bf16 v[58:61], v[142:145], v[170:173], v[58:61]
	v_mfma_f32_16x16x32_bf16 v[46:49], v[134:137], v[190:193], v[46:49]
	v_mfma_f32_16x16x32_bf16 v[42:45], v[142:145], v[190:193], v[42:45]
	v_mfma_f32_16x16x32_bf16 v[30:33], v[134:137], v[198:201], v[30:33]
	v_mfma_f32_16x16x32_bf16 v[26:29], v[142:145], v[198:201], v[26:29]
	s_waitcnt lgkmcnt(0)
	v_mfma_f32_16x16x32_bf16 v[14:17], v[134:137], v[206:209], v[14:17]
	v_mfma_f32_16x16x32_bf16 v[10:13], v[142:145], v[206:209], v[10:13]
	s_setprio 0
	s_setprio 1
	v_mfma_f32_16x16x32_bf16 v[54:57], v[146:149], v[166:169], v[54:57]
	v_mfma_f32_16x16x32_bf16 v[50:53], v[154:157], v[166:169], v[50:53]
	v_mfma_f32_16x16x32_bf16 v[38:41], v[146:149], v[186:189], v[38:41]
	v_mfma_f32_16x16x32_bf16 v[34:37], v[154:157], v[186:189], v[34:37]
	v_mfma_f32_16x16x32_bf16 v[22:25], v[146:149], v[194:197], v[22:25]
	v_mfma_f32_16x16x32_bf16 v[18:21], v[154:157], v[194:197], v[18:21]
	v_mfma_f32_16x16x32_bf16 v[6:9], v[146:149], v[202:205], v[6:9]
	v_mfma_f32_16x16x32_bf16 v[2:5], v[154:157], v[202:205], v[2:5]
	v_mfma_f32_16x16x32_bf16 v[54:57], v[150:153], v[170:173], v[54:57]
	v_mfma_f32_16x16x32_bf16 v[50:53], v[158:161], v[170:173], v[50:53]
	v_mfma_f32_16x16x32_bf16 v[38:41], v[150:153], v[190:193], v[38:41]
	v_mfma_f32_16x16x32_bf16 v[34:37], v[158:161], v[190:193], v[34:37]
	v_mfma_f32_16x16x32_bf16 v[22:25], v[150:153], v[198:201], v[22:25]
	v_mfma_f32_16x16x32_bf16 v[18:21], v[158:161], v[198:201], v[18:21]
	s_setprio 2
	s_barrier
	v_mfma_f32_16x16x32_bf16 v[6:9], v[150:153], v[206:209], v[6:9]
	v_mfma_f32_16x16x32_bf16 v[2:5], v[158:161], v[206:209], v[2:5]
	s_setprio 0
	ds_read_b128 v[130:133], v184
	ds_read_b128 v[134:137], v184 offset:1024
	ds_read_b128 v[138:141], v184 offset:2048
	ds_read_b128 v[142:145], v184 offset:3072
	ds_read_b128 v[146:149], v185
	ds_read_b128 v[150:153], v185 offset:1024
	ds_read_b128 v[154:157], v185 offset:2048
	ds_read_b128 v[158:161], v185 offset:3072
	ds_read_b128 v[166:169], v183 offset:32768
	ds_read_b128 v[170:173], v183 offset:33792
	ds_read_b128 v[186:189], v183 offset:34816
	ds_read_b128 v[190:193], v183 offset:35840
	ds_read_b128 v[194:197], v183 offset:36864
	ds_read_b128 v[198:201], v183 offset:37888
	ds_read_b128 v[202:205], v183 offset:38912
	ds_read_b128 v[206:209], v183 offset:39936
	s_mov_b32 s79, m0
	s_mov_b32 m0, s40
	s_nop 0
	global_load_lds_dwordx4 v1, s[28:29]
	s_mov_b32 m0, s79
	s_nop 0
	s_mov_b32 s79, m0
	s_mov_b32 m0, s47
	s_nop 0
	global_load_lds_dwordx4 v177, s[28:29]
	s_mov_b32 m0, s79
	s_add_u32 s28, s28, 0x80000
	s_addc_u32 s29, s29, 0
	s_mov_b32 s79, m0
	s_mov_b32 m0, s48
	s_nop 0
	global_load_lds_dwordx4 v1, s[28:29]
	s_mov_b32 m0, s79
	s_nop 0
	s_mov_b32 s79, m0
	s_mov_b32 m0, s49
	s_nop 0
	global_load_lds_dwordx4 v177, s[28:29]
	s_mov_b32 m0, s79
	s_waitcnt vmcnt(8)
	s_waitcnt lgkmcnt(0)
	s_barrier
	s_setprio 1
	s_waitcnt lgkmcnt(7)
	v_mfma_f32_16x16x32_bf16 v[126:129], v[130:133], v[166:169], v[126:129]
	v_mfma_f32_16x16x32_bf16 v[122:125], v[138:141], v[166:169], v[122:125]
	s_waitcnt lgkmcnt(5)
	v_mfma_f32_16x16x32_bf16 v[118:121], v[130:133], v[186:189], v[118:121]
	v_mfma_f32_16x16x32_bf16 v[114:117], v[138:141], v[186:189], v[114:117]
	s_waitcnt lgkmcnt(3)
	v_mfma_f32_16x16x32_bf16 v[94:97], v[130:133], v[194:197], v[94:97]
	v_mfma_f32_16x16x32_bf16 v[90:93], v[138:141], v[194:197], v[90:93]
	s_waitcnt lgkmcnt(1)
	v_mfma_f32_16x16x32_bf16 v[86:89], v[130:133], v[202:205], v[86:89]
	v_mfma_f32_16x16x32_bf16 v[78:81], v[138:141], v[202:205], v[78:81]
	v_mfma_f32_16x16x32_bf16 v[126:129], v[134:137], v[170:173], v[126:129]
	v_mfma_f32_16x16x32_bf16 v[122:125], v[142:145], v[170:173], v[122:125]
	v_mfma_f32_16x16x32_bf16 v[118:121], v[134:137], v[190:193], v[118:121]
	v_mfma_f32_16x16x32_bf16 v[114:117], v[142:145], v[190:193], v[114:117]
	v_mfma_f32_16x16x32_bf16 v[94:97], v[134:137], v[198:201], v[94:97]
	v_mfma_f32_16x16x32_bf16 v[90:93], v[142:145], v[198:201], v[90:93]
	s_waitcnt lgkmcnt(0)
	v_mfma_f32_16x16x32_bf16 v[86:89], v[134:137], v[206:209], v[86:89]
	v_mfma_f32_16x16x32_bf16 v[78:81], v[142:145], v[206:209], v[78:81]
	s_setprio 0
	s_setprio 1
	v_mfma_f32_16x16x32_bf16 v[110:113], v[146:149], v[166:169], v[110:113]
	v_mfma_f32_16x16x32_bf16 v[106:109], v[154:157], v[166:169], v[106:109]
	v_mfma_f32_16x16x32_bf16 v[102:105], v[146:149], v[186:189], v[102:105]
	v_mfma_f32_16x16x32_bf16 v[98:101], v[154:157], v[186:189], v[98:101]
	v_mfma_f32_16x16x32_bf16 v[82:85], v[146:149], v[194:197], v[82:85]
	v_mfma_f32_16x16x32_bf16 v[74:77], v[154:157], v[194:197], v[74:77]
	v_mfma_f32_16x16x32_bf16 v[70:73], v[146:149], v[202:205], v[70:73]
	v_mfma_f32_16x16x32_bf16 v[66:69], v[154:157], v[202:205], v[66:69]
	v_mfma_f32_16x16x32_bf16 v[110:113], v[150:153], v[170:173], v[110:113]
	v_mfma_f32_16x16x32_bf16 v[106:109], v[158:161], v[170:173], v[106:109]
	v_mfma_f32_16x16x32_bf16 v[102:105], v[150:153], v[190:193], v[102:105]
	v_mfma_f32_16x16x32_bf16 v[98:101], v[158:161], v[190:193], v[98:101]
	v_mfma_f32_16x16x32_bf16 v[82:85], v[150:153], v[198:201], v[82:85]
	v_mfma_f32_16x16x32_bf16 v[74:77], v[158:161], v[198:201], v[74:77]
	s_setprio 2
	s_barrier
	v_mfma_f32_16x16x32_bf16 v[70:73], v[150:153], v[206:209], v[70:73]
	v_mfma_f32_16x16x32_bf16 v[66:69], v[158:161], v[206:209], v[66:69]
	s_setprio 0
	ds_read_b128 v[166:169], v183 offset:49152
	ds_read_b128 v[170:173], v183 offset:50176
	ds_read_b128 v[186:189], v183 offset:51200
	ds_read_b128 v[190:193], v183 offset:52224
	ds_read_b128 v[194:197], v183 offset:53248
	ds_read_b128 v[198:201], v183 offset:54272
	ds_read_b128 v[202:205], v183 offset:55296
	ds_read_b128 v[206:209], v183 offset:56320
	s_add_u32 s28, s26, 0x80
	s_addc_u32 s29, s27, 0
	s_mov_b32 s79, m0
	s_mov_b32 m0, s56
	s_nop 0
	global_load_lds_dwordx4 v176, s[28:29]
	s_mov_b32 m0, s79
	s_add_u32 s26, s26, 0x80080
	s_mov_b32 s79, m0
	s_mov_b32 m0, s57
	s_nop 0
	global_load_lds_dwordx4 v178, s[28:29]
	s_mov_b32 m0, s79
	s_addc_u32 s27, s27, 0
	s_mov_b32 s28, m0
	s_mov_b32 m0, s58
	s_nop 0
	global_load_lds_dwordx4 v176, s[26:27]
	s_mov_b32 m0, s28
	s_nop 0
	s_mov_b32 s28, m0
	s_mov_b32 m0, s59
	s_nop 0
	global_load_lds_dwordx4 v178, s[26:27]
	s_mov_b32 m0, s28
	s_waitcnt vmcnt(4)
	s_waitcnt lgkmcnt(0)
	s_barrier
	s_setprio 1
	s_waitcnt lgkmcnt(7)
	v_mfma_f32_16x16x32_bf16 v[62:65], v[130:133], v[166:169], v[62:65]
	v_mfma_f32_16x16x32_bf16 v[58:61], v[138:141], v[166:169], v[58:61]
	s_waitcnt lgkmcnt(5)
	v_mfma_f32_16x16x32_bf16 v[46:49], v[130:133], v[186:189], v[46:49]
	v_mfma_f32_16x16x32_bf16 v[42:45], v[138:141], v[186:189], v[42:45]
	s_waitcnt lgkmcnt(3)
	v_mfma_f32_16x16x32_bf16 v[30:33], v[130:133], v[194:197], v[30:33]
	v_mfma_f32_16x16x32_bf16 v[26:29], v[138:141], v[194:197], v[26:29]
	s_waitcnt lgkmcnt(1)
	v_mfma_f32_16x16x32_bf16 v[14:17], v[130:133], v[202:205], v[14:17]
	v_mfma_f32_16x16x32_bf16 v[10:13], v[138:141], v[202:205], v[10:13]
	v_mfma_f32_16x16x32_bf16 v[62:65], v[134:137], v[170:173], v[62:65]
	v_mfma_f32_16x16x32_bf16 v[58:61], v[142:145], v[170:173], v[58:61]
	v_mfma_f32_16x16x32_bf16 v[46:49], v[134:137], v[190:193], v[46:49]
	v_mfma_f32_16x16x32_bf16 v[42:45], v[142:145], v[190:193], v[42:45]
	v_mfma_f32_16x16x32_bf16 v[30:33], v[134:137], v[198:201], v[30:33]
	v_mfma_f32_16x16x32_bf16 v[26:29], v[142:145], v[198:201], v[26:29]
	s_waitcnt lgkmcnt(0)
	v_mfma_f32_16x16x32_bf16 v[14:17], v[134:137], v[206:209], v[14:17]
	v_mfma_f32_16x16x32_bf16 v[10:13], v[142:145], v[206:209], v[10:13]
	s_setprio 0
	s_setprio 1
	v_mfma_f32_16x16x32_bf16 v[54:57], v[146:149], v[166:169], v[54:57]
	v_mfma_f32_16x16x32_bf16 v[50:53], v[154:157], v[166:169], v[50:53]
	v_mfma_f32_16x16x32_bf16 v[38:41], v[146:149], v[186:189], v[38:41]
	v_mfma_f32_16x16x32_bf16 v[34:37], v[154:157], v[186:189], v[34:37]
	v_mfma_f32_16x16x32_bf16 v[22:25], v[146:149], v[194:197], v[22:25]
	v_mfma_f32_16x16x32_bf16 v[18:21], v[154:157], v[194:197], v[18:21]
	v_mfma_f32_16x16x32_bf16 v[6:9], v[146:149], v[202:205], v[6:9]
	v_mfma_f32_16x16x32_bf16 v[2:5], v[154:157], v[202:205], v[2:5]
	v_mfma_f32_16x16x32_bf16 v[54:57], v[150:153], v[170:173], v[54:57]
	v_mfma_f32_16x16x32_bf16 v[50:53], v[158:161], v[170:173], v[50:53]
	v_mfma_f32_16x16x32_bf16 v[38:41], v[150:153], v[190:193], v[38:41]
	v_mfma_f32_16x16x32_bf16 v[34:37], v[158:161], v[190:193], v[34:37]
	v_mfma_f32_16x16x32_bf16 v[22:25], v[150:153], v[198:201], v[22:25]
	v_mfma_f32_16x16x32_bf16 v[18:21], v[158:161], v[198:201], v[18:21]
	s_setprio 2
	s_barrier
	v_mfma_f32_16x16x32_bf16 v[6:9], v[150:153], v[206:209], v[6:9]
	v_mfma_f32_16x16x32_bf16 v[2:5], v[158:161], v[206:209], v[2:5]
	s_setprio 0
	s_add_i32 s78, s78, 2
	s_add_u32 s74, s74, 0x100
	s_addc_u32 s75, s75, 0
	s_add_u32 s24, s24, 0x100
	s_addc_u32 s25, s25, 0
	s_add_u32 s76, s76, 0x100
	s_addc_u32 s77, s77, 0
	s_cmp_gt_u32 s78, 29
	s_cbranch_scc0 .LBB0_2410
	s_and_b64 vcc, exec, s[8:9]
	s_cbranch_vccz .LBB0_2413
	s_barrier
.LBB0_2413:
	v_lshl_or_b32 v130, s23, 8, v180
	v_ashrrev_i32_e32 v131, 31, v130
	v_lshl_add_u32 v146, s22, 8, v179
	v_lshlrev_b64 v[166:167], 1, v[130:131]
	v_ashrrev_i32_e32 v147, 31, v146
	v_lshl_add_u64 v[168:169], s[6:7], 0, v[166:167]
	v_lshlrev_b64 v[170:171], 12, v[146:147]
	v_lshl_add_u64 v[132:133], v[168:169], 0, v[170:171]
	global_load_dwordx4 v[186:189], v[132:133], off
	global_load_dwordx4 v[190:193], v[132:133], off offset:256
	s_ashr_i32 s15, s22, 31
	v_or_b32_e32 v132, 16, v146
	s_lshr_b32 s15, s15, 28
	v_ashrrev_i32_e32 v133, 31, v132
	v_lshlrev_b64 v[202:203], 12, v[132:133]
	s_add_i32 s15, s22, s15
	v_lshl_add_u64 v[148:149], v[168:169], 0, v[202:203]
	s_ashr_i32 s15, s15, 4
	global_load_dwordx4 v[194:197], v[148:149], off
	s_mul_hi_i32 s17, s15, 0x12000
	s_mul_i32 s15, s15, 0x12000
	s_add_u32 s22, s62, s15
	s_addc_u32 s23, s63, s17
	v_lshl_add_u64 v[130:131], v[130:131], 2, s[22:23]
	global_load_dwordx4 v[142:145], v[130:131], off
	global_load_dwordx4 v[138:141], v[130:131], off offset:16
	global_load_dwordx4 v[134:137], v[130:131], off offset:512
	s_nop 0
	global_load_dwordx4 v[130:133], v[130:131], off offset:528
	s_nop 0
	global_load_dwordx4 v[198:201], v[148:149], off offset:256
	v_or_b32_e32 v148, 32, v146
	v_ashrrev_i32_e32 v149, 31, v148
	v_lshlrev_b64 v[174:175], 12, v[148:149]
	v_lshl_add_u64 v[148:149], v[168:169], 0, v[174:175]
	global_load_dwordx4 v[150:153], v[148:149], off
	v_or_b32_e32 v146, 48, v146
	v_ashrrev_i32_e32 v147, 31, v146
	v_lshlrev_b64 v[172:173], 12, v[146:147]
	v_lshl_add_u64 v[146:147], s[6:7], 0, v[170:171]
	v_lshl_add_u64 v[204:205], v[168:169], 0, v[172:173]
	v_lshl_add_u64 v[206:207], v[146:147], 0, v[166:167]
	global_load_dwordx4 v[158:161], v[148:149], off offset:256
	global_load_dwordx4 v[154:157], v[204:205], off
	s_nop 0
	global_load_dwordx4 v[146:149], v[204:205], off offset:256
	s_mov_b64 s[22:23], 0x80000
	s_andn2_b64 vcc, exec, s[2:3]
	s_mov_b64 s[2:3], -1
	s_waitcnt vmcnt(11)
	v_cvt_f32_f16_e32 v204, v186
	v_cvt_f32_f16_sdwa v205, v186 dst_sel:DWORD dst_unused:UNUSED_PAD src0_sel:WORD_1
	v_cvt_f32_f16_e32 v186, v187
	v_cvt_f32_f16_sdwa v187, v187 dst_sel:DWORD dst_unused:UNUSED_PAD src0_sel:WORD_1
	v_cvt_f32_f16_e32 v208, v188
	v_cvt_f32_f16_sdwa v209, v188 dst_sel:DWORD dst_unused:UNUSED_PAD src0_sel:WORD_1
	v_cvt_f32_f16_e32 v188, v189
	v_cvt_f32_f16_sdwa v189, v189 dst_sel:DWORD dst_unused:UNUSED_PAD src0_sel:WORD_1
	s_waitcnt vmcnt(10)
	v_cvt_f32_f16_e32 v210, v190
	v_cvt_f32_f16_sdwa v211, v190 dst_sel:DWORD dst_unused:UNUSED_PAD src0_sel:WORD_1
	v_cvt_f32_f16_e32 v190, v191
	v_cvt_f32_f16_sdwa v191, v191 dst_sel:DWORD dst_unused:UNUSED_PAD src0_sel:WORD_1
	v_cvt_f32_f16_e32 v212, v192
	v_cvt_f32_f16_sdwa v213, v192 dst_sel:DWORD dst_unused:UNUSED_PAD src0_sel:WORD_1
	v_cvt_f32_f16_e32 v192, v193
	v_cvt_f32_f16_sdwa v193, v193 dst_sel:DWORD dst_unused:UNUSED_PAD src0_sel:WORD_1
	s_waitcnt vmcnt(9)
	v_cvt_f32_f16_e32 v214, v194
	v_cvt_f32_f16_sdwa v215, v194 dst_sel:DWORD dst_unused:UNUSED_PAD src0_sel:WORD_1
	v_cvt_f32_f16_e32 v194, v195
	v_cvt_f32_f16_sdwa v195, v195 dst_sel:DWORD dst_unused:UNUSED_PAD src0_sel:WORD_1
	v_cvt_f32_f16_e32 v216, v196
	v_cvt_f32_f16_sdwa v217, v196 dst_sel:DWORD dst_unused:UNUSED_PAD src0_sel:WORD_1
	v_cvt_f32_f16_e32 v196, v197
	v_cvt_f32_f16_sdwa v197, v197 dst_sel:DWORD dst_unused:UNUSED_PAD src0_sel:WORD_1
	s_waitcnt vmcnt(8)
	v_pk_fma_f32 v[128:129], v[128:129], v[144:145], v[186:187]
	v_pk_fma_f32 v[126:127], v[126:127], v[142:143], v[204:205]
	s_waitcnt vmcnt(7)
	v_pk_fma_f32 v[124:125], v[124:125], v[140:141], v[188:189]
	v_pk_fma_f32 v[122:123], v[122:123], v[138:139], v[208:209]
	s_waitcnt vmcnt(6)
	v_pk_fma_f32 v[112:113], v[112:113], v[136:137], v[190:191]
	v_pk_fma_f32 v[110:111], v[110:111], v[134:135], v[210:211]
	s_waitcnt vmcnt(5)
	v_pk_fma_f32 v[186:187], v[108:109], v[132:133], v[192:193]
	v_pk_fma_f32 v[188:189], v[106:107], v[130:131], v[212:213]
	v_cvt_pk_f16_f32 v106, v126, v127
	v_cvt_pk_f16_f32 v107, v128, v129
	v_cvt_pk_f16_f32 v108, v122, v123
	v_cvt_pk_f16_f32 v109, v124, v125
	v_pk_fma_f32 v[120:121], v[120:121], v[144:145], v[194:195]
	v_pk_fma_f32 v[118:119], v[118:119], v[142:143], v[214:215]
	v_pk_fma_f32 v[190:191], v[116:117], v[140:141], v[196:197]
	v_pk_fma_f32 v[116:117], v[114:115], v[138:139], v[216:217]
	v_cvt_pk_f16_f32 v110, v110, v111
	v_cvt_pk_f16_f32 v111, v112, v113
	v_cvt_pk_f16_f32 v112, v188, v189
	v_cvt_pk_f16_f32 v113, v186, v187
	global_store_dwordx4 v[206:207], v[106:109], off
	global_store_dwordx4 v[206:207], v[110:113], off offset:256
	v_cvt_pk_f16_f32 v114, v118, v119
	v_lshl_add_u64 v[106:107], s[6:7], 0, v[202:203]
	v_cvt_pk_f16_f32 v115, v120, v121
	v_cvt_pk_f16_f32 v116, v116, v117
	v_cvt_pk_f16_f32 v117, v190, v191
	v_lshl_add_u64 v[106:107], v[106:107], 0, v[166:167]
	global_store_dwordx4 v[106:107], v[114:117], off
	s_waitcnt vmcnt(7)
	v_cvt_f32_f16_e32 v108, v198
	v_cvt_f32_f16_sdwa v109, v198 dst_sel:DWORD dst_unused:UNUSED_PAD src0_sel:WORD_1
	v_cvt_f32_f16_e32 v110, v199
	v_cvt_f32_f16_sdwa v111, v199 dst_sel:DWORD dst_unused:UNUSED_PAD src0_sel:WORD_1
	v_cvt_f32_f16_e32 v112, v200
	v_cvt_f32_f16_e32 v114, v201
	v_cvt_f32_f16_sdwa v115, v201 dst_sel:DWORD dst_unused:UNUSED_PAD src0_sel:WORD_1
	v_cvt_f32_f16_sdwa v113, v200 dst_sel:DWORD dst_unused:UNUSED_PAD src0_sel:WORD_1
	v_pk_fma_f32 v[104:105], v[104:105], v[136:137], v[110:111]
	v_pk_fma_f32 v[102:103], v[102:103], v[134:135], v[108:109]
	v_pk_fma_f32 v[108:109], v[100:101], v[132:133], v[114:115]
	v_pk_fma_f32 v[100:101], v[98:99], v[130:131], v[112:113]
	v_lshl_add_u64 v[110:111], v[170:171], 0, s[22:23]
	v_cvt_pk_f16_f32 v98, v102, v103
	v_cvt_pk_f16_f32 v99, v104, v105
	v_cvt_pk_f16_f32 v100, v100, v101
	v_cvt_pk_f16_f32 v101, v108, v109
	v_lshl_add_u64 v[112:113], v[168:169], 0, v[110:111]
	global_store_dwordx4 v[106:107], v[98:101], off offset:256
	s_waitcnt vmcnt(7)
	v_cvt_f32_f16_e32 v102, v150
	v_cvt_f32_f16_sdwa v103, v150 dst_sel:DWORD dst_unused:UNUSED_PAD src0_sel:WORD_1
	v_cvt_f32_f16_e32 v104, v151
	v_cvt_f32_f16_sdwa v105, v151 dst_sel:DWORD dst_unused:UNUSED_PAD src0_sel:WORD_1
	v_cvt_f32_f16_e32 v106, v152
	v_cvt_f32_f16_e32 v108, v153
	global_load_dwordx4 v[98:101], v[112:113], off
	v_cvt_f32_f16_sdwa v109, v153 dst_sel:DWORD dst_unused:UNUSED_PAD src0_sel:WORD_1
	v_cvt_f32_f16_sdwa v107, v152 dst_sel:DWORD dst_unused:UNUSED_PAD src0_sel:WORD_1
	v_pk_fma_f32 v[96:97], v[96:97], v[144:145], v[104:105]
	v_pk_fma_f32 v[94:95], v[94:95], v[142:143], v[102:103]
	v_pk_fma_f32 v[102:103], v[92:93], v[140:141], v[108:109]
	v_pk_fma_f32 v[92:93], v[90:91], v[138:139], v[106:107]
	v_cvt_pk_f16_f32 v90, v94, v95
	v_cvt_pk_f16_f32 v91, v96, v97
	v_cvt_pk_f16_f32 v92, v92, v93
	v_cvt_pk_f16_f32 v93, v102, v103
	v_lshl_add_u64 v[94:95], s[6:7], 0, v[174:175]
	s_waitcnt vmcnt(7)
	v_cvt_f32_f16_e32 v96, v158
	v_cvt_f32_f16_sdwa v97, v158 dst_sel:DWORD dst_unused:UNUSED_PAD src0_sel:WORD_1
	v_cvt_f32_f16_e32 v102, v159
	v_cvt_f32_f16_sdwa v103, v159 dst_sel:DWORD dst_unused:UNUSED_PAD src0_sel:WORD_1
	v_cvt_f32_f16_e32 v104, v160
	v_cvt_f32_f16_e32 v106, v161
	v_cvt_f32_f16_sdwa v107, v161 dst_sel:DWORD dst_unused:UNUSED_PAD src0_sel:WORD_1
	v_cvt_f32_f16_sdwa v105, v160 dst_sel:DWORD dst_unused:UNUSED_PAD src0_sel:WORD_1
	v_lshl_add_u64 v[94:95], v[94:95], 0, v[166:167]
	global_store_dwordx4 v[94:95], v[90:93], off
	global_load_dwordx4 v[90:93], v[112:113], off offset:256
	v_pk_fma_f32 v[84:85], v[84:85], v[136:137], v[102:103]
	v_pk_fma_f32 v[82:83], v[82:83], v[134:135], v[96:97]
	v_pk_fma_f32 v[96:97], v[76:77], v[132:133], v[106:107]
	v_pk_fma_f32 v[76:77], v[74:75], v[130:131], v[104:105]
	v_cvt_pk_f16_f32 v74, v82, v83
	v_cvt_pk_f16_f32 v75, v84, v85
	v_cvt_pk_f16_f32 v76, v76, v77
	v_cvt_pk_f16_f32 v77, v96, v97
	s_mov_b64 s[22:23], 0x90000
	global_store_dwordx4 v[94:95], v[74:77], off offset:256
	v_lshl_add_u64 v[94:95], v[170:171], 0, s[22:23]
	v_lshl_add_u64 v[84:85], v[168:169], 0, v[94:95]
	s_waitcnt vmcnt(9)
	v_cvt_f32_f16_e32 v82, v154
	v_cvt_f32_f16_sdwa v83, v154 dst_sel:DWORD dst_unused:UNUSED_PAD src0_sel:WORD_1
	global_load_dwordx4 v[74:77], v[84:85], off
	v_cvt_f32_f16_e32 v96, v155
	v_cvt_f32_f16_sdwa v97, v155 dst_sel:DWORD dst_unused:UNUSED_PAD src0_sel:WORD_1
	v_cvt_f32_f16_e32 v102, v156
	v_cvt_f32_f16_e32 v104, v157
	v_cvt_f32_f16_sdwa v105, v157 dst_sel:DWORD dst_unused:UNUSED_PAD src0_sel:WORD_1
	v_cvt_f32_f16_sdwa v103, v156 dst_sel:DWORD dst_unused:UNUSED_PAD src0_sel:WORD_1
	v_pk_fma_f32 v[82:83], v[86:87], v[142:143], v[82:83]
	v_pk_fma_f32 v[88:89], v[88:89], v[144:145], v[96:97]
	v_pk_fma_f32 v[86:87], v[80:81], v[140:141], v[104:105]
	v_pk_fma_f32 v[80:81], v[78:79], v[138:139], v[102:103]
	v_cvt_pk_f16_f32 v78, v82, v83
	v_lshl_add_u64 v[82:83], s[6:7], 0, v[172:173]
	v_cvt_pk_f16_f32 v79, v88, v89
	v_cvt_pk_f16_f32 v80, v80, v81
	v_cvt_pk_f16_f32 v81, v86, v87
	v_lshl_add_u64 v[82:83], v[82:83], 0, v[166:167]
	global_store_dwordx4 v[82:83], v[78:81], off
	global_load_dwordx4 v[78:81], v[84:85], off offset:256
	s_waitcnt vmcnt(11)
	v_cvt_f32_f16_e32 v84, v147
	v_cvt_f32_f16_sdwa v85, v147 dst_sel:DWORD dst_unused:UNUSED_PAD src0_sel:WORD_1
	v_cvt_f32_f16_e32 v96, v149
	v_cvt_f32_f16_sdwa v97, v149 dst_sel:DWORD dst_unused:UNUSED_PAD src0_sel:WORD_1
	v_cvt_f32_f16_e32 v86, v146
	v_cvt_f32_f16_sdwa v87, v146 dst_sel:DWORD dst_unused:UNUSED_PAD src0_sel:WORD_1
	v_cvt_f32_f16_e32 v88, v148
	v_cvt_f32_f16_sdwa v89, v148 dst_sel:DWORD dst_unused:UNUSED_PAD src0_sel:WORD_1
	v_pk_fma_f32 v[72:73], v[72:73], v[136:137], v[84:85]
	v_pk_fma_f32 v[84:85], v[68:69], v[132:133], v[96:97]
	v_lshl_add_u64 v[96:97], v[170:171], 0, s[10:11]
	v_pk_fma_f32 v[70:71], v[70:71], v[134:135], v[86:87]
	v_lshl_add_u64 v[86:87], v[168:169], 0, v[96:97]
	v_pk_fma_f32 v[68:69], v[66:67], v[130:131], v[88:89]
	v_cvt_pk_f16_f32 v66, v70, v71
	v_cvt_pk_f16_f32 v67, v72, v73
	global_load_dwordx4 v[70:73], v[86:87], off
	v_cvt_pk_f16_f32 v68, v68, v69
	v_cvt_pk_f16_f32 v69, v84, v85
	global_store_dwordx4 v[82:83], v[66:69], off offset:256
	global_load_dwordx4 v[82:85], v[86:87], off offset:256
	v_lshl_add_u64 v[102:103], v[170:171], 0, s[12:13]
	v_lshl_add_u64 v[66:67], v[168:169], 0, v[102:103]
	global_load_dwordx4 v[86:89], v[66:67], off
	s_nop 0
	global_load_dwordx4 v[66:69], v[66:67], off offset:256
	s_waitcnt vmcnt(11)
	v_cvt_f32_f16_e32 v104, v98
	v_cvt_f32_f16_sdwa v105, v98 dst_sel:DWORD dst_unused:UNUSED_PAD src0_sel:WORD_1
	v_cvt_f32_f16_e32 v98, v99
	v_cvt_f32_f16_sdwa v99, v99 dst_sel:DWORD dst_unused:UNUSED_PAD src0_sel:WORD_1
	v_cvt_f32_f16_e32 v106, v100
	v_cvt_f32_f16_e32 v108, v101
	v_cvt_f32_f16_sdwa v109, v101 dst_sel:DWORD dst_unused:UNUSED_PAD src0_sel:WORD_1
	v_cvt_f32_f16_sdwa v107, v100 dst_sel:DWORD dst_unused:UNUSED_PAD src0_sel:WORD_1
	v_pk_fma_f32 v[62:63], v[62:63], v[142:143], v[104:105]
	v_pk_fma_f32 v[64:65], v[64:65], v[144:145], v[98:99]
	v_pk_fma_f32 v[98:99], v[60:61], v[140:141], v[108:109]
	v_pk_fma_f32 v[60:61], v[58:59], v[138:139], v[106:107]
	v_cvt_pk_f16_f32 v58, v62, v63
	v_lshl_add_u64 v[62:63], s[6:7], 0, v[110:111]
	v_cvt_pk_f16_f32 v59, v64, v65
	v_cvt_pk_f16_f32 v60, v60, v61
	v_cvt_pk_f16_f32 v61, v98, v99
	v_lshl_add_u64 v[62:63], v[62:63], 0, v[166:167]
	global_store_dwordx4 v[62:63], v[58:61], off
	s_waitcnt vmcnt(10)
	v_cvt_f32_f16_e32 v64, v92
	v_cvt_f32_f16_e32 v58, v90
	v_cvt_f32_f16_sdwa v59, v90 dst_sel:DWORD dst_unused:UNUSED_PAD src0_sel:WORD_1
	v_cvt_f32_f16_e32 v60, v91
	v_cvt_f32_f16_sdwa v61, v91 dst_sel:DWORD dst_unused:UNUSED_PAD src0_sel:WORD_1
	v_cvt_f32_f16_e32 v90, v93
	v_cvt_f32_f16_sdwa v91, v93 dst_sel:DWORD dst_unused:UNUSED_PAD src0_sel:WORD_1
	v_cvt_f32_f16_sdwa v65, v92 dst_sel:DWORD dst_unused:UNUSED_PAD src0_sel:WORD_1
	v_pk_fma_f32 v[56:57], v[56:57], v[136:137], v[60:61]
	v_pk_fma_f32 v[54:55], v[54:55], v[134:135], v[58:59]
	v_pk_fma_f32 v[58:59], v[52:53], v[132:133], v[90:91]
	v_pk_fma_f32 v[52:53], v[50:51], v[130:131], v[64:65]
	v_cvt_pk_f16_f32 v50, v54, v55
	v_cvt_pk_f16_f32 v51, v56, v57
	v_cvt_pk_f16_f32 v52, v52, v53
	v_cvt_pk_f16_f32 v53, v58, v59
	global_store_dwordx4 v[62:63], v[50:53], off offset:256
	s_waitcnt vmcnt(9)
	v_cvt_f32_f16_e32 v54, v76
	v_cvt_f32_f16_e32 v56, v77
	v_cvt_f32_f16_e32 v50, v74
	v_cvt_f32_f16_sdwa v51, v74 dst_sel:DWORD dst_unused:UNUSED_PAD src0_sel:WORD_1
	v_cvt_f32_f16_e32 v52, v75
	v_cvt_f32_f16_sdwa v53, v75 dst_sel:DWORD dst_unused:UNUSED_PAD src0_sel:WORD_1
	v_cvt_f32_f16_sdwa v57, v77 dst_sel:DWORD dst_unused:UNUSED_PAD src0_sel:WORD_1
	v_cvt_f32_f16_sdwa v55, v76 dst_sel:DWORD dst_unused:UNUSED_PAD src0_sel:WORD_1
	v_pk_fma_f32 v[46:47], v[46:47], v[142:143], v[50:51]
	v_pk_fma_f32 v[48:49], v[48:49], v[144:145], v[52:53]
	v_pk_fma_f32 v[50:51], v[44:45], v[140:141], v[56:57]
	v_pk_fma_f32 v[44:45], v[42:43], v[138:139], v[54:55]
	v_cvt_pk_f16_f32 v42, v46, v47
	v_lshl_add_u64 v[46:47], s[6:7], 0, v[94:95]
	v_cvt_pk_f16_f32 v43, v48, v49
	v_cvt_pk_f16_f32 v44, v44, v45
	v_cvt_pk_f16_f32 v45, v50, v51
	v_lshl_add_u64 v[46:47], v[46:47], 0, v[166:167]
	global_store_dwordx4 v[46:47], v[42:45], off
	s_waitcnt vmcnt(8)
	v_cvt_f32_f16_e32 v48, v80
	v_cvt_f32_f16_e32 v50, v81
	v_cvt_f32_f16_e32 v42, v78
	v_cvt_f32_f16_sdwa v43, v78 dst_sel:DWORD dst_unused:UNUSED_PAD src0_sel:WORD_1
	v_cvt_f32_f16_e32 v44, v79
	v_cvt_f32_f16_sdwa v45, v79 dst_sel:DWORD dst_unused:UNUSED_PAD src0_sel:WORD_1
	v_cvt_f32_f16_sdwa v51, v81 dst_sel:DWORD dst_unused:UNUSED_PAD src0_sel:WORD_1
	v_cvt_f32_f16_sdwa v49, v80 dst_sel:DWORD dst_unused:UNUSED_PAD src0_sel:WORD_1
	v_pk_fma_f32 v[38:39], v[38:39], v[134:135], v[42:43]
	v_pk_fma_f32 v[40:41], v[40:41], v[136:137], v[44:45]
	v_pk_fma_f32 v[42:43], v[36:37], v[132:133], v[50:51]
	v_pk_fma_f32 v[36:37], v[34:35], v[130:131], v[48:49]
	v_cvt_pk_f16_f32 v34, v38, v39
	v_cvt_pk_f16_f32 v35, v40, v41
	v_cvt_pk_f16_f32 v36, v36, v37
	v_cvt_pk_f16_f32 v37, v42, v43
	global_store_dwordx4 v[46:47], v[34:37], off offset:256
	s_waitcnt vmcnt(8)
	v_cvt_f32_f16_e32 v38, v72
	v_cvt_f32_f16_e32 v40, v73
	v_cvt_f32_f16_e32 v34, v70
	v_cvt_f32_f16_sdwa v35, v70 dst_sel:DWORD dst_unused:UNUSED_PAD src0_sel:WORD_1
	v_cvt_f32_f16_e32 v36, v71
	v_cvt_f32_f16_sdwa v37, v71 dst_sel:DWORD dst_unused:UNUSED_PAD src0_sel:WORD_1
	v_cvt_f32_f16_sdwa v41, v73 dst_sel:DWORD dst_unused:UNUSED_PAD src0_sel:WORD_1
	v_cvt_f32_f16_sdwa v39, v72 dst_sel:DWORD dst_unused:UNUSED_PAD src0_sel:WORD_1
	v_pk_fma_f32 v[30:31], v[30:31], v[142:143], v[34:35]
	v_pk_fma_f32 v[32:33], v[32:33], v[144:145], v[36:37]
	v_pk_fma_f32 v[34:35], v[28:29], v[140:141], v[40:41]
	v_pk_fma_f32 v[28:29], v[26:27], v[138:139], v[38:39]
	v_cvt_pk_f16_f32 v26, v30, v31
	v_lshl_add_u64 v[30:31], s[6:7], 0, v[96:97]
	v_cvt_pk_f16_f32 v27, v32, v33
	v_cvt_pk_f16_f32 v28, v28, v29
	v_cvt_pk_f16_f32 v29, v34, v35
	v_lshl_add_u64 v[30:31], v[30:31], 0, v[166:167]
	global_store_dwordx4 v[30:31], v[26:29], off
	s_waitcnt vmcnt(7)
	v_cvt_f32_f16_e32 v32, v84
	v_cvt_f32_f16_e32 v34, v85
	v_cvt_f32_f16_e32 v26, v82
	v_cvt_f32_f16_sdwa v27, v82 dst_sel:DWORD dst_unused:UNUSED_PAD src0_sel:WORD_1
	v_cvt_f32_f16_e32 v28, v83
	v_cvt_f32_f16_sdwa v29, v83 dst_sel:DWORD dst_unused:UNUSED_PAD src0_sel:WORD_1
	v_cvt_f32_f16_sdwa v35, v85 dst_sel:DWORD dst_unused:UNUSED_PAD src0_sel:WORD_1
	v_cvt_f32_f16_sdwa v33, v84 dst_sel:DWORD dst_unused:UNUSED_PAD src0_sel:WORD_1
	v_pk_fma_f32 v[22:23], v[22:23], v[134:135], v[26:27]
	v_pk_fma_f32 v[24:25], v[24:25], v[136:137], v[28:29]
	v_pk_fma_f32 v[26:27], v[20:21], v[132:133], v[34:35]
	v_pk_fma_f32 v[20:21], v[18:19], v[130:131], v[32:33]
	v_cvt_pk_f16_f32 v18, v22, v23
	v_cvt_pk_f16_f32 v19, v24, v25
	v_cvt_pk_f16_f32 v20, v20, v21
	v_cvt_pk_f16_f32 v21, v26, v27
	global_store_dwordx4 v[30:31], v[18:21], off offset:256
	s_waitcnt vmcnt(7)
	v_cvt_f32_f16_e32 v22, v88
	v_cvt_f32_f16_e32 v24, v89
	v_cvt_f32_f16_e32 v18, v86
	v_cvt_f32_f16_sdwa v19, v86 dst_sel:DWORD dst_unused:UNUSED_PAD src0_sel:WORD_1
	v_cvt_f32_f16_e32 v20, v87
	v_cvt_f32_f16_sdwa v21, v87 dst_sel:DWORD dst_unused:UNUSED_PAD src0_sel:WORD_1
	v_cvt_f32_f16_sdwa v25, v89 dst_sel:DWORD dst_unused:UNUSED_PAD src0_sel:WORD_1
	v_cvt_f32_f16_sdwa v23, v88 dst_sel:DWORD dst_unused:UNUSED_PAD src0_sel:WORD_1
	v_pk_fma_f32 v[14:15], v[14:15], v[142:143], v[18:19]
	v_pk_fma_f32 v[16:17], v[16:17], v[144:145], v[20:21]
	v_pk_fma_f32 v[18:19], v[12:13], v[140:141], v[24:25]
	v_pk_fma_f32 v[12:13], v[10:11], v[138:139], v[22:23]
	v_cvt_pk_f16_f32 v10, v14, v15
	v_lshl_add_u64 v[14:15], s[6:7], 0, v[102:103]
	v_cvt_pk_f16_f32 v11, v16, v17
	v_cvt_pk_f16_f32 v12, v12, v13
	v_cvt_pk_f16_f32 v13, v18, v19
	v_lshl_add_u64 v[14:15], v[14:15], 0, v[166:167]
	global_store_dwordx4 v[14:15], v[10:13], off
	s_waitcnt vmcnt(7)
	v_cvt_f32_f16_e32 v16, v68
	v_cvt_f32_f16_e32 v18, v69
	v_cvt_f32_f16_e32 v10, v66
	v_cvt_f32_f16_sdwa v11, v66 dst_sel:DWORD dst_unused:UNUSED_PAD src0_sel:WORD_1
	v_cvt_f32_f16_e32 v12, v67
	v_cvt_f32_f16_sdwa v13, v67 dst_sel:DWORD dst_unused:UNUSED_PAD src0_sel:WORD_1
	v_cvt_f32_f16_sdwa v19, v69 dst_sel:DWORD dst_unused:UNUSED_PAD src0_sel:WORD_1
	v_cvt_f32_f16_sdwa v17, v68 dst_sel:DWORD dst_unused:UNUSED_PAD src0_sel:WORD_1
	v_pk_fma_f32 v[6:7], v[6:7], v[134:135], v[10:11]
	v_pk_fma_f32 v[8:9], v[8:9], v[136:137], v[12:13]
	v_pk_fma_f32 v[10:11], v[4:5], v[132:133], v[18:19]
	v_pk_fma_f32 v[4:5], v[2:3], v[130:131], v[16:17]
	v_cvt_pk_f16_f32 v2, v6, v7
	v_cvt_pk_f16_f32 v3, v8, v9
	v_cvt_pk_f16_f32 v4, v4, v5
	v_cvt_pk_f16_f32 v5, v10, v11
	global_store_dwordx4 v[14:15], v[2:5], off offset:256
	s_cbranch_vccnz .LBB0_2402
	s_andn2_b64 vcc, exec, s[4:5]
	s_cbranch_vccnz .LBB0_2401
	s_mov_b32 s99, 1
	s_branch .LBB0_2401

.LBB0_2593:
	s_ashr_i32 s11, s10, 31
	s_lshl_b64 s[12:13], s[10:11], 20
	s_add_u32 s12, s26, s12
	s_addc_u32 s13, s27, s13
	s_and_b64 s[14:15], s[2:3], exec
	s_cselect_b32 s11, s13, s21
	s_cselect_b32 s62, s12, s20
	s_ashr_i32 s9, s8, 31
	s_lshl_b64 s[14:15], s[8:9], 20
	s_add_u32 s14, s28, s14
	s_addc_u32 s15, s29, s15
	s_and_b64 s[22:23], s[2:3], exec
	s_cselect_b32 s9, s15, s19
	s_cselect_b32 s63, s14, s18
	s_add_u32 s64, s18, 0x100
	s_addc_u32 s65, s19, 0
	s_add_u32 s18, s20, 0x80080
	s_addc_u32 s19, s21, 0
	s_add_u32 s66, s20, 0x100
	v_mov_b32_e32 v2, 0
	s_addc_u32 s67, s21, 0
	s_mov_b32 s70, -2
	v_mov_b32_e32 v3, v2
	v_mov_b32_e32 v4, v2
	v_mov_b32_e32 v5, v2
	v_mov_b32_e32 v6, v2
	v_mov_b32_e32 v7, v2
	v_mov_b32_e32 v8, v2
	v_mov_b32_e32 v9, v2
	v_mov_b32_e32 v18, v2
	v_mov_b32_e32 v19, v2
	v_mov_b32_e32 v20, v2
	v_mov_b32_e32 v21, v2
	v_mov_b32_e32 v22, v2
	v_mov_b32_e32 v23, v2
	v_mov_b32_e32 v24, v2
	v_mov_b32_e32 v25, v2
	v_mov_b32_e32 v34, v2
	v_mov_b32_e32 v35, v2
	v_mov_b32_e32 v36, v2
	v_mov_b32_e32 v37, v2
	v_mov_b32_e32 v38, v2
	v_mov_b32_e32 v39, v2
	v_mov_b32_e32 v40, v2
	v_mov_b32_e32 v41, v2
	v_mov_b32_e32 v50, v2
	v_mov_b32_e32 v51, v2
	v_mov_b32_e32 v52, v2
	v_mov_b32_e32 v53, v2
	v_mov_b32_e32 v54, v2
	v_mov_b32_e32 v55, v2
	v_mov_b32_e32 v56, v2
	v_mov_b32_e32 v57, v2
	v_mov_b32_e32 v10, v2
	v_mov_b32_e32 v11, v2
	v_mov_b32_e32 v12, v2
	v_mov_b32_e32 v13, v2
	v_mov_b32_e32 v14, v2
	v_mov_b32_e32 v15, v2
	v_mov_b32_e32 v16, v2
	v_mov_b32_e32 v17, v2
	v_mov_b32_e32 v26, v2
	v_mov_b32_e32 v27, v2
	v_mov_b32_e32 v28, v2
	v_mov_b32_e32 v29, v2
	v_mov_b32_e32 v30, v2
	v_mov_b32_e32 v31, v2
	v_mov_b32_e32 v32, v2
	v_mov_b32_e32 v33, v2
	v_mov_b32_e32 v42, v2
	v_mov_b32_e32 v43, v2
	v_mov_b32_e32 v44, v2
	v_mov_b32_e32 v45, v2
	v_mov_b32_e32 v46, v2
	v_mov_b32_e32 v47, v2
	v_mov_b32_e32 v48, v2
	v_mov_b32_e32 v49, v2
	v_mov_b32_e32 v58, v2
	v_mov_b32_e32 v59, v2
	v_mov_b32_e32 v60, v2
	v_mov_b32_e32 v61, v2
	v_mov_b32_e32 v62, v2
	v_mov_b32_e32 v63, v2
	v_mov_b32_e32 v64, v2
	v_mov_b32_e32 v65, v2
	v_mov_b32_e32 v66, v2
	v_mov_b32_e32 v67, v2
	v_mov_b32_e32 v68, v2
	v_mov_b32_e32 v69, v2
	v_mov_b32_e32 v70, v2
	v_mov_b32_e32 v71, v2
	v_mov_b32_e32 v72, v2
	v_mov_b32_e32 v73, v2
	v_mov_b32_e32 v82, v2
	v_mov_b32_e32 v83, v2
	v_mov_b32_e32 v84, v2
	v_mov_b32_e32 v85, v2
	v_mov_b32_e32 v86, v2
	v_mov_b32_e32 v87, v2
	v_mov_b32_e32 v88, v2
	v_mov_b32_e32 v89, v2
	v_mov_b32_e32 v98, v2
	v_mov_b32_e32 v99, v2
	v_mov_b32_e32 v100, v2
	v_mov_b32_e32 v101, v2
	v_mov_b32_e32 v102, v2
	v_mov_b32_e32 v103, v2
	v_mov_b32_e32 v104, v2
	v_mov_b32_e32 v105, v2
	v_mov_b32_e32 v114, v2
	v_mov_b32_e32 v115, v2
	v_mov_b32_e32 v116, v2
	v_mov_b32_e32 v117, v2
	v_mov_b32_e32 v118, v2
	v_mov_b32_e32 v119, v2
	v_mov_b32_e32 v120, v2
	v_mov_b32_e32 v121, v2
	v_mov_b32_e32 v74, v2
	v_mov_b32_e32 v75, v2
	v_mov_b32_e32 v76, v2
	v_mov_b32_e32 v77, v2
	v_mov_b32_e32 v78, v2
	v_mov_b32_e32 v79, v2
	v_mov_b32_e32 v80, v2
	v_mov_b32_e32 v81, v2
	v_mov_b32_e32 v90, v2
	v_mov_b32_e32 v91, v2
	v_mov_b32_e32 v92, v2
	v_mov_b32_e32 v93, v2
	v_mov_b32_e32 v94, v2
	v_mov_b32_e32 v95, v2
	v_mov_b32_e32 v96, v2
	v_mov_b32_e32 v97, v2
	v_mov_b32_e32 v106, v2
	v_mov_b32_e32 v107, v2
	v_mov_b32_e32 v108, v2
	v_mov_b32_e32 v109, v2
	v_mov_b32_e32 v110, v2
	v_mov_b32_e32 v111, v2
	v_mov_b32_e32 v112, v2
	v_mov_b32_e32 v113, v2
	v_mov_b32_e32 v122, v2
	v_mov_b32_e32 v123, v2
	v_mov_b32_e32 v124, v2
	v_mov_b32_e32 v125, v2
	v_mov_b32_e32 v126, v2
	v_mov_b32_e32 v127, v2
	v_mov_b32_e32 v128, v2
	v_mov_b32_e32 v129, v2
	s_cmp_eq_u32 s99, 0
	s_cbranch_scc1 .Lro_skip_2
	s_barrier
	s_mov_b32 s99, 0
.Lro_skip_2:
.LBB0_2594:
	ds_read_b128 v[148:151], v143
	ds_read_b128 v[152:155], v143 offset:1024
	ds_read_b128 v[156:159], v143 offset:2048
	ds_read_b128 v[160:163], v143 offset:3072
	ds_read_b128 v[164:167], v144
	ds_read_b128 v[168:171], v144 offset:1024
	ds_read_b128 v[172:175], v144 offset:2048
	ds_read_b128 v[176:179], v144 offset:3072
	s_cmp_eq_u32 s70, 28
	s_cselect_b32 s21, s9, s65
	s_cselect_b32 s20, s63, s64
	s_cselect_b32 s23, s11, s67
	s_cselect_b32 s22, s62, s66
	ds_read_b128 v[180:183], v145
	ds_read_b128 v[184:187], v145 offset:1024
	ds_read_b128 v[188:191], v145 offset:2048
	ds_read_b128 v[192:195], v145 offset:3072
	ds_read_b128 v[196:199], v145 offset:4096
	ds_read_b128 v[200:203], v145 offset:5120
	ds_read_b128 v[204:207], v145 offset:6144
	ds_read_b128 v[208:211], v145 offset:7168
	s_add_u32 s74, s18, 0xfff80000
	s_addc_u32 s75, s19, -1
	s_mov_b32 s71, m0
	s_mov_b32 m0, s48
	s_nop 0
	global_load_lds_dwordx4 v138, s[74:75]
	s_mov_b32 m0, s71
	s_nop 0
	s_mov_b32 s71, m0
	s_mov_b32 m0, s57
	s_nop 0
	global_load_lds_dwordx4 v140, s[74:75]
	s_mov_b32 m0, s71
	s_nop 0
	s_mov_b32 s71, m0
	s_mov_b32 m0, s49
	s_nop 0
	global_load_lds_dwordx4 v138, s[18:19]
	s_mov_b32 m0, s71
	s_nop 0
	s_mov_b32 s71, m0
	s_mov_b32 m0, s58
	s_nop 0
	global_load_lds_dwordx4 v140, s[18:19]
	s_mov_b32 m0, s71
	s_waitcnt vmcnt(8)
	s_waitcnt lgkmcnt(0)
	s_barrier
	s_setprio 1
	s_waitcnt lgkmcnt(7)
	v_mfma_f32_16x16x32_bf16 v[126:129], v[148:151], v[180:183], v[126:129]
	v_mfma_f32_16x16x32_bf16 v[122:125], v[156:159], v[180:183], v[122:125]
	s_waitcnt lgkmcnt(5)
	v_mfma_f32_16x16x32_bf16 v[110:113], v[148:151], v[188:191], v[110:113]
	v_mfma_f32_16x16x32_bf16 v[106:109], v[156:159], v[188:191], v[106:109]
	s_waitcnt lgkmcnt(3)
	v_mfma_f32_16x16x32_bf16 v[94:97], v[148:151], v[196:199], v[94:97]
	v_mfma_f32_16x16x32_bf16 v[90:93], v[156:159], v[196:199], v[90:93]
	s_waitcnt lgkmcnt(1)
	v_mfma_f32_16x16x32_bf16 v[78:81], v[148:151], v[204:207], v[78:81]
	v_mfma_f32_16x16x32_bf16 v[74:77], v[156:159], v[204:207], v[74:77]
	v_mfma_f32_16x16x32_bf16 v[126:129], v[152:155], v[184:187], v[126:129]
	v_mfma_f32_16x16x32_bf16 v[122:125], v[160:163], v[184:187], v[122:125]
	v_mfma_f32_16x16x32_bf16 v[110:113], v[152:155], v[192:195], v[110:113]
	v_mfma_f32_16x16x32_bf16 v[106:109], v[160:163], v[192:195], v[106:109]
	v_mfma_f32_16x16x32_bf16 v[94:97], v[152:155], v[200:203], v[94:97]
	v_mfma_f32_16x16x32_bf16 v[90:93], v[160:163], v[200:203], v[90:93]
	s_waitcnt lgkmcnt(0)
	v_mfma_f32_16x16x32_bf16 v[78:81], v[152:155], v[208:211], v[78:81]
	v_mfma_f32_16x16x32_bf16 v[74:77], v[160:163], v[208:211], v[74:77]
	s_setprio 0
	s_setprio 1
	v_mfma_f32_16x16x32_bf16 v[118:121], v[164:167], v[180:183], v[118:121]
	v_mfma_f32_16x16x32_bf16 v[114:117], v[172:175], v[180:183], v[114:117]
	v_mfma_f32_16x16x32_bf16 v[102:105], v[164:167], v[188:191], v[102:105]
	v_mfma_f32_16x16x32_bf16 v[98:101], v[172:175], v[188:191], v[98:101]
	v_mfma_f32_16x16x32_bf16 v[86:89], v[164:167], v[196:199], v[86:89]
	v_mfma_f32_16x16x32_bf16 v[82:85], v[172:175], v[196:199], v[82:85]
	v_mfma_f32_16x16x32_bf16 v[70:73], v[164:167], v[204:207], v[70:73]
	v_mfma_f32_16x16x32_bf16 v[66:69], v[172:175], v[204:207], v[66:69]
	v_mfma_f32_16x16x32_bf16 v[118:121], v[168:171], v[184:187], v[118:121]
	v_mfma_f32_16x16x32_bf16 v[114:117], v[176:179], v[184:187], v[114:117]
	v_mfma_f32_16x16x32_bf16 v[102:105], v[168:171], v[192:195], v[102:105]
	v_mfma_f32_16x16x32_bf16 v[98:101], v[176:179], v[192:195], v[98:101]
	v_mfma_f32_16x16x32_bf16 v[86:89], v[168:171], v[200:203], v[86:89]
	v_mfma_f32_16x16x32_bf16 v[82:85], v[176:179], v[200:203], v[82:85]
	s_setprio 2
	s_barrier
	v_mfma_f32_16x16x32_bf16 v[70:73], v[168:171], v[208:211], v[70:73]
	v_mfma_f32_16x16x32_bf16 v[66:69], v[176:179], v[208:211], v[66:69]
	s_setprio 0
	ds_read_b128 v[180:183], v145 offset:16384
	ds_read_b128 v[184:187], v145 offset:17408
	ds_read_b128 v[188:191], v145 offset:18432
	ds_read_b128 v[192:195], v145 offset:19456
	ds_read_b128 v[196:199], v145 offset:20480
	ds_read_b128 v[200:203], v145 offset:21504
	ds_read_b128 v[204:207], v145 offset:22528
	ds_read_b128 v[208:211], v145 offset:23552
	s_mov_b32 s71, m0
	s_mov_b32 m0, s35
	s_nop 0
	global_load_lds_dwordx4 v139, s[20:21]
	s_mov_b32 m0, s71
	s_add_u32 s74, s20, 0x80000
	s_mov_b32 s71, m0
	s_mov_b32 m0, s36
	s_nop 0
	global_load_lds_dwordx4 v141, s[20:21]
	s_mov_b32 m0, s71
	s_addc_u32 s75, s21, 0
	s_mov_b32 s71, m0
	s_mov_b32 m0, s37
	s_nop 0
	global_load_lds_dwordx4 v139, s[74:75]
	s_mov_b32 m0, s71
	s_nop 0
	s_mov_b32 s71, m0
	s_mov_b32 m0, s40
	s_nop 0
	global_load_lds_dwordx4 v141, s[74:75]
	s_mov_b32 m0, s71
	s_waitcnt vmcnt(4)
	s_waitcnt lgkmcnt(0)
	s_barrier
	s_setprio 1
	s_waitcnt lgkmcnt(7)
	v_mfma_f32_16x16x32_bf16 v[62:65], v[148:151], v[180:183], v[62:65]
	v_mfma_f32_16x16x32_bf16 v[58:61], v[156:159], v[180:183], v[58:61]
	s_waitcnt lgkmcnt(5)
	v_mfma_f32_16x16x32_bf16 v[46:49], v[148:151], v[188:191], v[46:49]
	v_mfma_f32_16x16x32_bf16 v[42:45], v[156:159], v[188:191], v[42:45]
	s_waitcnt lgkmcnt(3)
	v_mfma_f32_16x16x32_bf16 v[30:33], v[148:151], v[196:199], v[30:33]
	v_mfma_f32_16x16x32_bf16 v[26:29], v[156:159], v[196:199], v[26:29]
	s_waitcnt lgkmcnt(1)
	v_mfma_f32_16x16x32_bf16 v[14:17], v[148:151], v[204:207], v[14:17]
	v_mfma_f32_16x16x32_bf16 v[10:13], v[156:159], v[204:207], v[10:13]
	v_mfma_f32_16x16x32_bf16 v[62:65], v[152:155], v[184:187], v[62:65]
	v_mfma_f32_16x16x32_bf16 v[58:61], v[160:163], v[184:187], v[58:61]
	v_mfma_f32_16x16x32_bf16 v[46:49], v[152:155], v[192:195], v[46:49]
	v_mfma_f32_16x16x32_bf16 v[42:45], v[160:163], v[192:195], v[42:45]
	v_mfma_f32_16x16x32_bf16 v[30:33], v[152:155], v[200:203], v[30:33]
	v_mfma_f32_16x16x32_bf16 v[26:29], v[160:163], v[200:203], v[26:29]
	s_waitcnt lgkmcnt(0)
	v_mfma_f32_16x16x32_bf16 v[14:17], v[152:155], v[208:211], v[14:17]
	v_mfma_f32_16x16x32_bf16 v[10:13], v[160:163], v[208:211], v[10:13]
	s_setprio 0
	s_setprio 1
	v_mfma_f32_16x16x32_bf16 v[54:57], v[164:167], v[180:183], v[54:57]
	v_mfma_f32_16x16x32_bf16 v[50:53], v[172:175], v[180:183], v[50:53]
	v_mfma_f32_16x16x32_bf16 v[38:41], v[164:167], v[188:191], v[38:41]
	v_mfma_f32_16x16x32_bf16 v[34:37], v[172:175], v[188:191], v[34:37]
	v_mfma_f32_16x16x32_bf16 v[22:25], v[164:167], v[196:199], v[22:25]
	v_mfma_f32_16x16x32_bf16 v[18:21], v[172:175], v[196:199], v[18:21]
	v_mfma_f32_16x16x32_bf16 v[6:9], v[164:167], v[204:207], v[6:9]
	v_mfma_f32_16x16x32_bf16 v[2:5], v[172:175], v[204:207], v[2:5]
	v_mfma_f32_16x16x32_bf16 v[54:57], v[168:171], v[184:187], v[54:57]
	v_mfma_f32_16x16x32_bf16 v[50:53], v[176:179], v[184:187], v[50:53]
	v_mfma_f32_16x16x32_bf16 v[38:41], v[168:171], v[192:195], v[38:41]
	v_mfma_f32_16x16x32_bf16 v[34:37], v[176:179], v[192:195], v[34:37]
	v_mfma_f32_16x16x32_bf16 v[22:25], v[168:171], v[200:203], v[22:25]
	v_mfma_f32_16x16x32_bf16 v[18:21], v[176:179], v[200:203], v[18:21]
	s_setprio 2
	s_barrier
	v_mfma_f32_16x16x32_bf16 v[6:9], v[168:171], v[208:211], v[6:9]
	v_mfma_f32_16x16x32_bf16 v[2:5], v[176:179], v[208:211], v[2:5]
	s_setprio 0
	ds_read_b128 v[148:151], v146
	ds_read_b128 v[152:155], v146 offset:1024
	ds_read_b128 v[156:159], v146 offset:2048
	ds_read_b128 v[160:163], v146 offset:3072
	ds_read_b128 v[164:167], v147
	ds_read_b128 v[168:171], v147 offset:1024
	ds_read_b128 v[172:175], v147 offset:2048
	ds_read_b128 v[176:179], v147 offset:3072
	ds_read_b128 v[180:183], v145 offset:32768
	ds_read_b128 v[184:187], v145 offset:33792
	ds_read_b128 v[188:191], v145 offset:34816
	ds_read_b128 v[192:195], v145 offset:35840
	ds_read_b128 v[196:199], v145 offset:36864
	ds_read_b128 v[200:203], v145 offset:37888
	ds_read_b128 v[204:207], v145 offset:38912
	ds_read_b128 v[208:211], v145 offset:39936
	s_mov_b32 s71, m0
	s_mov_b32 m0, s31
	s_nop 0
	global_load_lds_dwordx4 v138, s[22:23]
	s_mov_b32 m0, s71
	s_nop 0
	s_mov_b32 s71, m0
	s_mov_b32 m0, s41
	s_nop 0
	global_load_lds_dwordx4 v140, s[22:23]
	s_mov_b32 m0, s71
	s_add_u32 s22, s22, 0x80000
	s_addc_u32 s23, s23, 0
	s_mov_b32 s71, m0
	s_mov_b32 m0, s42
	s_nop 0
	global_load_lds_dwordx4 v138, s[22:23]
	s_mov_b32 m0, s71
	s_nop 0
	s_mov_b32 s71, m0
	s_mov_b32 m0, s43
	s_nop 0
	global_load_lds_dwordx4 v140, s[22:23]
	s_mov_b32 m0, s71
	s_waitcnt vmcnt(8)
	s_waitcnt lgkmcnt(0)
	s_barrier
	s_setprio 1
	s_waitcnt lgkmcnt(7)
	v_mfma_f32_16x16x32_bf16 v[126:129], v[148:151], v[180:183], v[126:129]
	v_mfma_f32_16x16x32_bf16 v[122:125], v[156:159], v[180:183], v[122:125]
	s_waitcnt lgkmcnt(5)
	v_mfma_f32_16x16x32_bf16 v[110:113], v[148:151], v[188:191], v[110:113]
	v_mfma_f32_16x16x32_bf16 v[106:109], v[156:159], v[188:191], v[106:109]
	s_waitcnt lgkmcnt(3)
	v_mfma_f32_16x16x32_bf16 v[94:97], v[148:151], v[196:199], v[94:97]
	v_mfma_f32_16x16x32_bf16 v[90:93], v[156:159], v[196:199], v[90:93]
	s_waitcnt lgkmcnt(1)
	v_mfma_f32_16x16x32_bf16 v[78:81], v[148:151], v[204:207], v[78:81]
	v_mfma_f32_16x16x32_bf16 v[74:77], v[156:159], v[204:207], v[74:77]
	v_mfma_f32_16x16x32_bf16 v[126:129], v[152:155], v[184:187], v[126:129]
	v_mfma_f32_16x16x32_bf16 v[122:125], v[160:163], v[184:187], v[122:125]
	v_mfma_f32_16x16x32_bf16 v[110:113], v[152:155], v[192:195], v[110:113]
	v_mfma_f32_16x16x32_bf16 v[106:109], v[160:163], v[192:195], v[106:109]
	v_mfma_f32_16x16x32_bf16 v[94:97], v[152:155], v[200:203], v[94:97]
	v_mfma_f32_16x16x32_bf16 v[90:93], v[160:163], v[200:203], v[90:93]
	s_waitcnt lgkmcnt(0)
	v_mfma_f32_16x16x32_bf16 v[78:81], v[152:155], v[208:211], v[78:81]
	v_mfma_f32_16x16x32_bf16 v[74:77], v[160:163], v[208:211], v[74:77]
	s_setprio 0
	s_setprio 1
	v_mfma_f32_16x16x32_bf16 v[118:121], v[164:167], v[180:183], v[118:121]
	v_mfma_f32_16x16x32_bf16 v[114:117], v[172:175], v[180:183], v[114:117]
	v_mfma_f32_16x16x32_bf16 v[102:105], v[164:167], v[188:191], v[102:105]
	v_mfma_f32_16x16x32_bf16 v[98:101], v[172:175], v[188:191], v[98:101]
	v_mfma_f32_16x16x32_bf16 v[86:89], v[164:167], v[196:199], v[86:89]
	v_mfma_f32_16x16x32_bf16 v[82:85], v[172:175], v[196:199], v[82:85]
	v_mfma_f32_16x16x32_bf16 v[70:73], v[164:167], v[204:207], v[70:73]
	v_mfma_f32_16x16x32_bf16 v[66:69], v[172:175], v[204:207], v[66:69]
	v_mfma_f32_16x16x32_bf16 v[118:121], v[168:171], v[184:187], v[118:121]
	v_mfma_f32_16x16x32_bf16 v[114:117], v[176:179], v[184:187], v[114:117]
	v_mfma_f32_16x16x32_bf16 v[102:105], v[168:171], v[192:195], v[102:105]
	v_mfma_f32_16x16x32_bf16 v[98:101], v[176:179], v[192:195], v[98:101]
	v_mfma_f32_16x16x32_bf16 v[86:89], v[168:171], v[200:203], v[86:89]
	v_mfma_f32_16x16x32_bf16 v[82:85], v[176:179], v[200:203], v[82:85]
	s_setprio 2
	s_barrier
	v_mfma_f32_16x16x32_bf16 v[70:73], v[168:171], v[208:211], v[70:73]
	v_mfma_f32_16x16x32_bf16 v[66:69], v[176:179], v[208:211], v[66:69]
	s_setprio 0
	ds_read_b128 v[180:183], v145 offset:49152
	ds_read_b128 v[184:187], v145 offset:50176
	ds_read_b128 v[188:191], v145 offset:51200
	ds_read_b128 v[192:195], v145 offset:52224
	ds_read_b128 v[196:199], v145 offset:53248
	ds_read_b128 v[200:203], v145 offset:54272
	ds_read_b128 v[204:207], v145 offset:55296
	ds_read_b128 v[208:211], v145 offset:56320
	s_add_u32 s22, s20, 0x80
	s_addc_u32 s23, s21, 0
	s_mov_b32 s71, m0
	s_mov_b32 m0, s44
	s_nop 0
	global_load_lds_dwordx4 v139, s[22:23]
	s_mov_b32 m0, s71
	s_add_u32 s20, s20, 0x80080
	s_mov_b32 s71, m0
	s_mov_b32 m0, s45
	s_nop 0
	global_load_lds_dwordx4 v141, s[22:23]
	s_mov_b32 m0, s71
	s_addc_u32 s21, s21, 0
	s_mov_b32 s22, m0
	s_mov_b32 m0, s46
	s_nop 0
	global_load_lds_dwordx4 v139, s[20:21]
	s_mov_b32 m0, s22
	s_nop 0
	s_mov_b32 s22, m0
	s_mov_b32 m0, s47
	s_nop 0
	global_load_lds_dwordx4 v141, s[20:21]
	s_mov_b32 m0, s22
	s_waitcnt vmcnt(4)
	s_waitcnt lgkmcnt(0)
	s_barrier
	s_setprio 1
	s_waitcnt lgkmcnt(7)
	v_mfma_f32_16x16x32_bf16 v[62:65], v[148:151], v[180:183], v[62:65]
	v_mfma_f32_16x16x32_bf16 v[58:61], v[156:159], v[180:183], v[58:61]
	s_waitcnt lgkmcnt(5)
	v_mfma_f32_16x16x32_bf16 v[46:49], v[148:151], v[188:191], v[46:49]
	v_mfma_f32_16x16x32_bf16 v[42:45], v[156:159], v[188:191], v[42:45]
	s_waitcnt lgkmcnt(3)
	v_mfma_f32_16x16x32_bf16 v[30:33], v[148:151], v[196:199], v[30:33]
	v_mfma_f32_16x16x32_bf16 v[26:29], v[156:159], v[196:199], v[26:29]
	s_waitcnt lgkmcnt(1)
	v_mfma_f32_16x16x32_bf16 v[14:17], v[148:151], v[204:207], v[14:17]
	v_mfma_f32_16x16x32_bf16 v[10:13], v[156:159], v[204:207], v[10:13]
	v_mfma_f32_16x16x32_bf16 v[62:65], v[152:155], v[184:187], v[62:65]
	v_mfma_f32_16x16x32_bf16 v[58:61], v[160:163], v[184:187], v[58:61]
	v_mfma_f32_16x16x32_bf16 v[46:49], v[152:155], v[192:195], v[46:49]
	v_mfma_f32_16x16x32_bf16 v[42:45], v[160:163], v[192:195], v[42:45]
	v_mfma_f32_16x16x32_bf16 v[30:33], v[152:155], v[200:203], v[30:33]
	v_mfma_f32_16x16x32_bf16 v[26:29], v[160:163], v[200:203], v[26:29]
	s_waitcnt lgkmcnt(0)
	v_mfma_f32_16x16x32_bf16 v[14:17], v[152:155], v[208:211], v[14:17]
	v_mfma_f32_16x16x32_bf16 v[10:13], v[160:163], v[208:211], v[10:13]
	s_setprio 0
	s_setprio 1
	v_mfma_f32_16x16x32_bf16 v[54:57], v[164:167], v[180:183], v[54:57]
	v_mfma_f32_16x16x32_bf16 v[50:53], v[172:175], v[180:183], v[50:53]
	v_mfma_f32_16x16x32_bf16 v[38:41], v[164:167], v[188:191], v[38:41]
	v_mfma_f32_16x16x32_bf16 v[34:37], v[172:175], v[188:191], v[34:37]
	v_mfma_f32_16x16x32_bf16 v[22:25], v[164:167], v[196:199], v[22:25]
	v_mfma_f32_16x16x32_bf16 v[18:21], v[172:175], v[196:199], v[18:21]
	v_mfma_f32_16x16x32_bf16 v[6:9], v[164:167], v[204:207], v[6:9]
	v_mfma_f32_16x16x32_bf16 v[2:5], v[172:175], v[204:207], v[2:5]
	v_mfma_f32_16x16x32_bf16 v[54:57], v[168:171], v[184:187], v[54:57]
	v_mfma_f32_16x16x32_bf16 v[50:53], v[176:179], v[184:187], v[50:53]
	v_mfma_f32_16x16x32_bf16 v[38:41], v[168:171], v[192:195], v[38:41]
	v_mfma_f32_16x16x32_bf16 v[34:37], v[176:179], v[192:195], v[34:37]
	v_mfma_f32_16x16x32_bf16 v[22:25], v[168:171], v[200:203], v[22:25]
	v_mfma_f32_16x16x32_bf16 v[18:21], v[176:179], v[200:203], v[18:21]
	s_setprio 2
	s_barrier
	v_mfma_f32_16x16x32_bf16 v[6:9], v[168:171], v[208:211], v[6:9]
	v_mfma_f32_16x16x32_bf16 v[2:5], v[176:179], v[208:211], v[2:5]
	s_setprio 0
	s_add_i32 s70, s70, 2
	s_add_u32 s64, s64, 0x100
	s_addc_u32 s65, s65, 0
	s_add_u32 s18, s18, 0x100
	s_addc_u32 s19, s19, 0
	s_add_u32 s66, s66, 0x100
	s_addc_u32 s67, s67, 0
	s_cmp_gt_u32 s70, 29
	s_cbranch_scc0 .LBB0_2594
	s_and_b64 vcc, exec, s[6:7]
	s_cbranch_vccz .LBB0_2597
	s_barrier
.LBB0_2597:
	v_exp_f32_e32 v150, v126
	v_exp_f32_e32 v152, v122
	v_exp_f32_e32 v151, v127
	v_exp_f32_e32 v156, v124
	v_exp_f32_e32 v157, v125
	v_exp_f32_e32 v153, v123
	v_exp_f32_e32 v154, v128
	v_exp_f32_e32 v155, v129
	s_lshl_b32 s9, s17, 1
	v_pk_add_f32 v[150:151], v[150:151], 1.0 op_sel_hi:[1,0]
	v_pk_add_f32 v[156:157], v[156:157], 1.0 op_sel_hi:[1,0]
	v_pk_add_f32 v[152:153], v[152:153], 1.0 op_sel_hi:[1,0]
	v_lshl_add_u32 v136, s16, 8, v142
	s_or_b32 s16, s9, s56
	v_rcp_f32_e32 v150, v150
	v_rcp_f32_e32 v152, v152
	v_rcp_f32_e32 v151, v151
	v_rcp_f32_e32 v153, v153
	v_rcp_f32_e32 v156, v156
	v_rcp_f32_e32 v157, v157
	s_ashr_i32 s17, s16, 31
	v_pk_add_f32 v[154:155], v[154:155], 1.0 op_sel_hi:[1,0]
	s_lshl_b64 s[16:17], s[16:17], 14
	v_ashrrev_i32_e32 v137, 31, v136
	v_rcp_f32_e32 v154, v154
	v_rcp_f32_e32 v155, v155
	v_lshl_add_u64 v[148:149], s[16:17], 0, v[136:137]
	v_pk_mul_f32 v[118:119], v[126:127], v[118:119]
	v_pk_mul_f32 v[116:117], v[124:125], v[116:117]
	v_pk_mul_f32 v[114:115], v[122:123], v[114:115]
	v_lshlrev_b64 v[148:149], 7, v[148:149]
	v_pk_mul_f32 v[118:119], v[150:151], v[118:119]
	v_pk_mul_f32 v[122:123], v[156:157], v[116:117]
	v_pk_mul_f32 v[116:117], v[152:153], v[114:115]
	v_lshl_add_u64 v[148:149], v[130:131], 0, v[148:149]
	v_pk_mul_f32 v[120:121], v[128:129], v[120:121]
	v_cvt_pk_bf16_f32 v114, v118, v119
	v_cvt_pk_bf16_f32 v116, v116, v117
	v_cvt_pk_bf16_f32 v117, v122, v123
	v_exp_f32_e32 v118, v106
	v_exp_f32_e32 v122, v108
	v_exp_f32_e32 v123, v109
	v_exp_f32_e32 v119, v107
	v_pk_mul_f32 v[120:121], v[154:155], v[120:121]
	v_pk_mul_f32 v[100:101], v[108:109], v[100:101]
	v_cvt_pk_bf16_f32 v115, v120, v121
	global_store_dwordx4 v[148:149], v[114:117], off
	v_exp_f32_e32 v120, v112
	v_exp_f32_e32 v121, v113
	v_exp_f32_e32 v116, v110
	v_exp_f32_e32 v117, v111
	v_pk_add_f32 v[122:123], v[122:123], 1.0 op_sel_hi:[1,0]
	v_pk_add_f32 v[118:119], v[118:119], 1.0 op_sel_hi:[1,0]
	v_rcp_f32_e32 v122, v122
	v_pk_add_f32 v[116:117], v[116:117], 1.0 op_sel_hi:[1,0]
	v_rcp_f32_e32 v118, v118
	v_rcp_f32_e32 v119, v119
	v_rcp_f32_e32 v123, v123
	v_or_b32_e32 v114, 16, v136
	v_pk_add_f32 v[120:121], v[120:121], 1.0 op_sel_hi:[1,0]
	v_rcp_f32_e32 v116, v116
	v_rcp_f32_e32 v117, v117
	v_ashrrev_i32_e32 v115, 31, v114
	v_rcp_f32_e32 v120, v120
	v_rcp_f32_e32 v121, v121
	v_lshl_add_u64 v[114:115], s[16:17], 0, v[114:115]
	v_pk_mul_f32 v[98:99], v[106:107], v[98:99]
	v_lshlrev_b64 v[114:115], 7, v[114:115]
	v_pk_mul_f32 v[102:103], v[110:111], v[102:103]
	v_pk_mul_f32 v[106:107], v[122:123], v[100:101]
	v_pk_mul_f32 v[100:101], v[118:119], v[98:99]
	v_lshl_add_u64 v[114:115], v[130:131], 0, v[114:115]
	v_pk_mul_f32 v[104:105], v[112:113], v[104:105]
	v_pk_mul_f32 v[102:103], v[116:117], v[102:103]
	v_cvt_pk_bf16_f32 v100, v100, v101
	v_cvt_pk_bf16_f32 v101, v106, v107
	v_pk_mul_f32 v[104:105], v[120:121], v[104:105]
	v_cvt_pk_bf16_f32 v98, v102, v103
	v_exp_f32_e32 v102, v90
	v_cvt_pk_bf16_f32 v99, v104, v105
	global_store_dwordx4 v[114:115], v[98:101], off
	v_exp_f32_e32 v106, v92
	v_exp_f32_e32 v107, v93
	v_exp_f32_e32 v100, v94
	v_exp_f32_e32 v101, v95
	v_exp_f32_e32 v103, v91
	v_exp_f32_e32 v104, v96
	v_exp_f32_e32 v105, v97
	v_pk_add_f32 v[100:101], v[100:101], 1.0 op_sel_hi:[1,0]
	v_pk_add_f32 v[106:107], v[106:107], 1.0 op_sel_hi:[1,0]
	v_pk_add_f32 v[102:103], v[102:103], 1.0 op_sel_hi:[1,0]
	v_rcp_f32_e32 v100, v100
	v_rcp_f32_e32 v102, v102
	v_rcp_f32_e32 v101, v101
	v_rcp_f32_e32 v103, v103
	v_rcp_f32_e32 v106, v106
	v_rcp_f32_e32 v107, v107
	v_or_b32_e32 v98, 32, v136
	v_pk_add_f32 v[104:105], v[104:105], 1.0 op_sel_hi:[1,0]
	v_ashrrev_i32_e32 v99, 31, v98
	v_rcp_f32_e32 v104, v104
	v_rcp_f32_e32 v105, v105
	v_lshl_add_u64 v[98:99], s[16:17], 0, v[98:99]
	v_pk_mul_f32 v[86:87], v[94:95], v[86:87]
	v_pk_mul_f32 v[84:85], v[92:93], v[84:85]
	v_pk_mul_f32 v[82:83], v[90:91], v[82:83]
	v_lshlrev_b64 v[98:99], 7, v[98:99]
	v_pk_mul_f32 v[86:87], v[100:101], v[86:87]
	v_pk_mul_f32 v[90:91], v[106:107], v[84:85]
	v_pk_mul_f32 v[84:85], v[102:103], v[82:83]
	v_lshl_add_u64 v[98:99], v[130:131], 0, v[98:99]
	v_pk_mul_f32 v[88:89], v[96:97], v[88:89]
	v_cvt_pk_bf16_f32 v82, v86, v87
	v_cvt_pk_bf16_f32 v84, v84, v85
	v_cvt_pk_bf16_f32 v85, v90, v91
	v_exp_f32_e32 v86, v74
	v_exp_f32_e32 v90, v76
	v_exp_f32_e32 v91, v77
	v_exp_f32_e32 v87, v75
	v_pk_mul_f32 v[88:89], v[104:105], v[88:89]
	v_pk_mul_f32 v[68:69], v[76:77], v[68:69]
	v_cvt_pk_bf16_f32 v83, v88, v89
	global_store_dwordx4 v[98:99], v[82:85], off
	v_exp_f32_e32 v88, v80
	v_exp_f32_e32 v89, v81
	v_exp_f32_e32 v84, v78
	v_exp_f32_e32 v85, v79
	v_pk_add_f32 v[90:91], v[90:91], 1.0 op_sel_hi:[1,0]
	v_pk_add_f32 v[86:87], v[86:87], 1.0 op_sel_hi:[1,0]
	v_rcp_f32_e32 v90, v90
	v_pk_add_f32 v[84:85], v[84:85], 1.0 op_sel_hi:[1,0]
	v_rcp_f32_e32 v86, v86
	v_rcp_f32_e32 v87, v87
	v_rcp_f32_e32 v91, v91
	v_or_b32_e32 v82, 48, v136
	v_pk_add_f32 v[88:89], v[88:89], 1.0 op_sel_hi:[1,0]
	v_rcp_f32_e32 v84, v84
	v_rcp_f32_e32 v85, v85
	v_ashrrev_i32_e32 v83, 31, v82
	v_rcp_f32_e32 v88, v88
	v_rcp_f32_e32 v89, v89
	v_lshl_add_u64 v[82:83], s[16:17], 0, v[82:83]
	v_pk_mul_f32 v[66:67], v[74:75], v[66:67]
	v_lshlrev_b64 v[82:83], 7, v[82:83]
	v_pk_mul_f32 v[70:71], v[78:79], v[70:71]
	v_pk_mul_f32 v[74:75], v[90:91], v[68:69]
	v_pk_mul_f32 v[68:69], v[86:87], v[66:67]
	v_lshl_add_u64 v[82:83], v[130:131], 0, v[82:83]
	v_pk_mul_f32 v[72:73], v[80:81], v[72:73]
	v_pk_mul_f32 v[70:71], v[84:85], v[70:71]
	v_cvt_pk_bf16_f32 v68, v68, v69
	v_cvt_pk_bf16_f32 v69, v74, v75
	v_pk_mul_f32 v[72:73], v[88:89], v[72:73]
	v_cvt_pk_bf16_f32 v66, v70, v71
	v_exp_f32_e32 v70, v58
	v_cvt_pk_bf16_f32 v67, v72, v73
	global_store_dwordx4 v[82:83], v[66:69], off
	v_exp_f32_e32 v74, v60
	v_exp_f32_e32 v75, v61
	v_exp_f32_e32 v68, v62
	v_exp_f32_e32 v69, v63
	v_exp_f32_e32 v71, v59
	v_exp_f32_e32 v72, v64
	v_exp_f32_e32 v73, v65
	v_pk_add_f32 v[68:69], v[68:69], 1.0 op_sel_hi:[1,0]
	v_pk_add_f32 v[74:75], v[74:75], 1.0 op_sel_hi:[1,0]
	v_pk_add_f32 v[70:71], v[70:71], 1.0 op_sel_hi:[1,0]
	v_rcp_f32_e32 v68, v68
	v_rcp_f32_e32 v70, v70
	v_rcp_f32_e32 v69, v69
	v_rcp_f32_e32 v71, v71
	v_rcp_f32_e32 v74, v74
	v_rcp_f32_e32 v75, v75
	v_add_u32_e32 v66, 0x80, v136
	v_pk_add_f32 v[72:73], v[72:73], 1.0 op_sel_hi:[1,0]
	v_ashrrev_i32_e32 v67, 31, v66
	v_rcp_f32_e32 v72, v72
	v_rcp_f32_e32 v73, v73
	v_lshl_add_u64 v[66:67], s[16:17], 0, v[66:67]
	v_pk_mul_f32 v[54:55], v[62:63], v[54:55]
	v_pk_mul_f32 v[52:53], v[60:61], v[52:53]
	v_pk_mul_f32 v[50:51], v[58:59], v[50:51]
	v_lshlrev_b64 v[66:67], 7, v[66:67]
	v_pk_mul_f32 v[54:55], v[68:69], v[54:55]
	v_pk_mul_f32 v[58:59], v[74:75], v[52:53]
	v_pk_mul_f32 v[52:53], v[70:71], v[50:51]
	v_lshl_add_u64 v[66:67], v[130:131], 0, v[66:67]
	v_pk_mul_f32 v[56:57], v[64:65], v[56:57]
	v_cvt_pk_bf16_f32 v50, v54, v55
	v_cvt_pk_bf16_f32 v52, v52, v53
	v_cvt_pk_bf16_f32 v53, v58, v59
	v_exp_f32_e32 v54, v42
	v_exp_f32_e32 v58, v44
	v_exp_f32_e32 v59, v45
	v_exp_f32_e32 v55, v43
	v_pk_mul_f32 v[56:57], v[72:73], v[56:57]
	v_pk_mul_f32 v[36:37], v[44:45], v[36:37]
	v_cvt_pk_bf16_f32 v51, v56, v57
	global_store_dwordx4 v[66:67], v[50:53], off
	v_exp_f32_e32 v56, v48
	v_exp_f32_e32 v57, v49
	v_exp_f32_e32 v52, v46
	v_exp_f32_e32 v53, v47
	v_pk_add_f32 v[58:59], v[58:59], 1.0 op_sel_hi:[1,0]
	v_pk_add_f32 v[54:55], v[54:55], 1.0 op_sel_hi:[1,0]
	v_rcp_f32_e32 v58, v58
	v_pk_add_f32 v[52:53], v[52:53], 1.0 op_sel_hi:[1,0]
	v_rcp_f32_e32 v54, v54
	v_rcp_f32_e32 v55, v55
	v_rcp_f32_e32 v59, v59
	v_add_u32_e32 v50, 0x90, v136
	v_pk_add_f32 v[56:57], v[56:57], 1.0 op_sel_hi:[1,0]
	v_rcp_f32_e32 v52, v52
	v_rcp_f32_e32 v53, v53
	v_ashrrev_i32_e32 v51, 31, v50
	v_rcp_f32_e32 v56, v56
	v_rcp_f32_e32 v57, v57
	v_lshl_add_u64 v[50:51], s[16:17], 0, v[50:51]
	v_pk_mul_f32 v[34:35], v[42:43], v[34:35]
	v_lshlrev_b64 v[50:51], 7, v[50:51]
	v_pk_mul_f32 v[38:39], v[46:47], v[38:39]
	v_pk_mul_f32 v[42:43], v[58:59], v[36:37]
	v_pk_mul_f32 v[36:37], v[54:55], v[34:35]
	v_lshl_add_u64 v[50:51], v[130:131], 0, v[50:51]
	v_pk_mul_f32 v[40:41], v[48:49], v[40:41]
	v_pk_mul_f32 v[38:39], v[52:53], v[38:39]
	v_cvt_pk_bf16_f32 v36, v36, v37
	v_cvt_pk_bf16_f32 v37, v42, v43
	v_pk_mul_f32 v[40:41], v[56:57], v[40:41]
	v_cvt_pk_bf16_f32 v34, v38, v39
	v_exp_f32_e32 v38, v26
	v_cvt_pk_bf16_f32 v35, v40, v41
	global_store_dwordx4 v[50:51], v[34:37], off
	v_exp_f32_e32 v42, v28
	v_exp_f32_e32 v43, v29
	v_exp_f32_e32 v36, v30
	v_exp_f32_e32 v37, v31
	v_exp_f32_e32 v39, v27
	v_exp_f32_e32 v40, v32
	v_exp_f32_e32 v41, v33
	v_pk_add_f32 v[36:37], v[36:37], 1.0 op_sel_hi:[1,0]
	v_pk_add_f32 v[42:43], v[42:43], 1.0 op_sel_hi:[1,0]
	v_pk_add_f32 v[38:39], v[38:39], 1.0 op_sel_hi:[1,0]
	v_pk_add_f32 v[40:41], v[40:41], 1.0 op_sel_hi:[1,0]
	v_rcp_f32_e32 v36, v36
	v_rcp_f32_e32 v38, v38
	v_rcp_f32_e32 v37, v37
	v_rcp_f32_e32 v39, v39
	v_rcp_f32_e32 v42, v42
	v_rcp_f32_e32 v43, v43
	v_add_u32_e32 v34, 0xa0, v136
	v_rcp_f32_e32 v40, v40
	v_rcp_f32_e32 v41, v41
	v_ashrrev_i32_e32 v35, 31, v34
	v_lshl_add_u64 v[34:35], s[16:17], 0, v[34:35]
	v_pk_mul_f32 v[22:23], v[30:31], v[22:23]
	v_pk_mul_f32 v[20:21], v[28:29], v[20:21]
	v_pk_mul_f32 v[18:19], v[26:27], v[18:19]
	v_lshlrev_b64 v[34:35], 7, v[34:35]
	v_pk_mul_f32 v[24:25], v[32:33], v[24:25]
	v_pk_mul_f32 v[22:23], v[36:37], v[22:23]
	v_pk_mul_f32 v[26:27], v[42:43], v[20:21]
	v_pk_mul_f32 v[20:21], v[38:39], v[18:19]
	v_lshl_add_u64 v[34:35], v[130:131], 0, v[34:35]
	v_pk_mul_f32 v[24:25], v[40:41], v[24:25]
	v_cvt_pk_bf16_f32 v18, v22, v23
	v_cvt_pk_bf16_f32 v20, v20, v21
	v_cvt_pk_bf16_f32 v21, v26, v27
	v_exp_f32_e32 v22, v10
	v_exp_f32_e32 v26, v12
	v_exp_f32_e32 v27, v13
	v_exp_f32_e32 v23, v11
	v_cvt_pk_bf16_f32 v19, v24, v25
	global_store_dwordx4 v[34:35], v[18:21], off
	v_exp_f32_e32 v24, v16
	v_exp_f32_e32 v25, v17
	v_exp_f32_e32 v20, v14
	v_exp_f32_e32 v21, v15
	v_pk_add_f32 v[26:27], v[26:27], 1.0 op_sel_hi:[1,0]
	v_pk_add_f32 v[22:23], v[22:23], 1.0 op_sel_hi:[1,0]
	v_add_u32_e32 v18, 0xb0, v136
	v_pk_add_f32 v[24:25], v[24:25], 1.0 op_sel_hi:[1,0]
	v_pk_add_f32 v[20:21], v[20:21], 1.0 op_sel_hi:[1,0]
	v_rcp_f32_e32 v22, v22
	v_rcp_f32_e32 v23, v23
	v_rcp_f32_e32 v26, v26
	v_rcp_f32_e32 v27, v27
	v_ashrrev_i32_e32 v19, 31, v18
	v_rcp_f32_e32 v20, v20
	v_rcp_f32_e32 v21, v21
	v_rcp_f32_e32 v24, v24
	v_rcp_f32_e32 v25, v25
	v_lshl_add_u64 v[18:19], s[16:17], 0, v[18:19]
	v_lshlrev_b64 v[18:19], 7, v[18:19]
	v_pk_mul_f32 v[4:5], v[12:13], v[4:5]
	v_pk_mul_f32 v[2:3], v[10:11], v[2:3]
	v_lshl_add_u64 v[18:19], v[130:131], 0, v[18:19]
	v_pk_mul_f32 v[8:9], v[16:17], v[8:9]
	v_pk_mul_f32 v[6:7], v[14:15], v[6:7]
	v_pk_mul_f32 v[10:11], v[26:27], v[4:5]
	v_pk_mul_f32 v[4:5], v[22:23], v[2:3]
	s_andn2_b64 vcc, exec, s[2:3]
	s_mov_b64 s[2:3], -1
	v_pk_mul_f32 v[8:9], v[24:25], v[8:9]
	v_pk_mul_f32 v[6:7], v[20:21], v[6:7]
	v_cvt_pk_bf16_f32 v3, v8, v9
	v_cvt_pk_bf16_f32 v4, v4, v5
	v_cvt_pk_bf16_f32 v5, v10, v11
	s_nop 0
	v_cvt_pk_bf16_f32 v2, v6, v7
	global_store_dwordx4 v[18:19], v[2:5], off
	s_cbranch_vccnz .LBB0_2590
	s_andn2_b64 vcc, exec, s[4:5]
	s_cbranch_vccnz .LBB0_2589
	s_mov_b32 s99, 1
	s_branch .LBB0_2589

.LBB0_2791:
	s_ashr_i32 s21, s20, 31
	s_lshl_b64 s[22:23], s[20:21], 15
	s_add_u32 s22, s37, s22
	s_addc_u32 s23, s40, s23
	s_and_b64 s[24:25], s[2:3], exec
	s_cselect_b32 s21, s23, s31
	s_cselect_b32 s63, s22, s30
	s_ashr_i32 s19, s18, 31
	s_lshl_b64 s[24:25], s[18:19], 15
	s_add_u32 s24, s41, s24
	s_addc_u32 s25, s42, s25
	s_and_b64 s[34:35], s[2:3], exec
	s_cselect_b32 s19, s25, s29
	s_cselect_b32 s64, s24, s28
	s_add_u32 s65, s28, 0x80000
	s_addc_u32 s66, s29, 0
	s_add_u32 s28, s30, 0x204000
	s_addc_u32 s29, s31, 0
	s_add_u32 s67, s30, 0x400000
	v_mov_b32_e32 v2, 0
	s_addc_u32 s68, s31, 0
	s_mov_b32 s69, -2
	v_mov_b32_e32 v3, v2
	v_mov_b32_e32 v4, v2
	v_mov_b32_e32 v5, v2
	v_mov_b32_e32 v6, v2
	v_mov_b32_e32 v7, v2
	s_waitcnt vmcnt(25)
	v_mov_b32_e32 v8, v2
	s_waitcnt vmcnt(24)
	v_mov_b32_e32 v9, v2
	s_waitcnt vmcnt(4)
	v_mov_b32_e32 v18, v2
	v_mov_b32_e32 v19, v2
	v_mov_b32_e32 v20, v2
	v_mov_b32_e32 v21, v2
	s_waitcnt vmcnt(2)
	v_mov_b32_e32 v22, v2
	v_mov_b32_e32 v23, v2
	v_mov_b32_e32 v24, v2
	v_mov_b32_e32 v25, v2
	v_mov_b32_e32 v34, v2
	v_mov_b32_e32 v35, v2
	v_mov_b32_e32 v36, v2
	v_mov_b32_e32 v37, v2
	v_mov_b32_e32 v38, v2
	v_mov_b32_e32 v39, v2
	v_mov_b32_e32 v40, v2
	v_mov_b32_e32 v41, v2
	v_mov_b32_e32 v50, v2
	v_mov_b32_e32 v51, v2
	v_mov_b32_e32 v52, v2
	v_mov_b32_e32 v53, v2
	v_mov_b32_e32 v54, v2
	v_mov_b32_e32 v55, v2
	v_mov_b32_e32 v56, v2
	v_mov_b32_e32 v57, v2
	v_mov_b32_e32 v10, v2
	v_mov_b32_e32 v11, v2
	v_mov_b32_e32 v12, v2
	v_mov_b32_e32 v13, v2
	v_mov_b32_e32 v14, v2
	v_mov_b32_e32 v15, v2
	v_mov_b32_e32 v16, v2
	v_mov_b32_e32 v17, v2
	v_mov_b32_e32 v26, v2
	v_mov_b32_e32 v27, v2
	v_mov_b32_e32 v28, v2
	v_mov_b32_e32 v29, v2
	v_mov_b32_e32 v30, v2
	v_mov_b32_e32 v31, v2
	s_waitcnt vmcnt(1)
	v_mov_b32_e32 v32, v2
	s_waitcnt vmcnt(0)
	v_mov_b32_e32 v33, v2
	v_mov_b32_e32 v42, v2
	v_mov_b32_e32 v43, v2
	v_mov_b32_e32 v44, v2
	v_mov_b32_e32 v45, v2
	v_mov_b32_e32 v46, v2
	v_mov_b32_e32 v47, v2
	v_mov_b32_e32 v48, v2
	v_mov_b32_e32 v49, v2
	v_mov_b32_e32 v58, v2
	v_mov_b32_e32 v59, v2
	v_mov_b32_e32 v60, v2
	v_mov_b32_e32 v61, v2
	v_mov_b32_e32 v62, v2
	v_mov_b32_e32 v63, v2
	v_mov_b32_e32 v64, v2
	v_mov_b32_e32 v65, v2
	v_mov_b32_e32 v66, v2
	v_mov_b32_e32 v67, v2
	v_mov_b32_e32 v68, v2
	v_mov_b32_e32 v69, v2
	v_mov_b32_e32 v70, v2
	v_mov_b32_e32 v71, v2
	v_mov_b32_e32 v72, v2
	v_mov_b32_e32 v73, v2
	v_mov_b32_e32 v74, v2
	v_mov_b32_e32 v75, v2
	v_mov_b32_e32 v76, v2
	v_mov_b32_e32 v77, v2
	v_mov_b32_e32 v82, v2
	v_mov_b32_e32 v83, v2
	v_mov_b32_e32 v84, v2
	v_mov_b32_e32 v85, v2
	v_mov_b32_e32 v98, v2
	v_mov_b32_e32 v99, v2
	v_mov_b32_e32 v100, v2
	v_mov_b32_e32 v101, v2
	v_mov_b32_e32 v102, v2
	v_mov_b32_e32 v103, v2
	v_mov_b32_e32 v104, v2
	v_mov_b32_e32 v105, v2
	v_mov_b32_e32 v106, v2
	v_mov_b32_e32 v107, v2
	v_mov_b32_e32 v108, v2
	v_mov_b32_e32 v109, v2
	v_mov_b32_e32 v114, v2
	v_mov_b32_e32 v115, v2
	v_mov_b32_e32 v116, v2
	v_mov_b32_e32 v117, v2
	v_mov_b32_e32 v78, v2
	v_mov_b32_e32 v79, v2
	v_mov_b32_e32 v80, v2
	v_mov_b32_e32 v81, v2
	v_mov_b32_e32 v86, v2
	v_mov_b32_e32 v87, v2
	v_mov_b32_e32 v88, v2
	v_mov_b32_e32 v89, v2
	v_mov_b32_e32 v90, v2
	v_mov_b32_e32 v91, v2
	v_mov_b32_e32 v92, v2
	v_mov_b32_e32 v93, v2
	v_mov_b32_e32 v94, v2
	v_mov_b32_e32 v95, v2
	v_mov_b32_e32 v96, v2
	v_mov_b32_e32 v97, v2
	v_mov_b32_e32 v110, v2
	v_mov_b32_e32 v111, v2
	v_mov_b32_e32 v112, v2
	v_mov_b32_e32 v113, v2
	v_mov_b32_e32 v118, v2
	v_mov_b32_e32 v119, v2
	v_mov_b32_e32 v120, v2
	v_mov_b32_e32 v121, v2
	v_mov_b32_e32 v122, v2
	v_mov_b32_e32 v123, v2
	v_mov_b32_e32 v124, v2
	v_mov_b32_e32 v125, v2
	v_mov_b32_e32 v126, v2
	v_mov_b32_e32 v127, v2
	v_mov_b32_e32 v128, v2
	v_mov_b32_e32 v129, v2
	s_cmp_eq_u32 s99, 0
	s_cbranch_scc1 .Lro_skip_1
	s_barrier
	s_mov_b32 s99, 0
.Lro_skip_1:
.LBB0_2792:
	ds_read_b128 v[130:133], v181
	ds_read_b128 v[134:137], v181 offset:1024
	ds_read_b128 v[138:141], v181 offset:2048
	ds_read_b128 v[142:145], v181 offset:3072
	ds_read_b128 v[150:153], v182
	ds_read_b128 v[154:157], v182 offset:1024
	ds_read_b128 v[158:161], v182 offset:2048
	ds_read_b128 v[162:165], v182 offset:3072
	s_cmpk_eq_i32 s69, 0x52
	s_cselect_b32 s31, s19, s66
	s_cselect_b32 s30, s64, s65
	s_cselect_b32 s35, s21, s68
	s_cselect_b32 s34, s63, s67
	ds_read_b128 v[166:169], v183
	ds_read_b128 v[170:173], v183 offset:1024
	ds_read_b128 v[186:189], v183 offset:2048
	ds_read_b128 v[190:193], v183 offset:3072
	ds_read_b128 v[194:197], v183 offset:4096
	ds_read_b128 v[198:201], v183 offset:5120
	ds_read_b128 v[202:205], v183 offset:6144
	ds_read_b128 v[206:209], v183 offset:7168
	s_add_u32 s70, s28, 0xffffc000
	s_addc_u32 s71, s29, -1
	s_mov_b32 s73, m0
	s_mov_b32 m0, s57
	s_nop 0
	global_load_lds_dwordx4 v1, s[70:71]
	s_mov_b32 m0, s73
	s_nop 0
	s_mov_b32 s73, m0
	s_mov_b32 m0, s59
	s_nop 0
	global_load_lds_dwordx4 v177, s[70:71]
	s_mov_b32 m0, s73
	s_mov_b32 s70, m0
	s_mov_b32 m0, s58
	s_nop 0
	global_load_lds_dwordx4 v1, s[28:29]
	s_mov_b32 m0, s70
	s_nop 0
	s_mov_b32 s70, m0
	s_mov_b32 m0, s60
	s_nop 0
	global_load_lds_dwordx4 v177, s[28:29]
	s_mov_b32 m0, s70
	s_waitcnt vmcnt(8)
	s_waitcnt lgkmcnt(0)
	s_barrier
	s_setprio 1
	s_waitcnt lgkmcnt(7)
	v_mfma_f32_16x16x32_bf16 v[126:129], v[130:133], v[166:169], v[126:129]
	v_mfma_f32_16x16x32_bf16 v[122:125], v[138:141], v[166:169], v[122:125]
	s_waitcnt lgkmcnt(5)
	v_mfma_f32_16x16x32_bf16 v[118:121], v[130:133], v[186:189], v[118:121]
	v_mfma_f32_16x16x32_bf16 v[110:113], v[138:141], v[186:189], v[110:113]
	s_waitcnt lgkmcnt(3)
	v_mfma_f32_16x16x32_bf16 v[94:97], v[130:133], v[194:197], v[94:97]
	v_mfma_f32_16x16x32_bf16 v[90:93], v[138:141], v[194:197], v[90:93]
	s_waitcnt lgkmcnt(1)
	v_mfma_f32_16x16x32_bf16 v[86:89], v[130:133], v[202:205], v[86:89]
	v_mfma_f32_16x16x32_bf16 v[78:81], v[138:141], v[202:205], v[78:81]
	v_mfma_f32_16x16x32_bf16 v[126:129], v[134:137], v[170:173], v[126:129]
	v_mfma_f32_16x16x32_bf16 v[122:125], v[142:145], v[170:173], v[122:125]
	v_mfma_f32_16x16x32_bf16 v[118:121], v[134:137], v[190:193], v[118:121]
	v_mfma_f32_16x16x32_bf16 v[110:113], v[142:145], v[190:193], v[110:113]
	v_mfma_f32_16x16x32_bf16 v[94:97], v[134:137], v[198:201], v[94:97]
	v_mfma_f32_16x16x32_bf16 v[90:93], v[142:145], v[198:201], v[90:93]
	s_waitcnt lgkmcnt(0)
	v_mfma_f32_16x16x32_bf16 v[86:89], v[134:137], v[206:209], v[86:89]
	v_mfma_f32_16x16x32_bf16 v[78:81], v[142:145], v[206:209], v[78:81]
	s_setprio 0
	s_setprio 1
	v_mfma_f32_16x16x32_bf16 v[114:117], v[150:153], v[166:169], v[114:117]
	v_mfma_f32_16x16x32_bf16 v[106:109], v[158:161], v[166:169], v[106:109]
	v_mfma_f32_16x16x32_bf16 v[102:105], v[150:153], v[186:189], v[102:105]
	v_mfma_f32_16x16x32_bf16 v[98:101], v[158:161], v[186:189], v[98:101]
	v_mfma_f32_16x16x32_bf16 v[82:85], v[150:153], v[194:197], v[82:85]
	v_mfma_f32_16x16x32_bf16 v[74:77], v[158:161], v[194:197], v[74:77]
	v_mfma_f32_16x16x32_bf16 v[70:73], v[150:153], v[202:205], v[70:73]
	v_mfma_f32_16x16x32_bf16 v[66:69], v[158:161], v[202:205], v[66:69]
	v_mfma_f32_16x16x32_bf16 v[114:117], v[154:157], v[170:173], v[114:117]
	v_mfma_f32_16x16x32_bf16 v[106:109], v[162:165], v[170:173], v[106:109]
	v_mfma_f32_16x16x32_bf16 v[102:105], v[154:157], v[190:193], v[102:105]
	v_mfma_f32_16x16x32_bf16 v[98:101], v[162:165], v[190:193], v[98:101]
	v_mfma_f32_16x16x32_bf16 v[82:85], v[154:157], v[198:201], v[82:85]
	v_mfma_f32_16x16x32_bf16 v[74:77], v[162:165], v[198:201], v[74:77]
	s_setprio 2
	s_barrier
	v_mfma_f32_16x16x32_bf16 v[70:73], v[154:157], v[206:209], v[70:73]
	v_mfma_f32_16x16x32_bf16 v[66:69], v[162:165], v[206:209], v[66:69]
	s_setprio 0
	ds_read_b128 v[166:169], v183 offset:16384
	ds_read_b128 v[170:173], v183 offset:17408
	ds_read_b128 v[186:189], v183 offset:18432
	ds_read_b128 v[190:193], v183 offset:19456
	ds_read_b128 v[194:197], v183 offset:20480
	ds_read_b128 v[198:201], v183 offset:21504
	ds_read_b128 v[202:205], v183 offset:22528
	ds_read_b128 v[206:209], v183 offset:23552
	s_mov_b32 s70, m0
	s_mov_b32 m0, s27
	s_nop 0
	global_load_lds_dwordx4 v176, s[30:31]
	s_mov_b32 m0, s70
	s_nop 0
	s_mov_b32 s70, m0
	s_mov_b32 m0, s45
	s_nop 0
	global_load_lds_dwordx4 v178, s[30:31]
	s_mov_b32 m0, s70
	s_add_u32 s70, s30, 0x4000
	s_addc_u32 s71, s31, 0
	s_mov_b32 s73, m0
	s_mov_b32 m0, s46
	s_nop 0
	global_load_lds_dwordx4 v176, s[70:71]
	s_mov_b32 m0, s73
	s_nop 0
	s_mov_b32 s73, m0
	s_mov_b32 m0, s47
	s_nop 0
	global_load_lds_dwordx4 v178, s[70:71]
	s_mov_b32 m0, s73
	s_waitcnt vmcnt(4)
	s_waitcnt lgkmcnt(0)
	s_barrier
	s_setprio 1
	s_waitcnt lgkmcnt(7)
	v_mfma_f32_16x16x32_bf16 v[62:65], v[130:133], v[166:169], v[62:65]
	v_mfma_f32_16x16x32_bf16 v[58:61], v[138:141], v[166:169], v[58:61]
	s_waitcnt lgkmcnt(5)
	v_mfma_f32_16x16x32_bf16 v[46:49], v[130:133], v[186:189], v[46:49]
	v_mfma_f32_16x16x32_bf16 v[42:45], v[138:141], v[186:189], v[42:45]
	s_waitcnt lgkmcnt(3)
	v_mfma_f32_16x16x32_bf16 v[30:33], v[130:133], v[194:197], v[30:33]
	v_mfma_f32_16x16x32_bf16 v[26:29], v[138:141], v[194:197], v[26:29]
	s_waitcnt lgkmcnt(1)
	v_mfma_f32_16x16x32_bf16 v[14:17], v[130:133], v[202:205], v[14:17]
	v_mfma_f32_16x16x32_bf16 v[10:13], v[138:141], v[202:205], v[10:13]
	v_mfma_f32_16x16x32_bf16 v[62:65], v[134:137], v[170:173], v[62:65]
	v_mfma_f32_16x16x32_bf16 v[58:61], v[142:145], v[170:173], v[58:61]
	v_mfma_f32_16x16x32_bf16 v[46:49], v[134:137], v[190:193], v[46:49]
	v_mfma_f32_16x16x32_bf16 v[42:45], v[142:145], v[190:193], v[42:45]
	v_mfma_f32_16x16x32_bf16 v[30:33], v[134:137], v[198:201], v[30:33]
	v_mfma_f32_16x16x32_bf16 v[26:29], v[142:145], v[198:201], v[26:29]
	s_waitcnt lgkmcnt(0)
	v_mfma_f32_16x16x32_bf16 v[14:17], v[134:137], v[206:209], v[14:17]
	v_mfma_f32_16x16x32_bf16 v[10:13], v[142:145], v[206:209], v[10:13]
	s_setprio 0
	s_setprio 1
	v_mfma_f32_16x16x32_bf16 v[54:57], v[150:153], v[166:169], v[54:57]
	v_mfma_f32_16x16x32_bf16 v[50:53], v[158:161], v[166:169], v[50:53]
	v_mfma_f32_16x16x32_bf16 v[38:41], v[150:153], v[186:189], v[38:41]
	v_mfma_f32_16x16x32_bf16 v[34:37], v[158:161], v[186:189], v[34:37]
	v_mfma_f32_16x16x32_bf16 v[22:25], v[150:153], v[194:197], v[22:25]
	v_mfma_f32_16x16x32_bf16 v[18:21], v[158:161], v[194:197], v[18:21]
	v_mfma_f32_16x16x32_bf16 v[6:9], v[150:153], v[202:205], v[6:9]
	v_mfma_f32_16x16x32_bf16 v[2:5], v[158:161], v[202:205], v[2:5]
	v_mfma_f32_16x16x32_bf16 v[54:57], v[154:157], v[170:173], v[54:57]
	v_mfma_f32_16x16x32_bf16 v[50:53], v[162:165], v[170:173], v[50:53]
	v_mfma_f32_16x16x32_bf16 v[38:41], v[154:157], v[190:193], v[38:41]
	v_mfma_f32_16x16x32_bf16 v[34:37], v[162:165], v[190:193], v[34:37]
	v_mfma_f32_16x16x32_bf16 v[22:25], v[154:157], v[198:201], v[22:25]
	v_mfma_f32_16x16x32_bf16 v[18:21], v[162:165], v[198:201], v[18:21]
	s_setprio 2
	s_barrier
	v_mfma_f32_16x16x32_bf16 v[6:9], v[154:157], v[206:209], v[6:9]
	v_mfma_f32_16x16x32_bf16 v[2:5], v[162:165], v[206:209], v[2:5]
	s_setprio 0
	ds_read_b128 v[130:133], v184
	ds_read_b128 v[134:137], v184 offset:1024
	ds_read_b128 v[138:141], v184 offset:2048
	ds_read_b128 v[142:145], v184 offset:3072
	ds_read_b128 v[150:153], v185
	ds_read_b128 v[154:157], v185 offset:1024
	ds_read_b128 v[158:161], v185 offset:2048
	ds_read_b128 v[162:165], v185 offset:3072
	ds_read_b128 v[166:169], v183 offset:32768
	ds_read_b128 v[170:173], v183 offset:33792
	ds_read_b128 v[186:189], v183 offset:34816
	ds_read_b128 v[190:193], v183 offset:35840
	ds_read_b128 v[194:197], v183 offset:36864
	ds_read_b128 v[198:201], v183 offset:37888
	ds_read_b128 v[202:205], v183 offset:38912
	ds_read_b128 v[206:209], v183 offset:39936
	s_mov_b32 s70, m0
	s_mov_b32 m0, s44
	s_nop 0
	global_load_lds_dwordx4 v1, s[34:35]
	s_mov_b32 m0, s70
	s_nop 0
	s_mov_b32 s70, m0
	s_mov_b32 m0, s48
	s_nop 0
	global_load_lds_dwordx4 v177, s[34:35]
	s_mov_b32 m0, s70
	s_add_u32 s34, s34, 0x4000
	s_addc_u32 s35, s35, 0
	s_mov_b32 s70, m0
	s_mov_b32 m0, s49
	s_nop 0
	global_load_lds_dwordx4 v1, s[34:35]
	s_mov_b32 m0, s70
	s_nop 0
	s_mov_b32 s70, m0
	s_mov_b32 m0, s50
	s_nop 0
	global_load_lds_dwordx4 v177, s[34:35]
	s_mov_b32 m0, s70
	s_waitcnt vmcnt(8)
	s_waitcnt lgkmcnt(0)
	s_barrier
	s_setprio 1
	s_waitcnt lgkmcnt(7)
	v_mfma_f32_16x16x32_bf16 v[126:129], v[130:133], v[166:169], v[126:129]
	v_mfma_f32_16x16x32_bf16 v[122:125], v[138:141], v[166:169], v[122:125]
	s_waitcnt lgkmcnt(5)
	v_mfma_f32_16x16x32_bf16 v[118:121], v[130:133], v[186:189], v[118:121]
	v_mfma_f32_16x16x32_bf16 v[110:113], v[138:141], v[186:189], v[110:113]
	s_waitcnt lgkmcnt(3)
	v_mfma_f32_16x16x32_bf16 v[94:97], v[130:133], v[194:197], v[94:97]
	v_mfma_f32_16x16x32_bf16 v[90:93], v[138:141], v[194:197], v[90:93]
	s_waitcnt lgkmcnt(1)
	v_mfma_f32_16x16x32_bf16 v[86:89], v[130:133], v[202:205], v[86:89]
	v_mfma_f32_16x16x32_bf16 v[78:81], v[138:141], v[202:205], v[78:81]
	v_mfma_f32_16x16x32_bf16 v[126:129], v[134:137], v[170:173], v[126:129]
	v_mfma_f32_16x16x32_bf16 v[122:125], v[142:145], v[170:173], v[122:125]
	v_mfma_f32_16x16x32_bf16 v[118:121], v[134:137], v[190:193], v[118:121]
	v_mfma_f32_16x16x32_bf16 v[110:113], v[142:145], v[190:193], v[110:113]
	v_mfma_f32_16x16x32_bf16 v[94:97], v[134:137], v[198:201], v[94:97]
	v_mfma_f32_16x16x32_bf16 v[90:93], v[142:145], v[198:201], v[90:93]
	s_waitcnt lgkmcnt(0)
	v_mfma_f32_16x16x32_bf16 v[86:89], v[134:137], v[206:209], v[86:89]
	v_mfma_f32_16x16x32_bf16 v[78:81], v[142:145], v[206:209], v[78:81]
	s_setprio 0
	s_setprio 1
	v_mfma_f32_16x16x32_bf16 v[114:117], v[150:153], v[166:169], v[114:117]
	v_mfma_f32_16x16x32_bf16 v[106:109], v[158:161], v[166:169], v[106:109]
	v_mfma_f32_16x16x32_bf16 v[102:105], v[150:153], v[186:189], v[102:105]
	v_mfma_f32_16x16x32_bf16 v[98:101], v[158:161], v[186:189], v[98:101]
	v_mfma_f32_16x16x32_bf16 v[82:85], v[150:153], v[194:197], v[82:85]
	v_mfma_f32_16x16x32_bf16 v[74:77], v[158:161], v[194:197], v[74:77]
	v_mfma_f32_16x16x32_bf16 v[70:73], v[150:153], v[202:205], v[70:73]
	v_mfma_f32_16x16x32_bf16 v[66:69], v[158:161], v[202:205], v[66:69]
	v_mfma_f32_16x16x32_bf16 v[114:117], v[154:157], v[170:173], v[114:117]
	v_mfma_f32_16x16x32_bf16 v[106:109], v[162:165], v[170:173], v[106:109]
	v_mfma_f32_16x16x32_bf16 v[102:105], v[154:157], v[190:193], v[102:105]
	v_mfma_f32_16x16x32_bf16 v[98:101], v[162:165], v[190:193], v[98:101]
	v_mfma_f32_16x16x32_bf16 v[82:85], v[154:157], v[198:201], v[82:85]
	v_mfma_f32_16x16x32_bf16 v[74:77], v[162:165], v[198:201], v[74:77]
	s_setprio 2
	s_barrier
	v_mfma_f32_16x16x32_bf16 v[70:73], v[154:157], v[206:209], v[70:73]
	v_mfma_f32_16x16x32_bf16 v[66:69], v[162:165], v[206:209], v[66:69]
	s_setprio 0
	ds_read_b128 v[166:169], v183 offset:49152
	ds_read_b128 v[170:173], v183 offset:50176
	ds_read_b128 v[186:189], v183 offset:51200
	ds_read_b128 v[190:193], v183 offset:52224
	ds_read_b128 v[194:197], v183 offset:53248
	ds_read_b128 v[198:201], v183 offset:54272
	ds_read_b128 v[202:205], v183 offset:55296
	ds_read_b128 v[206:209], v183 offset:56320
	s_add_u32 s34, s30, 0x40000
	s_addc_u32 s35, s31, 0
	s_mov_b32 s70, m0
	s_mov_b32 m0, s51
	s_nop 0
	global_load_lds_dwordx4 v176, s[34:35]
	s_mov_b32 m0, s70
	s_add_u32 s30, s30, 0x44000
	s_mov_b32 s70, m0
	s_mov_b32 m0, s52
	s_nop 0
	global_load_lds_dwordx4 v178, s[34:35]
	s_mov_b32 m0, s70
	s_addc_u32 s31, s31, 0
	s_mov_b32 s34, m0
	s_mov_b32 m0, s53
	s_nop 0
	global_load_lds_dwordx4 v176, s[30:31]
	s_mov_b32 m0, s34
	s_nop 0
	s_mov_b32 s34, m0
	s_mov_b32 m0, s54
	s_nop 0
	global_load_lds_dwordx4 v178, s[30:31]
	s_mov_b32 m0, s34
	s_waitcnt vmcnt(4)
	s_waitcnt lgkmcnt(0)
	s_barrier
	s_setprio 1
	s_waitcnt lgkmcnt(7)
	v_mfma_f32_16x16x32_bf16 v[62:65], v[130:133], v[166:169], v[62:65]
	v_mfma_f32_16x16x32_bf16 v[58:61], v[138:141], v[166:169], v[58:61]
	s_waitcnt lgkmcnt(5)
	v_mfma_f32_16x16x32_bf16 v[46:49], v[130:133], v[186:189], v[46:49]
	v_mfma_f32_16x16x32_bf16 v[42:45], v[138:141], v[186:189], v[42:45]
	s_waitcnt lgkmcnt(3)
	v_mfma_f32_16x16x32_bf16 v[30:33], v[130:133], v[194:197], v[30:33]
	v_mfma_f32_16x16x32_bf16 v[26:29], v[138:141], v[194:197], v[26:29]
	s_waitcnt lgkmcnt(1)
	v_mfma_f32_16x16x32_bf16 v[14:17], v[130:133], v[202:205], v[14:17]
	v_mfma_f32_16x16x32_bf16 v[10:13], v[138:141], v[202:205], v[10:13]
	v_mfma_f32_16x16x32_bf16 v[62:65], v[134:137], v[170:173], v[62:65]
	v_mfma_f32_16x16x32_bf16 v[58:61], v[142:145], v[170:173], v[58:61]
	v_mfma_f32_16x16x32_bf16 v[46:49], v[134:137], v[190:193], v[46:49]
	v_mfma_f32_16x16x32_bf16 v[42:45], v[142:145], v[190:193], v[42:45]
	v_mfma_f32_16x16x32_bf16 v[30:33], v[134:137], v[198:201], v[30:33]
	v_mfma_f32_16x16x32_bf16 v[26:29], v[142:145], v[198:201], v[26:29]
	s_waitcnt lgkmcnt(0)
	v_mfma_f32_16x16x32_bf16 v[14:17], v[134:137], v[206:209], v[14:17]
	v_mfma_f32_16x16x32_bf16 v[10:13], v[142:145], v[206:209], v[10:13]
	s_setprio 0
	s_setprio 1
	v_mfma_f32_16x16x32_bf16 v[54:57], v[150:153], v[166:169], v[54:57]
	v_mfma_f32_16x16x32_bf16 v[50:53], v[158:161], v[166:169], v[50:53]
	v_mfma_f32_16x16x32_bf16 v[38:41], v[150:153], v[186:189], v[38:41]
	v_mfma_f32_16x16x32_bf16 v[34:37], v[158:161], v[186:189], v[34:37]
	v_mfma_f32_16x16x32_bf16 v[22:25], v[150:153], v[194:197], v[22:25]
	v_mfma_f32_16x16x32_bf16 v[18:21], v[158:161], v[194:197], v[18:21]
	v_mfma_f32_16x16x32_bf16 v[6:9], v[150:153], v[202:205], v[6:9]
	v_mfma_f32_16x16x32_bf16 v[2:5], v[158:161], v[202:205], v[2:5]
	v_mfma_f32_16x16x32_bf16 v[54:57], v[154:157], v[170:173], v[54:57]
	v_mfma_f32_16x16x32_bf16 v[50:53], v[162:165], v[170:173], v[50:53]
	v_mfma_f32_16x16x32_bf16 v[38:41], v[154:157], v[190:193], v[38:41]
	v_mfma_f32_16x16x32_bf16 v[34:37], v[162:165], v[190:193], v[34:37]
	v_mfma_f32_16x16x32_bf16 v[22:25], v[154:157], v[198:201], v[22:25]
	v_mfma_f32_16x16x32_bf16 v[18:21], v[162:165], v[198:201], v[18:21]
	s_setprio 2
	s_barrier
	v_mfma_f32_16x16x32_bf16 v[6:9], v[154:157], v[206:209], v[6:9]
	v_mfma_f32_16x16x32_bf16 v[2:5], v[162:165], v[206:209], v[2:5]
	s_setprio 0
	s_add_i32 s69, s69, 2
	s_add_u32 s65, s65, 0x80000
	s_addc_u32 s66, s66, 0
	s_add_u32 s28, s28, 0x400000
	s_addc_u32 s29, s29, 0
	s_add_u32 s67, s67, 0x400000
	s_addc_u32 s68, s68, 0
	s_cmpk_gt_u32 s69, 0x53
	s_cbranch_scc0 .LBB0_2792
	s_and_b64 vcc, exec, s[8:9]
	s_cbranch_vccz .LBB0_2795
	s_barrier
.LBB0_2795:
	v_lshl_or_b32 v130, s62, 8, v180
	v_ashrrev_i32_e32 v131, 31, v130
	v_lshl_add_u32 v132, s26, 8, v179
	v_lshlrev_b64 v[150:151], 1, v[130:131]
	v_ashrrev_i32_e32 v133, 31, v132
	v_lshl_add_u64 v[168:169], s[6:7], 0, v[150:151]
	v_lshlrev_b64 v[170:171], 12, v[132:133]
	v_lshl_add_u64 v[134:135], v[168:169], 0, v[170:171]
	s_ashr_i32 s19, s26, 31
	global_load_dwordx4 v[152:155], v[134:135], off
	global_load_dwordx4 v[156:159], v[134:135], off offset:256
	s_lshr_b32 s19, s19, 28
	v_or_b32_e32 v134, 16, v132
	s_add_i32 s19, s26, s19
	v_ashrrev_i32_e32 v135, 31, v134
	v_lshlrev_b64 v[206:207], 12, v[134:135]
	s_ashr_i32 s19, s19, 4
	v_lshl_add_u64 v[134:135], v[168:169], 0, v[206:207]
	s_mul_hi_i32 s21, s19, 0x12000
	s_mul_i32 s19, s19, 0x12000
	global_load_dwordx4 v[186:189], v[134:135], off
	s_add_u32 s28, s55, s19
	s_addc_u32 s29, s56, s21
	v_lshl_add_u64 v[130:131], v[130:131], 2, s[28:29]
	global_load_dwordx4 v[160:163], v[130:131], off
	global_load_dwordx4 v[190:193], v[130:131], off offset:16
	global_load_dwordx4 v[194:197], v[130:131], off offset:512
	global_load_dwordx4 v[198:201], v[130:131], off offset:528
	global_load_dwordx4 v[202:205], v[134:135], off offset:256
	v_or_b32_e32 v130, 32, v132
	v_or_b32_e32 v132, 48, v132
	v_ashrrev_i32_e32 v131, 31, v130
	v_ashrrev_i32_e32 v133, 31, v132
	v_lshlrev_b64 v[174:175], 12, v[130:131]
	v_lshlrev_b64 v[172:173], 12, v[132:133]
	v_lshl_add_u64 v[130:131], s[6:7], 0, v[170:171]
	v_lshl_add_u64 v[132:133], v[168:169], 0, v[174:175]
	v_lshl_add_u64 v[164:165], v[168:169], 0, v[172:173]
	v_lshl_add_u64 v[208:209], v[130:131], 0, v[150:151]
	global_load_dwordx4 v[142:145], v[132:133], off
	global_load_dwordx4 v[138:141], v[132:133], off offset:256
	global_load_dwordx4 v[134:137], v[164:165], off
	s_nop 0
	global_load_dwordx4 v[130:133], v[164:165], off offset:256
	s_andn2_b64 vcc, exec, s[2:3]
	s_mov_b64 s[2:3], -1
	s_waitcnt vmcnt(11)
	v_cvt_f32_f16_e32 v210, v152
	v_cvt_f32_f16_sdwa v211, v152 dst_sel:DWORD dst_unused:UNUSED_PAD src0_sel:WORD_1
	v_cvt_f32_f16_e32 v212, v153
	v_cvt_f32_f16_sdwa v213, v153 dst_sel:DWORD dst_unused:UNUSED_PAD src0_sel:WORD_1
	v_cvt_f32_f16_e32 v214, v154
	v_cvt_f32_f16_sdwa v215, v154 dst_sel:DWORD dst_unused:UNUSED_PAD src0_sel:WORD_1
	v_cvt_f32_f16_e32 v216, v155
	v_cvt_f32_f16_sdwa v217, v155 dst_sel:DWORD dst_unused:UNUSED_PAD src0_sel:WORD_1
	s_waitcnt vmcnt(10)
	v_cvt_f32_f16_e32 v218, v156
	v_cvt_f32_f16_sdwa v219, v156 dst_sel:DWORD dst_unused:UNUSED_PAD src0_sel:WORD_1
	v_cvt_f32_f16_e32 v220, v157
	v_cvt_f32_f16_sdwa v221, v157 dst_sel:DWORD dst_unused:UNUSED_PAD src0_sel:WORD_1
	v_cvt_f32_f16_e32 v222, v158
	v_cvt_f32_f16_sdwa v223, v158 dst_sel:DWORD dst_unused:UNUSED_PAD src0_sel:WORD_1
	v_cvt_f32_f16_e32 v224, v159
	v_cvt_f32_f16_sdwa v225, v159 dst_sel:DWORD dst_unused:UNUSED_PAD src0_sel:WORD_1
	s_waitcnt vmcnt(9)
	v_cvt_f32_f16_e32 v226, v186
	v_cvt_f32_f16_sdwa v227, v186 dst_sel:DWORD dst_unused:UNUSED_PAD src0_sel:WORD_1
	v_cvt_f32_f16_e32 v186, v187
	v_cvt_f32_f16_sdwa v187, v187 dst_sel:DWORD dst_unused:UNUSED_PAD src0_sel:WORD_1
	v_cvt_f32_f16_e32 v228, v188
	v_cvt_f32_f16_sdwa v229, v188 dst_sel:DWORD dst_unused:UNUSED_PAD src0_sel:WORD_1
	v_cvt_f32_f16_e32 v230, v189
	v_cvt_f32_f16_sdwa v231, v189 dst_sel:DWORD dst_unused:UNUSED_PAD src0_sel:WORD_1
	s_waitcnt vmcnt(8)
	v_pk_mul_f32 v[164:165], v[162:163], 0.5 op_sel_hi:[1,0]
	v_pk_mul_f32 v[166:167], v[160:161], 0.5 op_sel_hi:[1,0]
	s_waitcnt vmcnt(7)
	v_pk_mul_f32 v[160:161], v[192:193], 0.5 op_sel_hi:[1,0]
	v_pk_mul_f32 v[162:163], v[190:191], 0.5 op_sel_hi:[1,0]
	s_waitcnt vmcnt(6)
	v_pk_mul_f32 v[156:157], v[196:197], 0.5 op_sel_hi:[1,0]
	v_pk_mul_f32 v[158:159], v[194:195], 0.5 op_sel_hi:[1,0]
	s_waitcnt vmcnt(5)
	v_pk_mul_f32 v[152:153], v[200:201], 0.5 op_sel_hi:[1,0]
	v_pk_mul_f32 v[154:155], v[198:199], 0.5 op_sel_hi:[1,0]
	v_pk_fma_f32 v[128:129], v[128:129], v[164:165], v[212:213]
	v_pk_fma_f32 v[126:127], v[126:127], v[166:167], v[210:211]
	v_pk_fma_f32 v[124:125], v[124:125], v[160:161], v[216:217]
	v_pk_fma_f32 v[122:123], v[122:123], v[162:163], v[214:215]
	v_pk_fma_f32 v[116:117], v[116:117], v[156:157], v[220:221]
	v_pk_fma_f32 v[114:115], v[114:115], v[158:159], v[218:219]
	v_pk_fma_f32 v[190:191], v[108:109], v[152:153], v[224:225]
	v_pk_fma_f32 v[192:193], v[106:107], v[154:155], v[222:223]
	v_cvt_pk_f16_f32 v106, v126, v127
	v_cvt_pk_f16_f32 v107, v128, v129
	v_cvt_pk_f16_f32 v108, v122, v123
	v_cvt_pk_f16_f32 v109, v124, v125
	v_cvt_pk_f16_f32 v114, v114, v115
	v_cvt_pk_f16_f32 v115, v116, v117
	v_cvt_pk_f16_f32 v116, v192, v193
	v_cvt_pk_f16_f32 v117, v190, v191
	global_store_dwordx4 v[208:209], v[106:109], off
	global_store_dwordx4 v[208:209], v[114:117], off offset:256
	v_pk_fma_f32 v[110:111], v[110:111], v[162:163], v[228:229]
	v_pk_fma_f32 v[108:109], v[120:121], v[164:165], v[186:187]
	v_pk_fma_f32 v[106:107], v[118:119], v[166:167], v[226:227]
	v_pk_fma_f32 v[112:113], v[112:113], v[160:161], v[230:231]
	v_cvt_pk_f16_f32 v106, v106, v107
	v_cvt_pk_f16_f32 v107, v108, v109
	v_cvt_pk_f16_f32 v108, v110, v111
	v_lshl_add_u64 v[110:111], s[6:7], 0, v[206:207]
	v_cvt_pk_f16_f32 v109, v112, v113
	v_lshl_add_u64 v[110:111], v[110:111], 0, v[150:151]
	global_store_dwordx4 v[110:111], v[106:109], off
	s_waitcnt vmcnt(7)
	v_cvt_f32_f16_e32 v112, v204
	v_cvt_f32_f16_e32 v114, v205
	v_cvt_f32_f16_e32 v106, v202
	v_cvt_f32_f16_sdwa v107, v202 dst_sel:DWORD dst_unused:UNUSED_PAD src0_sel:WORD_1
	v_cvt_f32_f16_e32 v108, v203
	v_cvt_f32_f16_sdwa v109, v203 dst_sel:DWORD dst_unused:UNUSED_PAD src0_sel:WORD_1
	v_cvt_f32_f16_sdwa v115, v205 dst_sel:DWORD dst_unused:UNUSED_PAD src0_sel:WORD_1
	v_cvt_f32_f16_sdwa v113, v204 dst_sel:DWORD dst_unused:UNUSED_PAD src0_sel:WORD_1
	v_pk_fma_f32 v[102:103], v[102:103], v[158:159], v[106:107]
	v_pk_fma_f32 v[104:105], v[104:105], v[156:157], v[108:109]
	v_pk_fma_f32 v[106:107], v[100:101], v[152:153], v[114:115]
	v_pk_fma_f32 v[100:101], v[98:99], v[154:155], v[112:113]
	v_cvt_pk_f16_f32 v98, v102, v103
	v_cvt_pk_f16_f32 v99, v104, v105
	v_cvt_pk_f16_f32 v100, v100, v101
	v_cvt_pk_f16_f32 v101, v106, v107
	global_store_dwordx4 v[110:111], v[98:101], off offset:256
	v_lshl_add_u64 v[110:111], v[170:171], 0, s[10:11]
	v_lshl_add_u64 v[112:113], v[168:169], 0, v[110:111]
	s_waitcnt vmcnt(7)
	v_cvt_f32_f16_e32 v102, v142
	v_cvt_f32_f16_sdwa v103, v142 dst_sel:DWORD dst_unused:UNUSED_PAD src0_sel:WORD_1
	v_cvt_f32_f16_e32 v104, v143
	v_cvt_f32_f16_sdwa v105, v143 dst_sel:DWORD dst_unused:UNUSED_PAD src0_sel:WORD_1
	v_cvt_f32_f16_e32 v106, v144
	v_cvt_f32_f16_e32 v108, v145
	global_load_dwordx4 v[98:101], v[112:113], off
	v_cvt_f32_f16_sdwa v109, v145 dst_sel:DWORD dst_unused:UNUSED_PAD src0_sel:WORD_1
	v_cvt_f32_f16_sdwa v107, v144 dst_sel:DWORD dst_unused:UNUSED_PAD src0_sel:WORD_1
	v_pk_fma_f32 v[96:97], v[96:97], v[164:165], v[104:105]
	v_pk_fma_f32 v[94:95], v[94:95], v[166:167], v[102:103]
	v_pk_fma_f32 v[102:103], v[92:93], v[160:161], v[108:109]
	v_pk_fma_f32 v[92:93], v[90:91], v[162:163], v[106:107]
	v_cvt_pk_f16_f32 v90, v94, v95
	v_cvt_pk_f16_f32 v91, v96, v97
	v_cvt_pk_f16_f32 v92, v92, v93
	v_cvt_pk_f16_f32 v93, v102, v103
	v_lshl_add_u64 v[94:95], s[6:7], 0, v[174:175]
	s_waitcnt vmcnt(7)
	v_cvt_f32_f16_e32 v96, v138
	v_cvt_f32_f16_sdwa v97, v138 dst_sel:DWORD dst_unused:UNUSED_PAD src0_sel:WORD_1
	v_cvt_f32_f16_e32 v102, v139
	v_cvt_f32_f16_sdwa v103, v139 dst_sel:DWORD dst_unused:UNUSED_PAD src0_sel:WORD_1
	v_cvt_f32_f16_e32 v104, v140
	v_cvt_f32_f16_e32 v106, v141
	v_cvt_f32_f16_sdwa v107, v141 dst_sel:DWORD dst_unused:UNUSED_PAD src0_sel:WORD_1
	v_cvt_f32_f16_sdwa v105, v140 dst_sel:DWORD dst_unused:UNUSED_PAD src0_sel:WORD_1
	v_lshl_add_u64 v[94:95], v[94:95], 0, v[150:151]
	global_store_dwordx4 v[94:95], v[90:93], off
	global_load_dwordx4 v[90:93], v[112:113], off offset:256
	v_pk_fma_f32 v[84:85], v[84:85], v[156:157], v[102:103]
	v_pk_fma_f32 v[82:83], v[82:83], v[158:159], v[96:97]
	v_pk_fma_f32 v[96:97], v[76:77], v[152:153], v[106:107]
	v_pk_fma_f32 v[76:77], v[74:75], v[154:155], v[104:105]
	v_cvt_pk_f16_f32 v74, v82, v83
	v_cvt_pk_f16_f32 v75, v84, v85
	v_cvt_pk_f16_f32 v76, v76, v77
	v_cvt_pk_f16_f32 v77, v96, v97
	global_store_dwordx4 v[94:95], v[74:77], off offset:256
	v_lshl_add_u64 v[94:95], v[170:171], 0, s[12:13]
	v_lshl_add_u64 v[84:85], v[168:169], 0, v[94:95]
	s_waitcnt vmcnt(9)
	v_cvt_f32_f16_e32 v82, v134
	v_cvt_f32_f16_sdwa v83, v134 dst_sel:DWORD dst_unused:UNUSED_PAD src0_sel:WORD_1
	global_load_dwordx4 v[74:77], v[84:85], off
	v_cvt_f32_f16_e32 v96, v135
	v_cvt_f32_f16_sdwa v97, v135 dst_sel:DWORD dst_unused:UNUSED_PAD src0_sel:WORD_1
	v_cvt_f32_f16_e32 v102, v136
	v_cvt_f32_f16_e32 v104, v137
	v_cvt_f32_f16_sdwa v105, v137 dst_sel:DWORD dst_unused:UNUSED_PAD src0_sel:WORD_1
	v_cvt_f32_f16_sdwa v103, v136 dst_sel:DWORD dst_unused:UNUSED_PAD src0_sel:WORD_1
	v_pk_fma_f32 v[82:83], v[86:87], v[166:167], v[82:83]
	v_pk_fma_f32 v[88:89], v[88:89], v[164:165], v[96:97]
	v_pk_fma_f32 v[86:87], v[80:81], v[160:161], v[104:105]
	v_pk_fma_f32 v[80:81], v[78:79], v[162:163], v[102:103]
	v_cvt_pk_f16_f32 v78, v82, v83
	v_lshl_add_u64 v[82:83], s[6:7], 0, v[172:173]
	v_cvt_pk_f16_f32 v79, v88, v89
	v_cvt_pk_f16_f32 v80, v80, v81
	v_cvt_pk_f16_f32 v81, v86, v87
	v_lshl_add_u64 v[82:83], v[82:83], 0, v[150:151]
	global_store_dwordx4 v[82:83], v[78:81], off
	global_load_dwordx4 v[78:81], v[84:85], off offset:256
	s_waitcnt vmcnt(11)
	v_cvt_f32_f16_e32 v84, v131
	v_cvt_f32_f16_sdwa v85, v131 dst_sel:DWORD dst_unused:UNUSED_PAD src0_sel:WORD_1
	v_cvt_f32_f16_e32 v96, v133
	v_cvt_f32_f16_sdwa v97, v133 dst_sel:DWORD dst_unused:UNUSED_PAD src0_sel:WORD_1
	v_cvt_f32_f16_e32 v86, v130
	v_cvt_f32_f16_sdwa v87, v130 dst_sel:DWORD dst_unused:UNUSED_PAD src0_sel:WORD_1
	v_cvt_f32_f16_e32 v88, v132
	v_cvt_f32_f16_sdwa v89, v132 dst_sel:DWORD dst_unused:UNUSED_PAD src0_sel:WORD_1
	v_pk_fma_f32 v[72:73], v[72:73], v[156:157], v[84:85]
	v_pk_fma_f32 v[84:85], v[68:69], v[152:153], v[96:97]
	v_lshl_add_u64 v[96:97], v[170:171], 0, s[14:15]
	v_pk_fma_f32 v[70:71], v[70:71], v[158:159], v[86:87]
	v_lshl_add_u64 v[86:87], v[168:169], 0, v[96:97]
	v_pk_fma_f32 v[68:69], v[66:67], v[154:155], v[88:89]
	v_cvt_pk_f16_f32 v66, v70, v71
	v_cvt_pk_f16_f32 v67, v72, v73
	global_load_dwordx4 v[70:73], v[86:87], off
	v_cvt_pk_f16_f32 v68, v68, v69
	v_cvt_pk_f16_f32 v69, v84, v85
	global_store_dwordx4 v[82:83], v[66:69], off offset:256
	global_load_dwordx4 v[82:85], v[86:87], off offset:256
	v_lshl_add_u64 v[102:103], v[170:171], 0, s[16:17]
	v_lshl_add_u64 v[66:67], v[168:169], 0, v[102:103]
	global_load_dwordx4 v[86:89], v[66:67], off
	s_nop 0
	global_load_dwordx4 v[66:69], v[66:67], off offset:256
	s_waitcnt vmcnt(11)
	v_cvt_f32_f16_e32 v104, v98
	v_cvt_f32_f16_sdwa v105, v98 dst_sel:DWORD dst_unused:UNUSED_PAD src0_sel:WORD_1
	v_cvt_f32_f16_e32 v98, v99
	v_cvt_f32_f16_sdwa v99, v99 dst_sel:DWORD dst_unused:UNUSED_PAD src0_sel:WORD_1
	v_cvt_f32_f16_e32 v106, v100
	v_cvt_f32_f16_e32 v108, v101
	v_cvt_f32_f16_sdwa v109, v101 dst_sel:DWORD dst_unused:UNUSED_PAD src0_sel:WORD_1
	v_cvt_f32_f16_sdwa v107, v100 dst_sel:DWORD dst_unused:UNUSED_PAD src0_sel:WORD_1
	v_pk_fma_f32 v[62:63], v[62:63], v[166:167], v[104:105]
	v_pk_fma_f32 v[64:65], v[64:65], v[164:165], v[98:99]
	v_pk_fma_f32 v[98:99], v[60:61], v[160:161], v[108:109]
	v_pk_fma_f32 v[60:61], v[58:59], v[162:163], v[106:107]
	v_cvt_pk_f16_f32 v58, v62, v63
	v_lshl_add_u64 v[62:63], s[6:7], 0, v[110:111]
	v_cvt_pk_f16_f32 v59, v64, v65
	v_cvt_pk_f16_f32 v60, v60, v61
	v_cvt_pk_f16_f32 v61, v98, v99
	v_lshl_add_u64 v[62:63], v[62:63], 0, v[150:151]
	global_store_dwordx4 v[62:63], v[58:61], off
	s_waitcnt vmcnt(10)
	v_cvt_f32_f16_e32 v64, v92
	v_cvt_f32_f16_e32 v58, v90
	v_cvt_f32_f16_sdwa v59, v90 dst_sel:DWORD dst_unused:UNUSED_PAD src0_sel:WORD_1
	v_cvt_f32_f16_e32 v60, v91
	v_cvt_f32_f16_sdwa v61, v91 dst_sel:DWORD dst_unused:UNUSED_PAD src0_sel:WORD_1
	v_cvt_f32_f16_e32 v90, v93
	v_cvt_f32_f16_sdwa v91, v93 dst_sel:DWORD dst_unused:UNUSED_PAD src0_sel:WORD_1
	v_cvt_f32_f16_sdwa v65, v92 dst_sel:DWORD dst_unused:UNUSED_PAD src0_sel:WORD_1
	v_pk_fma_f32 v[56:57], v[56:57], v[156:157], v[60:61]
	v_pk_fma_f32 v[54:55], v[54:55], v[158:159], v[58:59]
	v_pk_fma_f32 v[58:59], v[52:53], v[152:153], v[90:91]
	v_pk_fma_f32 v[52:53], v[50:51], v[154:155], v[64:65]
	v_cvt_pk_f16_f32 v50, v54, v55
	v_cvt_pk_f16_f32 v51, v56, v57
	v_cvt_pk_f16_f32 v52, v52, v53
	v_cvt_pk_f16_f32 v53, v58, v59
	global_store_dwordx4 v[62:63], v[50:53], off offset:256
	s_waitcnt vmcnt(9)
	v_cvt_f32_f16_e32 v54, v76
	v_cvt_f32_f16_e32 v56, v77
	v_cvt_f32_f16_e32 v50, v74
	v_cvt_f32_f16_sdwa v51, v74 dst_sel:DWORD dst_unused:UNUSED_PAD src0_sel:WORD_1
	v_cvt_f32_f16_e32 v52, v75
	v_cvt_f32_f16_sdwa v53, v75 dst_sel:DWORD dst_unused:UNUSED_PAD src0_sel:WORD_1
	v_cvt_f32_f16_sdwa v57, v77 dst_sel:DWORD dst_unused:UNUSED_PAD src0_sel:WORD_1
	v_cvt_f32_f16_sdwa v55, v76 dst_sel:DWORD dst_unused:UNUSED_PAD src0_sel:WORD_1
	v_pk_fma_f32 v[46:47], v[46:47], v[166:167], v[50:51]
	v_pk_fma_f32 v[48:49], v[48:49], v[164:165], v[52:53]
	v_pk_fma_f32 v[50:51], v[44:45], v[160:161], v[56:57]
	v_pk_fma_f32 v[44:45], v[42:43], v[162:163], v[54:55]
	v_cvt_pk_f16_f32 v42, v46, v47
	v_lshl_add_u64 v[46:47], s[6:7], 0, v[94:95]
	v_cvt_pk_f16_f32 v43, v48, v49
	v_cvt_pk_f16_f32 v44, v44, v45
	v_cvt_pk_f16_f32 v45, v50, v51
	v_lshl_add_u64 v[46:47], v[46:47], 0, v[150:151]
	global_store_dwordx4 v[46:47], v[42:45], off
	s_waitcnt vmcnt(8)
	v_cvt_f32_f16_e32 v48, v80
	v_cvt_f32_f16_e32 v50, v81
	v_cvt_f32_f16_e32 v42, v78
	v_cvt_f32_f16_sdwa v43, v78 dst_sel:DWORD dst_unused:UNUSED_PAD src0_sel:WORD_1
	v_cvt_f32_f16_e32 v44, v79
	v_cvt_f32_f16_sdwa v45, v79 dst_sel:DWORD dst_unused:UNUSED_PAD src0_sel:WORD_1
	v_cvt_f32_f16_sdwa v51, v81 dst_sel:DWORD dst_unused:UNUSED_PAD src0_sel:WORD_1
	v_cvt_f32_f16_sdwa v49, v80 dst_sel:DWORD dst_unused:UNUSED_PAD src0_sel:WORD_1
	v_pk_fma_f32 v[38:39], v[38:39], v[158:159], v[42:43]
	v_pk_fma_f32 v[40:41], v[40:41], v[156:157], v[44:45]
	v_pk_fma_f32 v[42:43], v[36:37], v[152:153], v[50:51]
	v_pk_fma_f32 v[36:37], v[34:35], v[154:155], v[48:49]
	v_cvt_pk_f16_f32 v34, v38, v39
	v_cvt_pk_f16_f32 v35, v40, v41
	v_cvt_pk_f16_f32 v36, v36, v37
	v_cvt_pk_f16_f32 v37, v42, v43
	global_store_dwordx4 v[46:47], v[34:37], off offset:256
	s_waitcnt vmcnt(8)
	v_cvt_f32_f16_e32 v38, v72
	v_cvt_f32_f16_e32 v40, v73
	v_cvt_f32_f16_e32 v34, v70
	v_cvt_f32_f16_sdwa v35, v70 dst_sel:DWORD dst_unused:UNUSED_PAD src0_sel:WORD_1
	v_cvt_f32_f16_e32 v36, v71
	v_cvt_f32_f16_sdwa v37, v71 dst_sel:DWORD dst_unused:UNUSED_PAD src0_sel:WORD_1
	v_cvt_f32_f16_sdwa v41, v73 dst_sel:DWORD dst_unused:UNUSED_PAD src0_sel:WORD_1
	v_cvt_f32_f16_sdwa v39, v72 dst_sel:DWORD dst_unused:UNUSED_PAD src0_sel:WORD_1
	v_pk_fma_f32 v[30:31], v[30:31], v[166:167], v[34:35]
	v_pk_fma_f32 v[32:33], v[32:33], v[164:165], v[36:37]
	v_pk_fma_f32 v[34:35], v[28:29], v[160:161], v[40:41]
	v_pk_fma_f32 v[28:29], v[26:27], v[162:163], v[38:39]
	v_cvt_pk_f16_f32 v26, v30, v31
	v_lshl_add_u64 v[30:31], s[6:7], 0, v[96:97]
	v_cvt_pk_f16_f32 v27, v32, v33
	v_cvt_pk_f16_f32 v28, v28, v29
	v_cvt_pk_f16_f32 v29, v34, v35
	v_lshl_add_u64 v[30:31], v[30:31], 0, v[150:151]
	global_store_dwordx4 v[30:31], v[26:29], off
	s_waitcnt vmcnt(7)
	v_cvt_f32_f16_e32 v32, v84
	v_cvt_f32_f16_e32 v34, v85
	v_cvt_f32_f16_e32 v26, v82
	v_cvt_f32_f16_sdwa v27, v82 dst_sel:DWORD dst_unused:UNUSED_PAD src0_sel:WORD_1
	v_cvt_f32_f16_e32 v28, v83
	v_cvt_f32_f16_sdwa v29, v83 dst_sel:DWORD dst_unused:UNUSED_PAD src0_sel:WORD_1
	v_cvt_f32_f16_sdwa v35, v85 dst_sel:DWORD dst_unused:UNUSED_PAD src0_sel:WORD_1
	v_cvt_f32_f16_sdwa v33, v84 dst_sel:DWORD dst_unused:UNUSED_PAD src0_sel:WORD_1
	v_pk_fma_f32 v[22:23], v[22:23], v[158:159], v[26:27]
	v_pk_fma_f32 v[24:25], v[24:25], v[156:157], v[28:29]
	v_pk_fma_f32 v[26:27], v[20:21], v[152:153], v[34:35]
	v_pk_fma_f32 v[20:21], v[18:19], v[154:155], v[32:33]
	v_cvt_pk_f16_f32 v18, v22, v23
	v_cvt_pk_f16_f32 v19, v24, v25
	v_cvt_pk_f16_f32 v20, v20, v21
	v_cvt_pk_f16_f32 v21, v26, v27
	global_store_dwordx4 v[30:31], v[18:21], off offset:256
	s_waitcnt vmcnt(7)
	v_cvt_f32_f16_e32 v22, v88
	v_cvt_f32_f16_e32 v24, v89
	v_cvt_f32_f16_e32 v18, v86
	v_cvt_f32_f16_sdwa v19, v86 dst_sel:DWORD dst_unused:UNUSED_PAD src0_sel:WORD_1
	v_cvt_f32_f16_e32 v20, v87
	v_cvt_f32_f16_sdwa v21, v87 dst_sel:DWORD dst_unused:UNUSED_PAD src0_sel:WORD_1
	v_cvt_f32_f16_sdwa v25, v89 dst_sel:DWORD dst_unused:UNUSED_PAD src0_sel:WORD_1
	v_cvt_f32_f16_sdwa v23, v88 dst_sel:DWORD dst_unused:UNUSED_PAD src0_sel:WORD_1
	v_pk_fma_f32 v[14:15], v[14:15], v[166:167], v[18:19]
	v_pk_fma_f32 v[16:17], v[16:17], v[164:165], v[20:21]
	v_pk_fma_f32 v[18:19], v[12:13], v[160:161], v[24:25]
	v_pk_fma_f32 v[12:13], v[10:11], v[162:163], v[22:23]
	v_cvt_pk_f16_f32 v10, v14, v15
	v_lshl_add_u64 v[14:15], s[6:7], 0, v[102:103]
	v_cvt_pk_f16_f32 v11, v16, v17
	v_cvt_pk_f16_f32 v12, v12, v13
	v_cvt_pk_f16_f32 v13, v18, v19
	v_lshl_add_u64 v[14:15], v[14:15], 0, v[150:151]
	global_store_dwordx4 v[14:15], v[10:13], off
	s_waitcnt vmcnt(7)
	v_cvt_f32_f16_e32 v16, v68
	v_cvt_f32_f16_e32 v18, v69
	v_cvt_f32_f16_e32 v10, v66
	v_cvt_f32_f16_sdwa v11, v66 dst_sel:DWORD dst_unused:UNUSED_PAD src0_sel:WORD_1
	v_cvt_f32_f16_e32 v12, v67
	v_cvt_f32_f16_sdwa v13, v67 dst_sel:DWORD dst_unused:UNUSED_PAD src0_sel:WORD_1
	v_cvt_f32_f16_sdwa v19, v69 dst_sel:DWORD dst_unused:UNUSED_PAD src0_sel:WORD_1
	v_cvt_f32_f16_sdwa v17, v68 dst_sel:DWORD dst_unused:UNUSED_PAD src0_sel:WORD_1
	v_pk_fma_f32 v[6:7], v[6:7], v[158:159], v[10:11]
	v_pk_fma_f32 v[8:9], v[8:9], v[156:157], v[12:13]
	v_pk_fma_f32 v[10:11], v[4:5], v[152:153], v[18:19]
	v_pk_fma_f32 v[4:5], v[2:3], v[154:155], v[16:17]
	v_cvt_pk_f16_f32 v2, v6, v7
	v_cvt_pk_f16_f32 v3, v8, v9
	v_cvt_pk_f16_f32 v4, v4, v5
	v_cvt_pk_f16_f32 v5, v10, v11
	global_store_dwordx4 v[14:15], v[2:5], off offset:256
	s_cbranch_vccnz .LBB0_2784
	s_andn2_b64 vcc, exec, s[4:5]
	s_cbranch_vccnz .LBB0_2783
	s_mov_b32 s99, 1
	s_branch .LBB0_2783
